# rstd (row sum-of-squares -> rsqrt) memoised per token row in spare LDS across tiles/segments of the same rows
# speedup vs baseline: 1.0153x; 1.0153x over previous
; __global__ void __launch_bounds__(NTHR, 2) mega_kernel(Params p) {
;   __shared__ __attribute__((aligned(16))) unsigned char smem[SMEM_BYTES];
;   __shared__ uint4 xb_words;
;   if (threadIdx.x == 0) xb_words = make_uint4(0u, 0u, 0u, 0u);
;   __syncthreads();
_Z11mega_kernel6Params:
	s_mov_b32 s36, s2
	s_load_dwordx2 s[2:3], s[0:1], 0xd0
	s_load_dwordx4 s[4:7], s[0:1], 0xc0
	v_and_b32_e32 v220, 0x3ff, v0
	v_mov_b32_e32 v244, 0
	v_mov_b32_e32 v245, 0
	v_lshlrev_b32_e32 v246, 3, v220
	v_add_u32_e32 v246, 0x24010, v246
	ds_write_b64 v246, v[244:245]
	s_waitcnt lgkmcnt(0)
	v_writelane_b32 v241, s2, 0
	s_nop 1
	v_writelane_b32 v241, s3, 1
	v_writelane_b32 v241, s4, 2
	s_nop 1
	v_writelane_b32 v241, s5, 3
	v_writelane_b32 v241, s6, 4
	v_writelane_b32 v241, s7, 5
	v_cmp_eq_u32_e64 s[4:5], 0, v220
	s_mov_b64 s[2:3], exec
	s_nop 0
	v_writelane_b32 v241, s4, 6
	s_nop 1
	v_writelane_b32 v241, s5, 7
	s_and_b64 s[4:5], s[2:3], s[4:5]
	s_mov_b64 exec, s[4:5]
	s_cbranch_execz .LBB0_2
	v_mov_b32_e32 v2, 0
	v_mov_b32_e32 v3, v2
	v_mov_b32_e32 v4, v2
	v_mov_b32_e32 v5, v2
	v_mov_b32_e32 v1, 0x24000
	ds_write_b128 v1, v[2:5]

; DI void stage4(bf16_t* stg, int row, int col, const f32x4& v, float s) { *(u32x2*)(stg + row * STG_LD + col) = (u32x2){pk2(v[0] * s, v[1] * s), pk2(v[2] * s, v[3] * s)}; }
; DI float rstd_from16(const float* p, float inv_n) {
;   const f32x4 a = *(const f32x4*)p, b = *(const f32x4*)(p + 4), c = *(const f32x4*)(p + 8), d = *(const f32x4*)(p + 12);
;   const float s = ((a[0] + a[1]) + (a[2] + a[3])) + ((b[0] + b[1]) + (b[2] + b[3])) + ((c[0] + c[1]) + (c[2] + c[3])) + ((d[0] + d[1]) + (d[2] + d[3]));
;   return rsqrtf(s * inv_n + EPS_);
; template <bool SWAP> DI void inproj_tile(const Params& p, int layer, int tm, int tn, bf16_t* smem) {
;     ...
;         const int row = i * 16 + l15, t = trow0 + row; const float rs = rstd_from16(ssq + (size_t)t * 16, 1.f / 1024.f) * qs;
;         if (kind == 1) {
;           const float* rp = (const float*)(p.ws + O_ROPE8) + (size_t)t * 16 + (quad & 1) * 8;
;           f32x4 v, o;
; #pragma unroll
;           for (int r = 0; r < 4; ++r) { v[r] = acc[i][0][r] * rs; o[r] = __shfl_xor(v[r], 32); }
; #pragma unroll
;           for (int r = 0; r < 4; ++r) { const float cs = rp[2 * r], sn = rp[2 * r + 1]; v[r] = quad < 2 ? v[r] * cs - o[r] * sn : v[r] * cs + o[r] * sn; }
;           stage4(stg, row, quad * 4, v, 1.f);
;         } else stage4(stg, row, quad * 4, acc[i][0], rs);
.LBB0_200:
.LBB0_201:
	s_or_saveexec_b64 s[0:1], s[0:1]
	v_mov_b32_e32 v131, s33
	s_xor_b64 exec, exec, s[0:1]
	v_lshlrev_b32_e32 v130, 6, v136
	v_mov_b32_e32 v132, 0
	v_mov_b32_e32 v131, 0x3e38aa3b
	v_mov_b64_e32 v[128:129], 0x200
	v_mov_b64_e32 v[134:135], s[28:29]
	s_andn2_b64 s[2:3], s[2:3], exec
	s_andn2_b64 s[46:47], s[46:47], exec
	s_or_b64 exec, exec, s[0:1]
	v_or_b32_e32 v138, v147, v146
	v_ashrrev_i32_e32 v139, 31, v138
	v_lshlrev_b64 v[136:137], 6, v[138:139]
	v_lshl_add_u64 v[136:137], s[8:9], 0, v[136:137]
	s_xor_b64 s[48:49], s[2:3], -1
	v_cmp_gt_u32_e32 vcc, 32, v145
	v_bfe_u32 v244, v136, 6, 8
	v_lshlrev_b32_e32 v244, 3, v244
	v_add_u32_e32 v244, 0x24010, v244
	v_or_b32_e32 v246, 1, v136
	ds_read_b64 v[248:249], v244
	s_waitcnt lgkmcnt(0)
	v_cmp_ne_u32_e64 s[100:101], v248, v246
	s_nop 1
	s_and_saveexec_b64 s[98:99], s[100:101]
	s_cbranch_execz .LrcA0_0
	global_load_dwordx4 v[140:143], v[136:137], off
	global_load_dwordx4 v[148:151], v[136:137], off offset:16
	global_load_dwordx4 v[152:155], v[136:137], off offset:32
	global_load_dwordx4 v[156:159], v[136:137], off offset:48
	s_waitcnt vmcnt(3)
	v_mov_b32_e32 v136, v141
	v_mov_b32_e32 v137, v142
	v_mov_b32_e32 v141, v143
	s_waitcnt vmcnt(2)
	v_mov_b32_e32 v142, v149
	v_mov_b32_e32 v143, v150
	v_mov_b32_e32 v149, v151
	v_pk_add_f32 v[136:137], v[136:137], v[140:141]
	v_pk_add_f32 v[140:141], v[142:143], v[148:149]
	v_pk_add_f32 v[136:137], v[136:137], v[136:137] op_sel:[0,1] op_sel_hi:[1,0]
	v_pk_add_f32 v[140:141], v[140:141], v[140:141] op_sel:[0,1] op_sel_hi:[1,0]
	s_waitcnt vmcnt(1)
	v_add_f32_e32 v150, v152, v153
	v_add_f32_e32 v152, v154, v155
	s_waitcnt vmcnt(0)
	v_mov_b32_e32 v151, v158
	v_mov_b32_e32 v153, v159
	v_mov_b32_e32 v137, v156
	v_mov_b32_e32 v141, v157
	v_pk_add_f32 v[142:143], v[150:151], v[152:153]
	v_pk_add_f32 v[136:137], v[136:137], v[140:141]
	s_nop 0
	v_pk_add_f32 v[136:137], v[136:137], v[142:143]
	s_nop 0
	v_add_f32_e32 v136, v136, v137
	v_fmamk_f32 v136, v136, 0x3a800000, v185
	v_mul_f32_e32 v137, 0x4b800000, v136
	v_cmp_gt_f32_e64 s[0:1], s60, v136
	s_nop 1
	v_cndmask_b32_e64 v136, v136, v137, s[0:1]
	v_rsq_f32_e32 v136, v136
	s_nop 0
	v_mul_f32_e32 v137, 0x45800000, v136
	v_cndmask_b32_e64 v136, v136, v137, s[0:1]
	s_nop 0
	v_mov_b32_e32 v247, v136
	ds_write_b64 v244, v[246:247]
.LrcA0_0:
	s_or_b64 exec, exec, s[98:99]
	s_waitcnt vmcnt(0)
	v_cndmask_b32_e64 v136, v249, v136, s[100:101]
	v_mul_f32_e32 v136, v131, v136
	s_and_saveexec_b64 s[0:1], s[48:49]
	s_xor_b64 s[0:1], exec, s[0:1]
	v_pk_mul_f32 v[140:141], v[124:125], v[136:137] op_sel_hi:[1,0]
	v_pk_mul_f32 v[142:143], v[126:127], v[136:137] op_sel_hi:[1,0]
	v_cvt_pk_bf16_f32 v140, v140, v141
	s_or_saveexec_b64 s[2:3], s[0:1]
	v_lshlrev_b32_e32 v149, 3, v144
	v_and_b32_e32 v141, 8, v149
	v_lshlrev_b64 v[138:139], 4, v[138:139]
	v_lshlrev_b32_e32 v176, 2, v141
	s_xor_b64 exec, exec, s[2:3]
	s_cbranch_execz .LBB0_207
	v_lshl_add_u64 v[140:141], v[138:139], 2, s[30:31]
	v_lshl_add_u64 v[150:151], v[140:141], 0, v[176:177]
	global_load_dwordx4 v[140:143], v[150:151], off
	s_nop 0
	global_load_dwordx4 v[150:153], v[150:151], off offset:16
	v_and_b32_e32 v158, 64, v193
	v_xor_b32_e32 v148, 32, v193
	v_pk_mul_f32 v[154:155], v[124:125], v[136:137] op_sel_hi:[1,0]
	v_pk_mul_f32 v[156:157], v[126:127], v[136:137] op_sel_hi:[1,0]
	v_add_u32_e32 v137, 64, v158
	v_cmp_lt_i32_e64 s[0:1], v148, v137
	s_waitcnt vmcnt(1)
	v_mov_b32_e32 v163, v142
	v_cndmask_b32_e64 v137, v193, v148, s[0:1]
	v_lshlrev_b32_e32 v137, 2, v137
	ds_bpermute_b32 v158, v137, v154
	ds_bpermute_b32 v159, v137, v155
	ds_bpermute_b32 v160, v137, v156
	ds_bpermute_b32 v161, v137, v157
	v_mov_b32_e32 v142, v141
	s_waitcnt vmcnt(0)
	v_mov_b32_e32 v141, v152
	v_mov_b32_e32 v152, v151
	s_waitcnt lgkmcnt(2)
	v_pk_mul_f32 v[142:143], v[142:143], v[158:159]
	v_mov_b32_e32 v162, v140
	v_mov_b32_e32 v140, v150
	s_waitcnt lgkmcnt(0)
	v_pk_mul_f32 v[150:151], v[152:153], v[160:161]
	v_cndmask_b32_e64 v143, v143, -v143, vcc
	v_cndmask_b32_e64 v142, v142, -v142, vcc
	v_cndmask_b32_e64 v151, v151, -v151, vcc
	v_cndmask_b32_e64 v150, v150, -v150, vcc
	v_pk_fma_f32 v[152:153], v[154:155], v[162:163], v[142:143]
	v_pk_fma_f32 v[142:143], v[156:157], v[140:141], v[150:151]
	v_cvt_pk_bf16_f32 v140, v152, v153

; DI void stage4(bf16_t* stg, int row, int col, const f32x4& v, float s) { *(u32x2*)(stg + row * STG_LD + col) = (u32x2){pk2(v[0] * s, v[1] * s), pk2(v[2] * s, v[3] * s)}; }
; DI float rstd_from16(const float* p, float inv_n) {
;   const f32x4 a = *(const f32x4*)p, b = *(const f32x4*)(p + 4), c = *(const f32x4*)(p + 8), d = *(const f32x4*)(p + 12);
;   const float s = ((a[0] + a[1]) + (a[2] + a[3])) + ((b[0] + b[1]) + (b[2] + b[3])) + ((c[0] + c[1]) + (c[2] + c[3])) + ((d[0] + d[1]) + (d[2] + d[3]));
;   return rsqrtf(s * inv_n + EPS_);
; template <bool SWAP> DI void inproj_tile(const Params& p, int layer, int tm, int tn, bf16_t* smem) {
;     ...
;         const int row = i * 16 + l15, t = trow0 + row; const float rs = rstd_from16(ssq + (size_t)t * 16, 1.f / 1024.f) * qs;
;         if (kind == 1) {
;           const float* rp = (const float*)(p.ws + O_ROPE8) + (size_t)t * 16 + (quad & 1) * 8;
;           f32x4 v, o;
; #pragma unroll
;           for (int r = 0; r < 4; ++r) { v[r] = acc[i][0][r] * rs; o[r] = __shfl_xor(v[r], 32); }
; #pragma unroll
;           for (int r = 0; r < 4; ++r) { const float cs = rp[2 * r], sn = rp[2 * r + 1]; v[r] = quad < 2 ? v[r] * cs - o[r] * sn : v[r] * cs + o[r] * sn; }
;           stage4(stg, row, quad * 4, v, 1.f);
;         } else stage4(stg, row, quad * 4, acc[i][0], rs);
.LBB0_210:
	s_or_b64 exec, exec, s[50:51]
	v_or3_b32 v138, v146, v147, 16
	v_ashrrev_i32_e32 v139, 31, v138
	s_waitcnt lgkmcnt(0)
	v_lshlrev_b64 v[136:137], 6, v[138:139]
	v_lshl_add_u64 v[136:137], s[8:9], 0, v[136:137]
	v_bfe_u32 v244, v136, 6, 8
	v_lshlrev_b32_e32 v244, 3, v244
	v_add_u32_e32 v244, 0x24010, v244
	v_or_b32_e32 v246, 1, v136
	ds_read_b64 v[248:249], v244
	s_waitcnt lgkmcnt(0)
	v_cmp_ne_u32_e64 s[100:101], v248, v246
	s_nop 1
	s_and_saveexec_b64 s[98:99], s[100:101]
	s_cbranch_execz .LrcA0_1
	global_load_dwordx4 v[140:143], v[136:137], off
	global_load_dwordx4 v[152:155], v[136:137], off offset:16
	global_load_dwordx4 v[156:159], v[136:137], off offset:32
	global_load_dwordx4 v[160:163], v[136:137], off offset:48
	s_waitcnt vmcnt(3)
	v_mov_b32_e32 v136, v141
	v_mov_b32_e32 v137, v142
	v_mov_b32_e32 v141, v143
	s_waitcnt vmcnt(2)
	v_mov_b32_e32 v142, v153
	v_mov_b32_e32 v143, v154
	v_mov_b32_e32 v153, v155
	v_pk_add_f32 v[136:137], v[136:137], v[140:141]
	v_pk_add_f32 v[140:141], v[142:143], v[152:153]
	v_pk_add_f32 v[136:137], v[136:137], v[136:137] op_sel:[0,1] op_sel_hi:[1,0]
	v_pk_add_f32 v[140:141], v[140:141], v[140:141] op_sel:[0,1] op_sel_hi:[1,0]
	s_waitcnt vmcnt(1)
	v_add_f32_e32 v154, v156, v157
	v_add_f32_e32 v156, v158, v159
	s_waitcnt vmcnt(0)
	v_mov_b32_e32 v155, v162
	v_mov_b32_e32 v157, v163
	v_mov_b32_e32 v137, v160
	v_mov_b32_e32 v141, v161
	v_pk_add_f32 v[142:143], v[154:155], v[156:157]
	v_pk_add_f32 v[136:137], v[136:137], v[140:141]
	s_nop 0
	v_pk_add_f32 v[136:137], v[136:137], v[142:143]
	s_nop 0
	v_add_f32_e32 v136, v136, v137
	v_fmamk_f32 v136, v136, 0x3a800000, v185
	v_mul_f32_e32 v137, 0x4b800000, v136
	v_cmp_gt_f32_e64 s[2:3], s60, v136
	s_nop 1
	v_cndmask_b32_e64 v136, v136, v137, s[2:3]
	v_rsq_f32_e32 v136, v136
	s_nop 0
	v_mul_f32_e32 v137, 0x45800000, v136
	v_cndmask_b32_e64 v136, v136, v137, s[2:3]
	s_nop 0
	v_mov_b32_e32 v247, v136
	ds_write_b64 v244, v[246:247]
.LrcA0_1:
	s_or_b64 exec, exec, s[98:99]
	s_waitcnt vmcnt(0)
	v_cndmask_b32_e64 v136, v249, v136, s[100:101]
	v_mul_f32_e32 v136, v131, v136
	s_and_saveexec_b64 s[2:3], s[48:49]
	s_xor_b64 s[2:3], exec, s[2:3]
	v_pk_mul_f32 v[140:141], v[108:109], v[136:137] op_sel_hi:[1,0]
	v_pk_mul_f32 v[142:143], v[110:111], v[136:137] op_sel_hi:[1,0]
	v_cvt_pk_bf16_f32 v140, v140, v141
	s_or_saveexec_b64 s[50:51], s[2:3]
	v_lshlrev_b64 v[138:139], 4, v[138:139]
	s_xor_b64 exec, exec, s[50:51]
	s_cbranch_execz .LBB0_214
	v_lshl_add_u64 v[140:141], v[138:139], 2, s[30:31]
	v_lshl_add_u64 v[152:153], v[140:141], 0, v[176:177]
	global_load_dwordx4 v[140:143], v[152:153], off
	s_nop 0
	global_load_dwordx4 v[152:155], v[152:153], off offset:16
	v_and_b32_e32 v160, 64, v193
	v_xor_b32_e32 v149, 32, v193
	v_pk_mul_f32 v[156:157], v[108:109], v[136:137] op_sel_hi:[1,0]
	v_pk_mul_f32 v[158:159], v[110:111], v[136:137] op_sel_hi:[1,0]
	v_add_u32_e32 v137, 64, v160
	v_cmp_lt_i32_e64 s[2:3], v149, v137
	s_waitcnt vmcnt(1)
	v_mov_b32_e32 v165, v142
	v_cndmask_b32_e64 v137, v193, v149, s[2:3]
	v_lshlrev_b32_e32 v137, 2, v137
	ds_bpermute_b32 v160, v137, v156
	ds_bpermute_b32 v161, v137, v157
	ds_bpermute_b32 v162, v137, v158
	ds_bpermute_b32 v163, v137, v159
	v_mov_b32_e32 v142, v141
	s_waitcnt vmcnt(0)
	v_mov_b32_e32 v141, v154
	v_mov_b32_e32 v154, v153
	s_waitcnt lgkmcnt(2)
	v_pk_mul_f32 v[142:143], v[142:143], v[160:161]
	v_mov_b32_e32 v164, v140
	v_mov_b32_e32 v140, v152
	s_waitcnt lgkmcnt(0)
	v_pk_mul_f32 v[152:153], v[154:155], v[162:163]
	v_cndmask_b32_e64 v143, v143, -v143, vcc
	v_cndmask_b32_e64 v142, v142, -v142, vcc
	v_cndmask_b32_e64 v153, v153, -v153, vcc
	v_cndmask_b32_e64 v152, v152, -v152, vcc
	v_pk_fma_f32 v[154:155], v[156:157], v[164:165], v[142:143]
	v_pk_fma_f32 v[142:143], v[158:159], v[140:141], v[152:153]
	v_cvt_pk_bf16_f32 v140, v154, v155

; DI void stage4(bf16_t* stg, int row, int col, const f32x4& v, float s) { *(u32x2*)(stg + row * STG_LD + col) = (u32x2){pk2(v[0] * s, v[1] * s), pk2(v[2] * s, v[3] * s)}; }
; DI float rstd_from16(const float* p, float inv_n) {
;   const f32x4 a = *(const f32x4*)p, b = *(const f32x4*)(p + 4), c = *(const f32x4*)(p + 8), d = *(const f32x4*)(p + 12);
;   const float s = ((a[0] + a[1]) + (a[2] + a[3])) + ((b[0] + b[1]) + (b[2] + b[3])) + ((c[0] + c[1]) + (c[2] + c[3])) + ((d[0] + d[1]) + (d[2] + d[3]));
;   return rsqrtf(s * inv_n + EPS_);
; template <bool SWAP> DI void inproj_tile(const Params& p, int layer, int tm, int tn, bf16_t* smem) {
;     ...
;         const int row = i * 16 + l15, t = trow0 + row; const float rs = rstd_from16(ssq + (size_t)t * 16, 1.f / 1024.f) * qs;
;         if (kind == 1) {
;           const float* rp = (const float*)(p.ws + O_ROPE8) + (size_t)t * 16 + (quad & 1) * 8;
;           f32x4 v, o;
; #pragma unroll
;           for (int r = 0; r < 4; ++r) { v[r] = acc[i][0][r] * rs; o[r] = __shfl_xor(v[r], 32); }
; #pragma unroll
;           for (int r = 0; r < 4; ++r) { const float cs = rp[2 * r], sn = rp[2 * r + 1]; v[r] = quad < 2 ? v[r] * cs - o[r] * sn : v[r] * cs + o[r] * sn; }
;           stage4(stg, row, quad * 4, v, 1.f);
;         } else stage4(stg, row, quad * 4, acc[i][0], rs);
.LBB0_217:
	s_or_b64 exec, exec, s[50:51]
	v_or3_b32 v138, v146, v147, 32
	v_ashrrev_i32_e32 v139, 31, v138
	s_waitcnt lgkmcnt(0)
	v_lshlrev_b64 v[136:137], 6, v[138:139]
	v_lshl_add_u64 v[136:137], s[8:9], 0, v[136:137]
	v_bfe_u32 v244, v136, 6, 8
	v_lshlrev_b32_e32 v244, 3, v244
	v_add_u32_e32 v244, 0x24010, v244
	v_or_b32_e32 v246, 1, v136
	ds_read_b64 v[248:249], v244
	s_waitcnt lgkmcnt(0)
	v_cmp_ne_u32_e64 s[100:101], v248, v246
	s_nop 1
	s_and_saveexec_b64 s[98:99], s[100:101]
	s_cbranch_execz .LrcA0_2
	global_load_dwordx4 v[140:143], v[136:137], off
	global_load_dwordx4 v[152:155], v[136:137], off offset:16
	global_load_dwordx4 v[156:159], v[136:137], off offset:32
	global_load_dwordx4 v[160:163], v[136:137], off offset:48
	s_waitcnt vmcnt(3)
	v_mov_b32_e32 v136, v141
	v_mov_b32_e32 v137, v142
	v_mov_b32_e32 v141, v143
	s_waitcnt vmcnt(2)
	v_mov_b32_e32 v142, v153
	v_mov_b32_e32 v143, v154
	v_mov_b32_e32 v153, v155
	v_pk_add_f32 v[136:137], v[136:137], v[140:141]
	v_pk_add_f32 v[140:141], v[142:143], v[152:153]
	v_pk_add_f32 v[136:137], v[136:137], v[136:137] op_sel:[0,1] op_sel_hi:[1,0]
	v_pk_add_f32 v[140:141], v[140:141], v[140:141] op_sel:[0,1] op_sel_hi:[1,0]
	s_waitcnt vmcnt(1)
	v_add_f32_e32 v154, v156, v157
	v_add_f32_e32 v156, v158, v159
	s_waitcnt vmcnt(0)
	v_mov_b32_e32 v155, v162
	v_mov_b32_e32 v157, v163
	v_mov_b32_e32 v137, v160
	v_mov_b32_e32 v141, v161
	v_pk_add_f32 v[142:143], v[154:155], v[156:157]
	v_pk_add_f32 v[136:137], v[136:137], v[140:141]
	s_nop 0
	v_pk_add_f32 v[136:137], v[136:137], v[142:143]
	s_nop 0
	v_add_f32_e32 v136, v136, v137
	v_fmamk_f32 v136, v136, 0x3a800000, v185
	v_mul_f32_e32 v137, 0x4b800000, v136
	v_cmp_gt_f32_e64 s[2:3], s60, v136
	s_nop 1
	v_cndmask_b32_e64 v136, v136, v137, s[2:3]
	v_rsq_f32_e32 v136, v136
	s_nop 0
	v_mul_f32_e32 v137, 0x45800000, v136
	v_cndmask_b32_e64 v136, v136, v137, s[2:3]
	s_nop 0
	v_mov_b32_e32 v247, v136
	ds_write_b64 v244, v[246:247]
.LrcA0_2:
	s_or_b64 exec, exec, s[98:99]
	s_waitcnt vmcnt(0)
	v_cndmask_b32_e64 v136, v249, v136, s[100:101]
	v_mul_f32_e32 v136, v131, v136
	s_and_saveexec_b64 s[2:3], s[48:49]
	s_xor_b64 s[2:3], exec, s[2:3]
	v_pk_mul_f32 v[140:141], v[92:93], v[136:137] op_sel_hi:[1,0]
	v_pk_mul_f32 v[142:143], v[94:95], v[136:137] op_sel_hi:[1,0]
	v_cvt_pk_bf16_f32 v140, v140, v141
	s_or_saveexec_b64 s[50:51], s[2:3]
	v_lshlrev_b64 v[138:139], 4, v[138:139]
	s_xor_b64 exec, exec, s[50:51]
	s_cbranch_execz .LBB0_221
	v_lshl_add_u64 v[140:141], v[138:139], 2, s[30:31]
	v_lshl_add_u64 v[152:153], v[140:141], 0, v[176:177]
	global_load_dwordx4 v[140:143], v[152:153], off
	s_nop 0
	global_load_dwordx4 v[152:155], v[152:153], off offset:16
	v_and_b32_e32 v161, 64, v193
	v_xor_b32_e32 v160, 32, v193
	v_pk_mul_f32 v[156:157], v[92:93], v[136:137] op_sel_hi:[1,0]
	v_pk_mul_f32 v[158:159], v[94:95], v[136:137] op_sel_hi:[1,0]
	v_add_u32_e32 v137, 64, v161
	v_cmp_lt_i32_e64 s[2:3], v160, v137
	s_waitcnt vmcnt(1)
	v_mov_b32_e32 v165, v142
	v_cndmask_b32_e64 v137, v193, v160, s[2:3]
	v_lshlrev_b32_e32 v137, 2, v137
	ds_bpermute_b32 v160, v137, v156
	ds_bpermute_b32 v161, v137, v157
	ds_bpermute_b32 v162, v137, v158
	ds_bpermute_b32 v163, v137, v159
	v_mov_b32_e32 v142, v141
	s_waitcnt vmcnt(0)
	v_mov_b32_e32 v141, v154
	v_mov_b32_e32 v154, v153
	s_waitcnt lgkmcnt(2)
	v_pk_mul_f32 v[142:143], v[142:143], v[160:161]
	v_mov_b32_e32 v164, v140
	v_mov_b32_e32 v140, v152
	s_waitcnt lgkmcnt(0)
	v_pk_mul_f32 v[152:153], v[154:155], v[162:163]
	v_cndmask_b32_e64 v143, v143, -v143, vcc
	v_cndmask_b32_e64 v142, v142, -v142, vcc
	v_cndmask_b32_e64 v153, v153, -v153, vcc
	v_cndmask_b32_e64 v152, v152, -v152, vcc
	v_pk_fma_f32 v[154:155], v[156:157], v[164:165], v[142:143]
	v_pk_fma_f32 v[142:143], v[158:159], v[140:141], v[152:153]
	v_cvt_pk_bf16_f32 v140, v154, v155

; DI void stage4(bf16_t* stg, int row, int col, const f32x4& v, float s) { *(u32x2*)(stg + row * STG_LD + col) = (u32x2){pk2(v[0] * s, v[1] * s), pk2(v[2] * s, v[3] * s)}; }
; DI float rstd_from16(const float* p, float inv_n) {
;   const f32x4 a = *(const f32x4*)p, b = *(const f32x4*)(p + 4), c = *(const f32x4*)(p + 8), d = *(const f32x4*)(p + 12);
;   const float s = ((a[0] + a[1]) + (a[2] + a[3])) + ((b[0] + b[1]) + (b[2] + b[3])) + ((c[0] + c[1]) + (c[2] + c[3])) + ((d[0] + d[1]) + (d[2] + d[3]));
;   return rsqrtf(s * inv_n + EPS_);
; template <bool SWAP> DI void inproj_tile(const Params& p, int layer, int tm, int tn, bf16_t* smem) {
;     ...
;         const int row = i * 16 + l15, t = trow0 + row; const float rs = rstd_from16(ssq + (size_t)t * 16, 1.f / 1024.f) * qs;
;         if (kind == 1) {
;           const float* rp = (const float*)(p.ws + O_ROPE8) + (size_t)t * 16 + (quad & 1) * 8;
;           f32x4 v, o;
; #pragma unroll
;           for (int r = 0; r < 4; ++r) { v[r] = acc[i][0][r] * rs; o[r] = __shfl_xor(v[r], 32); }
; #pragma unroll
;           for (int r = 0; r < 4; ++r) { const float cs = rp[2 * r], sn = rp[2 * r + 1]; v[r] = quad < 2 ? v[r] * cs - o[r] * sn : v[r] * cs + o[r] * sn; }
;           stage4(stg, row, quad * 4, v, 1.f);
;         } else stage4(stg, row, quad * 4, acc[i][0], rs);
.LBB0_224:
	s_or_b64 exec, exec, s[50:51]
	v_or3_b32 v138, v146, v147, 48
	v_ashrrev_i32_e32 v139, 31, v138
	s_waitcnt lgkmcnt(0)
	v_lshlrev_b64 v[136:137], 6, v[138:139]
	v_lshl_add_u64 v[136:137], s[8:9], 0, v[136:137]
	v_bfe_u32 v244, v136, 6, 8
	v_lshlrev_b32_e32 v244, 3, v244
	v_add_u32_e32 v244, 0x24010, v244
	v_or_b32_e32 v246, 1, v136
	ds_read_b64 v[248:249], v244
	s_waitcnt lgkmcnt(0)
	v_cmp_ne_u32_e64 s[100:101], v248, v246
	s_nop 1
	s_and_saveexec_b64 s[98:99], s[100:101]
	s_cbranch_execz .LrcA0_3
	global_load_dwordx4 v[140:143], v[136:137], off
	global_load_dwordx4 v[152:155], v[136:137], off offset:16
	global_load_dwordx4 v[156:159], v[136:137], off offset:32
	global_load_dwordx4 v[160:163], v[136:137], off offset:48
	s_waitcnt vmcnt(3)
	v_mov_b32_e32 v136, v141
	v_mov_b32_e32 v137, v142
	v_mov_b32_e32 v141, v143
	s_waitcnt vmcnt(2)
	v_mov_b32_e32 v142, v153
	v_mov_b32_e32 v143, v154
	v_mov_b32_e32 v153, v155
	v_pk_add_f32 v[136:137], v[136:137], v[140:141]
	v_pk_add_f32 v[140:141], v[142:143], v[152:153]
	v_pk_add_f32 v[136:137], v[136:137], v[136:137] op_sel:[0,1] op_sel_hi:[1,0]
	v_pk_add_f32 v[140:141], v[140:141], v[140:141] op_sel:[0,1] op_sel_hi:[1,0]
	s_waitcnt vmcnt(1)
	v_add_f32_e32 v154, v156, v157
	v_add_f32_e32 v156, v158, v159
	s_waitcnt vmcnt(0)
	v_mov_b32_e32 v155, v162
	v_mov_b32_e32 v157, v163
	v_mov_b32_e32 v137, v160
	v_mov_b32_e32 v141, v161
	v_pk_add_f32 v[142:143], v[154:155], v[156:157]
	v_pk_add_f32 v[136:137], v[136:137], v[140:141]
	s_nop 0
	v_pk_add_f32 v[136:137], v[136:137], v[142:143]
	s_nop 0
	v_add_f32_e32 v136, v136, v137
	v_fmamk_f32 v136, v136, 0x3a800000, v185
	v_mul_f32_e32 v137, 0x4b800000, v136
	v_cmp_gt_f32_e64 s[2:3], s60, v136
	s_nop 1
	v_cndmask_b32_e64 v136, v136, v137, s[2:3]
	v_rsq_f32_e32 v136, v136
	s_nop 0
	v_mul_f32_e32 v137, 0x45800000, v136
	v_cndmask_b32_e64 v136, v136, v137, s[2:3]
	s_nop 0
	v_mov_b32_e32 v247, v136
	ds_write_b64 v244, v[246:247]
.LrcA0_3:
	s_or_b64 exec, exec, s[98:99]
	s_waitcnt vmcnt(0)
	v_cndmask_b32_e64 v136, v249, v136, s[100:101]
	v_mul_f32_e32 v136, v131, v136
	s_and_saveexec_b64 s[2:3], s[48:49]
	s_xor_b64 s[2:3], exec, s[2:3]
	v_pk_mul_f32 v[140:141], v[76:77], v[136:137] op_sel_hi:[1,0]
	v_pk_mul_f32 v[142:143], v[78:79], v[136:137] op_sel_hi:[1,0]
	v_cvt_pk_bf16_f32 v140, v140, v141
	s_or_saveexec_b64 s[50:51], s[2:3]
	v_lshlrev_b64 v[138:139], 4, v[138:139]
	s_xor_b64 exec, exec, s[50:51]
	s_cbranch_execz .LBB0_228
	v_lshl_add_u64 v[140:141], v[138:139], 2, s[30:31]
	v_lshl_add_u64 v[152:153], v[140:141], 0, v[176:177]
	global_load_dwordx4 v[140:143], v[152:153], off
	s_nop 0
	global_load_dwordx4 v[152:155], v[152:153], off offset:16
	v_and_b32_e32 v161, 64, v193
	v_xor_b32_e32 v160, 32, v193
	v_pk_mul_f32 v[156:157], v[76:77], v[136:137] op_sel_hi:[1,0]
	v_pk_mul_f32 v[158:159], v[78:79], v[136:137] op_sel_hi:[1,0]
	v_add_u32_e32 v137, 64, v161
	v_cmp_lt_i32_e64 s[2:3], v160, v137
	s_waitcnt vmcnt(1)
	v_mov_b32_e32 v165, v142
	v_cndmask_b32_e64 v137, v193, v160, s[2:3]
	v_lshlrev_b32_e32 v137, 2, v137
	ds_bpermute_b32 v160, v137, v156
	ds_bpermute_b32 v161, v137, v157
	ds_bpermute_b32 v162, v137, v158
	ds_bpermute_b32 v163, v137, v159
	v_mov_b32_e32 v142, v141
	s_waitcnt vmcnt(0)
	v_mov_b32_e32 v141, v154
	v_mov_b32_e32 v154, v153
	s_waitcnt lgkmcnt(2)
	v_pk_mul_f32 v[142:143], v[142:143], v[160:161]
	v_mov_b32_e32 v164, v140
	v_mov_b32_e32 v140, v152
	s_waitcnt lgkmcnt(0)
	v_pk_mul_f32 v[152:153], v[154:155], v[162:163]
	v_cndmask_b32_e64 v143, v143, -v143, vcc
	v_cndmask_b32_e64 v142, v142, -v142, vcc
	v_cndmask_b32_e64 v153, v153, -v153, vcc
	v_cndmask_b32_e64 v152, v152, -v152, vcc
	v_pk_fma_f32 v[154:155], v[156:157], v[164:165], v[142:143]
	v_pk_fma_f32 v[142:143], v[158:159], v[140:141], v[152:153]
	v_cvt_pk_bf16_f32 v140, v154, v155

; DI void stage4(bf16_t* stg, int row, int col, const f32x4& v, float s) { *(u32x2*)(stg + row * STG_LD + col) = (u32x2){pk2(v[0] * s, v[1] * s), pk2(v[2] * s, v[3] * s)}; }
; DI float rstd_from16(const float* p, float inv_n) {
;   const f32x4 a = *(const f32x4*)p, b = *(const f32x4*)(p + 4), c = *(const f32x4*)(p + 8), d = *(const f32x4*)(p + 12);
;   const float s = ((a[0] + a[1]) + (a[2] + a[3])) + ((b[0] + b[1]) + (b[2] + b[3])) + ((c[0] + c[1]) + (c[2] + c[3])) + ((d[0] + d[1]) + (d[2] + d[3]));
;   return rsqrtf(s * inv_n + EPS_);
; template <bool SWAP> DI void inproj_tile(const Params& p, int layer, int tm, int tn, bf16_t* smem) {
;     ...
;         const int row = i * 16 + l15, t = trow0 + row; const float rs = rstd_from16(ssq + (size_t)t * 16, 1.f / 1024.f) * qs;
;         if (kind == 1) {
;           const float* rp = (const float*)(p.ws + O_ROPE8) + (size_t)t * 16 + (quad & 1) * 8;
;           f32x4 v, o;
; #pragma unroll
;           for (int r = 0; r < 4; ++r) { v[r] = acc[i][0][r] * rs; o[r] = __shfl_xor(v[r], 32); }
; #pragma unroll
;           for (int r = 0; r < 4; ++r) { const float cs = rp[2 * r], sn = rp[2 * r + 1]; v[r] = quad < 2 ? v[r] * cs - o[r] * sn : v[r] * cs + o[r] * sn; }
;           stage4(stg, row, quad * 4, v, 1.f);
;         } else stage4(stg, row, quad * 4, acc[i][0], rs);
.LBB0_231:
	s_or_b64 exec, exec, s[50:51]
	v_or3_b32 v138, v146, v147, 64
	v_ashrrev_i32_e32 v139, 31, v138
	s_waitcnt lgkmcnt(0)
	v_lshlrev_b64 v[136:137], 6, v[138:139]
	v_lshl_add_u64 v[136:137], s[8:9], 0, v[136:137]
	v_bfe_u32 v244, v136, 6, 8
	v_lshlrev_b32_e32 v244, 3, v244
	v_add_u32_e32 v244, 0x24010, v244
	v_or_b32_e32 v246, 1, v136
	ds_read_b64 v[248:249], v244
	s_waitcnt lgkmcnt(0)
	v_cmp_ne_u32_e64 s[100:101], v248, v246
	s_nop 1
	s_and_saveexec_b64 s[98:99], s[100:101]
	s_cbranch_execz .LrcA0_4
	global_load_dwordx4 v[140:143], v[136:137], off
	global_load_dwordx4 v[152:155], v[136:137], off offset:16
	global_load_dwordx4 v[156:159], v[136:137], off offset:32
	global_load_dwordx4 v[160:163], v[136:137], off offset:48
	s_waitcnt vmcnt(3)
	v_mov_b32_e32 v136, v141
	v_mov_b32_e32 v137, v142
	v_mov_b32_e32 v141, v143
	s_waitcnt vmcnt(2)
	v_mov_b32_e32 v142, v153
	v_mov_b32_e32 v143, v154
	v_mov_b32_e32 v153, v155
	v_pk_add_f32 v[136:137], v[136:137], v[140:141]
	v_pk_add_f32 v[140:141], v[142:143], v[152:153]
	v_pk_add_f32 v[136:137], v[136:137], v[136:137] op_sel:[0,1] op_sel_hi:[1,0]
	v_pk_add_f32 v[140:141], v[140:141], v[140:141] op_sel:[0,1] op_sel_hi:[1,0]
	s_waitcnt vmcnt(1)
	v_add_f32_e32 v154, v156, v157
	v_add_f32_e32 v156, v158, v159
	s_waitcnt vmcnt(0)
	v_mov_b32_e32 v155, v162
	v_mov_b32_e32 v157, v163
	v_mov_b32_e32 v137, v160
	v_mov_b32_e32 v141, v161
	v_pk_add_f32 v[142:143], v[154:155], v[156:157]
	v_pk_add_f32 v[136:137], v[136:137], v[140:141]
	s_nop 0
	v_pk_add_f32 v[136:137], v[136:137], v[142:143]
	s_nop 0
	v_add_f32_e32 v136, v136, v137
	v_fmamk_f32 v136, v136, 0x3a800000, v185
	v_mul_f32_e32 v137, 0x4b800000, v136
	v_cmp_gt_f32_e64 s[2:3], s60, v136
	s_nop 1
	v_cndmask_b32_e64 v136, v136, v137, s[2:3]
	v_rsq_f32_e32 v136, v136
	s_nop 0
	v_mul_f32_e32 v137, 0x45800000, v136
	v_cndmask_b32_e64 v136, v136, v137, s[2:3]
	s_nop 0
	v_mov_b32_e32 v247, v136
	ds_write_b64 v244, v[246:247]
.LrcA0_4:
	s_or_b64 exec, exec, s[98:99]
	s_waitcnt vmcnt(0)
	v_cndmask_b32_e64 v136, v249, v136, s[100:101]
	v_mul_f32_e32 v136, v131, v136
	s_and_saveexec_b64 s[2:3], s[48:49]
	s_xor_b64 s[2:3], exec, s[2:3]
	v_pk_mul_f32 v[140:141], v[60:61], v[136:137] op_sel_hi:[1,0]
	v_pk_mul_f32 v[142:143], v[62:63], v[136:137] op_sel_hi:[1,0]
	v_cvt_pk_bf16_f32 v140, v140, v141
	s_or_saveexec_b64 s[50:51], s[2:3]
	v_lshlrev_b64 v[138:139], 4, v[138:139]
	s_xor_b64 exec, exec, s[50:51]
	s_cbranch_execz .LBB0_235
	v_lshl_add_u64 v[140:141], v[138:139], 2, s[30:31]
	v_lshl_add_u64 v[152:153], v[140:141], 0, v[176:177]
	global_load_dwordx4 v[140:143], v[152:153], off
	s_nop 0
	global_load_dwordx4 v[152:155], v[152:153], off offset:16
	v_and_b32_e32 v161, 64, v193
	v_xor_b32_e32 v160, 32, v193
	v_pk_mul_f32 v[156:157], v[60:61], v[136:137] op_sel_hi:[1,0]
	v_pk_mul_f32 v[158:159], v[62:63], v[136:137] op_sel_hi:[1,0]
	v_add_u32_e32 v137, 64, v161
	v_cmp_lt_i32_e64 s[2:3], v160, v137
	s_waitcnt vmcnt(1)
	v_mov_b32_e32 v165, v142
	v_cndmask_b32_e64 v137, v193, v160, s[2:3]
	v_lshlrev_b32_e32 v137, 2, v137
	ds_bpermute_b32 v160, v137, v156
	ds_bpermute_b32 v161, v137, v157
	ds_bpermute_b32 v162, v137, v158
	ds_bpermute_b32 v163, v137, v159
	v_mov_b32_e32 v142, v141
	s_waitcnt vmcnt(0)
	v_mov_b32_e32 v141, v154
	v_mov_b32_e32 v154, v153
	s_waitcnt lgkmcnt(2)
	v_pk_mul_f32 v[142:143], v[142:143], v[160:161]
	v_mov_b32_e32 v164, v140
	v_mov_b32_e32 v140, v152
	s_waitcnt lgkmcnt(0)
	v_pk_mul_f32 v[152:153], v[154:155], v[162:163]
	v_cndmask_b32_e64 v143, v143, -v143, vcc
	v_cndmask_b32_e64 v142, v142, -v142, vcc
	v_cndmask_b32_e64 v153, v153, -v153, vcc
	v_cndmask_b32_e64 v152, v152, -v152, vcc
	v_pk_fma_f32 v[154:155], v[156:157], v[164:165], v[142:143]
	v_pk_fma_f32 v[142:143], v[158:159], v[140:141], v[152:153]
	v_cvt_pk_bf16_f32 v140, v154, v155

; DI void stage4(bf16_t* stg, int row, int col, const f32x4& v, float s) { *(u32x2*)(stg + row * STG_LD + col) = (u32x2){pk2(v[0] * s, v[1] * s), pk2(v[2] * s, v[3] * s)}; }
; DI float rstd_from16(const float* p, float inv_n) {
;   const f32x4 a = *(const f32x4*)p, b = *(const f32x4*)(p + 4), c = *(const f32x4*)(p + 8), d = *(const f32x4*)(p + 12);
;   const float s = ((a[0] + a[1]) + (a[2] + a[3])) + ((b[0] + b[1]) + (b[2] + b[3])) + ((c[0] + c[1]) + (c[2] + c[3])) + ((d[0] + d[1]) + (d[2] + d[3]));
;   return rsqrtf(s * inv_n + EPS_);
; template <bool SWAP> DI void inproj_tile(const Params& p, int layer, int tm, int tn, bf16_t* smem) {
;     ...
;         const int row = i * 16 + l15, t = trow0 + row; const float rs = rstd_from16(ssq + (size_t)t * 16, 1.f / 1024.f) * qs;
;         if (kind == 1) {
;           const float* rp = (const float*)(p.ws + O_ROPE8) + (size_t)t * 16 + (quad & 1) * 8;
;           f32x4 v, o;
; #pragma unroll
;           for (int r = 0; r < 4; ++r) { v[r] = acc[i][0][r] * rs; o[r] = __shfl_xor(v[r], 32); }
; #pragma unroll
;           for (int r = 0; r < 4; ++r) { const float cs = rp[2 * r], sn = rp[2 * r + 1]; v[r] = quad < 2 ? v[r] * cs - o[r] * sn : v[r] * cs + o[r] * sn; }
;           stage4(stg, row, quad * 4, v, 1.f);
;         } else stage4(stg, row, quad * 4, acc[i][0], rs);
.LBB0_238:
	s_or_b64 exec, exec, s[50:51]
	v_or3_b32 v138, v146, v147, s62
	v_ashrrev_i32_e32 v139, 31, v138
	s_waitcnt lgkmcnt(0)
	v_lshlrev_b64 v[136:137], 6, v[138:139]
	v_lshl_add_u64 v[136:137], s[8:9], 0, v[136:137]
	v_bfe_u32 v244, v136, 6, 8
	v_lshlrev_b32_e32 v244, 3, v244
	v_add_u32_e32 v244, 0x24010, v244
	v_or_b32_e32 v246, 1, v136
	ds_read_b64 v[248:249], v244
	s_waitcnt lgkmcnt(0)
	v_cmp_ne_u32_e64 s[100:101], v248, v246
	s_nop 1
	s_and_saveexec_b64 s[98:99], s[100:101]
	s_cbranch_execz .LrcA0_5
	global_load_dwordx4 v[140:143], v[136:137], off
	global_load_dwordx4 v[152:155], v[136:137], off offset:16
	global_load_dwordx4 v[156:159], v[136:137], off offset:32
	global_load_dwordx4 v[160:163], v[136:137], off offset:48
	s_waitcnt vmcnt(3)
	v_mov_b32_e32 v136, v141
	v_mov_b32_e32 v137, v142
	v_mov_b32_e32 v141, v143
	s_waitcnt vmcnt(2)
	v_mov_b32_e32 v142, v153
	v_mov_b32_e32 v143, v154
	v_mov_b32_e32 v153, v155
	v_pk_add_f32 v[136:137], v[136:137], v[140:141]
	v_pk_add_f32 v[140:141], v[142:143], v[152:153]
	v_pk_add_f32 v[136:137], v[136:137], v[136:137] op_sel:[0,1] op_sel_hi:[1,0]
	v_pk_add_f32 v[140:141], v[140:141], v[140:141] op_sel:[0,1] op_sel_hi:[1,0]
	s_waitcnt vmcnt(1)
	v_add_f32_e32 v154, v156, v157
	v_add_f32_e32 v156, v158, v159
	s_waitcnt vmcnt(0)
	v_mov_b32_e32 v155, v162
	v_mov_b32_e32 v157, v163
	v_mov_b32_e32 v137, v160
	v_mov_b32_e32 v141, v161
	v_pk_add_f32 v[142:143], v[154:155], v[156:157]
	v_pk_add_f32 v[136:137], v[136:137], v[140:141]
	s_nop 0
	v_pk_add_f32 v[136:137], v[136:137], v[142:143]
	s_nop 0
	v_add_f32_e32 v136, v136, v137
	v_fmamk_f32 v136, v136, 0x3a800000, v185
	v_mul_f32_e32 v137, 0x4b800000, v136
	v_cmp_gt_f32_e64 s[2:3], s60, v136
	s_nop 1
	v_cndmask_b32_e64 v136, v136, v137, s[2:3]
	v_rsq_f32_e32 v136, v136
	s_nop 0
	v_mul_f32_e32 v137, 0x45800000, v136
	v_cndmask_b32_e64 v136, v136, v137, s[2:3]
	s_nop 0
	v_mov_b32_e32 v247, v136
	ds_write_b64 v244, v[246:247]
.LrcA0_5:
	s_or_b64 exec, exec, s[98:99]
	s_waitcnt vmcnt(0)
	v_cndmask_b32_e64 v136, v249, v136, s[100:101]
	v_mul_f32_e32 v136, v131, v136
	s_and_saveexec_b64 s[2:3], s[48:49]
	s_xor_b64 s[2:3], exec, s[2:3]
	v_pk_mul_f32 v[140:141], v[44:45], v[136:137] op_sel_hi:[1,0]
	v_pk_mul_f32 v[142:143], v[46:47], v[136:137] op_sel_hi:[1,0]
	v_cvt_pk_bf16_f32 v140, v140, v141
	s_or_saveexec_b64 s[50:51], s[2:3]
	v_lshlrev_b64 v[138:139], 4, v[138:139]
	s_xor_b64 exec, exec, s[50:51]
	s_cbranch_execz .LBB0_242
	v_lshl_add_u64 v[140:141], v[138:139], 2, s[30:31]
	v_lshl_add_u64 v[152:153], v[140:141], 0, v[176:177]
	global_load_dwordx4 v[140:143], v[152:153], off
	s_nop 0
	global_load_dwordx4 v[152:155], v[152:153], off offset:16
	v_and_b32_e32 v161, 64, v193
	v_xor_b32_e32 v160, 32, v193
	v_pk_mul_f32 v[156:157], v[44:45], v[136:137] op_sel_hi:[1,0]
	v_pk_mul_f32 v[158:159], v[46:47], v[136:137] op_sel_hi:[1,0]
	v_add_u32_e32 v137, 64, v161
	v_cmp_lt_i32_e64 s[2:3], v160, v137
	s_waitcnt vmcnt(1)
	v_mov_b32_e32 v165, v142
	v_cndmask_b32_e64 v137, v193, v160, s[2:3]
	v_lshlrev_b32_e32 v137, 2, v137
	ds_bpermute_b32 v160, v137, v156
	ds_bpermute_b32 v161, v137, v157
	ds_bpermute_b32 v162, v137, v158
	ds_bpermute_b32 v163, v137, v159
	v_mov_b32_e32 v142, v141
	s_waitcnt vmcnt(0)
	v_mov_b32_e32 v141, v154
	v_mov_b32_e32 v154, v153
	s_waitcnt lgkmcnt(2)
	v_pk_mul_f32 v[142:143], v[142:143], v[160:161]
	v_mov_b32_e32 v164, v140
	v_mov_b32_e32 v140, v152
	s_waitcnt lgkmcnt(0)
	v_pk_mul_f32 v[152:153], v[154:155], v[162:163]
	v_cndmask_b32_e64 v143, v143, -v143, vcc
	v_cndmask_b32_e64 v142, v142, -v142, vcc
	v_cndmask_b32_e64 v153, v153, -v153, vcc
	v_cndmask_b32_e64 v152, v152, -v152, vcc
	v_pk_fma_f32 v[154:155], v[156:157], v[164:165], v[142:143]
	v_pk_fma_f32 v[142:143], v[158:159], v[140:141], v[152:153]
	v_cvt_pk_bf16_f32 v140, v154, v155

; DI void stage4(bf16_t* stg, int row, int col, const f32x4& v, float s) { *(u32x2*)(stg + row * STG_LD + col) = (u32x2){pk2(v[0] * s, v[1] * s), pk2(v[2] * s, v[3] * s)}; }
; DI float rstd_from16(const float* p, float inv_n) {
;   const f32x4 a = *(const f32x4*)p, b = *(const f32x4*)(p + 4), c = *(const f32x4*)(p + 8), d = *(const f32x4*)(p + 12);
;   const float s = ((a[0] + a[1]) + (a[2] + a[3])) + ((b[0] + b[1]) + (b[2] + b[3])) + ((c[0] + c[1]) + (c[2] + c[3])) + ((d[0] + d[1]) + (d[2] + d[3]));
;   return rsqrtf(s * inv_n + EPS_);
; template <bool SWAP> DI void inproj_tile(const Params& p, int layer, int tm, int tn, bf16_t* smem) {
;     ...
;         const int row = i * 16 + l15, t = trow0 + row; const float rs = rstd_from16(ssq + (size_t)t * 16, 1.f / 1024.f) * qs;
;         if (kind == 1) {
;           const float* rp = (const float*)(p.ws + O_ROPE8) + (size_t)t * 16 + (quad & 1) * 8;
;           f32x4 v, o;
; #pragma unroll
;           for (int r = 0; r < 4; ++r) { v[r] = acc[i][0][r] * rs; o[r] = __shfl_xor(v[r], 32); }
; #pragma unroll
;           for (int r = 0; r < 4; ++r) { const float cs = rp[2 * r], sn = rp[2 * r + 1]; v[r] = quad < 2 ? v[r] * cs - o[r] * sn : v[r] * cs + o[r] * sn; }
;           stage4(stg, row, quad * 4, v, 1.f);
;         } else stage4(stg, row, quad * 4, acc[i][0], rs);
.LBB0_245:
	s_or_b64 exec, exec, s[50:51]
	v_or3_b32 v138, v146, v147, s63
	v_ashrrev_i32_e32 v139, 31, v138
	s_waitcnt lgkmcnt(0)
	v_lshlrev_b64 v[136:137], 6, v[138:139]
	v_lshl_add_u64 v[136:137], s[8:9], 0, v[136:137]
	v_bfe_u32 v244, v136, 6, 8
	v_lshlrev_b32_e32 v244, 3, v244
	v_add_u32_e32 v244, 0x24010, v244
	v_or_b32_e32 v246, 1, v136
	ds_read_b64 v[248:249], v244
	s_waitcnt lgkmcnt(0)
	v_cmp_ne_u32_e64 s[100:101], v248, v246
	s_nop 1
	s_and_saveexec_b64 s[98:99], s[100:101]
	s_cbranch_execz .LrcA0_6
	global_load_dwordx4 v[140:143], v[136:137], off
	global_load_dwordx4 v[152:155], v[136:137], off offset:16
	global_load_dwordx4 v[156:159], v[136:137], off offset:32
	global_load_dwordx4 v[160:163], v[136:137], off offset:48
	s_waitcnt vmcnt(3)
	v_mov_b32_e32 v136, v141
	v_mov_b32_e32 v137, v142
	v_mov_b32_e32 v141, v143
	s_waitcnt vmcnt(2)
	v_mov_b32_e32 v142, v153
	v_mov_b32_e32 v143, v154
	v_mov_b32_e32 v153, v155
	v_pk_add_f32 v[136:137], v[136:137], v[140:141]
	v_pk_add_f32 v[140:141], v[142:143], v[152:153]
	v_pk_add_f32 v[136:137], v[136:137], v[136:137] op_sel:[0,1] op_sel_hi:[1,0]
	v_pk_add_f32 v[140:141], v[140:141], v[140:141] op_sel:[0,1] op_sel_hi:[1,0]
	s_waitcnt vmcnt(1)
	v_add_f32_e32 v154, v156, v157
	v_add_f32_e32 v156, v158, v159
	s_waitcnt vmcnt(0)
	v_mov_b32_e32 v155, v162
	v_mov_b32_e32 v157, v163
	v_mov_b32_e32 v137, v160
	v_mov_b32_e32 v141, v161
	v_pk_add_f32 v[142:143], v[154:155], v[156:157]
	v_pk_add_f32 v[136:137], v[136:137], v[140:141]
	s_nop 0
	v_pk_add_f32 v[136:137], v[136:137], v[142:143]
	s_nop 0
	v_add_f32_e32 v136, v136, v137
	v_fmamk_f32 v136, v136, 0x3a800000, v185
	v_mul_f32_e32 v137, 0x4b800000, v136
	v_cmp_gt_f32_e64 s[2:3], s60, v136
	s_nop 1
	v_cndmask_b32_e64 v136, v136, v137, s[2:3]
	v_rsq_f32_e32 v136, v136
	s_nop 0
	v_mul_f32_e32 v137, 0x45800000, v136
	v_cndmask_b32_e64 v136, v136, v137, s[2:3]
	s_nop 0
	v_mov_b32_e32 v247, v136
	ds_write_b64 v244, v[246:247]
.LrcA0_6:
	s_or_b64 exec, exec, s[98:99]
	s_waitcnt vmcnt(0)
	v_cndmask_b32_e64 v136, v249, v136, s[100:101]
	v_mul_f32_e32 v136, v131, v136
	s_and_saveexec_b64 s[2:3], s[48:49]
	s_xor_b64 s[2:3], exec, s[2:3]
	v_pk_mul_f32 v[140:141], v[28:29], v[136:137] op_sel_hi:[1,0]
	v_pk_mul_f32 v[142:143], v[30:31], v[136:137] op_sel_hi:[1,0]
	v_cvt_pk_bf16_f32 v140, v140, v141
	s_or_saveexec_b64 s[50:51], s[2:3]
	v_lshlrev_b64 v[138:139], 4, v[138:139]
	s_xor_b64 exec, exec, s[50:51]
	s_cbranch_execz .LBB0_249
	v_lshl_add_u64 v[140:141], v[138:139], 2, s[30:31]
	v_lshl_add_u64 v[152:153], v[140:141], 0, v[176:177]
	global_load_dwordx4 v[140:143], v[152:153], off
	s_nop 0
	global_load_dwordx4 v[152:155], v[152:153], off offset:16
	v_and_b32_e32 v161, 64, v193
	v_xor_b32_e32 v160, 32, v193
	v_pk_mul_f32 v[156:157], v[28:29], v[136:137] op_sel_hi:[1,0]
	v_pk_mul_f32 v[158:159], v[30:31], v[136:137] op_sel_hi:[1,0]
	v_add_u32_e32 v137, 64, v161
	v_cmp_lt_i32_e64 s[2:3], v160, v137
	s_waitcnt vmcnt(1)
	v_mov_b32_e32 v165, v142
	v_cndmask_b32_e64 v137, v193, v160, s[2:3]
	v_lshlrev_b32_e32 v137, 2, v137
	ds_bpermute_b32 v160, v137, v156
	ds_bpermute_b32 v161, v137, v157
	ds_bpermute_b32 v162, v137, v158
	ds_bpermute_b32 v163, v137, v159
	v_mov_b32_e32 v142, v141
	s_waitcnt vmcnt(0)
	v_mov_b32_e32 v141, v154
	v_mov_b32_e32 v154, v153
	s_waitcnt lgkmcnt(2)
	v_pk_mul_f32 v[142:143], v[142:143], v[160:161]
	v_mov_b32_e32 v164, v140
	v_mov_b32_e32 v140, v152
	s_waitcnt lgkmcnt(0)
	v_pk_mul_f32 v[152:153], v[154:155], v[162:163]
	v_cndmask_b32_e64 v143, v143, -v143, vcc
	v_cndmask_b32_e64 v142, v142, -v142, vcc
	v_cndmask_b32_e64 v153, v153, -v153, vcc
	v_cndmask_b32_e64 v152, v152, -v152, vcc
	v_pk_fma_f32 v[154:155], v[156:157], v[164:165], v[142:143]
	v_pk_fma_f32 v[142:143], v[158:159], v[140:141], v[152:153]
	v_cvt_pk_bf16_f32 v140, v154, v155

; DI void stage4(bf16_t* stg, int row, int col, const f32x4& v, float s) { *(u32x2*)(stg + row * STG_LD + col) = (u32x2){pk2(v[0] * s, v[1] * s), pk2(v[2] * s, v[3] * s)}; }
; DI float rstd_from16(const float* p, float inv_n) {
;   const f32x4 a = *(const f32x4*)p, b = *(const f32x4*)(p + 4), c = *(const f32x4*)(p + 8), d = *(const f32x4*)(p + 12);
;   const float s = ((a[0] + a[1]) + (a[2] + a[3])) + ((b[0] + b[1]) + (b[2] + b[3])) + ((c[0] + c[1]) + (c[2] + c[3])) + ((d[0] + d[1]) + (d[2] + d[3]));
;   return rsqrtf(s * inv_n + EPS_);
; template <bool SWAP> DI void inproj_tile(const Params& p, int layer, int tm, int tn, bf16_t* smem) {
;     ...
;         const int row = i * 16 + l15, t = trow0 + row; const float rs = rstd_from16(ssq + (size_t)t * 16, 1.f / 1024.f) * qs;
;         if (kind == 1) {
;           const float* rp = (const float*)(p.ws + O_ROPE8) + (size_t)t * 16 + (quad & 1) * 8;
;           f32x4 v, o;
; #pragma unroll
;           for (int r = 0; r < 4; ++r) { v[r] = acc[i][0][r] * rs; o[r] = __shfl_xor(v[r], 32); }
; #pragma unroll
;           for (int r = 0; r < 4; ++r) { const float cs = rp[2 * r], sn = rp[2 * r + 1]; v[r] = quad < 2 ? v[r] * cs - o[r] * sn : v[r] * cs + o[r] * sn; }
;           stage4(stg, row, quad * 4, v, 1.f);
;         } else stage4(stg, row, quad * 4, acc[i][0], rs);
.LBB0_252:
	s_or_b64 exec, exec, s[50:51]
	v_or3_b32 v138, v146, v147, s41
	v_ashrrev_i32_e32 v139, 31, v138
	s_waitcnt lgkmcnt(0)
	v_lshlrev_b64 v[136:137], 6, v[138:139]
	v_lshl_add_u64 v[136:137], s[8:9], 0, v[136:137]
	v_bfe_u32 v244, v136, 6, 8
	v_lshlrev_b32_e32 v244, 3, v244
	v_add_u32_e32 v244, 0x24010, v244
	v_or_b32_e32 v246, 1, v136
	ds_read_b64 v[248:249], v244
	s_waitcnt lgkmcnt(0)
	v_cmp_ne_u32_e64 s[100:101], v248, v246
	s_nop 1
	s_and_saveexec_b64 s[98:99], s[100:101]
	s_cbranch_execz .LrcA0_7
	global_load_dwordx4 v[140:143], v[136:137], off
	global_load_dwordx4 v[150:153], v[136:137], off offset:16
	global_load_dwordx4 v[154:157], v[136:137], off offset:32
	global_load_dwordx4 v[158:161], v[136:137], off offset:48
	s_waitcnt vmcnt(3)
	v_mov_b32_e32 v136, v141
	v_mov_b32_e32 v137, v142
	v_mov_b32_e32 v141, v143
	s_waitcnt vmcnt(2)
	v_mov_b32_e32 v142, v151
	v_mov_b32_e32 v143, v152
	v_mov_b32_e32 v151, v153
	v_pk_add_f32 v[136:137], v[136:137], v[140:141]
	v_pk_add_f32 v[140:141], v[142:143], v[150:151]
	v_pk_add_f32 v[136:137], v[136:137], v[136:137] op_sel:[0,1] op_sel_hi:[1,0]
	v_pk_add_f32 v[140:141], v[140:141], v[140:141] op_sel:[0,1] op_sel_hi:[1,0]
	s_waitcnt vmcnt(1)
	v_add_f32_e32 v152, v154, v155
	v_add_f32_e32 v154, v156, v157
	s_waitcnt vmcnt(0)
	v_mov_b32_e32 v153, v160
	v_mov_b32_e32 v155, v161
	v_mov_b32_e32 v137, v158
	v_mov_b32_e32 v141, v159
	v_pk_add_f32 v[142:143], v[152:153], v[154:155]
	v_pk_add_f32 v[136:137], v[136:137], v[140:141]
	s_nop 0
	v_pk_add_f32 v[136:137], v[136:137], v[142:143]
	s_nop 0
	v_add_f32_e32 v136, v136, v137
	v_fmamk_f32 v136, v136, 0x3a800000, v185
	v_mul_f32_e32 v137, 0x4b800000, v136
	v_cmp_gt_f32_e64 s[2:3], s60, v136
	s_nop 1
	v_cndmask_b32_e64 v136, v136, v137, s[2:3]
	v_rsq_f32_e32 v136, v136
	s_nop 0
	v_mul_f32_e32 v137, 0x45800000, v136
	v_cndmask_b32_e64 v136, v136, v137, s[2:3]
	s_nop 0
	v_mov_b32_e32 v247, v136
	ds_write_b64 v244, v[246:247]
.LrcA0_7:
	s_or_b64 exec, exec, s[98:99]
	s_waitcnt vmcnt(0)
	v_cndmask_b32_e64 v136, v249, v136, s[100:101]
	v_mul_f32_e32 v136, v131, v136
	s_and_saveexec_b64 s[2:3], s[48:49]
	s_xor_b64 s[2:3], exec, s[2:3]
	v_pk_mul_f32 v[140:141], v[12:13], v[136:137] op_sel_hi:[1,0]
	v_pk_mul_f32 v[142:143], v[14:15], v[136:137] op_sel_hi:[1,0]
	v_cvt_pk_bf16_f32 v140, v140, v141
	s_or_saveexec_b64 s[48:49], s[2:3]
	v_lshlrev_b64 v[138:139], 4, v[138:139]
	s_xor_b64 exec, exec, s[48:49]
	s_cbranch_execz .LBB0_256
	v_lshl_add_u64 v[140:141], v[138:139], 2, s[30:31]
	v_lshl_add_u64 v[150:151], v[140:141], 0, v[176:177]
	global_load_dwordx4 v[140:143], v[150:151], off
	s_nop 0
	global_load_dwordx4 v[150:153], v[150:151], off offset:16
	v_and_b32_e32 v158, 64, v193
	v_xor_b32_e32 v131, 32, v193
	v_pk_mul_f32 v[154:155], v[12:13], v[136:137] op_sel_hi:[1,0]
	v_pk_mul_f32 v[156:157], v[14:15], v[136:137] op_sel_hi:[1,0]
	v_add_u32_e32 v137, 64, v158
	v_cmp_lt_i32_e64 s[2:3], v131, v137
	s_waitcnt vmcnt(1)
	v_mov_b32_e32 v163, v142
	v_cndmask_b32_e64 v131, v193, v131, s[2:3]
	v_lshlrev_b32_e32 v131, 2, v131
	ds_bpermute_b32 v158, v131, v154
	ds_bpermute_b32 v159, v131, v155
	ds_bpermute_b32 v160, v131, v156
	ds_bpermute_b32 v161, v131, v157
	v_mov_b32_e32 v142, v141
	s_waitcnt vmcnt(0)
	v_mov_b32_e32 v141, v152
	v_mov_b32_e32 v152, v151
	s_waitcnt lgkmcnt(2)
	v_pk_mul_f32 v[142:143], v[142:143], v[158:159]
	v_mov_b32_e32 v162, v140
	v_mov_b32_e32 v140, v150
	s_waitcnt lgkmcnt(0)
	v_pk_mul_f32 v[150:151], v[152:153], v[160:161]
	v_cndmask_b32_e64 v143, v143, -v143, vcc
	v_cndmask_b32_e64 v142, v142, -v142, vcc
	v_cndmask_b32_e64 v151, v151, -v151, vcc
	v_cndmask_b32_e64 v150, v150, -v150, vcc
	v_pk_fma_f32 v[152:153], v[154:155], v[162:163], v[142:143]
	v_pk_fma_f32 v[142:143], v[156:157], v[140:141], v[150:151]
	v_cvt_pk_bf16_f32 v140, v152, v153

; DI float sigmoidf_(float x) { return 1.f / (1.f + __expf(-x)); }
; DI float rstd_from16(const float* p, float inv_n) {
;   const f32x4 a = *(const f32x4*)p, b = *(const f32x4*)(p + 4), c = *(const f32x4*)(p + 8), d = *(const f32x4*)(p + 12);
;   const float s = ((a[0] + a[1]) + (a[2] + a[3])) + ((b[0] + b[1]) + (b[2] + b[3])) + ((c[0] + c[1]) + (c[2] + c[3])) + ((d[0] + d[1]) + (d[2] + d[3]));
;   return rsqrtf(s * inv_n + EPS_);
; template <bool SWAP> DI void inproj_tile(const Params& p, int layer, int tm, int tn, bf16_t* smem) {
;     ...
;         const int t = trow0 + i * 16 + l15; const float rs = rstd_from16(ssq + (size_t)t * 16, 1.f / 1024.f);
;         float* gt = (float*)(p.ws + O_GATES) + (size_t)t * 24; float* lf = (float*)(p.ws + O_LOGF) + (size_t)t * 8;
; #pragma unroll
;         for (int r = 0; r < 4; ++r) gt[quad * 4 + r] = sigmoidf_(acc[i][0][r] * rs);
.LBB0_260:
	s_or_b64 exec, exec, s[6:7]
	s_and_saveexec_b64 s[0:1], s[4:5]
	s_xor_b64 s[46:47], exec, s[0:1]
	s_cbranch_execz .LBB0_294
	v_or_b32_e32 v128, v147, v146
	v_ashrrev_i32_e32 v129, 31, v128
	v_lshlrev_b64 v[130:131], 6, v[128:129]
	v_lshl_add_u64 v[130:131], s[8:9], 0, v[130:131]
	v_bfe_u32 v244, v130, 6, 8
	v_lshlrev_b32_e32 v244, 3, v244
	v_add_u32_e32 v244, 0x24010, v244
	v_or_b32_e32 v246, 1, v130
	ds_read_b64 v[248:249], v244
	s_waitcnt lgkmcnt(0)
	v_cmp_ne_u32_e64 s[100:101], v248, v246
	s_nop 1
	s_and_saveexec_b64 s[98:99], s[100:101]
	s_cbranch_execz .LrcA0_8
	global_load_dwordx4 v[132:135], v[130:131], off
	global_load_dwordx4 v[136:139], v[130:131], off offset:16
	global_load_dwordx4 v[140:143], v[130:131], off offset:32
	global_load_dwordx4 v[146:149], v[130:131], off offset:48
	s_waitcnt vmcnt(6)
	s_waitcnt vmcnt(3)
	v_mov_b32_e32 v152, v133
	v_mov_b32_e32 v153, v134
	v_mov_b32_e32 v133, v135
	s_waitcnt vmcnt(2)
	v_mov_b32_e32 v134, v137
	v_mov_b32_e32 v135, v138
	v_mov_b32_e32 v137, v139
	v_pk_add_f32 v[132:133], v[152:153], v[132:133]
	v_pk_add_f32 v[134:135], v[134:135], v[136:137]
	v_pk_add_f32 v[132:133], v[132:133], v[132:133] op_sel:[0,1] op_sel_hi:[1,0]
	v_pk_add_f32 v[134:135], v[134:135], v[134:135] op_sel:[0,1] op_sel_hi:[1,0]
	s_waitcnt vmcnt(1)
	v_add_f32_e32 v138, v140, v141
	v_add_f32_e32 v140, v142, v143
	s_waitcnt vmcnt(0)
	v_mov_b32_e32 v139, v148
	v_mov_b32_e32 v141, v149
	v_mov_b32_e32 v133, v146
	v_mov_b32_e32 v135, v147
	v_pk_add_f32 v[136:137], v[138:139], v[140:141]
	v_pk_add_f32 v[132:133], v[132:133], v[134:135]
	s_nop 0
	v_pk_add_f32 v[132:133], v[132:133], v[136:137]
	s_nop 0
	v_add_f32_e32 v130, v132, v133
	v_fmamk_f32 v130, v130, 0x3a800000, v185
	v_mul_f32_e32 v132, 0x4b800000, v130
	v_cmp_gt_f32_e32 vcc, s60, v130
	s_nop 1
	v_cndmask_b32_e32 v130, v130, v132, vcc
	v_rsq_f32_e32 v130, v130
	v_mul_f32_e32 v134, 0x45800000, v130
	v_cndmask_b32_e32 v130, v130, v134, vcc
	s_nop 0
	v_mov_b32_e32 v247, v130
	ds_write_b64 v244, v[246:247]
.LrcA0_8:
	s_or_b64 exec, exec, s[98:99]
	s_waitcnt vmcnt(0)
	v_cndmask_b32_e64 v130, v249, v130, s[100:101]
	v_mov_b64_e32 v[150:151], s[10:11]
	v_lshlrev_b32_e32 v176, 4, v144
	v_cmp_lt_u32_e64 s[2:3], 31, v145
	v_lshlrev_b32_e32 v131, 2, v144
	v_mad_i64_i32 v[132:133], s[0:1], v128, s63, v[150:151]
	v_mul_f32_e32 v124, v124, v130
	v_mul_f32_e32 v125, v125, v130
	v_mul_f32_e32 v124, 0xbfb8aa3b, v124
	v_mul_f32_e32 v125, 0xbfb8aa3b, v125
	v_mul_f32_e32 v126, v126, v130
	v_mul_f32_e32 v127, v127, v130
	v_exp_f32_e32 v134, v124
	v_exp_f32_e32 v135, v125
	v_mul_f32_e32 v126, 0xbfb8aa3b, v126
	v_mul_f32_e32 v127, 0xbfb8aa3b, v127
	v_exp_f32_e32 v136, v126
	v_exp_f32_e32 v137, v127
	v_lshl_add_u64 v[126:127], v[132:133], 0, v[176:177]
	v_pk_add_f32 v[132:133], v[134:135], 1.0 op_sel_hi:[1,0]
	v_lshlrev_b64 v[124:125], 5, v[128:129]
	v_div_scale_f32 v129, s[0:1], v133, v133, 1.0
	v_pk_add_f32 v[134:135], v[136:137], 1.0 op_sel_hi:[1,0]
	v_div_scale_f32 v137, s[0:1], v132, v132, 1.0
	v_rcp_f32_e32 v143, v129
	v_div_scale_f32 v139, s[4:5], v135, v135, 1.0
	v_rcp_f32_e32 v145, v137
	v_div_scale_f32 v141, s[6:7], v134, v134, 1.0
	v_rcp_f32_e32 v146, v139
	v_rcp_f32_e32 v147, v141
	v_fma_f32 v148, -v129, v143, 1.0
	v_div_scale_f32 v136, vcc, 1.0, v133, 1.0
	v_fma_f32 v149, -v137, v145, 1.0
	v_fmac_f32_e32 v143, v148, v143
	v_div_scale_f32 v138, s[0:1], 1.0, v132, 1.0
	v_fma_f32 v150, -v139, v146, 1.0
	v_fmac_f32_e32 v145, v149, v145
	v_mul_f32_e32 v148, v136, v143
	v_div_scale_f32 v140, s[4:5], 1.0, v135, 1.0
	v_fma_f32 v151, -v141, v147, 1.0
	v_fmac_f32_e32 v146, v150, v146
	v_mul_f32_e32 v149, v138, v145
	v_fma_f32 v152, -v129, v148, v136
	v_div_scale_f32 v142, s[6:7], 1.0, v134, 1.0
	v_fmac_f32_e32 v147, v151, v147
	v_mul_f32_e32 v150, v140, v146
	v_fma_f32 v153, -v137, v149, v138
	v_fmac_f32_e32 v148, v152, v143
	v_mul_f32_e32 v151, v142, v147
	v_fma_f32 v154, -v139, v150, v140
	v_fmac_f32_e32 v149, v153, v145
	v_fma_f32 v129, -v129, v148, v136
	v_fma_f32 v155, -v141, v151, v142
	v_fmac_f32_e32 v150, v154, v146
	v_fma_f32 v136, -v137, v149, v138
	v_div_fmas_f32 v129, v129, v143, v148
	s_mov_b64 vcc, s[0:1]
	v_fmac_f32_e32 v151, v155, v147
	v_fma_f32 v137, -v139, v150, v140
	v_div_fixup_f32 v133, v129, v133, 1.0
	v_div_fmas_f32 v129, v136, v145, v149
	s_mov_b64 vcc, s[4:5]
	v_fma_f32 v138, -v141, v151, v142
	v_div_fixup_f32 v132, v129, v132, 1.0
	v_div_fmas_f32 v129, v137, v146, v150
	s_mov_b64 vcc, s[6:7]
	v_div_fixup_f32 v135, v129, v135, 1.0
	v_div_fmas_f32 v129, v138, v147, v151
	v_div_fixup_f32 v134, v129, v134, 1.0
	v_lshlrev_b32_e32 v176, 2, v131
	global_store_dwordx4 v[126:127], v[132:135], off
	s_and_saveexec_b64 s[0:1], s[2:3]
	s_xor_b64 s[0:1], exec, s[0:1]
	s_cbranch_execz .LBB0_263
; template <bool SWAP> DI void inproj_tile(const Params& p, int layer, int tm, int tn, bf16_t* smem) {
;     ...
;           for (int r = 0; r < 4; ++r) { const int h = (quad - 2) * 4 + r; const float xx = acc[i][1][r] * rs + p.b_forget[layer * 8 + h]; lf[h] = fminf(xx, 0.f) - log1pf(__expf(-fabsf(xx))); }
	v_readlane_b32 s72, v241, 8
	v_readlane_b32 s80, v241, 16
	v_readlane_b32 s81, v241, 17
	v_readlane_b32 s73, v241, 9
	v_readlane_b32 s74, v241, 10
	v_readlane_b32 s75, v241, 11
	v_readlane_b32 s76, v241, 12
	v_readlane_b32 s77, v241, 13
	global_load_dword v129, v176, s[80:81] offset:-32
	v_readlane_b32 s78, v241, 14
	v_readlane_b32 s79, v241, 15
	v_readlane_b32 s82, v241, 18
	v_readlane_b32 s83, v241, 19
	v_readlane_b32 s84, v241, 20
	v_readlane_b32 s85, v241, 21
	v_readlane_b32 s86, v241, 22
	v_readlane_b32 s87, v241, 23
	s_waitcnt vmcnt(0)
	v_fmac_f32_e32 v129, v120, v130
	v_mul_f32_e64 v126, |v129|, s64
	v_exp_f32_e32 v134, v126
	v_lshl_add_u64 v[126:127], s[12:13], 0, v[124:125]
	v_min_f32_e32 v129, 0, v129
	v_lshl_add_u64 v[126:127], v[126:127], 0, v[176:177]
	v_add_f32_e32 v135, 1.0, v134
	v_add_f32_e32 v136, -1.0, v135
	v_frexp_mant_f32_e32 v137, v135
	v_cvt_f64_f32_e32 v[132:133], v135
	v_sub_f32_e32 v138, v136, v135
	v_frexp_exp_i32_f64_e32 v132, v[132:133]
	v_cmp_gt_f32_e32 vcc, s65, v137
	v_sub_f32_e32 v136, v134, v136
	v_add_f32_e32 v133, 1.0, v138
	v_subbrev_co_u32_e32 v132, vcc, 0, v132, vcc
	v_add_f32_e32 v133, v136, v133
	v_sub_u32_e32 v136, 0, v132
	v_cvt_f32_i32_e32 v132, v132
	v_ldexp_f32 v135, v135, v136
	v_ldexp_f32 v133, v133, v136
	v_add_f32_e32 v136, -1.0, v135
	v_add_f32_e32 v137, 1.0, v135
	v_add_f32_e32 v138, 1.0, v136
	v_add_f32_e32 v139, -1.0, v137
	v_sub_f32_e32 v138, v135, v138
	v_sub_f32_e32 v135, v135, v139
	v_mul_f32_e32 v139, 0x3f317218, v132
	v_add_f32_e32 v138, v133, v138
	v_add_f32_e32 v133, v133, v135
	v_fma_f32 v135, v132, s66, -v139
	v_add_f32_e32 v140, v136, v138
	v_add_f32_e32 v141, v137, v133
	v_fmac_f32_e32 v135, 0xb102e308, v132
	v_sub_f32_e32 v132, v140, v136
	v_sub_f32_e32 v136, v141, v137
	v_rcp_f32_e32 v137, v141
	v_add_f32_e32 v142, v139, v135
	v_sub_f32_e32 v133, v133, v136
	v_sub_f32_e32 v136, v142, v139
	v_sub_f32_e32 v135, v135, v136
	v_mul_f32_e32 v136, v140, v137
	v_sub_f32_e32 v132, v138, v132
	v_mul_f32_e32 v138, v141, v136
	v_fma_f32 v139, v136, v141, -v138
	v_fmac_f32_e32 v139, v136, v133
	v_add_f32_e32 v143, v138, v139
	v_sub_f32_e32 v145, v140, v143
	v_sub_f32_e32 v138, v143, v138
	v_sub_f32_e32 v140, v140, v145
	v_sub_f32_e32 v138, v138, v139
	v_sub_f32_e32 v139, v140, v143
	v_add_f32_e32 v132, v132, v139
	v_add_f32_e32 v132, v138, v132
	v_add_f32_e32 v138, v145, v132
	v_mul_f32_e32 v139, v137, v138
	v_sub_f32_e32 v140, v145, v138
	v_mul_f32_e32 v143, v141, v139
	v_add_f32_e32 v132, v132, v140
	v_add_f32_e32 v140, v136, v139
	v_fma_f32 v141, v139, v141, -v143
	v_sub_f32_e32 v136, v140, v136
	v_fmac_f32_e32 v141, v139, v133
	v_sub_f32_e32 v133, v139, v136
	v_add_f32_e32 v136, v143, v141
	v_sub_f32_e32 v139, v136, v143
	v_sub_f32_e32 v143, v138, v136
	v_sub_f32_e32 v138, v138, v143
	v_sub_f32_e32 v136, v138, v136
	v_sub_f32_e32 v139, v139, v141
	v_add_f32_e32 v132, v132, v136
	v_add_f32_e32 v132, v139, v132
	v_add_f32_e32 v132, v143, v132
	v_mul_f32_e32 v132, v137, v132
	v_add_f32_e32 v132, v133, v132
	v_add_f32_e32 v133, v140, v132
	v_mul_f32_e32 v136, v133, v133
	v_fmamk_f32 v139, v136, 0x3e9b6dac, v186
	v_sub_f32_e32 v137, v133, v140
	v_ldexp_f32 v138, v133, 1
	v_mul_f32_e32 v133, v133, v136
	v_fmaak_f32 v136, v136, v139, 0x3f2aaada
	v_mul_f32_e32 v133, v133, v136
	v_add_f32_e32 v136, v138, v133
	v_sub_f32_e32 v132, v132, v137
	v_sub_f32_e32 v137, v136, v138
	v_ldexp_f32 v132, v132, 1
	v_sub_f32_e32 v133, v133, v137
	v_add_f32_e32 v132, v132, v133
	v_add_f32_e32 v133, v136, v132
	v_sub_f32_e32 v136, v133, v136
	v_add_f32_e32 v137, v142, v133
	v_sub_f32_e32 v132, v132, v136
	v_sub_f32_e32 v136, v137, v142
	v_sub_f32_e32 v138, v137, v136
	v_sub_f32_e32 v133, v133, v136
	v_add_f32_e32 v136, v135, v132
	v_sub_f32_e32 v138, v142, v138
	v_sub_f32_e32 v139, v136, v135
	v_add_f32_e32 v133, v133, v138
	v_sub_f32_e32 v138, v136, v139
	v_sub_f32_e32 v132, v132, v139
	v_sub_f32_e32 v135, v135, v138
	v_add_f32_e32 v133, v136, v133
	v_add_f32_e32 v132, v132, v135
	v_add_f32_e32 v135, v137, v133
	v_sub_f32_e32 v136, v135, v137
	v_sub_f32_e32 v133, v133, v136
	v_add_f32_e32 v132, v132, v133
	v_add_f32_e32 v132, v135, v132
	v_cmp_neq_f32_e32 vcc, s67, v134
	s_nop 1
	v_cndmask_b32_e32 v132, v194, v132, vcc
	v_cmp_ngt_f32_e32 vcc, -1.0, v134
	s_nop 1
	v_cndmask_b32_e32 v132, v195, v132, vcc
	v_cmp_neq_f32_e32 vcc, -1.0, v134
	s_nop 1
	v_cndmask_b32_e32 v132, v196, v132, vcc
	v_cmp_lt_f32_e64 vcc, |v134|, s68
	s_nop 1
	v_cndmask_b32_e32 v132, v132, v134, vcc
	v_sub_f32_e32 v129, v129, v132
	global_store_dword v[126:127], v129, off offset:-32
	global_load_dword v129, v176, s[80:81] offset:-28
	s_waitcnt vmcnt(0)
; template <bool SWAP> DI void inproj_tile(const Params& p, int layer, int tm, int tn, bf16_t* smem) {
;     ...
;           for (int r = 0; r < 4; ++r) { const int h = (quad - 2) * 4 + r; const float xx = acc[i][1][r] * rs + p.b_forget[layer * 8 + h]; lf[h] = fminf(xx, 0.f) - log1pf(__expf(-fabsf(xx))); }
	v_fmac_f32_e32 v129, v121, v130
	v_mul_f32_e64 v132, |v129|, s64
	v_exp_f32_e32 v134, v132
	v_min_f32_e32 v129, 0, v129
	v_add_f32_e32 v135, 1.0, v134
	v_add_f32_e32 v136, -1.0, v135
	v_frexp_mant_f32_e32 v137, v135
	v_cvt_f64_f32_e32 v[132:133], v135
	v_sub_f32_e32 v138, v136, v135
	v_frexp_exp_i32_f64_e32 v132, v[132:133]
	v_cmp_gt_f32_e32 vcc, s65, v137
	v_sub_f32_e32 v136, v134, v136
	v_add_f32_e32 v133, 1.0, v138
	v_subbrev_co_u32_e32 v132, vcc, 0, v132, vcc
	v_add_f32_e32 v133, v136, v133
	v_sub_u32_e32 v136, 0, v132
	v_cvt_f32_i32_e32 v132, v132
	v_ldexp_f32 v135, v135, v136
	v_ldexp_f32 v133, v133, v136
	v_add_f32_e32 v136, -1.0, v135
	v_add_f32_e32 v137, 1.0, v135
	v_add_f32_e32 v138, 1.0, v136
	v_add_f32_e32 v139, -1.0, v137
	v_sub_f32_e32 v138, v135, v138
	v_sub_f32_e32 v135, v135, v139
	v_mul_f32_e32 v139, 0x3f317218, v132
	v_add_f32_e32 v138, v133, v138
	v_add_f32_e32 v133, v133, v135
	v_fma_f32 v135, v132, s66, -v139
	v_add_f32_e32 v140, v136, v138
	v_add_f32_e32 v141, v137, v133
	v_fmac_f32_e32 v135, 0xb102e308, v132
	v_sub_f32_e32 v132, v140, v136
	v_sub_f32_e32 v136, v141, v137
	v_rcp_f32_e32 v137, v141
	v_add_f32_e32 v142, v139, v135
	v_sub_f32_e32 v133, v133, v136
	v_sub_f32_e32 v136, v142, v139
	v_sub_f32_e32 v135, v135, v136
	v_mul_f32_e32 v136, v140, v137
	v_sub_f32_e32 v132, v138, v132
	v_mul_f32_e32 v138, v141, v136
	v_fma_f32 v139, v136, v141, -v138
	v_fmac_f32_e32 v139, v136, v133
	v_add_f32_e32 v143, v138, v139
	v_sub_f32_e32 v145, v140, v143
	v_sub_f32_e32 v138, v143, v138
	v_sub_f32_e32 v140, v140, v145
	v_sub_f32_e32 v138, v138, v139
	v_sub_f32_e32 v139, v140, v143
	v_add_f32_e32 v132, v132, v139
	v_add_f32_e32 v132, v138, v132
	v_add_f32_e32 v138, v145, v132
	v_mul_f32_e32 v139, v137, v138
	v_sub_f32_e32 v140, v145, v138
	v_mul_f32_e32 v143, v141, v139
	v_add_f32_e32 v132, v132, v140
	v_add_f32_e32 v140, v136, v139
	v_fma_f32 v141, v139, v141, -v143
	v_sub_f32_e32 v136, v140, v136
	v_fmac_f32_e32 v141, v139, v133
	v_sub_f32_e32 v133, v139, v136
	v_add_f32_e32 v136, v143, v141
	v_sub_f32_e32 v139, v136, v143
	v_sub_f32_e32 v143, v138, v136
	v_sub_f32_e32 v138, v138, v143
	v_sub_f32_e32 v136, v138, v136
	v_sub_f32_e32 v139, v139, v141
	v_add_f32_e32 v132, v132, v136
	v_add_f32_e32 v132, v139, v132
	v_add_f32_e32 v132, v143, v132
	v_mul_f32_e32 v132, v137, v132
	v_add_f32_e32 v132, v133, v132
	v_add_f32_e32 v133, v140, v132
	v_mul_f32_e32 v136, v133, v133
	v_fmamk_f32 v139, v136, 0x3e9b6dac, v186
	v_sub_f32_e32 v137, v133, v140
	v_ldexp_f32 v138, v133, 1
	v_mul_f32_e32 v133, v133, v136
	v_fmaak_f32 v136, v136, v139, 0x3f2aaada
	v_mul_f32_e32 v133, v133, v136
	v_add_f32_e32 v136, v138, v133
	v_sub_f32_e32 v132, v132, v137
	v_sub_f32_e32 v137, v136, v138
	v_ldexp_f32 v132, v132, 1
	v_sub_f32_e32 v133, v133, v137
	v_add_f32_e32 v132, v132, v133
	v_add_f32_e32 v133, v136, v132
	v_sub_f32_e32 v136, v133, v136
	v_add_f32_e32 v137, v142, v133
	v_sub_f32_e32 v132, v132, v136
	v_sub_f32_e32 v136, v137, v142
	v_sub_f32_e32 v138, v137, v136
	v_sub_f32_e32 v133, v133, v136
	v_add_f32_e32 v136, v135, v132
	v_sub_f32_e32 v138, v142, v138
	v_sub_f32_e32 v139, v136, v135
	v_add_f32_e32 v133, v133, v138
	v_sub_f32_e32 v138, v136, v139
	v_sub_f32_e32 v132, v132, v139
	v_sub_f32_e32 v135, v135, v138
	v_add_f32_e32 v133, v136, v133
	v_add_f32_e32 v132, v132, v135
	v_add_f32_e32 v135, v137, v133
	v_sub_f32_e32 v136, v135, v137
	v_sub_f32_e32 v133, v133, v136
	v_add_f32_e32 v132, v132, v133
	v_add_f32_e32 v132, v135, v132
	v_cmp_neq_f32_e32 vcc, s67, v134
	s_nop 1
	v_cndmask_b32_e32 v132, v194, v132, vcc
	v_cmp_ngt_f32_e32 vcc, -1.0, v134
	s_nop 1
	v_cndmask_b32_e32 v132, v195, v132, vcc
	v_cmp_neq_f32_e32 vcc, -1.0, v134
	s_nop 1
	v_cndmask_b32_e32 v132, v196, v132, vcc
	v_cmp_lt_f32_e64 vcc, |v134|, s68
	s_nop 1
	v_cndmask_b32_e32 v132, v132, v134, vcc
	v_sub_f32_e32 v129, v129, v132
	global_store_dword v[126:127], v129, off offset:-28
	global_load_dword v129, v176, s[80:81] offset:-24
	s_waitcnt vmcnt(0)
	v_fmac_f32_e32 v129, v122, v130
	v_mul_f32_e64 v132, |v129|, s64
	v_exp_f32_e32 v134, v132
	v_min_f32_e32 v129, 0, v129
	v_add_f32_e32 v135, 1.0, v134
	v_add_f32_e32 v136, -1.0, v135
	v_frexp_mant_f32_e32 v137, v135
	v_cvt_f64_f32_e32 v[132:133], v135
	v_sub_f32_e32 v138, v136, v135
	v_frexp_exp_i32_f64_e32 v132, v[132:133]
	v_cmp_gt_f32_e32 vcc, s65, v137
	v_sub_f32_e32 v136, v134, v136
	v_add_f32_e32 v133, 1.0, v138
	v_subbrev_co_u32_e32 v132, vcc, 0, v132, vcc
	v_add_f32_e32 v133, v136, v133
	v_sub_u32_e32 v136, 0, v132
	v_cvt_f32_i32_e32 v132, v132
	v_ldexp_f32 v135, v135, v136
	v_ldexp_f32 v133, v133, v136
	v_add_f32_e32 v136, -1.0, v135
	v_add_f32_e32 v137, 1.0, v135
	v_add_f32_e32 v138, 1.0, v136
	v_add_f32_e32 v139, -1.0, v137
	v_sub_f32_e32 v138, v135, v138
	v_sub_f32_e32 v135, v135, v139
	v_mul_f32_e32 v139, 0x3f317218, v132
	v_add_f32_e32 v138, v133, v138
	v_add_f32_e32 v133, v133, v135
	v_fma_f32 v135, v132, s66, -v139
	v_add_f32_e32 v140, v136, v138
	v_add_f32_e32 v141, v137, v133
	v_fmac_f32_e32 v135, 0xb102e308, v132
	v_sub_f32_e32 v132, v140, v136
	v_sub_f32_e32 v136, v141, v137
	v_rcp_f32_e32 v137, v141
	v_add_f32_e32 v142, v139, v135
	v_sub_f32_e32 v133, v133, v136
	v_sub_f32_e32 v136, v142, v139
	v_sub_f32_e32 v135, v135, v136
	v_mul_f32_e32 v136, v140, v137
	v_sub_f32_e32 v132, v138, v132
	v_mul_f32_e32 v138, v141, v136
	v_fma_f32 v139, v136, v141, -v138
	v_fmac_f32_e32 v139, v136, v133
	v_add_f32_e32 v143, v138, v139
	v_sub_f32_e32 v145, v140, v143
	v_sub_f32_e32 v138, v143, v138
	v_sub_f32_e32 v140, v140, v145
	v_sub_f32_e32 v138, v138, v139
	v_sub_f32_e32 v139, v140, v143
	v_add_f32_e32 v132, v132, v139
; template <bool SWAP> DI void inproj_tile(const Params& p, int layer, int tm, int tn, bf16_t* smem) {
;     ...
;           for (int r = 0; r < 4; ++r) { const int h = (quad - 2) * 4 + r; const float xx = acc[i][1][r] * rs + p.b_forget[layer * 8 + h]; lf[h] = fminf(xx, 0.f) - log1pf(__expf(-fabsf(xx))); }
	v_add_f32_e32 v132, v138, v132
	v_add_f32_e32 v138, v145, v132
	v_mul_f32_e32 v139, v137, v138
	v_sub_f32_e32 v140, v145, v138
	v_mul_f32_e32 v143, v141, v139
	v_add_f32_e32 v132, v132, v140
	v_add_f32_e32 v140, v136, v139
	v_fma_f32 v141, v139, v141, -v143
	v_sub_f32_e32 v136, v140, v136
	v_fmac_f32_e32 v141, v139, v133
	v_sub_f32_e32 v133, v139, v136
	v_add_f32_e32 v136, v143, v141
	v_sub_f32_e32 v139, v136, v143
	v_sub_f32_e32 v143, v138, v136
	v_sub_f32_e32 v138, v138, v143
	v_sub_f32_e32 v136, v138, v136
	v_sub_f32_e32 v139, v139, v141
	v_add_f32_e32 v132, v132, v136
	v_add_f32_e32 v132, v139, v132
	v_add_f32_e32 v132, v143, v132
	v_mul_f32_e32 v132, v137, v132
	v_add_f32_e32 v132, v133, v132
	v_add_f32_e32 v133, v140, v132
	v_mul_f32_e32 v136, v133, v133
	v_fmamk_f32 v139, v136, 0x3e9b6dac, v186
	v_sub_f32_e32 v137, v133, v140
	v_ldexp_f32 v138, v133, 1
	v_mul_f32_e32 v133, v133, v136
	v_fmaak_f32 v136, v136, v139, 0x3f2aaada
	v_mul_f32_e32 v133, v133, v136
	v_add_f32_e32 v136, v138, v133
	v_sub_f32_e32 v132, v132, v137
	v_sub_f32_e32 v137, v136, v138
	v_ldexp_f32 v132, v132, 1
	v_sub_f32_e32 v133, v133, v137
	v_add_f32_e32 v132, v132, v133
	v_add_f32_e32 v133, v136, v132
	v_sub_f32_e32 v136, v133, v136
	v_add_f32_e32 v137, v142, v133
	v_sub_f32_e32 v132, v132, v136
	v_sub_f32_e32 v136, v137, v142
	v_sub_f32_e32 v138, v137, v136
	v_sub_f32_e32 v133, v133, v136
	v_add_f32_e32 v136, v135, v132
	v_sub_f32_e32 v138, v142, v138
	v_sub_f32_e32 v139, v136, v135
	v_add_f32_e32 v133, v133, v138
	v_sub_f32_e32 v138, v136, v139
	v_sub_f32_e32 v132, v132, v139
	v_sub_f32_e32 v135, v135, v138
	v_add_f32_e32 v133, v136, v133
	v_add_f32_e32 v132, v132, v135
	v_add_f32_e32 v135, v137, v133
	v_sub_f32_e32 v136, v135, v137
	v_sub_f32_e32 v133, v133, v136
	v_add_f32_e32 v132, v132, v133
	v_add_f32_e32 v132, v135, v132
	v_cmp_neq_f32_e32 vcc, s67, v134
	s_nop 1
	v_cndmask_b32_e32 v132, v194, v132, vcc
	v_cmp_ngt_f32_e32 vcc, -1.0, v134
	s_nop 1
	v_cndmask_b32_e32 v132, v195, v132, vcc
	v_cmp_neq_f32_e32 vcc, -1.0, v134
	s_nop 1
	v_cndmask_b32_e32 v132, v196, v132, vcc
	v_cmp_lt_f32_e64 vcc, |v134|, s68
	s_nop 1
	v_cndmask_b32_e32 v132, v132, v134, vcc
	v_sub_f32_e32 v129, v129, v132
	global_store_dword v[126:127], v129, off offset:-24
	global_load_dword v129, v176, s[80:81] offset:-20
	s_waitcnt vmcnt(0)
	v_fmac_f32_e32 v129, v123, v130
	v_mul_f32_e64 v132, |v129|, s64
	v_exp_f32_e32 v134, v132
	v_min_f32_e32 v129, 0, v129
	v_add_f32_e32 v135, 1.0, v134
	v_add_f32_e32 v136, -1.0, v135
	v_frexp_mant_f32_e32 v137, v135
	v_cvt_f64_f32_e32 v[132:133], v135
	v_sub_f32_e32 v138, v136, v135
	v_frexp_exp_i32_f64_e32 v132, v[132:133]
	v_cmp_gt_f32_e32 vcc, s65, v137
	v_sub_f32_e32 v136, v134, v136
	v_add_f32_e32 v133, 1.0, v138
	v_subbrev_co_u32_e32 v132, vcc, 0, v132, vcc
	v_add_f32_e32 v133, v136, v133
	v_sub_u32_e32 v136, 0, v132
	v_cvt_f32_i32_e32 v132, v132
	v_ldexp_f32 v135, v135, v136
	v_ldexp_f32 v133, v133, v136
	v_add_f32_e32 v136, -1.0, v135
	v_add_f32_e32 v137, 1.0, v135
	v_add_f32_e32 v138, 1.0, v136
	v_add_f32_e32 v139, -1.0, v137
	v_sub_f32_e32 v138, v135, v138
	v_sub_f32_e32 v135, v135, v139
	v_mul_f32_e32 v139, 0x3f317218, v132
	v_add_f32_e32 v138, v133, v138
	v_add_f32_e32 v133, v133, v135
	v_fma_f32 v135, v132, s66, -v139
	v_add_f32_e32 v140, v136, v138
	v_add_f32_e32 v141, v137, v133
	v_fmac_f32_e32 v135, 0xb102e308, v132
	v_sub_f32_e32 v132, v140, v136
	v_sub_f32_e32 v136, v141, v137
	v_rcp_f32_e32 v137, v141
	v_add_f32_e32 v142, v139, v135
	v_sub_f32_e32 v133, v133, v136
	v_sub_f32_e32 v136, v142, v139
	v_sub_f32_e32 v135, v135, v136
	v_mul_f32_e32 v136, v140, v137
	v_sub_f32_e32 v132, v138, v132
	v_mul_f32_e32 v138, v141, v136
	v_fma_f32 v139, v136, v141, -v138
	v_fmac_f32_e32 v139, v136, v133
	v_add_f32_e32 v143, v138, v139
	v_sub_f32_e32 v145, v140, v143
	v_sub_f32_e32 v138, v143, v138
	v_sub_f32_e32 v140, v140, v145
	v_sub_f32_e32 v138, v138, v139
	v_sub_f32_e32 v139, v140, v143
	v_add_f32_e32 v132, v132, v139
	v_add_f32_e32 v132, v138, v132
	v_add_f32_e32 v138, v145, v132
	v_mul_f32_e32 v139, v137, v138
	v_sub_f32_e32 v140, v145, v138
	v_mul_f32_e32 v143, v141, v139
	v_add_f32_e32 v132, v132, v140
	v_add_f32_e32 v140, v136, v139
	v_fma_f32 v141, v139, v141, -v143
	v_sub_f32_e32 v136, v140, v136
	v_fmac_f32_e32 v141, v139, v133
	v_sub_f32_e32 v133, v139, v136
	v_add_f32_e32 v136, v143, v141
	v_sub_f32_e32 v139, v136, v143
	v_sub_f32_e32 v143, v138, v136
	v_sub_f32_e32 v138, v138, v143
	v_sub_f32_e32 v136, v138, v136
	v_sub_f32_e32 v139, v139, v141
	v_add_f32_e32 v132, v132, v136
	v_add_f32_e32 v132, v139, v132
	v_add_f32_e32 v132, v143, v132
	v_mul_f32_e32 v132, v137, v132
	v_add_f32_e32 v132, v133, v132
	v_add_f32_e32 v133, v140, v132
	v_mul_f32_e32 v136, v133, v133
	v_fmamk_f32 v139, v136, 0x3e9b6dac, v186
	v_sub_f32_e32 v137, v133, v140
	v_ldexp_f32 v138, v133, 1
	v_mul_f32_e32 v133, v133, v136
	v_fmaak_f32 v136, v136, v139, 0x3f2aaada
	v_mul_f32_e32 v133, v133, v136
	v_add_f32_e32 v136, v138, v133
	v_sub_f32_e32 v132, v132, v137
	v_sub_f32_e32 v137, v136, v138
	v_ldexp_f32 v132, v132, 1
	v_sub_f32_e32 v133, v133, v137
	v_add_f32_e32 v132, v132, v133
	v_add_f32_e32 v133, v136, v132
	v_sub_f32_e32 v136, v133, v136
	v_add_f32_e32 v137, v142, v133
	v_sub_f32_e32 v132, v132, v136
	v_sub_f32_e32 v136, v137, v142
	v_sub_f32_e32 v138, v137, v136
	v_sub_f32_e32 v133, v133, v136
	v_add_f32_e32 v136, v135, v132
	v_sub_f32_e32 v138, v142, v138
	v_sub_f32_e32 v139, v136, v135
	v_add_f32_e32 v133, v133, v138
	v_sub_f32_e32 v138, v136, v139
	v_sub_f32_e32 v132, v132, v139
	v_sub_f32_e32 v135, v135, v138
	v_add_f32_e32 v133, v136, v133
	v_add_f32_e32 v132, v132, v135
	v_add_f32_e32 v135, v137, v133
	v_sub_f32_e32 v136, v135, v137
	v_sub_f32_e32 v133, v133, v136
	v_add_f32_e32 v132, v132, v133
	v_add_f32_e32 v132, v135, v132
	v_cmp_neq_f32_e32 vcc, s67, v134
	s_nop 1
	v_cndmask_b32_e32 v132, v194, v132, vcc
	v_cmp_ngt_f32_e32 vcc, -1.0, v134
	s_nop 1
	v_cndmask_b32_e32 v132, v195, v132, vcc
	v_cmp_neq_f32_e32 vcc, -1.0, v134
	s_nop 1
	v_cndmask_b32_e32 v132, v196, v132, vcc
	v_cmp_lt_f32_e64 vcc, |v134|, s68
	s_nop 1
	v_cndmask_b32_e32 v132, v132, v134, vcc
	v_sub_f32_e32 v129, v129, v132
	global_store_dword v[126:127], v129, off offset:-20

; DI int TIDX() { int t = (int)threadIdx.x; asm volatile("" : "+v"(t)); return t; }
; DI float sigmoidf_(float x) { return 1.f / (1.f + __expf(-x)); }
; DI float rstd_from16(const float* p, float inv_n) {
;   const f32x4 a = *(const f32x4*)p, b = *(const f32x4*)(p + 4), c = *(const f32x4*)(p + 8), d = *(const f32x4*)(p + 12);
;   const float s = ((a[0] + a[1]) + (a[2] + a[3])) + ((b[0] + b[1]) + (b[2] + b[3])) + ((c[0] + c[1]) + (c[2] + c[3])) + ((d[0] + d[1]) + (d[2] + d[3]));
;   return rsqrtf(s * inv_n + EPS_);
; DI void merge_tile(const Params& p, int layer, int tm, int tn, bf16_t* smem) {
;     ...
;       const int t2 = TIDX(), row0 = tm * 256 + ((t2 >> 8) & 1) * 128 + (t2 & 15);
; #pragma unroll
;       for (int i = 0; i < 8; ++i) {
;         asm volatile("" ::: "memory");
;         const float rs = rstd_from16((const float*)(p.ws + O_SSQ) + (size_t)(row0 + i * 16) * 16, 1.f / 1024.f);
; #pragma unroll
;         for (int j = 0; j < 2; ++j) {
;           unsigned w = 0;
; #pragma unroll
;           for (int r = 0; r < 4; ++r) w |= (unsigned)__float2int_rn(sigmoidf_(acc[i][j][r] * rs) * 255.f) << (8 * r);
;           gsp[(i * 2 + j) * NTHR] = w;
.LBB0_851:
	v_mov_b32_e32 v152, v220
	v_mov_b64_e32 v[214:215], v[26:27]
	v_lshrrev_b32_e32 v153, 1, v152
	v_and_b32_e32 v153, 0x80, v153
	v_and_b32_e32 v152, 15, v152
	v_or3_b32 v152, v152, v153, s37
	v_ashrrev_i32_e32 v153, 31, v152
	v_lshlrev_b64 v[154:155], 6, v[152:153]
	v_lshl_add_u64 v[166:167], s[0:1], 0, v[154:155]
	v_bfe_u32 v244, v166, 6, 8
	v_lshlrev_b32_e32 v244, 3, v244
	v_add_u32_e32 v244, 0x24010, v244
	v_or_b32_e32 v246, 1, v166
	ds_read_b64 v[248:249], v244
	s_waitcnt lgkmcnt(0)
	v_cmp_ne_u32_e64 s[100:101], v248, v246
	s_nop 1
	s_and_saveexec_b64 s[98:99], s[100:101]
	s_cbranch_execz .LrcE0_0
	global_load_dwordx4 v[154:157], v[166:167], off offset:48
	global_load_dwordx4 v[158:161], v[166:167], off offset:32
	global_load_dwordx4 v[162:165], v[166:167], off offset:16
	s_nop 0
	global_load_dwordx4 v[166:169], v[166:167], off
	s_waitcnt vmcnt(2)
	v_add_f32_e32 v158, v158, v159
	v_add_f32_e32 v160, v160, v161
	s_waitcnt vmcnt(0)
	v_mov_b32_e32 v170, v167
	v_mov_b32_e32 v171, v168
	v_mov_b32_e32 v167, v169
	v_mov_b32_e32 v168, v163
	v_mov_b32_e32 v169, v164
	v_mov_b32_e32 v163, v165
	v_pk_add_f32 v[166:167], v[170:171], v[166:167]
	v_pk_add_f32 v[162:163], v[168:169], v[162:163]
	v_pk_add_f32 v[166:167], v[166:167], v[166:167] op_sel:[0,1] op_sel_hi:[1,0]
	v_pk_add_f32 v[162:163], v[162:163], v[162:163] op_sel:[0,1] op_sel_hi:[1,0]
	v_mov_b32_e32 v167, v154
	v_mov_b32_e32 v163, v155
	v_mov_b32_e32 v159, v156
	v_mov_b32_e32 v161, v157
	v_pk_add_f32 v[154:155], v[166:167], v[162:163]
	v_pk_add_f32 v[156:157], v[158:159], v[160:161]
	v_pk_add_f32 v[154:155], v[154:155], v[156:157]
	v_add_f32_e32 v153, v154, v155
	v_fmamk_f32 v153, v153, 0x3a800000, v225
	v_cmp_gt_f32_e32 vcc, s35, v153
	v_mul_f32_e32 v154, 0x4b800000, v153
	v_cndmask_b32_e32 v153, v153, v154, vcc
	v_rsq_f32_e32 v153, v153
	v_mul_f32_e32 v154, 0x45800000, v153
	v_cndmask_b32_e32 v153, v153, v154, vcc
	s_nop 0
	v_mov_b32_e32 v247, v153
	ds_write_b64 v244, v[246:247]
.LrcE0_0:
	s_or_b64 exec, exec, s[98:99]
	s_waitcnt vmcnt(0)
	v_cndmask_b32_e64 v153, v249, v153, s[100:101]
	v_mov_b64_e32 v[210:211], v[30:31]
	v_mov_b64_e32 v[206:207], v[34:35]
	v_mov_b64_e32 v[202:203], v[38:39]
	v_mov_b64_e32 v[198:199], v[42:43]
	v_mov_b64_e32 v[194:195], v[46:47]
	v_mov_b64_e32 v[190:191], v[50:51]
	v_mov_b64_e32 v[186:187], v[54:55]
	v_mov_b64_e32 v[182:183], v[58:59]
	v_mov_b64_e32 v[178:179], v[62:63]
	v_mov_b64_e32 v[174:175], v[66:67]
	v_mov_b64_e32 v[212:213], v[24:25]
	v_mov_b64_e32 v[208:209], v[28:29]
	v_mov_b64_e32 v[204:205], v[32:33]
	v_mov_b64_e32 v[200:201], v[36:37]
	v_mov_b64_e32 v[196:197], v[40:41]
	v_mov_b64_e32 v[192:193], v[44:45]
	v_mov_b64_e32 v[188:189], v[48:49]
	v_mov_b64_e32 v[184:185], v[52:53]
	v_mov_b64_e32 v[180:181], v[56:57]
	v_mov_b64_e32 v[176:177], v[60:61]
	v_mov_b64_e32 v[172:173], v[64:65]
	v_mov_b64_e32 v[170:171], v[70:71]
	v_mov_b64_e32 v[166:167], v[74:75]
	v_mov_b64_e32 v[168:169], v[68:69]
	v_mov_b64_e32 v[164:165], v[72:73]
	v_mul_f32_e32 v148, v148, v153
	v_mul_f32_e32 v148, 0xbfb8aa3b, v148
	v_exp_f32_e32 v148, v148
	v_mul_f32_e32 v149, v149, v153
	v_mul_f32_e32 v149, 0xbfb8aa3b, v149
	v_exp_f32_e32 v149, v149
	v_add_f32_e32 v148, 1.0, v148
	v_div_scale_f32 v154, s[22:23], v148, v148, 1.0
	v_rcp_f32_e32 v155, v154
	v_add_f32_e32 v149, 1.0, v149
	v_mul_f32_e32 v144, v144, v153
	v_mul_f32_e32 v144, 0xbfb8aa3b, v144
	v_fma_f32 v156, -v154, v155, 1.0
	v_fmac_f32_e32 v155, v156, v155
	v_div_scale_f32 v156, vcc, 1.0, v148, 1.0
	v_mul_f32_e32 v157, v156, v155
	v_fma_f32 v158, -v154, v157, v156
	v_fmac_f32_e32 v157, v158, v155
	v_fma_f32 v154, -v154, v157, v156
	v_div_fmas_f32 v154, v154, v155, v157
	v_div_fixup_f32 v148, v154, v148, 1.0
	v_div_scale_f32 v154, s[22:23], v149, v149, 1.0
	v_rcp_f32_e32 v155, v154
	v_mul_f32_e32 v148, 0x437f0000, v148
	v_rndne_f32_e32 v148, v148
	v_cvt_i32_f32_e32 v148, v148
	v_fma_f32 v156, -v154, v155, 1.0
	v_fmac_f32_e32 v155, v156, v155
	v_div_scale_f32 v156, vcc, 1.0, v149, 1.0
	v_mul_f32_e32 v157, v156, v155
	v_fma_f32 v158, -v154, v157, v156
	v_fmac_f32_e32 v157, v158, v155
	v_fma_f32 v154, -v154, v157, v156
	v_div_fmas_f32 v154, v154, v155, v157
	v_div_fixup_f32 v149, v154, v149, 1.0
	v_mul_f32_e32 v149, 0x437f0000, v149
	v_rndne_f32_e32 v149, v149
	v_cvt_i32_f32_e32 v149, v149
	v_exp_f32_e32 v144, v144
	v_mul_f32_e32 v145, v145, v153
	v_mul_f32_e32 v145, 0xbfb8aa3b, v145
	v_lshl_or_b32 v148, v149, 8, v148
	v_mul_f32_e32 v149, v150, v153
	v_mul_f32_e32 v149, 0xbfb8aa3b, v149
	v_exp_f32_e32 v149, v149
	v_add_f32_e32 v144, 1.0, v144
	v_exp_f32_e32 v145, v145
	v_add_f32_e32 v149, 1.0, v149
	v_div_scale_f32 v150, s[22:23], v149, v149, 1.0
	v_rcp_f32_e32 v154, v150
	v_add_f32_e32 v145, 1.0, v145
	v_fma_f32 v155, -v150, v154, 1.0
	v_fmac_f32_e32 v154, v155, v154
	v_div_scale_f32 v155, vcc, 1.0, v149, 1.0
	v_mul_f32_e32 v156, v155, v154
	v_fma_f32 v157, -v150, v156, v155
	v_fmac_f32_e32 v156, v157, v154
	v_fma_f32 v150, -v150, v156, v155
	v_div_fmas_f32 v150, v150, v154, v156
	v_div_fixup_f32 v149, v150, v149, 1.0
	v_mul_f32_e32 v150, v151, v153
	v_mul_f32_e32 v150, 0xbfb8aa3b, v150
	v_exp_f32_e32 v150, v150
	v_mul_f32_e32 v149, 0x437f0000, v149
	v_rndne_f32_e32 v149, v149
	v_cvt_i32_f32_sdwa v149, v149 dst_sel:WORD_1 dst_unused:UNUSED_PAD src0_sel:DWORD
	v_add_f32_e32 v150, 1.0, v150
	v_div_scale_f32 v151, s[22:23], v150, v150, 1.0
	v_rcp_f32_e32 v154, v151
	s_nop 0
	v_fma_f32 v155, -v151, v154, 1.0
	v_fmac_f32_e32 v154, v155, v154
	v_div_scale_f32 v155, vcc, 1.0, v150, 1.0
	v_mul_f32_e32 v156, v155, v154
	v_fma_f32 v157, -v151, v156, v155
	v_fmac_f32_e32 v156, v157, v154
	v_fma_f32 v151, -v151, v156, v155
; DI float sigmoidf_(float x) { return 1.f / (1.f + __expf(-x)); }
; DI void merge_tile(const Params& p, int layer, int tm, int tn, bf16_t* smem) {
;     ...
;         const float rs = rstd_from16((const float*)(p.ws + O_SSQ) + (size_t)(row0 + i * 16) * 16, 1.f / 1024.f);
; #pragma unroll
;         for (int j = 0; j < 2; ++j) {
;           unsigned w = 0;
; #pragma unroll
;           for (int r = 0; r < 4; ++r) w |= (unsigned)__float2int_rn(sigmoidf_(acc[i][j][r] * rs) * 255.f) << (8 * r);
;           gsp[(i * 2 + j) * NTHR] = w;
	v_div_fmas_f32 v151, v151, v154, v156
	v_div_fixup_f32 v150, v151, v150, 1.0
	v_mul_f32_e32 v150, 0x437f0000, v150
	v_rndne_f32_e32 v150, v150
	v_cvt_i32_f32_sdwa v150, v150 dst_sel:BYTE_3 dst_unused:UNUSED_PAD src0_sel:DWORD
	s_nop 0
	v_or3_b32 v148, v148, v149, v150
	v_div_scale_f32 v149, s[22:23], v144, v144, 1.0
	v_rcp_f32_e32 v150, v149
	s_nop 0
	v_fma_f32 v151, -v149, v150, 1.0
	v_fmac_f32_e32 v150, v151, v150
	v_div_scale_f32 v151, vcc, 1.0, v144, 1.0
	v_mul_f32_e32 v154, v151, v150
	v_fma_f32 v155, -v149, v154, v151
	v_fmac_f32_e32 v154, v155, v150
	v_fma_f32 v149, -v149, v154, v151
	v_div_fmas_f32 v149, v149, v150, v154
	v_div_fixup_f32 v144, v149, v144, 1.0
	v_div_scale_f32 v149, s[22:23], v145, v145, 1.0
	v_rcp_f32_e32 v150, v149
	v_mul_f32_e32 v144, 0x437f0000, v144
	v_rndne_f32_e32 v144, v144
	v_cvt_i32_f32_e32 v144, v144
	v_fma_f32 v151, -v149, v150, 1.0
	v_fmac_f32_e32 v150, v151, v150
	v_div_scale_f32 v151, vcc, 1.0, v145, 1.0
	v_mul_f32_e32 v154, v151, v150
	v_fma_f32 v155, -v149, v154, v151
	v_fmac_f32_e32 v154, v155, v150
	v_fma_f32 v149, -v149, v154, v151
	v_div_fmas_f32 v149, v149, v150, v154
	v_div_fixup_f32 v145, v149, v145, 1.0
	v_mul_f32_e32 v145, 0x437f0000, v145
	v_rndne_f32_e32 v145, v145
	v_cvt_i32_f32_e32 v145, v145
	v_lshl_or_b32 v144, v145, 8, v144
	v_mul_f32_e32 v145, v146, v153
	v_mul_f32_e32 v145, 0xbfb8aa3b, v145
	v_exp_f32_e32 v145, v145
	s_nop 0
	v_add_f32_e32 v145, 1.0, v145
	v_div_scale_f32 v146, s[22:23], v145, v145, 1.0
	v_rcp_f32_e32 v149, v146
	s_nop 0
	v_fma_f32 v150, -v146, v149, 1.0
	v_fmac_f32_e32 v149, v150, v149
	v_div_scale_f32 v150, vcc, 1.0, v145, 1.0
	v_mul_f32_e32 v151, v150, v149
	v_fma_f32 v154, -v146, v151, v150
	v_fmac_f32_e32 v151, v154, v149
	v_fma_f32 v146, -v146, v151, v150
	v_div_fmas_f32 v146, v146, v149, v151
	v_div_fixup_f32 v145, v146, v145, 1.0
	v_mul_f32_e32 v146, v147, v153
	v_mul_f32_e32 v146, 0xbfb8aa3b, v146
	v_exp_f32_e32 v146, v146
	v_mul_f32_e32 v145, 0x437f0000, v145
	v_rndne_f32_e32 v145, v145
	v_cvt_i32_f32_sdwa v145, v145 dst_sel:WORD_1 dst_unused:UNUSED_PAD src0_sel:DWORD
	v_add_f32_e32 v146, 1.0, v146
	v_div_scale_f32 v147, s[22:23], v146, v146, 1.0
	v_rcp_f32_e32 v149, v147
	s_nop 0
	v_fma_f32 v150, -v147, v149, 1.0
	v_fmac_f32_e32 v149, v150, v149
	v_div_scale_f32 v150, vcc, 1.0, v146, 1.0
	v_mul_f32_e32 v151, v150, v149
	v_fma_f32 v153, -v147, v151, v150
	v_fmac_f32_e32 v151, v153, v149
	v_fma_f32 v147, -v147, v151, v150
	v_div_fmas_f32 v147, v147, v149, v151
	v_div_fixup_f32 v146, v147, v146, 1.0
	v_mul_f32_e32 v146, 0x437f0000, v146
	v_rndne_f32_e32 v146, v146
	v_cvt_i32_f32_sdwa v146, v146 dst_sel:BYTE_3 dst_unused:UNUSED_PAD src0_sel:DWORD
	s_nop 0
	v_or3_b32 v144, v144, v145, v146
	ds_write2st64_b32 v228, v148, v144 offset1:8
	v_or_b32_e32 v144, 16, v152
	v_ashrrev_i32_e32 v145, 31, v144
	v_lshlrev_b64 v[144:145], 6, v[144:145]
	v_lshl_add_u64 v[158:159], s[0:1], 0, v[144:145]
	v_bfe_u32 v244, v158, 6, 8
	v_lshlrev_b32_e32 v244, 3, v244
	v_add_u32_e32 v244, 0x24010, v244
	v_or_b32_e32 v246, 1, v158
	ds_read_b64 v[248:249], v244
	s_waitcnt lgkmcnt(0)
	v_cmp_ne_u32_e64 s[100:101], v248, v246
	s_nop 1
	s_and_saveexec_b64 s[98:99], s[100:101]
	s_cbranch_execz .LrcE0_1
	global_load_dwordx4 v[144:147], v[158:159], off offset:48
	global_load_dwordx4 v[148:151], v[158:159], off offset:32
	global_load_dwordx4 v[154:157], v[158:159], off offset:16
	s_nop 0
	global_load_dwordx4 v[158:161], v[158:159], off
	s_waitcnt vmcnt(2)
	v_add_f32_e32 v148, v148, v149
	v_add_f32_e32 v150, v150, v151
	s_waitcnt vmcnt(0)
	v_mov_b32_e32 v162, v159
	v_mov_b32_e32 v163, v160
	v_mov_b32_e32 v159, v161
	v_mov_b32_e32 v160, v155
	v_mov_b32_e32 v161, v156
	v_mov_b32_e32 v155, v157
	v_pk_add_f32 v[158:159], v[162:163], v[158:159]
	v_pk_add_f32 v[154:155], v[160:161], v[154:155]
	v_pk_add_f32 v[158:159], v[158:159], v[158:159] op_sel:[0,1] op_sel_hi:[1,0]
	v_pk_add_f32 v[154:155], v[154:155], v[154:155] op_sel:[0,1] op_sel_hi:[1,0]
	v_mov_b32_e32 v159, v144
	v_mov_b32_e32 v155, v145
	v_mov_b32_e32 v149, v146
	v_mov_b32_e32 v151, v147
	v_pk_add_f32 v[144:145], v[158:159], v[154:155]
	v_pk_add_f32 v[146:147], v[148:149], v[150:151]
	v_pk_add_f32 v[144:145], v[144:145], v[146:147]
	v_add_f32_e32 v144, v144, v145
	v_fmamk_f32 v144, v144, 0x3a800000, v225
	v_cmp_gt_f32_e32 vcc, s35, v144
	v_mul_f32_e32 v145, 0x4b800000, v144
	v_cndmask_b32_e32 v144, v144, v145, vcc
	v_rsq_f32_e32 v144, v144
	v_mul_f32_e32 v145, 0x45800000, v144
	v_cndmask_b32_e32 v144, v144, v145, vcc
	s_nop 0
	v_mov_b32_e32 v247, v144
	ds_write_b64 v244, v[246:247]
; DI float sigmoidf_(float x) { return 1.f / (1.f + __expf(-x)); }
; DI void merge_tile(const Params& p, int layer, int tm, int tn, bf16_t* smem) {
;     ...
;         const float rs = rstd_from16((const float*)(p.ws + O_SSQ) + (size_t)(row0 + i * 16) * 16, 1.f / 1024.f);
; #pragma unroll
;         for (int j = 0; j < 2; ++j) {
;           unsigned w = 0;
; #pragma unroll
;           for (int r = 0; r < 4; ++r) w |= (unsigned)__float2int_rn(sigmoidf_(acc[i][j][r] * rs) * 255.f) << (8 * r);
;           gsp[(i * 2 + j) * NTHR] = w;
.LrcE0_1:
	s_or_b64 exec, exec, s[98:99]
	s_waitcnt vmcnt(0)
	v_cndmask_b32_e64 v144, v249, v144, s[100:101]
	v_mov_b64_e32 v[162:163], v[78:79]
	v_mov_b64_e32 v[158:159], v[82:83]
	v_mov_b64_e32 v[160:161], v[76:77]
	v_mov_b64_e32 v[156:157], v[80:81]
	v_mul_f32_e32 v140, v140, v144
	v_mul_f32_e32 v140, 0xbfb8aa3b, v140
	v_exp_f32_e32 v140, v140
	v_mul_f32_e32 v141, v141, v144
	v_mul_f32_e32 v141, 0xbfb8aa3b, v141
	v_exp_f32_e32 v141, v141
	v_add_f32_e32 v140, 1.0, v140
	v_div_scale_f32 v145, s[22:23], v140, v140, 1.0
	v_rcp_f32_e32 v146, v145
	v_add_f32_e32 v141, 1.0, v141
	v_mul_f32_e32 v136, v136, v144
	v_mul_f32_e32 v136, 0xbfb8aa3b, v136
	v_fma_f32 v147, -v145, v146, 1.0
	v_fmac_f32_e32 v146, v147, v146
	v_div_scale_f32 v147, vcc, 1.0, v140, 1.0
	v_mul_f32_e32 v148, v147, v146
	v_fma_f32 v149, -v145, v148, v147
	v_fmac_f32_e32 v148, v149, v146
	v_fma_f32 v145, -v145, v148, v147
	v_div_fmas_f32 v145, v145, v146, v148
	v_div_fixup_f32 v140, v145, v140, 1.0
	v_div_scale_f32 v145, s[22:23], v141, v141, 1.0
	v_rcp_f32_e32 v146, v145
	v_mul_f32_e32 v140, 0x437f0000, v140
	v_rndne_f32_e32 v140, v140
	v_cvt_i32_f32_e32 v140, v140
	v_fma_f32 v147, -v145, v146, 1.0
	v_fmac_f32_e32 v146, v147, v146
	v_div_scale_f32 v147, vcc, 1.0, v141, 1.0
	v_mul_f32_e32 v148, v147, v146
	v_fma_f32 v149, -v145, v148, v147
	v_fmac_f32_e32 v148, v149, v146
	v_fma_f32 v145, -v145, v148, v147
	v_div_fmas_f32 v145, v145, v146, v148
	v_div_fixup_f32 v141, v145, v141, 1.0
	v_mul_f32_e32 v141, 0x437f0000, v141
	v_rndne_f32_e32 v141, v141
	v_cvt_i32_f32_e32 v141, v141
	v_exp_f32_e32 v136, v136
	v_mul_f32_e32 v137, v137, v144
	v_mul_f32_e32 v137, 0xbfb8aa3b, v137
	v_lshl_or_b32 v140, v141, 8, v140
	v_mul_f32_e32 v141, v142, v144
	v_mul_f32_e32 v141, 0xbfb8aa3b, v141
	v_exp_f32_e32 v141, v141
	v_add_f32_e32 v136, 1.0, v136
	v_exp_f32_e32 v137, v137
	v_add_f32_e32 v141, 1.0, v141
	v_div_scale_f32 v142, s[22:23], v141, v141, 1.0
	v_rcp_f32_e32 v145, v142
	v_add_f32_e32 v137, 1.0, v137
	v_fma_f32 v146, -v142, v145, 1.0
	v_fmac_f32_e32 v145, v146, v145
	v_div_scale_f32 v146, vcc, 1.0, v141, 1.0
	v_mul_f32_e32 v147, v146, v145
	v_fma_f32 v148, -v142, v147, v146
	v_fmac_f32_e32 v147, v148, v145
	v_fma_f32 v142, -v142, v147, v146
	v_div_fmas_f32 v142, v142, v145, v147
	v_div_fixup_f32 v141, v142, v141, 1.0
	v_mul_f32_e32 v142, v143, v144
	v_mul_f32_e32 v142, 0xbfb8aa3b, v142
	v_exp_f32_e32 v142, v142
	v_mul_f32_e32 v141, 0x437f0000, v141
	v_rndne_f32_e32 v141, v141
	v_cvt_i32_f32_sdwa v141, v141 dst_sel:WORD_1 dst_unused:UNUSED_PAD src0_sel:DWORD
	v_add_f32_e32 v142, 1.0, v142
	v_div_scale_f32 v143, s[22:23], v142, v142, 1.0
	v_rcp_f32_e32 v145, v143
	s_nop 0
	v_fma_f32 v146, -v143, v145, 1.0
	v_fmac_f32_e32 v145, v146, v145
	v_div_scale_f32 v146, vcc, 1.0, v142, 1.0
	v_mul_f32_e32 v147, v146, v145
	v_fma_f32 v148, -v143, v147, v146
	v_fmac_f32_e32 v147, v148, v145
	v_fma_f32 v143, -v143, v147, v146
	v_div_fmas_f32 v143, v143, v145, v147
	v_div_fixup_f32 v142, v143, v142, 1.0
	v_mul_f32_e32 v142, 0x437f0000, v142
	v_rndne_f32_e32 v142, v142
	v_cvt_i32_f32_sdwa v142, v142 dst_sel:BYTE_3 dst_unused:UNUSED_PAD src0_sel:DWORD
	s_nop 0
	v_or3_b32 v140, v140, v141, v142
	v_div_scale_f32 v141, s[22:23], v136, v136, 1.0
	v_rcp_f32_e32 v142, v141
	s_nop 0
	v_fma_f32 v143, -v141, v142, 1.0
	v_fmac_f32_e32 v142, v143, v142
	v_div_scale_f32 v143, vcc, 1.0, v136, 1.0
	v_mul_f32_e32 v145, v143, v142
	v_fma_f32 v146, -v141, v145, v143
	v_fmac_f32_e32 v145, v146, v142
	v_fma_f32 v141, -v141, v145, v143
	v_div_fmas_f32 v141, v141, v142, v145
	v_div_fixup_f32 v136, v141, v136, 1.0
	v_div_scale_f32 v141, s[22:23], v137, v137, 1.0
	v_rcp_f32_e32 v142, v141
	v_mul_f32_e32 v136, 0x437f0000, v136
	v_rndne_f32_e32 v136, v136
	v_cvt_i32_f32_e32 v136, v136
	v_fma_f32 v143, -v141, v142, 1.0
	v_fmac_f32_e32 v142, v143, v142
	v_div_scale_f32 v143, vcc, 1.0, v137, 1.0
	v_mul_f32_e32 v145, v143, v142
	v_fma_f32 v146, -v141, v145, v143
	v_fmac_f32_e32 v145, v146, v142
	v_fma_f32 v141, -v141, v145, v143
	v_div_fmas_f32 v141, v141, v142, v145
	v_div_fixup_f32 v137, v141, v137, 1.0
	v_mul_f32_e32 v137, 0x437f0000, v137
	v_rndne_f32_e32 v137, v137
	v_cvt_i32_f32_e32 v137, v137
	v_lshl_or_b32 v136, v137, 8, v136
	v_mul_f32_e32 v137, v138, v144
	v_mul_f32_e32 v137, 0xbfb8aa3b, v137
	v_exp_f32_e32 v137, v137
	s_nop 0
	v_add_f32_e32 v137, 1.0, v137
	v_div_scale_f32 v138, s[22:23], v137, v137, 1.0
	v_rcp_f32_e32 v141, v138
	s_nop 0
	v_fma_f32 v142, -v138, v141, 1.0
	v_fmac_f32_e32 v141, v142, v141
	v_div_scale_f32 v142, vcc, 1.0, v137, 1.0
	v_mul_f32_e32 v143, v142, v141
	v_fma_f32 v145, -v138, v143, v142
	v_fmac_f32_e32 v143, v145, v141
	v_fma_f32 v138, -v138, v143, v142
	v_div_fmas_f32 v138, v138, v141, v143
	v_div_fixup_f32 v137, v138, v137, 1.0
	v_mul_f32_e32 v138, v139, v144
	v_mul_f32_e32 v138, 0xbfb8aa3b, v138
	v_exp_f32_e32 v138, v138
	v_mul_f32_e32 v137, 0x437f0000, v137
	v_rndne_f32_e32 v137, v137
	v_cvt_i32_f32_sdwa v137, v137 dst_sel:WORD_1 dst_unused:UNUSED_PAD src0_sel:DWORD
	v_add_f32_e32 v138, 1.0, v138
	v_div_scale_f32 v139, s[22:23], v138, v138, 1.0
	v_rcp_f32_e32 v141, v139
	s_nop 0
	v_fma_f32 v142, -v139, v141, 1.0
	v_fmac_f32_e32 v141, v142, v141
	v_div_scale_f32 v142, vcc, 1.0, v138, 1.0
	v_mul_f32_e32 v143, v142, v141
	v_fma_f32 v144, -v139, v143, v142
	v_fmac_f32_e32 v143, v144, v141
	v_fma_f32 v139, -v139, v143, v142
	v_div_fmas_f32 v139, v139, v141, v143
	v_div_fixup_f32 v138, v139, v138, 1.0
	v_mul_f32_e32 v138, 0x437f0000, v138
	v_rndne_f32_e32 v138, v138
	v_cvt_i32_f32_sdwa v138, v138 dst_sel:BYTE_3 dst_unused:UNUSED_PAD src0_sel:DWORD
	s_nop 0
	v_or3_b32 v136, v136, v137, v138
	ds_write2st64_b32 v228, v140, v136 offset0:16 offset1:24
	v_or_b32_e32 v136, 32, v152
	v_ashrrev_i32_e32 v137, 31, v136
	v_lshlrev_b64 v[136:137], 6, v[136:137]
	v_lshl_add_u64 v[148:149], s[0:1], 0, v[136:137]
	v_bfe_u32 v244, v148, 6, 8
	v_lshlrev_b32_e32 v244, 3, v244
	v_add_u32_e32 v244, 0x24010, v244
	v_or_b32_e32 v246, 1, v148
	ds_read_b64 v[248:249], v244
	s_waitcnt lgkmcnt(0)
	v_cmp_ne_u32_e64 s[100:101], v248, v246
	s_nop 1
	s_and_saveexec_b64 s[98:99], s[100:101]
	s_cbranch_execz .LrcE0_2
; DI float sigmoidf_(float x) { return 1.f / (1.f + __expf(-x)); }
; DI float rstd_from16(const float* p, float inv_n) {
;   const f32x4 a = *(const f32x4*)p, b = *(const f32x4*)(p + 4), c = *(const f32x4*)(p + 8), d = *(const f32x4*)(p + 12);
;   const float s = ((a[0] + a[1]) + (a[2] + a[3])) + ((b[0] + b[1]) + (b[2] + b[3])) + ((c[0] + c[1]) + (c[2] + c[3])) + ((d[0] + d[1]) + (d[2] + d[3]));
;   return rsqrtf(s * inv_n + EPS_);
; DI void merge_tile(const Params& p, int layer, int tm, int tn, bf16_t* smem) {
;     ...
;         const float rs = rstd_from16((const float*)(p.ws + O_SSQ) + (size_t)(row0 + i * 16) * 16, 1.f / 1024.f);
; #pragma unroll
;         for (int j = 0; j < 2; ++j) {
;           unsigned w = 0;
; #pragma unroll
;           for (int r = 0; r < 4; ++r) w |= (unsigned)__float2int_rn(sigmoidf_(acc[i][j][r] * rs) * 255.f) << (8 * r);
;           gsp[(i * 2 + j) * NTHR] = w;
	global_load_dwordx4 v[136:139], v[148:149], off offset:48
	global_load_dwordx4 v[140:143], v[148:149], off offset:32
	global_load_dwordx4 v[144:147], v[148:149], off offset:16
	s_nop 0
	global_load_dwordx4 v[148:151], v[148:149], off
	s_waitcnt vmcnt(2)
	v_add_f32_e32 v140, v140, v141
	v_add_f32_e32 v142, v142, v143
	s_waitcnt vmcnt(0)
	v_mov_b32_e32 v154, v149
	v_mov_b32_e32 v155, v150
	v_mov_b32_e32 v149, v151
	v_mov_b32_e32 v150, v145
	v_mov_b32_e32 v151, v146
	v_mov_b32_e32 v145, v147
	v_pk_add_f32 v[148:149], v[154:155], v[148:149]
	v_pk_add_f32 v[144:145], v[150:151], v[144:145]
	v_pk_add_f32 v[148:149], v[148:149], v[148:149] op_sel:[0,1] op_sel_hi:[1,0]
	v_pk_add_f32 v[144:145], v[144:145], v[144:145] op_sel:[0,1] op_sel_hi:[1,0]
	v_mov_b32_e32 v149, v136
	v_mov_b32_e32 v145, v137
	v_mov_b32_e32 v141, v138
	v_mov_b32_e32 v143, v139
	v_pk_add_f32 v[136:137], v[148:149], v[144:145]
	v_pk_add_f32 v[138:139], v[140:141], v[142:143]
	s_nop 0
	v_pk_add_f32 v[136:137], v[136:137], v[138:139]
	s_nop 0
	v_add_f32_e32 v136, v136, v137
	v_fmamk_f32 v136, v136, 0x3a800000, v225
	v_cmp_gt_f32_e32 vcc, s35, v136
	v_mul_f32_e32 v137, 0x4b800000, v136
	s_nop 0
	v_cndmask_b32_e32 v136, v136, v137, vcc
	v_rsq_f32_e32 v136, v136
	s_nop 0
	v_mul_f32_e32 v137, 0x45800000, v136
	v_cndmask_b32_e32 v136, v136, v137, vcc
	s_nop 0
	v_mov_b32_e32 v247, v136
	ds_write_b64 v244, v[246:247]
.LrcE0_2:
	s_or_b64 exec, exec, s[98:99]
	s_waitcnt vmcnt(0)
	v_cndmask_b32_e64 v136, v249, v136, s[100:101]
	v_mul_f32_e32 v132, v132, v136
	v_mul_f32_e32 v132, 0xbfb8aa3b, v132
	v_exp_f32_e32 v132, v132
	v_mul_f32_e32 v133, v133, v136
	v_mul_f32_e32 v133, 0xbfb8aa3b, v133
	v_exp_f32_e32 v133, v133
	v_add_f32_e32 v132, 1.0, v132
	v_div_scale_f32 v137, s[22:23], v132, v132, 1.0
	v_rcp_f32_e32 v138, v137
	v_add_f32_e32 v133, 1.0, v133
	v_mul_f32_e32 v128, v128, v136
	v_mul_f32_e32 v128, 0xbfb8aa3b, v128
	v_fma_f32 v139, -v137, v138, 1.0
	v_fmac_f32_e32 v138, v139, v138
	v_div_scale_f32 v139, vcc, 1.0, v132, 1.0
	v_mul_f32_e32 v140, v139, v138
	v_fma_f32 v141, -v137, v140, v139
	v_fmac_f32_e32 v140, v141, v138
	v_fma_f32 v137, -v137, v140, v139
	v_div_fmas_f32 v137, v137, v138, v140
	v_div_fixup_f32 v132, v137, v132, 1.0
	v_div_scale_f32 v137, s[22:23], v133, v133, 1.0
	v_rcp_f32_e32 v138, v137
	v_mul_f32_e32 v132, 0x437f0000, v132
	v_rndne_f32_e32 v132, v132
	v_cvt_i32_f32_e32 v132, v132
	v_fma_f32 v139, -v137, v138, 1.0
	v_fmac_f32_e32 v138, v139, v138
	v_div_scale_f32 v139, vcc, 1.0, v133, 1.0
	v_mul_f32_e32 v140, v139, v138
	v_fma_f32 v141, -v137, v140, v139
	v_fmac_f32_e32 v140, v141, v138
	v_fma_f32 v137, -v137, v140, v139
	v_div_fmas_f32 v137, v137, v138, v140
	v_div_fixup_f32 v133, v137, v133, 1.0
	v_mul_f32_e32 v133, 0x437f0000, v133
	v_rndne_f32_e32 v133, v133
	v_cvt_i32_f32_e32 v133, v133
	v_exp_f32_e32 v128, v128
	v_mul_f32_e32 v129, v129, v136
	v_mul_f32_e32 v129, 0xbfb8aa3b, v129
	v_lshl_or_b32 v132, v133, 8, v132
	v_mul_f32_e32 v133, v134, v136
	v_mul_f32_e32 v133, 0xbfb8aa3b, v133
	v_exp_f32_e32 v133, v133
	v_add_f32_e32 v128, 1.0, v128
	v_exp_f32_e32 v129, v129
	v_add_f32_e32 v133, 1.0, v133
	v_div_scale_f32 v134, s[22:23], v133, v133, 1.0
	v_rcp_f32_e32 v137, v134
	v_add_f32_e32 v129, 1.0, v129
	v_fma_f32 v138, -v134, v137, 1.0
	v_fmac_f32_e32 v137, v138, v137
	v_div_scale_f32 v138, vcc, 1.0, v133, 1.0
	v_mul_f32_e32 v139, v138, v137
	v_fma_f32 v140, -v134, v139, v138
	v_fmac_f32_e32 v139, v140, v137
	v_fma_f32 v134, -v134, v139, v138
	v_div_fmas_f32 v134, v134, v137, v139
	v_div_fixup_f32 v133, v134, v133, 1.0
	v_mul_f32_e32 v134, v135, v136
	v_mul_f32_e32 v134, 0xbfb8aa3b, v134
	v_exp_f32_e32 v134, v134
	v_mul_f32_e32 v133, 0x437f0000, v133
	v_rndne_f32_e32 v133, v133
	v_cvt_i32_f32_sdwa v133, v133 dst_sel:WORD_1 dst_unused:UNUSED_PAD src0_sel:DWORD
	v_add_f32_e32 v134, 1.0, v134
	v_div_scale_f32 v135, s[22:23], v134, v134, 1.0
	v_rcp_f32_e32 v137, v135
	s_nop 0
	v_fma_f32 v138, -v135, v137, 1.0
	v_fmac_f32_e32 v137, v138, v137
	v_div_scale_f32 v138, vcc, 1.0, v134, 1.0
	v_mul_f32_e32 v139, v138, v137
	v_fma_f32 v140, -v135, v139, v138
	v_fmac_f32_e32 v139, v140, v137
	v_fma_f32 v135, -v135, v139, v138
	v_div_fmas_f32 v135, v135, v137, v139
	v_div_fixup_f32 v134, v135, v134, 1.0
	v_mul_f32_e32 v134, 0x437f0000, v134
	v_rndne_f32_e32 v134, v134
	v_cvt_i32_f32_sdwa v134, v134 dst_sel:BYTE_3 dst_unused:UNUSED_PAD src0_sel:DWORD
	s_nop 0
	v_or3_b32 v132, v132, v133, v134
	v_div_scale_f32 v133, s[22:23], v128, v128, 1.0
	v_rcp_f32_e32 v134, v133
	s_nop 0
	v_fma_f32 v135, -v133, v134, 1.0
	v_fmac_f32_e32 v134, v135, v134
	v_div_scale_f32 v135, vcc, 1.0, v128, 1.0
	v_mul_f32_e32 v137, v135, v134
	v_fma_f32 v138, -v133, v137, v135
	v_fmac_f32_e32 v137, v138, v134
	v_fma_f32 v133, -v133, v137, v135
	v_div_fmas_f32 v133, v133, v134, v137
	v_div_fixup_f32 v128, v133, v128, 1.0
	v_div_scale_f32 v133, s[22:23], v129, v129, 1.0
	v_rcp_f32_e32 v134, v133
	v_mul_f32_e32 v128, 0x437f0000, v128
	v_rndne_f32_e32 v128, v128
	v_cvt_i32_f32_e32 v128, v128
	v_fma_f32 v135, -v133, v134, 1.0
	v_fmac_f32_e32 v134, v135, v134
	v_div_scale_f32 v135, vcc, 1.0, v129, 1.0
	v_mul_f32_e32 v137, v135, v134
	v_fma_f32 v138, -v133, v137, v135
	v_fmac_f32_e32 v137, v138, v134
	v_fma_f32 v133, -v133, v137, v135
	v_div_fmas_f32 v133, v133, v134, v137
	v_div_fixup_f32 v129, v133, v129, 1.0
	v_mul_f32_e32 v129, 0x437f0000, v129
	v_rndne_f32_e32 v129, v129
	v_cvt_i32_f32_e32 v129, v129
	v_lshl_or_b32 v128, v129, 8, v128
	v_mul_f32_e32 v129, v130, v136
	v_mul_f32_e32 v129, 0xbfb8aa3b, v129
	v_exp_f32_e32 v129, v129
	s_nop 0
	v_add_f32_e32 v129, 1.0, v129
	v_div_scale_f32 v130, s[22:23], v129, v129, 1.0
; DI float sigmoidf_(float x) { return 1.f / (1.f + __expf(-x)); }
; DI float rstd_from16(const float* p, float inv_n) {
;   const f32x4 a = *(const f32x4*)p, b = *(const f32x4*)(p + 4), c = *(const f32x4*)(p + 8), d = *(const f32x4*)(p + 12);
;   const float s = ((a[0] + a[1]) + (a[2] + a[3])) + ((b[0] + b[1]) + (b[2] + b[3])) + ((c[0] + c[1]) + (c[2] + c[3])) + ((d[0] + d[1]) + (d[2] + d[3]));
;   return rsqrtf(s * inv_n + EPS_);
; DI void merge_tile(const Params& p, int layer, int tm, int tn, bf16_t* smem) {
;     ...
;         const float rs = rstd_from16((const float*)(p.ws + O_SSQ) + (size_t)(row0 + i * 16) * 16, 1.f / 1024.f);
; #pragma unroll
;         for (int j = 0; j < 2; ++j) {
;           unsigned w = 0;
; #pragma unroll
;           for (int r = 0; r < 4; ++r) w |= (unsigned)__float2int_rn(sigmoidf_(acc[i][j][r] * rs) * 255.f) << (8 * r);
;           gsp[(i * 2 + j) * NTHR] = w;
	v_rcp_f32_e32 v133, v130
	s_nop 0
	v_fma_f32 v134, -v130, v133, 1.0
	v_fmac_f32_e32 v133, v134, v133
	v_div_scale_f32 v134, vcc, 1.0, v129, 1.0
	v_mul_f32_e32 v135, v134, v133
	v_fma_f32 v137, -v130, v135, v134
	v_fmac_f32_e32 v135, v137, v133
	v_fma_f32 v130, -v130, v135, v134
	v_div_fmas_f32 v130, v130, v133, v135
	v_div_fixup_f32 v129, v130, v129, 1.0
	v_mul_f32_e32 v130, v131, v136
	v_mul_f32_e32 v130, 0xbfb8aa3b, v130
	v_exp_f32_e32 v130, v130
	v_mul_f32_e32 v129, 0x437f0000, v129
	v_rndne_f32_e32 v129, v129
	v_cvt_i32_f32_sdwa v129, v129 dst_sel:WORD_1 dst_unused:UNUSED_PAD src0_sel:DWORD
	v_add_f32_e32 v130, 1.0, v130
	v_div_scale_f32 v131, s[22:23], v130, v130, 1.0
	v_rcp_f32_e32 v133, v131
	s_nop 0
	v_fma_f32 v134, -v131, v133, 1.0
	v_fmac_f32_e32 v133, v134, v133
	v_div_scale_f32 v134, vcc, 1.0, v130, 1.0
	v_mul_f32_e32 v135, v134, v133
	v_fma_f32 v136, -v131, v135, v134
	v_fmac_f32_e32 v135, v136, v133
	v_fma_f32 v131, -v131, v135, v134
	v_div_fmas_f32 v131, v131, v133, v135
	v_div_fixup_f32 v130, v131, v130, 1.0
	v_mul_f32_e32 v130, 0x437f0000, v130
	v_rndne_f32_e32 v130, v130
	v_cvt_i32_f32_sdwa v130, v130 dst_sel:BYTE_3 dst_unused:UNUSED_PAD src0_sel:DWORD
	s_nop 0
	v_or3_b32 v128, v128, v129, v130
	ds_write2st64_b32 v228, v132, v128 offset0:32 offset1:40
	v_or_b32_e32 v128, 48, v152
	v_ashrrev_i32_e32 v129, 31, v128
	v_lshlrev_b64 v[128:129], 6, v[128:129]
	v_lshl_add_u64 v[140:141], s[0:1], 0, v[128:129]
	v_bfe_u32 v244, v140, 6, 8
	v_lshlrev_b32_e32 v244, 3, v244
	v_add_u32_e32 v244, 0x24010, v244
	v_or_b32_e32 v246, 1, v140
	ds_read_b64 v[248:249], v244
	s_waitcnt lgkmcnt(0)
	v_cmp_ne_u32_e64 s[100:101], v248, v246
	s_nop 1
	s_and_saveexec_b64 s[98:99], s[100:101]
	s_cbranch_execz .LrcE0_3
	global_load_dwordx4 v[128:131], v[140:141], off offset:48
	global_load_dwordx4 v[132:135], v[140:141], off offset:32
	global_load_dwordx4 v[136:139], v[140:141], off offset:16
	s_nop 0
	global_load_dwordx4 v[140:143], v[140:141], off
	s_waitcnt vmcnt(2)
	v_add_f32_e32 v132, v132, v133
	v_add_f32_e32 v134, v134, v135
	s_waitcnt vmcnt(0)
	v_mov_b32_e32 v144, v141
	v_mov_b32_e32 v145, v142
	v_mov_b32_e32 v141, v143
	v_mov_b32_e32 v142, v137
	v_mov_b32_e32 v143, v138
	v_mov_b32_e32 v137, v139
	v_pk_add_f32 v[140:141], v[144:145], v[140:141]
	v_pk_add_f32 v[136:137], v[142:143], v[136:137]
	v_pk_add_f32 v[140:141], v[140:141], v[140:141] op_sel:[0,1] op_sel_hi:[1,0]
	v_pk_add_f32 v[136:137], v[136:137], v[136:137] op_sel:[0,1] op_sel_hi:[1,0]
	v_mov_b32_e32 v141, v128
	v_mov_b32_e32 v137, v129
	v_mov_b32_e32 v133, v130
	v_mov_b32_e32 v135, v131
	v_pk_add_f32 v[128:129], v[140:141], v[136:137]
	v_pk_add_f32 v[130:131], v[132:133], v[134:135]
	s_nop 0
	v_pk_add_f32 v[128:129], v[128:129], v[130:131]
	s_nop 0
	v_add_f32_e32 v128, v128, v129
	v_fmamk_f32 v128, v128, 0x3a800000, v225
	v_cmp_gt_f32_e32 vcc, s35, v128
	v_mul_f32_e32 v129, 0x4b800000, v128
	s_nop 0
	v_cndmask_b32_e32 v128, v128, v129, vcc
	v_rsq_f32_e32 v128, v128
	s_nop 0
	v_mul_f32_e32 v129, 0x45800000, v128
	v_cndmask_b32_e32 v128, v128, v129, vcc
	s_nop 0
	v_mov_b32_e32 v247, v128
	ds_write_b64 v244, v[246:247]
.LrcE0_3:
	s_or_b64 exec, exec, s[98:99]
	s_waitcnt vmcnt(0)
	v_cndmask_b32_e64 v128, v249, v128, s[100:101]
	v_mul_f32_e32 v124, v124, v128
	v_mul_f32_e32 v124, 0xbfb8aa3b, v124
	v_exp_f32_e32 v124, v124
	v_mul_f32_e32 v125, v125, v128
	v_mul_f32_e32 v125, 0xbfb8aa3b, v125
	v_exp_f32_e32 v125, v125
	v_add_f32_e32 v124, 1.0, v124
	v_div_scale_f32 v129, s[22:23], v124, v124, 1.0
	v_rcp_f32_e32 v130, v129
	v_add_f32_e32 v125, 1.0, v125
	v_mul_f32_e32 v120, v120, v128
	v_mul_f32_e32 v120, 0xbfb8aa3b, v120
	v_fma_f32 v131, -v129, v130, 1.0
	v_fmac_f32_e32 v130, v131, v130
	v_div_scale_f32 v131, vcc, 1.0, v124, 1.0
	v_mul_f32_e32 v132, v131, v130
	v_fma_f32 v133, -v129, v132, v131
	v_fmac_f32_e32 v132, v133, v130
	v_fma_f32 v129, -v129, v132, v131
	v_div_fmas_f32 v129, v129, v130, v132
	v_div_fixup_f32 v124, v129, v124, 1.0
	v_div_scale_f32 v129, s[22:23], v125, v125, 1.0
	v_rcp_f32_e32 v130, v129
	v_mul_f32_e32 v124, 0x437f0000, v124
	v_rndne_f32_e32 v124, v124
	v_cvt_i32_f32_e32 v124, v124
	v_fma_f32 v131, -v129, v130, 1.0
	v_fmac_f32_e32 v130, v131, v130
	v_div_scale_f32 v131, vcc, 1.0, v125, 1.0
	v_mul_f32_e32 v132, v131, v130
	v_fma_f32 v133, -v129, v132, v131
	v_fmac_f32_e32 v132, v133, v130
	v_fma_f32 v129, -v129, v132, v131
	v_div_fmas_f32 v129, v129, v130, v132
	v_div_fixup_f32 v125, v129, v125, 1.0
	v_mul_f32_e32 v125, 0x437f0000, v125
	v_rndne_f32_e32 v125, v125
	v_cvt_i32_f32_e32 v125, v125
	v_exp_f32_e32 v120, v120
	v_mul_f32_e32 v121, v121, v128
	v_mul_f32_e32 v121, 0xbfb8aa3b, v121
	v_lshl_or_b32 v124, v125, 8, v124
	v_mul_f32_e32 v125, v126, v128
	v_mul_f32_e32 v125, 0xbfb8aa3b, v125
	v_exp_f32_e32 v125, v125
	v_add_f32_e32 v120, 1.0, v120
	v_exp_f32_e32 v121, v121
	v_add_f32_e32 v125, 1.0, v125
	v_div_scale_f32 v126, s[22:23], v125, v125, 1.0
	v_rcp_f32_e32 v129, v126
	v_add_f32_e32 v121, 1.0, v121
	v_fma_f32 v130, -v126, v129, 1.0
	v_fmac_f32_e32 v129, v130, v129
	v_div_scale_f32 v130, vcc, 1.0, v125, 1.0
	v_mul_f32_e32 v131, v130, v129
	v_fma_f32 v132, -v126, v131, v130
	v_fmac_f32_e32 v131, v132, v129
	v_fma_f32 v126, -v126, v131, v130
	v_div_fmas_f32 v126, v126, v129, v131
	v_div_fixup_f32 v125, v126, v125, 1.0
	v_mul_f32_e32 v126, v127, v128
	v_mul_f32_e32 v126, 0xbfb8aa3b, v126
	v_exp_f32_e32 v126, v126
	v_mul_f32_e32 v125, 0x437f0000, v125
	v_rndne_f32_e32 v125, v125
	v_cvt_i32_f32_sdwa v125, v125 dst_sel:WORD_1 dst_unused:UNUSED_PAD src0_sel:DWORD
	v_add_f32_e32 v126, 1.0, v126
	v_div_scale_f32 v127, s[22:23], v126, v126, 1.0
	v_rcp_f32_e32 v129, v127
; DI float sigmoidf_(float x) { return 1.f / (1.f + __expf(-x)); }
; DI float rstd_from16(const float* p, float inv_n) {
;   const f32x4 a = *(const f32x4*)p, b = *(const f32x4*)(p + 4), c = *(const f32x4*)(p + 8), d = *(const f32x4*)(p + 12);
;   const float s = ((a[0] + a[1]) + (a[2] + a[3])) + ((b[0] + b[1]) + (b[2] + b[3])) + ((c[0] + c[1]) + (c[2] + c[3])) + ((d[0] + d[1]) + (d[2] + d[3]));
;   return rsqrtf(s * inv_n + EPS_);
; DI void merge_tile(const Params& p, int layer, int tm, int tn, bf16_t* smem) {
;     ...
;         const float rs = rstd_from16((const float*)(p.ws + O_SSQ) + (size_t)(row0 + i * 16) * 16, 1.f / 1024.f);
; #pragma unroll
;         for (int j = 0; j < 2; ++j) {
;           unsigned w = 0;
; #pragma unroll
;           for (int r = 0; r < 4; ++r) w |= (unsigned)__float2int_rn(sigmoidf_(acc[i][j][r] * rs) * 255.f) << (8 * r);
;           gsp[(i * 2 + j) * NTHR] = w;
	s_nop 0
	v_fma_f32 v130, -v127, v129, 1.0
	v_fmac_f32_e32 v129, v130, v129
	v_div_scale_f32 v130, vcc, 1.0, v126, 1.0
	v_mul_f32_e32 v131, v130, v129
	v_fma_f32 v132, -v127, v131, v130
	v_fmac_f32_e32 v131, v132, v129
	v_fma_f32 v127, -v127, v131, v130
	v_div_fmas_f32 v127, v127, v129, v131
	v_div_fixup_f32 v126, v127, v126, 1.0
	v_mul_f32_e32 v126, 0x437f0000, v126
	v_rndne_f32_e32 v126, v126
	v_cvt_i32_f32_sdwa v126, v126 dst_sel:BYTE_3 dst_unused:UNUSED_PAD src0_sel:DWORD
	s_nop 0
	v_or3_b32 v124, v124, v125, v126
	v_div_scale_f32 v125, s[22:23], v120, v120, 1.0
	v_rcp_f32_e32 v126, v125
	s_nop 0
	v_fma_f32 v127, -v125, v126, 1.0
	v_fmac_f32_e32 v126, v127, v126
	v_div_scale_f32 v127, vcc, 1.0, v120, 1.0
	v_mul_f32_e32 v129, v127, v126
	v_fma_f32 v130, -v125, v129, v127
	v_fmac_f32_e32 v129, v130, v126
	v_fma_f32 v125, -v125, v129, v127
	v_div_fmas_f32 v125, v125, v126, v129
	v_div_fixup_f32 v120, v125, v120, 1.0
	v_div_scale_f32 v125, s[22:23], v121, v121, 1.0
	v_rcp_f32_e32 v126, v125
	v_mul_f32_e32 v120, 0x437f0000, v120
	v_rndne_f32_e32 v120, v120
	v_cvt_i32_f32_e32 v120, v120
	v_fma_f32 v127, -v125, v126, 1.0
	v_fmac_f32_e32 v126, v127, v126
	v_div_scale_f32 v127, vcc, 1.0, v121, 1.0
	v_mul_f32_e32 v129, v127, v126
	v_fma_f32 v130, -v125, v129, v127
	v_fmac_f32_e32 v129, v130, v126
	v_fma_f32 v125, -v125, v129, v127
	v_div_fmas_f32 v125, v125, v126, v129
	v_div_fixup_f32 v121, v125, v121, 1.0
	v_mul_f32_e32 v121, 0x437f0000, v121
	v_rndne_f32_e32 v121, v121
	v_cvt_i32_f32_e32 v121, v121
	v_lshl_or_b32 v120, v121, 8, v120
	v_mul_f32_e32 v121, v122, v128
	v_mul_f32_e32 v121, 0xbfb8aa3b, v121
	v_exp_f32_e32 v121, v121
	s_nop 0
	v_add_f32_e32 v121, 1.0, v121
	v_div_scale_f32 v122, s[22:23], v121, v121, 1.0
	v_rcp_f32_e32 v125, v122
	s_nop 0
	v_fma_f32 v126, -v122, v125, 1.0
	v_fmac_f32_e32 v125, v126, v125
	v_div_scale_f32 v126, vcc, 1.0, v121, 1.0
	v_mul_f32_e32 v127, v126, v125
	v_fma_f32 v129, -v122, v127, v126
	v_fmac_f32_e32 v127, v129, v125
	v_fma_f32 v122, -v122, v127, v126
	v_div_fmas_f32 v122, v122, v125, v127
	v_div_fixup_f32 v121, v122, v121, 1.0
	v_mul_f32_e32 v122, v123, v128
	v_mul_f32_e32 v122, 0xbfb8aa3b, v122
	v_exp_f32_e32 v122, v122
	v_mul_f32_e32 v121, 0x437f0000, v121
	v_rndne_f32_e32 v121, v121
	v_cvt_i32_f32_sdwa v121, v121 dst_sel:WORD_1 dst_unused:UNUSED_PAD src0_sel:DWORD
	v_add_f32_e32 v122, 1.0, v122
	v_div_scale_f32 v123, s[22:23], v122, v122, 1.0
	v_rcp_f32_e32 v125, v123
	s_nop 0
	v_fma_f32 v126, -v123, v125, 1.0
	v_fmac_f32_e32 v125, v126, v125
	v_div_scale_f32 v126, vcc, 1.0, v122, 1.0
	v_mul_f32_e32 v127, v126, v125
	v_fma_f32 v128, -v123, v127, v126
	v_fmac_f32_e32 v127, v128, v125
	v_fma_f32 v123, -v123, v127, v126
	v_div_fmas_f32 v123, v123, v125, v127
	v_div_fixup_f32 v122, v123, v122, 1.0
	v_mul_f32_e32 v122, 0x437f0000, v122
	v_rndne_f32_e32 v122, v122
	v_cvt_i32_f32_sdwa v122, v122 dst_sel:BYTE_3 dst_unused:UNUSED_PAD src0_sel:DWORD
	s_nop 0
	v_or3_b32 v120, v120, v121, v122
	ds_write2st64_b32 v228, v124, v120 offset0:48 offset1:56
	v_or_b32_e32 v120, 64, v152
	v_ashrrev_i32_e32 v121, 31, v120
	v_lshlrev_b64 v[120:121], 6, v[120:121]
	v_lshl_add_u64 v[132:133], s[0:1], 0, v[120:121]
	v_bfe_u32 v244, v132, 6, 8
	v_lshlrev_b32_e32 v244, 3, v244
	v_add_u32_e32 v244, 0x24010, v244
	v_or_b32_e32 v246, 1, v132
	ds_read_b64 v[248:249], v244
	s_waitcnt lgkmcnt(0)
	v_cmp_ne_u32_e64 s[100:101], v248, v246
	s_nop 1
	s_and_saveexec_b64 s[98:99], s[100:101]
	s_cbranch_execz .LrcE0_4
	global_load_dwordx4 v[120:123], v[132:133], off offset:48
	global_load_dwordx4 v[124:127], v[132:133], off offset:32
	global_load_dwordx4 v[128:131], v[132:133], off offset:16
	s_nop 0
	global_load_dwordx4 v[132:135], v[132:133], off
	s_waitcnt vmcnt(2)
	v_add_f32_e32 v124, v124, v125
	v_add_f32_e32 v126, v126, v127
	s_waitcnt vmcnt(0)
	v_mov_b32_e32 v136, v133
	v_mov_b32_e32 v137, v134
	v_mov_b32_e32 v133, v135
	v_mov_b32_e32 v134, v129
	v_mov_b32_e32 v135, v130
	v_mov_b32_e32 v129, v131
	v_pk_add_f32 v[132:133], v[136:137], v[132:133]
	v_pk_add_f32 v[128:129], v[134:135], v[128:129]
	v_pk_add_f32 v[132:133], v[132:133], v[132:133] op_sel:[0,1] op_sel_hi:[1,0]
	v_pk_add_f32 v[128:129], v[128:129], v[128:129] op_sel:[0,1] op_sel_hi:[1,0]
	v_mov_b32_e32 v133, v120
	v_mov_b32_e32 v129, v121
	v_mov_b32_e32 v125, v122
	v_mov_b32_e32 v127, v123
	v_pk_add_f32 v[120:121], v[132:133], v[128:129]
	v_pk_add_f32 v[122:123], v[124:125], v[126:127]
	s_nop 0
	v_pk_add_f32 v[120:121], v[120:121], v[122:123]
	s_nop 0
	v_add_f32_e32 v120, v120, v121
	v_fmamk_f32 v120, v120, 0x3a800000, v225
	v_cmp_gt_f32_e32 vcc, s35, v120
	v_mul_f32_e32 v121, 0x4b800000, v120
	s_nop 0
	v_cndmask_b32_e32 v120, v120, v121, vcc
	v_rsq_f32_e32 v120, v120
	s_nop 0
	v_mul_f32_e32 v121, 0x45800000, v120
	v_cndmask_b32_e32 v120, v120, v121, vcc
	s_nop 0
	v_mov_b32_e32 v247, v120
	ds_write_b64 v244, v[246:247]
; DI float sigmoidf_(float x) { return 1.f / (1.f + __expf(-x)); }
; DI float rstd_from16(const float* p, float inv_n) {
;   const f32x4 a = *(const f32x4*)p, b = *(const f32x4*)(p + 4), c = *(const f32x4*)(p + 8), d = *(const f32x4*)(p + 12);
;   const float s = ((a[0] + a[1]) + (a[2] + a[3])) + ((b[0] + b[1]) + (b[2] + b[3])) + ((c[0] + c[1]) + (c[2] + c[3])) + ((d[0] + d[1]) + (d[2] + d[3]));
;   return rsqrtf(s * inv_n + EPS_);
; DI void merge_tile(const Params& p, int layer, int tm, int tn, bf16_t* smem) {
;     ...
;         const float rs = rstd_from16((const float*)(p.ws + O_SSQ) + (size_t)(row0 + i * 16) * 16, 1.f / 1024.f);
; #pragma unroll
;         for (int j = 0; j < 2; ++j) {
;           unsigned w = 0;
; #pragma unroll
;           for (int r = 0; r < 4; ++r) w |= (unsigned)__float2int_rn(sigmoidf_(acc[i][j][r] * rs) * 255.f) << (8 * r);
;           gsp[(i * 2 + j) * NTHR] = w;
.LrcE0_4:
	s_or_b64 exec, exec, s[98:99]
	s_waitcnt vmcnt(0)
	v_cndmask_b32_e64 v120, v249, v120, s[100:101]
	v_mul_f32_e32 v116, v116, v120
	v_mul_f32_e32 v116, 0xbfb8aa3b, v116
	v_exp_f32_e32 v116, v116
	v_mul_f32_e32 v117, v117, v120
	v_mul_f32_e32 v117, 0xbfb8aa3b, v117
	v_exp_f32_e32 v117, v117
	v_add_f32_e32 v116, 1.0, v116
	v_div_scale_f32 v121, s[22:23], v116, v116, 1.0
	v_rcp_f32_e32 v122, v121
	v_add_f32_e32 v117, 1.0, v117
	v_mul_f32_e32 v112, v112, v120
	v_mul_f32_e32 v112, 0xbfb8aa3b, v112
	v_fma_f32 v123, -v121, v122, 1.0
	v_fmac_f32_e32 v122, v123, v122
	v_div_scale_f32 v123, vcc, 1.0, v116, 1.0
	v_mul_f32_e32 v124, v123, v122
	v_fma_f32 v125, -v121, v124, v123
	v_fmac_f32_e32 v124, v125, v122
	v_fma_f32 v121, -v121, v124, v123
	v_div_fmas_f32 v121, v121, v122, v124
	v_div_fixup_f32 v116, v121, v116, 1.0
	v_div_scale_f32 v121, s[22:23], v117, v117, 1.0
	v_rcp_f32_e32 v122, v121
	v_mul_f32_e32 v116, 0x437f0000, v116
	v_rndne_f32_e32 v116, v116
	v_cvt_i32_f32_e32 v116, v116
	v_fma_f32 v123, -v121, v122, 1.0
	v_fmac_f32_e32 v122, v123, v122
	v_div_scale_f32 v123, vcc, 1.0, v117, 1.0
	v_mul_f32_e32 v124, v123, v122
	v_fma_f32 v125, -v121, v124, v123
	v_fmac_f32_e32 v124, v125, v122
	v_fma_f32 v121, -v121, v124, v123
	v_div_fmas_f32 v121, v121, v122, v124
	v_div_fixup_f32 v117, v121, v117, 1.0
	v_mul_f32_e32 v117, 0x437f0000, v117
	v_rndne_f32_e32 v117, v117
	v_cvt_i32_f32_e32 v117, v117
	v_exp_f32_e32 v112, v112
	v_mul_f32_e32 v113, v113, v120
	v_mul_f32_e32 v113, 0xbfb8aa3b, v113
	v_lshl_or_b32 v116, v117, 8, v116
	v_mul_f32_e32 v117, v118, v120
	v_mul_f32_e32 v117, 0xbfb8aa3b, v117
	v_exp_f32_e32 v117, v117
	v_add_f32_e32 v112, 1.0, v112
	v_exp_f32_e32 v113, v113
	v_add_f32_e32 v117, 1.0, v117
	v_div_scale_f32 v118, s[22:23], v117, v117, 1.0
	v_rcp_f32_e32 v121, v118
	v_add_f32_e32 v113, 1.0, v113
	v_fma_f32 v122, -v118, v121, 1.0
	v_fmac_f32_e32 v121, v122, v121
	v_div_scale_f32 v122, vcc, 1.0, v117, 1.0
	v_mul_f32_e32 v123, v122, v121
	v_fma_f32 v124, -v118, v123, v122
	v_fmac_f32_e32 v123, v124, v121
	v_fma_f32 v118, -v118, v123, v122
	v_div_fmas_f32 v118, v118, v121, v123
	v_div_fixup_f32 v117, v118, v117, 1.0
	v_mul_f32_e32 v118, v119, v120
	v_mul_f32_e32 v118, 0xbfb8aa3b, v118
	v_exp_f32_e32 v118, v118
	v_mul_f32_e32 v117, 0x437f0000, v117
	v_rndne_f32_e32 v117, v117
	v_cvt_i32_f32_sdwa v117, v117 dst_sel:WORD_1 dst_unused:UNUSED_PAD src0_sel:DWORD
	v_add_f32_e32 v118, 1.0, v118
	v_div_scale_f32 v119, s[22:23], v118, v118, 1.0
	v_rcp_f32_e32 v121, v119
	s_nop 0
	v_fma_f32 v122, -v119, v121, 1.0
	v_fmac_f32_e32 v121, v122, v121
	v_div_scale_f32 v122, vcc, 1.0, v118, 1.0
	v_mul_f32_e32 v123, v122, v121
	v_fma_f32 v124, -v119, v123, v122
	v_fmac_f32_e32 v123, v124, v121
	v_fma_f32 v119, -v119, v123, v122
	v_div_fmas_f32 v119, v119, v121, v123
	v_div_fixup_f32 v118, v119, v118, 1.0
	v_mul_f32_e32 v118, 0x437f0000, v118
	v_rndne_f32_e32 v118, v118
	v_cvt_i32_f32_sdwa v118, v118 dst_sel:BYTE_3 dst_unused:UNUSED_PAD src0_sel:DWORD
	s_nop 0
	v_or3_b32 v116, v116, v117, v118
	v_div_scale_f32 v117, s[22:23], v112, v112, 1.0
	v_rcp_f32_e32 v118, v117
	s_nop 0
	v_fma_f32 v119, -v117, v118, 1.0
	v_fmac_f32_e32 v118, v119, v118
	v_div_scale_f32 v119, vcc, 1.0, v112, 1.0
	v_mul_f32_e32 v121, v119, v118
	v_fma_f32 v122, -v117, v121, v119
	v_fmac_f32_e32 v121, v122, v118
	v_fma_f32 v117, -v117, v121, v119
	v_div_fmas_f32 v117, v117, v118, v121
	v_div_fixup_f32 v112, v117, v112, 1.0
	v_div_scale_f32 v117, s[22:23], v113, v113, 1.0
	v_rcp_f32_e32 v118, v117
	v_mul_f32_e32 v112, 0x437f0000, v112
	v_rndne_f32_e32 v112, v112
	v_cvt_i32_f32_e32 v112, v112
	v_fma_f32 v119, -v117, v118, 1.0
	v_fmac_f32_e32 v118, v119, v118
	v_div_scale_f32 v119, vcc, 1.0, v113, 1.0
	v_mul_f32_e32 v121, v119, v118
	v_fma_f32 v122, -v117, v121, v119
	v_fmac_f32_e32 v121, v122, v118
	v_fma_f32 v117, -v117, v121, v119
	v_div_fmas_f32 v117, v117, v118, v121
	v_div_fixup_f32 v113, v117, v113, 1.0
	v_mul_f32_e32 v113, 0x437f0000, v113
	v_rndne_f32_e32 v113, v113
	v_cvt_i32_f32_e32 v113, v113
	v_lshl_or_b32 v112, v113, 8, v112
	v_mul_f32_e32 v113, v114, v120
	v_mul_f32_e32 v113, 0xbfb8aa3b, v113
	v_exp_f32_e32 v113, v113
	s_nop 0
	v_add_f32_e32 v113, 1.0, v113
	v_div_scale_f32 v114, s[22:23], v113, v113, 1.0
	v_rcp_f32_e32 v117, v114
	s_nop 0
	v_fma_f32 v118, -v114, v117, 1.0
	v_fmac_f32_e32 v117, v118, v117
	v_div_scale_f32 v118, vcc, 1.0, v113, 1.0
	v_mul_f32_e32 v119, v118, v117
	v_fma_f32 v121, -v114, v119, v118
	v_fmac_f32_e32 v119, v121, v117
	v_fma_f32 v114, -v114, v119, v118
	v_div_fmas_f32 v114, v114, v117, v119
	v_div_fixup_f32 v113, v114, v113, 1.0
	v_mul_f32_e32 v114, v115, v120
	v_mul_f32_e32 v114, 0xbfb8aa3b, v114
	v_exp_f32_e32 v114, v114
	v_mul_f32_e32 v113, 0x437f0000, v113
	v_rndne_f32_e32 v113, v113
	v_cvt_i32_f32_sdwa v113, v113 dst_sel:WORD_1 dst_unused:UNUSED_PAD src0_sel:DWORD
	v_add_f32_e32 v114, 1.0, v114
	v_div_scale_f32 v115, s[22:23], v114, v114, 1.0
	v_rcp_f32_e32 v117, v115
	s_nop 0
	v_fma_f32 v118, -v115, v117, 1.0
	v_fmac_f32_e32 v117, v118, v117
	v_div_scale_f32 v118, vcc, 1.0, v114, 1.0
	v_mul_f32_e32 v119, v118, v117
	v_fma_f32 v120, -v115, v119, v118
	v_fmac_f32_e32 v119, v120, v117
	v_fma_f32 v115, -v115, v119, v118
	v_div_fmas_f32 v115, v115, v117, v119
	v_div_fixup_f32 v114, v115, v114, 1.0
	v_mul_f32_e32 v114, 0x437f0000, v114
	v_rndne_f32_e32 v114, v114
	v_cvt_i32_f32_sdwa v114, v114 dst_sel:BYTE_3 dst_unused:UNUSED_PAD src0_sel:DWORD
	s_nop 0
	v_or3_b32 v112, v112, v113, v114
	ds_write2st64_b32 v228, v116, v112 offset0:64 offset1:72
	v_or_b32_e32 v112, 0x50, v152
	v_ashrrev_i32_e32 v113, 31, v112
	v_lshlrev_b64 v[112:113], 6, v[112:113]
	v_lshl_add_u64 v[124:125], s[0:1], 0, v[112:113]
	v_bfe_u32 v244, v124, 6, 8
	v_lshlrev_b32_e32 v244, 3, v244
	v_add_u32_e32 v244, 0x24010, v244
	v_or_b32_e32 v246, 1, v124
	ds_read_b64 v[248:249], v244
	s_waitcnt lgkmcnt(0)
	v_cmp_ne_u32_e64 s[100:101], v248, v246
	s_nop 1
	s_and_saveexec_b64 s[98:99], s[100:101]
	s_cbranch_execz .LrcE0_5
; DI float sigmoidf_(float x) { return 1.f / (1.f + __expf(-x)); }
; DI float rstd_from16(const float* p, float inv_n) {
;   const f32x4 a = *(const f32x4*)p, b = *(const f32x4*)(p + 4), c = *(const f32x4*)(p + 8), d = *(const f32x4*)(p + 12);
;   const float s = ((a[0] + a[1]) + (a[2] + a[3])) + ((b[0] + b[1]) + (b[2] + b[3])) + ((c[0] + c[1]) + (c[2] + c[3])) + ((d[0] + d[1]) + (d[2] + d[3]));
;   return rsqrtf(s * inv_n + EPS_);
; DI void merge_tile(const Params& p, int layer, int tm, int tn, bf16_t* smem) {
;     ...
;         const float rs = rstd_from16((const float*)(p.ws + O_SSQ) + (size_t)(row0 + i * 16) * 16, 1.f / 1024.f);
; #pragma unroll
;         for (int j = 0; j < 2; ++j) {
;           unsigned w = 0;
; #pragma unroll
;           for (int r = 0; r < 4; ++r) w |= (unsigned)__float2int_rn(sigmoidf_(acc[i][j][r] * rs) * 255.f) << (8 * r);
;           gsp[(i * 2 + j) * NTHR] = w;
	global_load_dwordx4 v[112:115], v[124:125], off offset:48
	global_load_dwordx4 v[116:119], v[124:125], off offset:32
	global_load_dwordx4 v[120:123], v[124:125], off offset:16
	s_nop 0
	global_load_dwordx4 v[124:127], v[124:125], off
	s_waitcnt vmcnt(2)
	v_add_f32_e32 v116, v116, v117
	v_add_f32_e32 v118, v118, v119
	s_waitcnt vmcnt(0)
	v_mov_b32_e32 v128, v125
	v_mov_b32_e32 v129, v126
	v_mov_b32_e32 v125, v127
	v_mov_b32_e32 v126, v121
	v_mov_b32_e32 v127, v122
	v_mov_b32_e32 v121, v123
	v_pk_add_f32 v[124:125], v[128:129], v[124:125]
	v_pk_add_f32 v[120:121], v[126:127], v[120:121]
	v_pk_add_f32 v[124:125], v[124:125], v[124:125] op_sel:[0,1] op_sel_hi:[1,0]
	v_pk_add_f32 v[120:121], v[120:121], v[120:121] op_sel:[0,1] op_sel_hi:[1,0]
	v_mov_b32_e32 v125, v112
	v_mov_b32_e32 v121, v113
	v_mov_b32_e32 v117, v114
	v_mov_b32_e32 v119, v115
	v_pk_add_f32 v[112:113], v[124:125], v[120:121]
	v_pk_add_f32 v[114:115], v[116:117], v[118:119]
	s_nop 0
	v_pk_add_f32 v[112:113], v[112:113], v[114:115]
	s_nop 0
	v_add_f32_e32 v112, v112, v113
	v_fmamk_f32 v112, v112, 0x3a800000, v225
	v_cmp_gt_f32_e32 vcc, s35, v112
	v_mul_f32_e32 v113, 0x4b800000, v112
	s_nop 0
	v_cndmask_b32_e32 v112, v112, v113, vcc
	v_rsq_f32_e32 v112, v112
	s_nop 0
	v_mul_f32_e32 v113, 0x45800000, v112
	v_cndmask_b32_e32 v112, v112, v113, vcc
	s_nop 0
	v_mov_b32_e32 v247, v112
	ds_write_b64 v244, v[246:247]
.LrcE0_5:
	s_or_b64 exec, exec, s[98:99]
	s_waitcnt vmcnt(0)
	v_cndmask_b32_e64 v112, v249, v112, s[100:101]
	v_mul_f32_e32 v108, v108, v112
	v_mul_f32_e32 v108, 0xbfb8aa3b, v108
	v_exp_f32_e32 v108, v108
	v_mul_f32_e32 v109, v109, v112
	v_mul_f32_e32 v109, 0xbfb8aa3b, v109
	v_exp_f32_e32 v109, v109
	v_add_f32_e32 v108, 1.0, v108
	v_div_scale_f32 v113, s[22:23], v108, v108, 1.0
	v_rcp_f32_e32 v114, v113
	v_add_f32_e32 v109, 1.0, v109
	v_mul_f32_e32 v104, v104, v112
	v_mul_f32_e32 v104, 0xbfb8aa3b, v104
	v_fma_f32 v115, -v113, v114, 1.0
	v_fmac_f32_e32 v114, v115, v114
	v_div_scale_f32 v115, vcc, 1.0, v108, 1.0
	v_mul_f32_e32 v116, v115, v114
	v_fma_f32 v117, -v113, v116, v115
	v_fmac_f32_e32 v116, v117, v114
	v_fma_f32 v113, -v113, v116, v115
	v_div_fmas_f32 v113, v113, v114, v116
	v_div_fixup_f32 v108, v113, v108, 1.0
	v_div_scale_f32 v113, s[22:23], v109, v109, 1.0
	v_rcp_f32_e32 v114, v113
	v_mul_f32_e32 v108, 0x437f0000, v108
	v_rndne_f32_e32 v108, v108
	v_cvt_i32_f32_e32 v108, v108
	v_fma_f32 v115, -v113, v114, 1.0
	v_fmac_f32_e32 v114, v115, v114
	v_div_scale_f32 v115, vcc, 1.0, v109, 1.0
	v_mul_f32_e32 v116, v115, v114
	v_fma_f32 v117, -v113, v116, v115
	v_fmac_f32_e32 v116, v117, v114
	v_fma_f32 v113, -v113, v116, v115
	v_div_fmas_f32 v113, v113, v114, v116
	v_div_fixup_f32 v109, v113, v109, 1.0
	v_mul_f32_e32 v109, 0x437f0000, v109
	v_rndne_f32_e32 v109, v109
	v_cvt_i32_f32_e32 v109, v109
	v_exp_f32_e32 v104, v104
	v_mul_f32_e32 v105, v105, v112
	v_mul_f32_e32 v105, 0xbfb8aa3b, v105
	v_lshl_or_b32 v108, v109, 8, v108
	v_mul_f32_e32 v109, v110, v112
	v_mul_f32_e32 v109, 0xbfb8aa3b, v109
	v_exp_f32_e32 v109, v109
	v_add_f32_e32 v104, 1.0, v104
	v_exp_f32_e32 v105, v105
	v_add_f32_e32 v109, 1.0, v109
	v_div_scale_f32 v110, s[22:23], v109, v109, 1.0
	v_rcp_f32_e32 v113, v110
	v_add_f32_e32 v105, 1.0, v105
	v_fma_f32 v114, -v110, v113, 1.0
	v_fmac_f32_e32 v113, v114, v113
	v_div_scale_f32 v114, vcc, 1.0, v109, 1.0
	v_mul_f32_e32 v115, v114, v113
	v_fma_f32 v116, -v110, v115, v114
	v_fmac_f32_e32 v115, v116, v113
	v_fma_f32 v110, -v110, v115, v114
	v_div_fmas_f32 v110, v110, v113, v115
	v_div_fixup_f32 v109, v110, v109, 1.0
	v_mul_f32_e32 v110, v111, v112
	v_mul_f32_e32 v110, 0xbfb8aa3b, v110
	v_exp_f32_e32 v110, v110
	v_mul_f32_e32 v109, 0x437f0000, v109
	v_rndne_f32_e32 v109, v109
	v_cvt_i32_f32_sdwa v109, v109 dst_sel:WORD_1 dst_unused:UNUSED_PAD src0_sel:DWORD
	v_add_f32_e32 v110, 1.0, v110
	v_div_scale_f32 v111, s[22:23], v110, v110, 1.0
	v_rcp_f32_e32 v113, v111
	s_nop 0
	v_fma_f32 v114, -v111, v113, 1.0
	v_fmac_f32_e32 v113, v114, v113
	v_div_scale_f32 v114, vcc, 1.0, v110, 1.0
	v_mul_f32_e32 v115, v114, v113
	v_fma_f32 v116, -v111, v115, v114
	v_fmac_f32_e32 v115, v116, v113
	v_fma_f32 v111, -v111, v115, v114
	v_div_fmas_f32 v111, v111, v113, v115
	v_div_fixup_f32 v110, v111, v110, 1.0
	v_mul_f32_e32 v110, 0x437f0000, v110
	v_rndne_f32_e32 v110, v110
	v_cvt_i32_f32_sdwa v110, v110 dst_sel:BYTE_3 dst_unused:UNUSED_PAD src0_sel:DWORD
	s_nop 0
	v_or3_b32 v108, v108, v109, v110
	v_div_scale_f32 v109, s[22:23], v104, v104, 1.0
	v_rcp_f32_e32 v110, v109
	s_nop 0
	v_fma_f32 v111, -v109, v110, 1.0
	v_fmac_f32_e32 v110, v111, v110
	v_div_scale_f32 v111, vcc, 1.0, v104, 1.0
	v_mul_f32_e32 v113, v111, v110
	v_fma_f32 v114, -v109, v113, v111
	v_fmac_f32_e32 v113, v114, v110
	v_fma_f32 v109, -v109, v113, v111
	v_div_fmas_f32 v109, v109, v110, v113
	v_div_fixup_f32 v104, v109, v104, 1.0
	v_div_scale_f32 v109, s[22:23], v105, v105, 1.0
	v_rcp_f32_e32 v110, v109
	v_mul_f32_e32 v104, 0x437f0000, v104
	v_rndne_f32_e32 v104, v104
	v_cvt_i32_f32_e32 v104, v104
	v_fma_f32 v111, -v109, v110, 1.0
	v_fmac_f32_e32 v110, v111, v110
	v_div_scale_f32 v111, vcc, 1.0, v105, 1.0
	v_mul_f32_e32 v113, v111, v110
	v_fma_f32 v114, -v109, v113, v111
	v_fmac_f32_e32 v113, v114, v110
	v_fma_f32 v109, -v109, v113, v111
	v_div_fmas_f32 v109, v109, v110, v113
	v_div_fixup_f32 v105, v109, v105, 1.0
	v_mul_f32_e32 v105, 0x437f0000, v105
	v_rndne_f32_e32 v105, v105
	v_cvt_i32_f32_e32 v105, v105
	v_lshl_or_b32 v104, v105, 8, v104
	v_mul_f32_e32 v105, v106, v112
	v_mul_f32_e32 v105, 0xbfb8aa3b, v105
	v_exp_f32_e32 v105, v105
	s_nop 0
	v_add_f32_e32 v105, 1.0, v105
	v_div_scale_f32 v106, s[22:23], v105, v105, 1.0
; DI float sigmoidf_(float x) { return 1.f / (1.f + __expf(-x)); }
; DI float rstd_from16(const float* p, float inv_n) {
;   const f32x4 a = *(const f32x4*)p, b = *(const f32x4*)(p + 4), c = *(const f32x4*)(p + 8), d = *(const f32x4*)(p + 12);
;   const float s = ((a[0] + a[1]) + (a[2] + a[3])) + ((b[0] + b[1]) + (b[2] + b[3])) + ((c[0] + c[1]) + (c[2] + c[3])) + ((d[0] + d[1]) + (d[2] + d[3]));
;   return rsqrtf(s * inv_n + EPS_);
; DI void merge_tile(const Params& p, int layer, int tm, int tn, bf16_t* smem) {
;     ...
;         const float rs = rstd_from16((const float*)(p.ws + O_SSQ) + (size_t)(row0 + i * 16) * 16, 1.f / 1024.f);
; #pragma unroll
;         for (int j = 0; j < 2; ++j) {
;           unsigned w = 0;
; #pragma unroll
;           for (int r = 0; r < 4; ++r) w |= (unsigned)__float2int_rn(sigmoidf_(acc[i][j][r] * rs) * 255.f) << (8 * r);
;           gsp[(i * 2 + j) * NTHR] = w;
	v_rcp_f32_e32 v109, v106
	s_nop 0
	v_fma_f32 v110, -v106, v109, 1.0
	v_fmac_f32_e32 v109, v110, v109
	v_div_scale_f32 v110, vcc, 1.0, v105, 1.0
	v_mul_f32_e32 v111, v110, v109
	v_fma_f32 v113, -v106, v111, v110
	v_fmac_f32_e32 v111, v113, v109
	v_fma_f32 v106, -v106, v111, v110
	v_div_fmas_f32 v106, v106, v109, v111
	v_div_fixup_f32 v105, v106, v105, 1.0
	v_mul_f32_e32 v106, v107, v112
	v_mul_f32_e32 v106, 0xbfb8aa3b, v106
	v_exp_f32_e32 v106, v106
	v_mul_f32_e32 v105, 0x437f0000, v105
	v_rndne_f32_e32 v105, v105
	v_cvt_i32_f32_sdwa v105, v105 dst_sel:WORD_1 dst_unused:UNUSED_PAD src0_sel:DWORD
	v_add_f32_e32 v106, 1.0, v106
	v_div_scale_f32 v107, s[22:23], v106, v106, 1.0
	v_rcp_f32_e32 v109, v107
	s_nop 0
	v_fma_f32 v110, -v107, v109, 1.0
	v_fmac_f32_e32 v109, v110, v109
	v_div_scale_f32 v110, vcc, 1.0, v106, 1.0
	v_mul_f32_e32 v111, v110, v109
	v_fma_f32 v112, -v107, v111, v110
	v_fmac_f32_e32 v111, v112, v109
	v_fma_f32 v107, -v107, v111, v110
	v_div_fmas_f32 v107, v107, v109, v111
	v_div_fixup_f32 v106, v107, v106, 1.0
	v_mul_f32_e32 v106, 0x437f0000, v106
	v_rndne_f32_e32 v106, v106
	v_cvt_i32_f32_sdwa v106, v106 dst_sel:BYTE_3 dst_unused:UNUSED_PAD src0_sel:DWORD
	s_nop 0
	v_or3_b32 v104, v104, v105, v106
	ds_write2st64_b32 v228, v108, v104 offset0:80 offset1:88
	v_or_b32_e32 v104, 0x60, v152
	v_ashrrev_i32_e32 v105, 31, v104
	v_lshlrev_b64 v[104:105], 6, v[104:105]
	v_lshl_add_u64 v[116:117], s[0:1], 0, v[104:105]
	v_bfe_u32 v244, v116, 6, 8
	v_lshlrev_b32_e32 v244, 3, v244
	v_add_u32_e32 v244, 0x24010, v244
	v_or_b32_e32 v246, 1, v116
	ds_read_b64 v[248:249], v244
	s_waitcnt lgkmcnt(0)
	v_cmp_ne_u32_e64 s[100:101], v248, v246
	s_nop 1
	s_and_saveexec_b64 s[98:99], s[100:101]
	s_cbranch_execz .LrcE0_6
	global_load_dwordx4 v[104:107], v[116:117], off offset:48
	global_load_dwordx4 v[108:111], v[116:117], off offset:32
	global_load_dwordx4 v[112:115], v[116:117], off offset:16
	s_nop 0
	global_load_dwordx4 v[116:119], v[116:117], off
	s_waitcnt vmcnt(2)
	v_add_f32_e32 v108, v108, v109
	v_add_f32_e32 v110, v110, v111
	s_waitcnt vmcnt(0)
	v_mov_b32_e32 v120, v117
	v_mov_b32_e32 v121, v118
	v_mov_b32_e32 v117, v119
	v_mov_b32_e32 v118, v113
	v_mov_b32_e32 v119, v114
	v_mov_b32_e32 v113, v115
	v_pk_add_f32 v[116:117], v[120:121], v[116:117]
	v_pk_add_f32 v[112:113], v[118:119], v[112:113]
	v_pk_add_f32 v[116:117], v[116:117], v[116:117] op_sel:[0,1] op_sel_hi:[1,0]
	v_pk_add_f32 v[112:113], v[112:113], v[112:113] op_sel:[0,1] op_sel_hi:[1,0]
	v_mov_b32_e32 v117, v104
	v_mov_b32_e32 v113, v105
	v_mov_b32_e32 v109, v106
	v_mov_b32_e32 v111, v107
	v_pk_add_f32 v[104:105], v[116:117], v[112:113]
	v_pk_add_f32 v[106:107], v[108:109], v[110:111]
	s_nop 0
	v_pk_add_f32 v[104:105], v[104:105], v[106:107]
	s_nop 0
	v_add_f32_e32 v104, v104, v105
	v_fmamk_f32 v104, v104, 0x3a800000, v225
	v_cmp_gt_f32_e32 vcc, s35, v104
	v_mul_f32_e32 v105, 0x4b800000, v104
	s_nop 0
	v_cndmask_b32_e32 v104, v104, v105, vcc
	v_rsq_f32_e32 v104, v104
	s_nop 0
	v_mul_f32_e32 v105, 0x45800000, v104
	v_cndmask_b32_e32 v104, v104, v105, vcc
	s_nop 0
	v_mov_b32_e32 v247, v104
	ds_write_b64 v244, v[246:247]
.LrcE0_6:
	s_or_b64 exec, exec, s[98:99]
	s_waitcnt vmcnt(0)
	v_cndmask_b32_e64 v104, v249, v104, s[100:101]
	v_mul_f32_e32 v100, v100, v104
	v_mul_f32_e32 v100, 0xbfb8aa3b, v100
	v_exp_f32_e32 v100, v100
	v_mul_f32_e32 v101, v101, v104
	v_mul_f32_e32 v101, 0xbfb8aa3b, v101
	v_exp_f32_e32 v101, v101
	v_add_f32_e32 v100, 1.0, v100
	v_div_scale_f32 v105, s[22:23], v100, v100, 1.0
	v_rcp_f32_e32 v106, v105
	v_add_f32_e32 v101, 1.0, v101
	v_mul_f32_e32 v96, v96, v104
	v_mul_f32_e32 v96, 0xbfb8aa3b, v96
	v_fma_f32 v107, -v105, v106, 1.0
	v_fmac_f32_e32 v106, v107, v106
	v_div_scale_f32 v107, vcc, 1.0, v100, 1.0
	v_mul_f32_e32 v108, v107, v106
	v_fma_f32 v109, -v105, v108, v107
	v_fmac_f32_e32 v108, v109, v106
	v_fma_f32 v105, -v105, v108, v107
	v_div_fmas_f32 v105, v105, v106, v108
	v_div_fixup_f32 v100, v105, v100, 1.0
	v_div_scale_f32 v105, s[22:23], v101, v101, 1.0
	v_rcp_f32_e32 v106, v105
	v_mul_f32_e32 v100, 0x437f0000, v100
	v_rndne_f32_e32 v100, v100
	v_cvt_i32_f32_e32 v100, v100
	v_fma_f32 v107, -v105, v106, 1.0
	v_fmac_f32_e32 v106, v107, v106
	v_div_scale_f32 v107, vcc, 1.0, v101, 1.0
	v_mul_f32_e32 v108, v107, v106
	v_fma_f32 v109, -v105, v108, v107
	v_fmac_f32_e32 v108, v109, v106
	v_fma_f32 v105, -v105, v108, v107
	v_div_fmas_f32 v105, v105, v106, v108
	v_div_fixup_f32 v101, v105, v101, 1.0
	v_mul_f32_e32 v101, 0x437f0000, v101
	v_rndne_f32_e32 v101, v101
	v_cvt_i32_f32_e32 v101, v101
	v_exp_f32_e32 v96, v96
	v_mul_f32_e32 v97, v97, v104
	v_mul_f32_e32 v97, 0xbfb8aa3b, v97
	v_lshl_or_b32 v100, v101, 8, v100
	v_mul_f32_e32 v101, v102, v104
	v_mul_f32_e32 v101, 0xbfb8aa3b, v101
	v_exp_f32_e32 v101, v101
	v_add_f32_e32 v96, 1.0, v96
	v_exp_f32_e32 v97, v97
	v_add_f32_e32 v101, 1.0, v101
	v_div_scale_f32 v102, s[22:23], v101, v101, 1.0
	v_rcp_f32_e32 v105, v102
	v_add_f32_e32 v97, 1.0, v97
	v_fma_f32 v106, -v102, v105, 1.0
	v_fmac_f32_e32 v105, v106, v105
	v_div_scale_f32 v106, vcc, 1.0, v101, 1.0
	v_mul_f32_e32 v107, v106, v105
	v_fma_f32 v108, -v102, v107, v106
	v_fmac_f32_e32 v107, v108, v105
	v_fma_f32 v102, -v102, v107, v106
	v_div_fmas_f32 v102, v102, v105, v107
	v_div_fixup_f32 v101, v102, v101, 1.0
	v_mul_f32_e32 v102, v103, v104
	v_mul_f32_e32 v102, 0xbfb8aa3b, v102
	v_exp_f32_e32 v102, v102
	v_mul_f32_e32 v101, 0x437f0000, v101
	v_rndne_f32_e32 v101, v101
	v_cvt_i32_f32_sdwa v101, v101 dst_sel:WORD_1 dst_unused:UNUSED_PAD src0_sel:DWORD
	v_add_f32_e32 v102, 1.0, v102
	v_div_scale_f32 v103, s[22:23], v102, v102, 1.0
	v_rcp_f32_e32 v105, v103
	s_nop 0
; DI float sigmoidf_(float x) { return 1.f / (1.f + __expf(-x)); }
; DI float rstd_from16(const float* p, float inv_n) {
;   const f32x4 a = *(const f32x4*)p, b = *(const f32x4*)(p + 4), c = *(const f32x4*)(p + 8), d = *(const f32x4*)(p + 12);
;   const float s = ((a[0] + a[1]) + (a[2] + a[3])) + ((b[0] + b[1]) + (b[2] + b[3])) + ((c[0] + c[1]) + (c[2] + c[3])) + ((d[0] + d[1]) + (d[2] + d[3]));
;   return rsqrtf(s * inv_n + EPS_);
; DI void merge_tile(const Params& p, int layer, int tm, int tn, bf16_t* smem) {
;     ...
;         const float rs = rstd_from16((const float*)(p.ws + O_SSQ) + (size_t)(row0 + i * 16) * 16, 1.f / 1024.f);
; #pragma unroll
;         for (int j = 0; j < 2; ++j) {
;           unsigned w = 0;
; #pragma unroll
;           for (int r = 0; r < 4; ++r) w |= (unsigned)__float2int_rn(sigmoidf_(acc[i][j][r] * rs) * 255.f) << (8 * r);
;           gsp[(i * 2 + j) * NTHR] = w;
	v_fma_f32 v106, -v103, v105, 1.0
	v_fmac_f32_e32 v105, v106, v105
	v_div_scale_f32 v106, vcc, 1.0, v102, 1.0
	v_mul_f32_e32 v107, v106, v105
	v_fma_f32 v108, -v103, v107, v106
	v_fmac_f32_e32 v107, v108, v105
	v_fma_f32 v103, -v103, v107, v106
	v_div_fmas_f32 v103, v103, v105, v107
	v_div_fixup_f32 v102, v103, v102, 1.0
	v_mul_f32_e32 v102, 0x437f0000, v102
	v_rndne_f32_e32 v102, v102
	v_cvt_i32_f32_sdwa v102, v102 dst_sel:BYTE_3 dst_unused:UNUSED_PAD src0_sel:DWORD
	s_nop 0
	v_or3_b32 v100, v100, v101, v102
	v_div_scale_f32 v101, s[22:23], v96, v96, 1.0
	v_rcp_f32_e32 v102, v101
	s_nop 0
	v_fma_f32 v103, -v101, v102, 1.0
	v_fmac_f32_e32 v102, v103, v102
	v_div_scale_f32 v103, vcc, 1.0, v96, 1.0
	v_mul_f32_e32 v105, v103, v102
	v_fma_f32 v106, -v101, v105, v103
	v_fmac_f32_e32 v105, v106, v102
	v_fma_f32 v101, -v101, v105, v103
	v_div_fmas_f32 v101, v101, v102, v105
	v_div_fixup_f32 v96, v101, v96, 1.0
	v_div_scale_f32 v101, s[22:23], v97, v97, 1.0
	v_rcp_f32_e32 v102, v101
	v_mul_f32_e32 v96, 0x437f0000, v96
	v_rndne_f32_e32 v96, v96
	v_cvt_i32_f32_e32 v96, v96
	v_fma_f32 v103, -v101, v102, 1.0
	v_fmac_f32_e32 v102, v103, v102
	v_div_scale_f32 v103, vcc, 1.0, v97, 1.0
	v_mul_f32_e32 v105, v103, v102
	v_fma_f32 v106, -v101, v105, v103
	v_fmac_f32_e32 v105, v106, v102
	v_fma_f32 v101, -v101, v105, v103
	v_div_fmas_f32 v101, v101, v102, v105
	v_div_fixup_f32 v97, v101, v97, 1.0
	v_mul_f32_e32 v97, 0x437f0000, v97
	v_rndne_f32_e32 v97, v97
	v_cvt_i32_f32_e32 v97, v97
	v_lshl_or_b32 v96, v97, 8, v96
	v_mul_f32_e32 v97, v98, v104
	v_mul_f32_e32 v97, 0xbfb8aa3b, v97
	v_exp_f32_e32 v97, v97
	s_nop 0
	v_add_f32_e32 v97, 1.0, v97
	v_div_scale_f32 v98, s[22:23], v97, v97, 1.0
	v_rcp_f32_e32 v101, v98
	s_nop 0
	v_fma_f32 v102, -v98, v101, 1.0
	v_fmac_f32_e32 v101, v102, v101
	v_div_scale_f32 v102, vcc, 1.0, v97, 1.0
	v_mul_f32_e32 v103, v102, v101
	v_fma_f32 v105, -v98, v103, v102
	v_fmac_f32_e32 v103, v105, v101
	v_fma_f32 v98, -v98, v103, v102
	v_div_fmas_f32 v98, v98, v101, v103
	v_div_fixup_f32 v97, v98, v97, 1.0
	v_mul_f32_e32 v98, v99, v104
	v_mul_f32_e32 v98, 0xbfb8aa3b, v98
	v_exp_f32_e32 v98, v98
	v_mul_f32_e32 v97, 0x437f0000, v97
	v_rndne_f32_e32 v97, v97
	v_cvt_i32_f32_sdwa v97, v97 dst_sel:WORD_1 dst_unused:UNUSED_PAD src0_sel:DWORD
	v_add_f32_e32 v98, 1.0, v98
	v_div_scale_f32 v99, s[22:23], v98, v98, 1.0
	v_rcp_f32_e32 v101, v99
	s_nop 0
	v_fma_f32 v102, -v99, v101, 1.0
	v_fmac_f32_e32 v101, v102, v101
	v_div_scale_f32 v102, vcc, 1.0, v98, 1.0
	v_mul_f32_e32 v103, v102, v101
	v_fma_f32 v104, -v99, v103, v102
	v_fmac_f32_e32 v103, v104, v101
	v_fma_f32 v99, -v99, v103, v102
	v_div_fmas_f32 v99, v99, v101, v103
	v_div_fixup_f32 v98, v99, v98, 1.0
	v_mul_f32_e32 v98, 0x437f0000, v98
	v_rndne_f32_e32 v98, v98
	v_cvt_i32_f32_sdwa v98, v98 dst_sel:BYTE_3 dst_unused:UNUSED_PAD src0_sel:DWORD
	s_nop 0
	v_or3_b32 v96, v96, v97, v98
	ds_write2st64_b32 v228, v100, v96 offset0:96 offset1:104
	v_or_b32_e32 v96, 0x70, v152
	v_ashrrev_i32_e32 v97, 31, v96
	v_lshlrev_b64 v[96:97], 6, v[96:97]
	v_lshl_add_u64 v[108:109], s[0:1], 0, v[96:97]
	v_mov_b64_e32 v[154:155], v[86:87]
	v_mov_b64_e32 v[152:153], v[84:85]
	v_bfe_u32 v244, v108, 6, 8
	v_lshlrev_b32_e32 v244, 3, v244
	v_add_u32_e32 v244, 0x24010, v244
	v_or_b32_e32 v246, 1, v108
	ds_read_b64 v[248:249], v244
	s_waitcnt lgkmcnt(0)
	v_cmp_ne_u32_e64 s[100:101], v248, v246
	s_nop 1
	s_and_saveexec_b64 s[98:99], s[100:101]
	s_cbranch_execz .LrcE0_7
	global_load_dwordx4 v[96:99], v[108:109], off offset:48
	global_load_dwordx4 v[100:103], v[108:109], off offset:32
	global_load_dwordx4 v[104:107], v[108:109], off offset:16
	s_nop 0
	global_load_dwordx4 v[108:111], v[108:109], off
	s_waitcnt vmcnt(2)
	v_add_f32_e32 v100, v100, v101
	v_add_f32_e32 v102, v102, v103
	s_waitcnt vmcnt(0)
	v_mov_b32_e32 v112, v109
	v_mov_b32_e32 v113, v110
	v_mov_b32_e32 v109, v111
	v_mov_b32_e32 v110, v105
	v_mov_b32_e32 v111, v106
	v_mov_b32_e32 v105, v107
	v_pk_add_f32 v[108:109], v[112:113], v[108:109]
	v_pk_add_f32 v[104:105], v[110:111], v[104:105]
	v_pk_add_f32 v[108:109], v[108:109], v[108:109] op_sel:[0,1] op_sel_hi:[1,0]
	v_pk_add_f32 v[104:105], v[104:105], v[104:105] op_sel:[0,1] op_sel_hi:[1,0]
	v_mov_b32_e32 v109, v96
	v_mov_b32_e32 v105, v97
	v_mov_b32_e32 v101, v98
	v_mov_b32_e32 v103, v99
	v_pk_add_f32 v[96:97], v[108:109], v[104:105]
	v_pk_add_f32 v[98:99], v[100:101], v[102:103]
	s_nop 0
	v_pk_add_f32 v[96:97], v[96:97], v[98:99]
	s_nop 0
	v_add_f32_e32 v96, v96, v97
	v_fmamk_f32 v96, v96, 0x3a800000, v225
	v_cmp_gt_f32_e32 vcc, s35, v96
	v_mul_f32_e32 v97, 0x4b800000, v96
	s_nop 0
	v_cndmask_b32_e32 v96, v96, v97, vcc
	v_rsq_f32_e32 v96, v96
	s_nop 0
	v_mul_f32_e32 v97, 0x45800000, v96
	v_cndmask_b32_e32 v96, v96, v97, vcc
	s_nop 0
	v_mov_b32_e32 v247, v96
	ds_write_b64 v244, v[246:247]
; DI int TIDX() { int t = (int)threadIdx.x; asm volatile("" : "+v"(t)); return t; }
; DI float sigmoidf_(float x) { return 1.f / (1.f + __expf(-x)); }
; DI void merge_tile(const Params& p, int layer, int tm, int tn, bf16_t* smem) {
;     ...
;     if ((sg & 1) == 0) {
;       const int t2 = TIDX(), row0 = tm * 256 + ((t2 >> 8) & 1) * 128 + (t2 & 15);
; #pragma unroll
;       for (int i = 0; i < 8; ++i) {
;         asm volatile("" ::: "memory");
;         const float rs = rstd_from16((const float*)(p.ws + O_SSQ) + (size_t)(row0 + i * 16) * 16, 1.f / 1024.f);
; #pragma unroll
;         for (int j = 0; j < 2; ++j) {
;           unsigned w = 0;
; #pragma unroll
;           for (int r = 0; r < 4; ++r) w |= (unsigned)__float2int_rn(sigmoidf_(acc[i][j][r] * rs) * 255.f) << (8 * r);
;           gsp[(i * 2 + j) * NTHR] = w;
;         }
.LrcE0_7:
	s_or_b64 exec, exec, s[98:99]
	s_waitcnt vmcnt(0)
	v_cndmask_b32_e64 v96, v249, v96, s[100:101]
	v_mul_f32_e32 v92, v92, v96
	v_mul_f32_e32 v92, 0xbfb8aa3b, v92
	v_exp_f32_e32 v92, v92
	v_mul_f32_e32 v93, v93, v96
	v_mul_f32_e32 v93, 0xbfb8aa3b, v93
	v_exp_f32_e32 v93, v93
	v_add_f32_e32 v92, 1.0, v92
	v_div_scale_f32 v97, s[22:23], v92, v92, 1.0
	v_rcp_f32_e32 v98, v97
	v_add_f32_e32 v93, 1.0, v93
	v_mul_f32_e32 v88, v88, v96
	v_mul_f32_e32 v88, 0xbfb8aa3b, v88
	v_fma_f32 v99, -v97, v98, 1.0
	v_fmac_f32_e32 v98, v99, v98
	v_div_scale_f32 v99, vcc, 1.0, v92, 1.0
	v_mul_f32_e32 v100, v99, v98
	v_fma_f32 v101, -v97, v100, v99
	v_fmac_f32_e32 v100, v101, v98
	v_fma_f32 v97, -v97, v100, v99
	v_div_fmas_f32 v97, v97, v98, v100
	v_div_fixup_f32 v92, v97, v92, 1.0
	v_div_scale_f32 v97, s[22:23], v93, v93, 1.0
	v_rcp_f32_e32 v98, v97
	v_mul_f32_e32 v92, 0x437f0000, v92
	v_rndne_f32_e32 v92, v92
	v_cvt_i32_f32_e32 v92, v92
	v_fma_f32 v99, -v97, v98, 1.0
	v_fmac_f32_e32 v98, v99, v98
	v_div_scale_f32 v99, vcc, 1.0, v93, 1.0
	v_mul_f32_e32 v100, v99, v98
	v_fma_f32 v101, -v97, v100, v99
	v_fmac_f32_e32 v100, v101, v98
	v_fma_f32 v97, -v97, v100, v99
	v_div_fmas_f32 v97, v97, v98, v100
	v_div_fixup_f32 v93, v97, v93, 1.0
	v_mul_f32_e32 v93, 0x437f0000, v93
	v_rndne_f32_e32 v93, v93
	v_cvt_i32_f32_e32 v93, v93
	v_exp_f32_e32 v88, v88
	v_mul_f32_e32 v89, v89, v96
	v_mul_f32_e32 v89, 0xbfb8aa3b, v89
	v_lshl_or_b32 v92, v93, 8, v92
	v_mul_f32_e32 v93, v94, v96
	v_mul_f32_e32 v93, 0xbfb8aa3b, v93
	v_exp_f32_e32 v93, v93
	v_add_f32_e32 v88, 1.0, v88
	v_exp_f32_e32 v89, v89
	v_add_f32_e32 v93, 1.0, v93
	v_div_scale_f32 v94, s[22:23], v93, v93, 1.0
	v_rcp_f32_e32 v97, v94
	v_add_f32_e32 v89, 1.0, v89
	v_fma_f32 v98, -v94, v97, 1.0
	v_fmac_f32_e32 v97, v98, v97
	v_div_scale_f32 v98, vcc, 1.0, v93, 1.0
	v_mul_f32_e32 v99, v98, v97
	v_fma_f32 v100, -v94, v99, v98
	v_fmac_f32_e32 v99, v100, v97
	v_fma_f32 v94, -v94, v99, v98
	v_div_fmas_f32 v94, v94, v97, v99
	v_div_fixup_f32 v93, v94, v93, 1.0
	v_mul_f32_e32 v94, v95, v96
	v_mul_f32_e32 v94, 0xbfb8aa3b, v94
	v_exp_f32_e32 v94, v94
	v_mul_f32_e32 v93, 0x437f0000, v93
	v_rndne_f32_e32 v93, v93
	v_cvt_i32_f32_sdwa v93, v93 dst_sel:WORD_1 dst_unused:UNUSED_PAD src0_sel:DWORD
	v_add_f32_e32 v94, 1.0, v94
	v_div_scale_f32 v95, s[22:23], v94, v94, 1.0
	v_rcp_f32_e32 v97, v95
	s_nop 0
	v_fma_f32 v98, -v95, v97, 1.0
	v_fmac_f32_e32 v97, v98, v97
	v_div_scale_f32 v98, vcc, 1.0, v94, 1.0
	v_mul_f32_e32 v99, v98, v97
	v_fma_f32 v100, -v95, v99, v98
	v_fmac_f32_e32 v99, v100, v97
	v_fma_f32 v95, -v95, v99, v98
	v_div_fmas_f32 v95, v95, v97, v99
	v_div_fixup_f32 v94, v95, v94, 1.0
	v_mul_f32_e32 v94, 0x437f0000, v94
	v_rndne_f32_e32 v94, v94
	v_cvt_i32_f32_sdwa v94, v94 dst_sel:BYTE_3 dst_unused:UNUSED_PAD src0_sel:DWORD
	s_nop 0
	v_or3_b32 v92, v92, v93, v94
	v_div_scale_f32 v93, s[22:23], v88, v88, 1.0
	v_rcp_f32_e32 v94, v93
	s_nop 0
	v_fma_f32 v95, -v93, v94, 1.0
	v_fmac_f32_e32 v94, v95, v94
	v_div_scale_f32 v95, vcc, 1.0, v88, 1.0
	v_mul_f32_e32 v97, v95, v94
	v_fma_f32 v98, -v93, v97, v95
	v_fmac_f32_e32 v97, v98, v94
	v_fma_f32 v93, -v93, v97, v95
	v_div_fmas_f32 v93, v93, v94, v97
	v_div_fixup_f32 v88, v93, v88, 1.0
	v_div_scale_f32 v93, s[22:23], v89, v89, 1.0
	v_rcp_f32_e32 v94, v93
	v_mul_f32_e32 v88, 0x437f0000, v88
	v_rndne_f32_e32 v88, v88
	v_cvt_i32_f32_e32 v88, v88
	v_fma_f32 v95, -v93, v94, 1.0
	v_fmac_f32_e32 v94, v95, v94
	v_div_scale_f32 v95, vcc, 1.0, v89, 1.0
	v_mul_f32_e32 v97, v95, v94
	v_fma_f32 v98, -v93, v97, v95
	v_fmac_f32_e32 v97, v98, v94
	v_fma_f32 v93, -v93, v97, v95
	v_div_fmas_f32 v93, v93, v94, v97
	v_div_fixup_f32 v89, v93, v89, 1.0
	v_mul_f32_e32 v89, 0x437f0000, v89
	v_rndne_f32_e32 v89, v89
	v_cvt_i32_f32_e32 v89, v89
	v_lshl_or_b32 v88, v89, 8, v88
	v_mul_f32_e32 v89, v90, v96
	v_mul_f32_e32 v89, 0xbfb8aa3b, v89
	v_exp_f32_e32 v89, v89
	s_nop 0
	v_add_f32_e32 v89, 1.0, v89
	v_div_scale_f32 v90, s[22:23], v89, v89, 1.0
	v_rcp_f32_e32 v93, v90
	s_nop 0
	v_fma_f32 v94, -v90, v93, 1.0
	v_fmac_f32_e32 v93, v94, v93
	v_div_scale_f32 v94, vcc, 1.0, v89, 1.0
	v_mul_f32_e32 v95, v94, v93
	v_fma_f32 v97, -v90, v95, v94
	v_fmac_f32_e32 v95, v97, v93
	v_fma_f32 v90, -v90, v95, v94
	v_div_fmas_f32 v90, v90, v93, v95
	v_div_fixup_f32 v89, v90, v89, 1.0
	v_mul_f32_e32 v90, v91, v96
	v_mul_f32_e32 v90, 0xbfb8aa3b, v90
	v_exp_f32_e32 v90, v90
	v_mul_f32_e32 v89, 0x437f0000, v89
	v_rndne_f32_e32 v89, v89
	v_cvt_i32_f32_sdwa v89, v89 dst_sel:WORD_1 dst_unused:UNUSED_PAD src0_sel:DWORD
	v_add_f32_e32 v90, 1.0, v90
	v_div_scale_f32 v91, s[22:23], v90, v90, 1.0
	v_rcp_f32_e32 v93, v91
	s_nop 0
	v_fma_f32 v94, -v91, v93, 1.0
	v_fmac_f32_e32 v93, v94, v93
	v_div_scale_f32 v94, vcc, 1.0, v90, 1.0
	v_mul_f32_e32 v95, v94, v93
	v_fma_f32 v96, -v91, v95, v94
	v_fmac_f32_e32 v95, v96, v93
	v_fma_f32 v91, -v91, v95, v94
	v_div_fmas_f32 v91, v91, v93, v95
	v_div_fixup_f32 v90, v91, v90, 1.0
	v_mul_f32_e32 v90, 0x437f0000, v90
	v_rndne_f32_e32 v90, v90
	v_cvt_i32_f32_sdwa v90, v90 dst_sel:BYTE_3 dst_unused:UNUSED_PAD src0_sel:DWORD
	s_nop 0
	v_or3_b32 v88, v88, v89, v90
	ds_write2st64_b32 v228, v92, v88 offset0:112 offset1:120
	s_add_i32 s40, s40, 1
	s_cmp_lg_u32 s40, 6
	s_cbranch_scc0 .LBB0_833

; DI void store4(bf16_t* dst, const f32x4& v, float s) { *(u32x2*)dst = (u32x2){pk2(v[0] * s, v[1] * s), pk2(v[2] * s, v[3] * s)}; }
; DI float rstd_from16(const float* p, float inv_n) {
;   const f32x4 a = *(const f32x4*)p, b = *(const f32x4*)(p + 4), c = *(const f32x4*)(p + 8), d = *(const f32x4*)(p + 12);
;   const float s = ((a[0] + a[1]) + (a[2] + a[3])) + ((b[0] + b[1]) + (b[2] + b[3])) + ((c[0] + c[1]) + (c[2] + c[3])) + ((d[0] + d[1]) + (d[2] + d[3]));
;   return rsqrtf(s * inv_n + EPS_);
; DI void ffnup_tile(const Params& p, int layer, int b, int mt, int tn, bf16_t* smem) {
;     ...
;     bf16_t* dstb = (wn < 2 ? U : V) + (wn & 1) * 64 + quad * 4;
; #pragma unroll
;     for (int i = 0; i < 8; ++i) {
;       const int row = wm * 128 + i * 16 + l15, s = s0 + row;
;       const float rs = (s >= 0 && s < S_) ? rstd_from16((const float*)(p.ws + O_SSQ) + ((size_t)b * S_ + s) * 16, 1.f / 1024.f) : 0.f;
; #pragma unroll
;       for (int j = 0; j < 4; ++j) store4(dstb + row * LDU + j * 16, acc[i][j], rs);
;     }
.Lgm6_exit:
	v_mfma_f32_16x16x32_bf16 v[28:31], v[182:185], v[246:249], v[28:31]
	v_mfma_f32_16x16x32_bf16 v[12:15], v[182:185], v[250:253], v[12:15]
	v_mfma_f32_16x16x32_bf16 v[24:27], v[186:189], v[246:249], v[24:27]
	v_mfma_f32_16x16x32_bf16 v[8:11], v[186:189], v[250:253], v[8:11]
	v_mfma_f32_16x16x32_bf16 v[20:23], v[190:193], v[246:249], v[20:23]
	v_mfma_f32_16x16x32_bf16 v[4:7], v[190:193], v[250:253], v[4:7]
	v_mfma_f32_16x16x32_bf16 v[16:19], v[194:197], v[246:249], v[16:19]
	v_mfma_f32_16x16x32_bf16 v[0:3], v[194:197], v[250:253], v[0:3]
	s_nop 7
	s_waitcnt vmcnt(5)
	v_mov_b32_e32 v115, v220
	s_movk_i32 s0, 0xff80
	v_and_b32_e32 v113, 15, v115
	v_ashrrev_i32_e32 v112, 1, v115
	s_waitcnt vmcnt(4)
	v_and_or_b32 v118, v112, s0, v113
	v_add_u32_e32 v116, s29, v118
	s_lshl_b64 s[2:3], s[10:11], 12
	v_cmp_gt_u32_e32 vcc, s22, v116
	v_mov_b32_e32 v112, 0
	v_mov_b32_e32 v114, 0
	s_and_saveexec_b64 s[0:1], vcc
	s_cbranch_execz .LBB0_1052
	s_waitcnt vmcnt(3)
	v_or_b32_e32 v120, s2, v116
	v_mov_b32_e32 v121, s3
	v_lshlrev_b64 v[120:121], 6, v[120:121]
	s_waitcnt vmcnt(1)
	v_lshl_add_u64 v[132:133], s[8:9], 0, v[120:121]
	v_bfe_u32 v244, v132, 6, 8
	v_lshlrev_b32_e32 v244, 3, v244
	v_add_u32_e32 v244, 0x24010, v244
	v_or_b32_e32 v246, 2, v132
	ds_read_b64 v[248:249], v244
	s_waitcnt lgkmcnt(0)
	v_cmp_ne_u32_e64 s[100:101], v248, v246
	s_nop 1
	s_and_saveexec_b64 s[98:99], s[100:101]
	s_cbranch_execz .LrcG0_0
	global_load_dwordx4 v[120:123], v[132:133], off
	global_load_dwordx4 v[124:127], v[132:133], off offset:16
	global_load_dwordx4 v[128:131], v[132:133], off offset:32
	s_nop 0
	global_load_dwordx4 v[132:135], v[132:133], off offset:48
	s_waitcnt vmcnt(3)
	v_mov_b32_e32 v136, v121
	v_mov_b32_e32 v137, v122
	v_mov_b32_e32 v121, v123
	s_waitcnt vmcnt(2)
	v_mov_b32_e32 v122, v125
	v_mov_b32_e32 v123, v126
	v_mov_b32_e32 v125, v127
	v_pk_add_f32 v[120:121], v[136:137], v[120:121]
	v_pk_add_f32 v[122:123], v[122:123], v[124:125]
	v_pk_add_f32 v[120:121], v[120:121], v[120:121] op_sel:[0,1] op_sel_hi:[1,0]
	v_pk_add_f32 v[122:123], v[122:123], v[122:123] op_sel:[0,1] op_sel_hi:[1,0]
	s_waitcnt vmcnt(1)
	v_add_f32_e32 v126, v128, v129
	v_add_f32_e32 v128, v130, v131
	s_waitcnt vmcnt(0)
	v_mov_b32_e32 v127, v134
	v_mov_b32_e32 v129, v135
	v_mov_b32_e32 v121, v132
	v_mov_b32_e32 v123, v133
	v_pk_add_f32 v[124:125], v[126:127], v[128:129]
	v_pk_add_f32 v[120:121], v[120:121], v[122:123]
	s_nop 0
	v_pk_add_f32 v[120:121], v[120:121], v[124:125]
	s_nop 0
	v_add_f32_e32 v114, v120, v121
	v_fmamk_f32 v114, v114, 0x3a800000, v168
	v_mul_f32_e32 v117, 0x4b800000, v114
	v_cmp_gt_f32_e32 vcc, s24, v114
	s_nop 1
	v_cndmask_b32_e32 v114, v114, v117, vcc
	v_rsq_f32_e32 v114, v114
	s_nop 0
	v_mul_f32_e32 v117, 0x45800000, v114
	v_cndmask_b32_e32 v114, v114, v117, vcc
	s_nop 0
	v_mov_b32_e32 v247, v114
	ds_write_b64 v244, v[246:247]
.LrcG0_0:
	s_or_b64 exec, exec, s[98:99]
	s_waitcnt vmcnt(0)
	v_cndmask_b32_e64 v114, v249, v114, s[100:101]
.LBB0_1052:
	s_or_b64 exec, exec, s[0:1]
	v_bfe_i32 v117, v115, 7, 1
	v_and_b32_e32 v119, 64, v115
	s_waitcnt vmcnt(3)
	v_lshrrev_b32_e32 v120, 1, v115
	v_and_b32_e32 v117, 0x11000, v117
	v_lshlrev_b32_e32 v119, 1, v119
	v_and_b32_e32 v120, 24, v120
	v_or3_b32 v117, v117, v119, v120
	v_pk_mul_f32 v[120:121], v[156:157], v[114:115] op_sel_hi:[1,0]
	v_pk_mul_f32 v[122:123], v[158:159], v[114:115] op_sel_hi:[1,0]
	v_mul_lo_u32 v119, v118, s25
	v_cvt_pk_bf16_f32 v120, v120, v121
	v_cvt_pk_bf16_f32 v121, v122, v123
	v_pk_mul_f32 v[122:123], v[152:153], v[114:115] op_sel_hi:[1,0]
	v_pk_mul_f32 v[124:125], v[154:155], v[114:115] op_sel_hi:[1,0]
	v_add_u32_e32 v117, v117, v119
	v_cvt_pk_bf16_f32 v122, v122, v123
	v_cvt_pk_bf16_f32 v123, v124, v125
	ds_write2_b64 v117, v[120:121], v[122:123] offset1:4
	v_pk_mul_f32 v[120:121], v[148:149], v[114:115] op_sel_hi:[1,0]
	v_pk_mul_f32 v[122:123], v[150:151], v[114:115] op_sel_hi:[1,0]
	v_cvt_pk_bf16_f32 v120, v120, v121
	v_cvt_pk_bf16_f32 v121, v122, v123
	v_pk_mul_f32 v[122:123], v[144:145], v[114:115] op_sel_hi:[1,0]
	v_pk_mul_f32 v[124:125], v[146:147], v[114:115] op_sel_hi:[1,0]
	v_add3_u32 v114, s29, v118, 16
	v_cvt_pk_bf16_f32 v122, v122, v123
	v_cvt_pk_bf16_f32 v123, v124, v125
	v_cmp_gt_u32_e32 vcc, s22, v114
	ds_write2_b64 v117, v[120:121], v[122:123] offset0:8 offset1:12
	s_and_saveexec_b64 s[0:1], vcc
	s_cbranch_execz .LBB0_1054
	v_or_b32_e32 v120, s2, v114
	v_mov_b32_e32 v121, s3
	v_lshlrev_b64 v[120:121], 6, v[120:121]
	s_waitcnt vmcnt(1)
	v_lshl_add_u64 v[132:133], s[8:9], 0, v[120:121]
	v_bfe_u32 v244, v132, 6, 8
	v_lshlrev_b32_e32 v244, 3, v244
	v_add_u32_e32 v244, 0x24010, v244
	v_or_b32_e32 v246, 2, v132
	ds_read_b64 v[248:249], v244
	s_waitcnt lgkmcnt(0)
	v_cmp_ne_u32_e64 s[100:101], v248, v246
	s_nop 1
	s_and_saveexec_b64 s[98:99], s[100:101]
	s_cbranch_execz .LrcG0_1
	global_load_dwordx4 v[120:123], v[132:133], off
	global_load_dwordx4 v[124:127], v[132:133], off offset:16
	global_load_dwordx4 v[128:131], v[132:133], off offset:32
	s_nop 0
	global_load_dwordx4 v[132:135], v[132:133], off offset:48
	s_waitcnt vmcnt(3)
	v_mov_b32_e32 v136, v121
	v_mov_b32_e32 v137, v122
	v_mov_b32_e32 v121, v123
	s_waitcnt vmcnt(2)
	v_mov_b32_e32 v122, v125
	v_mov_b32_e32 v123, v126
	v_mov_b32_e32 v125, v127
	v_pk_add_f32 v[120:121], v[136:137], v[120:121]
	v_pk_add_f32 v[122:123], v[122:123], v[124:125]
	v_pk_add_f32 v[120:121], v[120:121], v[120:121] op_sel:[0,1] op_sel_hi:[1,0]
	v_pk_add_f32 v[122:123], v[122:123], v[122:123] op_sel:[0,1] op_sel_hi:[1,0]
	s_waitcnt vmcnt(1)
	v_add_f32_e32 v126, v128, v129
	v_add_f32_e32 v128, v130, v131
	s_waitcnt vmcnt(0)
	v_mov_b32_e32 v127, v134
	v_mov_b32_e32 v129, v135
	v_mov_b32_e32 v121, v132
	v_mov_b32_e32 v123, v133
	v_pk_add_f32 v[124:125], v[126:127], v[128:129]
	v_pk_add_f32 v[120:121], v[120:121], v[122:123]
	s_nop 0
	v_pk_add_f32 v[120:121], v[120:121], v[124:125]
	s_nop 0
	v_add_f32_e32 v112, v120, v121
	v_fmamk_f32 v112, v112, 0x3a800000, v168
	v_mul_f32_e32 v114, 0x4b800000, v112
	v_cmp_gt_f32_e32 vcc, s24, v112
	s_nop 1
	v_cndmask_b32_e32 v112, v112, v114, vcc
	v_rsq_f32_e32 v112, v112
	s_nop 0
	v_mul_f32_e32 v114, 0x45800000, v112
	v_cndmask_b32_e32 v112, v112, v114, vcc
	s_nop 0
	v_mov_b32_e32 v247, v112
	ds_write_b64 v244, v[246:247]
; DI void store4(bf16_t* dst, const f32x4& v, float s) { *(u32x2*)dst = (u32x2){pk2(v[0] * s, v[1] * s), pk2(v[2] * s, v[3] * s)}; }
; DI float rstd_from16(const float* p, float inv_n) {
;   const f32x4 a = *(const f32x4*)p, b = *(const f32x4*)(p + 4), c = *(const f32x4*)(p + 8), d = *(const f32x4*)(p + 12);
;   const float s = ((a[0] + a[1]) + (a[2] + a[3])) + ((b[0] + b[1]) + (b[2] + b[3])) + ((c[0] + c[1]) + (c[2] + c[3])) + ((d[0] + d[1]) + (d[2] + d[3]));
;   return rsqrtf(s * inv_n + EPS_);
; DI void ffnup_tile(const Params& p, int layer, int b, int mt, int tn, bf16_t* smem) {
;     ...
;     bf16_t* dstb = (wn < 2 ? U : V) + (wn & 1) * 64 + quad * 4;
; #pragma unroll
;     for (int i = 0; i < 8; ++i) {
;       const int row = wm * 128 + i * 16 + l15, s = s0 + row;
;       const float rs = (s >= 0 && s < S_) ? rstd_from16((const float*)(p.ws + O_SSQ) + ((size_t)b * S_ + s) * 16, 1.f / 1024.f) : 0.f;
; #pragma unroll
;       for (int j = 0; j < 4; ++j) store4(dstb + row * LDU + j * 16, acc[i][j], rs);
;     }
.LrcG0_1:
	s_or_b64 exec, exec, s[98:99]
	s_waitcnt vmcnt(0)
	v_cndmask_b32_e64 v112, v249, v112, s[100:101]
.LBB0_1054:
	s_or_b64 exec, exec, s[0:1]
	v_pk_mul_f32 v[104:105], v[104:105], v[112:113] op_sel_hi:[1,0]
	v_pk_mul_f32 v[106:107], v[106:107], v[112:113] op_sel_hi:[1,0]
	v_pk_mul_f32 v[100:101], v[100:101], v[112:113] op_sel_hi:[1,0]
	v_pk_mul_f32 v[102:103], v[102:103], v[112:113] op_sel_hi:[1,0]
	v_pk_mul_f32 v[96:97], v[96:97], v[112:113] op_sel_hi:[1,0]
	v_pk_mul_f32 v[98:99], v[98:99], v[112:113] op_sel_hi:[1,0]
	v_cvt_pk_bf16_f32 v104, v104, v105
	v_cvt_pk_bf16_f32 v105, v106, v107
	v_add_u32_e32 v106, 0x1000, v117
	v_cvt_pk_bf16_f32 v100, v100, v101
	v_cvt_pk_bf16_f32 v101, v102, v103
	v_cvt_pk_bf16_f32 v96, v96, v97
	v_cvt_pk_bf16_f32 v97, v98, v99
	v_pk_mul_f32 v[108:109], v[108:109], v[112:113] op_sel_hi:[1,0]
	v_pk_mul_f32 v[110:111], v[110:111], v[112:113] op_sel_hi:[1,0]
	ds_write2_b64 v106, v[100:101], v[96:97] offset0:40 offset1:44
	v_add3_u32 v97, s29, v118, 32
	v_cvt_pk_bf16_f32 v108, v108, v109
	v_cvt_pk_bf16_f32 v109, v110, v111
	v_cmp_gt_u32_e32 vcc, s22, v97
	v_mov_b32_e32 v96, 0
	v_mov_b32_e32 v98, 0
	ds_write2_b64 v106, v[108:109], v[104:105] offset0:32 offset1:36
	s_and_saveexec_b64 s[0:1], vcc
	s_cbranch_execz .LBB0_1056
	v_or_b32_e32 v98, s2, v97
	v_mov_b32_e32 v99, s3
	v_lshlrev_b64 v[98:99], 6, v[98:99]
	v_lshl_add_u64 v[110:111], s[8:9], 0, v[98:99]
	v_bfe_u32 v244, v110, 6, 8
	v_lshlrev_b32_e32 v244, 3, v244
	v_add_u32_e32 v244, 0x24010, v244
	v_or_b32_e32 v246, 2, v110
	ds_read_b64 v[248:249], v244
	s_waitcnt lgkmcnt(0)
	v_cmp_ne_u32_e64 s[100:101], v248, v246
	s_nop 1
	s_and_saveexec_b64 s[98:99], s[100:101]
	s_cbranch_execz .LrcG0_2
	global_load_dwordx4 v[98:101], v[110:111], off
	global_load_dwordx4 v[102:105], v[110:111], off offset:16
	global_load_dwordx4 v[106:109], v[110:111], off offset:32
	global_load_dwordx4 v[120:123], v[110:111], off offset:48
	s_waitcnt vmcnt(3)
	v_mov_b32_e32 v110, v99
	v_mov_b32_e32 v111, v100
	v_mov_b32_e32 v99, v101
	s_waitcnt vmcnt(2)
	v_mov_b32_e32 v100, v103
	v_mov_b32_e32 v101, v104
	v_mov_b32_e32 v103, v105
	v_pk_add_f32 v[98:99], v[110:111], v[98:99]
	v_pk_add_f32 v[100:101], v[100:101], v[102:103]
	v_pk_add_f32 v[98:99], v[98:99], v[98:99] op_sel:[0,1] op_sel_hi:[1,0]
	v_pk_add_f32 v[100:101], v[100:101], v[100:101] op_sel:[0,1] op_sel_hi:[1,0]
	s_waitcnt vmcnt(1)
	v_add_f32_e32 v104, v106, v107
	v_add_f32_e32 v106, v108, v109
	s_waitcnt vmcnt(0)
	v_mov_b32_e32 v105, v122
	v_mov_b32_e32 v107, v123
	v_mov_b32_e32 v99, v120
	v_mov_b32_e32 v101, v121
	v_pk_add_f32 v[102:103], v[104:105], v[106:107]
	v_pk_add_f32 v[98:99], v[98:99], v[100:101]
	s_nop 0
	v_pk_add_f32 v[98:99], v[98:99], v[102:103]
	s_nop 0
	v_add_f32_e32 v97, v98, v99
	v_fmamk_f32 v97, v97, 0x3a800000, v168
	v_mul_f32_e32 v98, 0x4b800000, v97
	v_cmp_gt_f32_e32 vcc, s24, v97
	s_nop 1
	v_cndmask_b32_e32 v97, v97, v98, vcc
	v_rsq_f32_e32 v97, v97
	s_nop 0
	v_mul_f32_e32 v98, 0x45800000, v97
	v_cndmask_b32_e32 v98, v97, v98, vcc
	s_nop 0
	v_mov_b32_e32 v247, v98
	ds_write_b64 v244, v[246:247]
.LrcG0_2:
	s_or_b64 exec, exec, s[98:99]
	s_waitcnt vmcnt(0)
	v_cndmask_b32_e64 v98, v249, v98, s[100:101]
.LBB0_1056:
	s_or_b64 exec, exec, s[0:1]
	v_pk_mul_f32 v[88:89], v[88:89], v[98:99] op_sel_hi:[1,0]
	v_pk_mul_f32 v[90:91], v[90:91], v[98:99] op_sel_hi:[1,0]
	v_pk_mul_f32 v[84:85], v[84:85], v[98:99] op_sel_hi:[1,0]
	v_pk_mul_f32 v[86:87], v[86:87], v[98:99] op_sel_hi:[1,0]
	v_pk_mul_f32 v[80:81], v[80:81], v[98:99] op_sel_hi:[1,0]
	v_pk_mul_f32 v[82:83], v[82:83], v[98:99] op_sel_hi:[1,0]
	v_cvt_pk_bf16_f32 v88, v88, v89
	v_cvt_pk_bf16_f32 v89, v90, v91
	v_add_u32_e32 v90, 0x2000, v117
	v_cvt_pk_bf16_f32 v84, v84, v85
	v_cvt_pk_bf16_f32 v85, v86, v87
	v_cvt_pk_bf16_f32 v80, v80, v81
	v_cvt_pk_bf16_f32 v81, v82, v83
	v_pk_mul_f32 v[92:93], v[92:93], v[98:99] op_sel_hi:[1,0]
	v_pk_mul_f32 v[94:95], v[94:95], v[98:99] op_sel_hi:[1,0]
	ds_write2_b64 v90, v[84:85], v[80:81] offset0:72 offset1:76
	v_add3_u32 v80, s29, v118, 48
	v_cvt_pk_bf16_f32 v92, v92, v93
	v_cvt_pk_bf16_f32 v93, v94, v95
	v_cmp_gt_u32_e32 vcc, s22, v80
	ds_write2_b64 v90, v[92:93], v[88:89] offset0:64 offset1:68
	s_and_saveexec_b64 s[0:1], vcc
	s_cbranch_execz .LBB0_1058
	v_or_b32_e32 v80, s2, v80
	v_mov_b32_e32 v81, s3
	v_lshlrev_b64 v[80:81], 6, v[80:81]
	v_lshl_add_u64 v[92:93], s[8:9], 0, v[80:81]
	v_bfe_u32 v244, v92, 6, 8
	v_lshlrev_b32_e32 v244, 3, v244
	v_add_u32_e32 v244, 0x24010, v244
	v_or_b32_e32 v246, 2, v92
	ds_read_b64 v[248:249], v244
	s_waitcnt lgkmcnt(0)
	v_cmp_ne_u32_e64 s[100:101], v248, v246
	s_nop 1
	s_and_saveexec_b64 s[98:99], s[100:101]
	s_cbranch_execz .LrcG0_3
	global_load_dwordx4 v[80:83], v[92:93], off
	global_load_dwordx4 v[84:87], v[92:93], off offset:16
	global_load_dwordx4 v[88:91], v[92:93], off offset:32
	s_nop 0
	global_load_dwordx4 v[92:95], v[92:93], off offset:48
	s_waitcnt vmcnt(3)
	v_mov_b32_e32 v96, v81
	v_mov_b32_e32 v97, v82
	v_mov_b32_e32 v81, v83
	s_waitcnt vmcnt(2)
	v_mov_b32_e32 v82, v85
	v_mov_b32_e32 v83, v86
	v_mov_b32_e32 v85, v87
	v_pk_add_f32 v[80:81], v[96:97], v[80:81]
	v_pk_add_f32 v[82:83], v[82:83], v[84:85]
	v_pk_add_f32 v[80:81], v[80:81], v[80:81] op_sel:[0,1] op_sel_hi:[1,0]
	v_pk_add_f32 v[82:83], v[82:83], v[82:83] op_sel:[0,1] op_sel_hi:[1,0]
	s_waitcnt vmcnt(1)
	v_add_f32_e32 v86, v88, v89
	v_add_f32_e32 v88, v90, v91
	s_waitcnt vmcnt(0)
	v_mov_b32_e32 v87, v94
	v_mov_b32_e32 v89, v95
	v_mov_b32_e32 v81, v92
	v_mov_b32_e32 v83, v93
	v_pk_add_f32 v[84:85], v[86:87], v[88:89]
	v_pk_add_f32 v[80:81], v[80:81], v[82:83]
	s_nop 0
	v_pk_add_f32 v[80:81], v[80:81], v[84:85]
	s_nop 0
	v_add_f32_e32 v80, v80, v81
	v_fmamk_f32 v80, v80, 0x3a800000, v168
	v_mul_f32_e32 v81, 0x4b800000, v80
	v_cmp_gt_f32_e32 vcc, s24, v80
	s_nop 1
	v_cndmask_b32_e32 v80, v80, v81, vcc
	v_rsq_f32_e32 v80, v80
	s_nop 0
	v_mul_f32_e32 v81, 0x45800000, v80
	v_cndmask_b32_e32 v96, v80, v81, vcc
	s_nop 0
	v_mov_b32_e32 v247, v96
	ds_write_b64 v244, v[246:247]
; DI void store4(bf16_t* dst, const f32x4& v, float s) { *(u32x2*)dst = (u32x2){pk2(v[0] * s, v[1] * s), pk2(v[2] * s, v[3] * s)}; }
; DI float rstd_from16(const float* p, float inv_n) {
;   const f32x4 a = *(const f32x4*)p, b = *(const f32x4*)(p + 4), c = *(const f32x4*)(p + 8), d = *(const f32x4*)(p + 12);
;   const float s = ((a[0] + a[1]) + (a[2] + a[3])) + ((b[0] + b[1]) + (b[2] + b[3])) + ((c[0] + c[1]) + (c[2] + c[3])) + ((d[0] + d[1]) + (d[2] + d[3]));
;   return rsqrtf(s * inv_n + EPS_);
; DI void ffnup_tile(const Params& p, int layer, int b, int mt, int tn, bf16_t* smem) {
;     ...
;     bf16_t* dstb = (wn < 2 ? U : V) + (wn & 1) * 64 + quad * 4;
; #pragma unroll
;     for (int i = 0; i < 8; ++i) {
;       const int row = wm * 128 + i * 16 + l15, s = s0 + row;
;       const float rs = (s >= 0 && s < S_) ? rstd_from16((const float*)(p.ws + O_SSQ) + ((size_t)b * S_ + s) * 16, 1.f / 1024.f) : 0.f;
; #pragma unroll
;       for (int j = 0; j < 4; ++j) store4(dstb + row * LDU + j * 16, acc[i][j], rs);
;     }
.LrcG0_3:
	s_or_b64 exec, exec, s[98:99]
	s_waitcnt vmcnt(0)
	v_cndmask_b32_e64 v96, v249, v96, s[100:101]
.LBB0_1058:
	s_or_b64 exec, exec, s[0:1]
	v_pk_mul_f32 v[72:73], v[72:73], v[96:97] op_sel_hi:[1,0]
	v_pk_mul_f32 v[74:75], v[74:75], v[96:97] op_sel_hi:[1,0]
	v_pk_mul_f32 v[68:69], v[68:69], v[96:97] op_sel_hi:[1,0]
	v_pk_mul_f32 v[70:71], v[70:71], v[96:97] op_sel_hi:[1,0]
	v_pk_mul_f32 v[64:65], v[64:65], v[96:97] op_sel_hi:[1,0]
	v_pk_mul_f32 v[66:67], v[66:67], v[96:97] op_sel_hi:[1,0]
	v_cvt_pk_bf16_f32 v72, v72, v73
	v_cvt_pk_bf16_f32 v73, v74, v75
	v_add_u32_e32 v74, 0x3000, v117
	v_cvt_pk_bf16_f32 v68, v68, v69
	v_cvt_pk_bf16_f32 v69, v70, v71
	v_cvt_pk_bf16_f32 v64, v64, v65
	v_cvt_pk_bf16_f32 v65, v66, v67
	v_pk_mul_f32 v[76:77], v[76:77], v[96:97] op_sel_hi:[1,0]
	v_pk_mul_f32 v[78:79], v[78:79], v[96:97] op_sel_hi:[1,0]
	ds_write2_b64 v74, v[68:69], v[64:65] offset0:104 offset1:108
	v_add3_u32 v65, s29, v118, 64
	v_cvt_pk_bf16_f32 v76, v76, v77
	v_cvt_pk_bf16_f32 v77, v78, v79
	v_cmp_gt_u32_e32 vcc, s22, v65
	v_mov_b32_e32 v64, 0
	v_mov_b32_e32 v66, 0
	ds_write2_b64 v74, v[76:77], v[72:73] offset0:96 offset1:100
	s_and_saveexec_b64 s[0:1], vcc
	s_cbranch_execz .LBB0_1060
	v_or_b32_e32 v66, s2, v65
	v_mov_b32_e32 v67, s3
	v_lshlrev_b64 v[66:67], 6, v[66:67]
	v_lshl_add_u64 v[78:79], s[8:9], 0, v[66:67]
	v_bfe_u32 v244, v78, 6, 8
	v_lshlrev_b32_e32 v244, 3, v244
	v_add_u32_e32 v244, 0x24010, v244
	v_or_b32_e32 v246, 2, v78
	ds_read_b64 v[248:249], v244
	s_waitcnt lgkmcnt(0)
	v_cmp_ne_u32_e64 s[100:101], v248, v246
	s_nop 1
	s_and_saveexec_b64 s[98:99], s[100:101]
	s_cbranch_execz .LrcG0_4
	global_load_dwordx4 v[66:69], v[78:79], off
	global_load_dwordx4 v[70:73], v[78:79], off offset:16
	global_load_dwordx4 v[74:77], v[78:79], off offset:32
	s_nop 0
	global_load_dwordx4 v[78:81], v[78:79], off offset:48
	s_waitcnt vmcnt(3)
	v_mov_b32_e32 v82, v67
	v_mov_b32_e32 v83, v68
	v_mov_b32_e32 v67, v69
	s_waitcnt vmcnt(2)
	v_mov_b32_e32 v68, v71
	v_mov_b32_e32 v69, v72
	v_mov_b32_e32 v71, v73
	v_pk_add_f32 v[66:67], v[82:83], v[66:67]
	v_pk_add_f32 v[68:69], v[68:69], v[70:71]
	v_pk_add_f32 v[66:67], v[66:67], v[66:67] op_sel:[0,1] op_sel_hi:[1,0]
	v_pk_add_f32 v[68:69], v[68:69], v[68:69] op_sel:[0,1] op_sel_hi:[1,0]
	s_waitcnt vmcnt(1)
	v_add_f32_e32 v72, v74, v75
	v_add_f32_e32 v74, v76, v77
	s_waitcnt vmcnt(0)
	v_mov_b32_e32 v73, v80
	v_mov_b32_e32 v75, v81
	v_mov_b32_e32 v67, v78
	v_mov_b32_e32 v69, v79
	v_pk_add_f32 v[70:71], v[72:73], v[74:75]
	v_pk_add_f32 v[66:67], v[66:67], v[68:69]
	s_nop 0
	v_pk_add_f32 v[66:67], v[66:67], v[70:71]
	s_nop 0
	v_add_f32_e32 v65, v66, v67
	v_fmamk_f32 v65, v65, 0x3a800000, v168
	v_mul_f32_e32 v66, 0x4b800000, v65
	v_cmp_gt_f32_e32 vcc, s24, v65
	s_nop 1
	v_cndmask_b32_e32 v65, v65, v66, vcc
	v_rsq_f32_e32 v65, v65
	s_nop 0
	v_mul_f32_e32 v66, 0x45800000, v65
	v_cndmask_b32_e32 v66, v65, v66, vcc
	s_nop 0
	v_mov_b32_e32 v247, v66
	ds_write_b64 v244, v[246:247]
.LrcG0_4:
	s_or_b64 exec, exec, s[98:99]
	s_waitcnt vmcnt(0)
	v_cndmask_b32_e64 v66, v249, v66, s[100:101]
.LBB0_1060:
	s_or_b64 exec, exec, s[0:1]
	v_pk_mul_f32 v[56:57], v[56:57], v[66:67] op_sel_hi:[1,0]
	v_pk_mul_f32 v[58:59], v[58:59], v[66:67] op_sel_hi:[1,0]
	v_pk_mul_f32 v[52:53], v[52:53], v[66:67] op_sel_hi:[1,0]
	v_pk_mul_f32 v[54:55], v[54:55], v[66:67] op_sel_hi:[1,0]
	v_pk_mul_f32 v[48:49], v[48:49], v[66:67] op_sel_hi:[1,0]
	v_pk_mul_f32 v[50:51], v[50:51], v[66:67] op_sel_hi:[1,0]
	v_cvt_pk_bf16_f32 v56, v56, v57
	v_cvt_pk_bf16_f32 v57, v58, v59
	v_add_u32_e32 v58, 0x4000, v117
	v_cvt_pk_bf16_f32 v52, v52, v53
	v_cvt_pk_bf16_f32 v53, v54, v55
	v_cvt_pk_bf16_f32 v48, v48, v49
	v_cvt_pk_bf16_f32 v49, v50, v51
	v_pk_mul_f32 v[60:61], v[60:61], v[66:67] op_sel_hi:[1,0]
	v_pk_mul_f32 v[62:63], v[62:63], v[66:67] op_sel_hi:[1,0]
	ds_write2_b64 v58, v[52:53], v[48:49] offset0:136 offset1:140
	v_add_u32_e32 v48, 0x50, v116
	v_cvt_pk_bf16_f32 v60, v60, v61
	v_cvt_pk_bf16_f32 v61, v62, v63
	v_cmp_gt_u32_e32 vcc, s22, v48
	ds_write2_b64 v58, v[60:61], v[56:57] offset0:128 offset1:132
	s_and_saveexec_b64 s[0:1], vcc
	s_cbranch_execz .LBB0_1062
	v_or_b32_e32 v48, s2, v48
	v_mov_b32_e32 v49, s3
	v_lshlrev_b64 v[48:49], 6, v[48:49]
	v_lshl_add_u64 v[60:61], s[8:9], 0, v[48:49]
	v_bfe_u32 v244, v60, 6, 8
	v_lshlrev_b32_e32 v244, 3, v244
	v_add_u32_e32 v244, 0x24010, v244
	v_or_b32_e32 v246, 2, v60
	ds_read_b64 v[248:249], v244
	s_waitcnt lgkmcnt(0)
	v_cmp_ne_u32_e64 s[100:101], v248, v246
	s_nop 1
	s_and_saveexec_b64 s[98:99], s[100:101]
	s_cbranch_execz .LrcG0_5
	global_load_dwordx4 v[48:51], v[60:61], off
	global_load_dwordx4 v[52:55], v[60:61], off offset:16
	global_load_dwordx4 v[56:59], v[60:61], off offset:32
	s_nop 0
	global_load_dwordx4 v[60:63], v[60:61], off offset:48
	s_waitcnt vmcnt(3)
	v_mov_b32_e32 v64, v49
	v_mov_b32_e32 v65, v50
	v_mov_b32_e32 v49, v51
	s_waitcnt vmcnt(2)
	v_mov_b32_e32 v50, v53
	v_mov_b32_e32 v51, v54
	v_mov_b32_e32 v53, v55
	v_pk_add_f32 v[48:49], v[64:65], v[48:49]
	v_pk_add_f32 v[50:51], v[50:51], v[52:53]
	v_pk_add_f32 v[48:49], v[48:49], v[48:49] op_sel:[0,1] op_sel_hi:[1,0]
	v_pk_add_f32 v[50:51], v[50:51], v[50:51] op_sel:[0,1] op_sel_hi:[1,0]
	s_waitcnt vmcnt(1)
	v_add_f32_e32 v54, v56, v57
	v_add_f32_e32 v56, v58, v59
	s_waitcnt vmcnt(0)
	v_mov_b32_e32 v55, v62
	v_mov_b32_e32 v57, v63
	v_mov_b32_e32 v49, v60
	v_mov_b32_e32 v51, v61
	v_pk_add_f32 v[52:53], v[54:55], v[56:57]
	v_pk_add_f32 v[48:49], v[48:49], v[50:51]
	s_nop 0
	v_pk_add_f32 v[48:49], v[48:49], v[52:53]
	s_nop 0
	v_add_f32_e32 v48, v48, v49
	v_fmamk_f32 v48, v48, 0x3a800000, v168
	v_mul_f32_e32 v49, 0x4b800000, v48
	v_cmp_gt_f32_e32 vcc, s24, v48
	s_nop 1
	v_cndmask_b32_e32 v48, v48, v49, vcc
	v_rsq_f32_e32 v48, v48
	s_nop 0
	v_mul_f32_e32 v49, 0x45800000, v48
	v_cndmask_b32_e32 v64, v48, v49, vcc
	s_nop 0
	v_mov_b32_e32 v247, v64
	ds_write_b64 v244, v[246:247]
; DI void store4(bf16_t* dst, const f32x4& v, float s) { *(u32x2*)dst = (u32x2){pk2(v[0] * s, v[1] * s), pk2(v[2] * s, v[3] * s)}; }
; DI float rstd_from16(const float* p, float inv_n) {
;   const f32x4 a = *(const f32x4*)p, b = *(const f32x4*)(p + 4), c = *(const f32x4*)(p + 8), d = *(const f32x4*)(p + 12);
;   const float s = ((a[0] + a[1]) + (a[2] + a[3])) + ((b[0] + b[1]) + (b[2] + b[3])) + ((c[0] + c[1]) + (c[2] + c[3])) + ((d[0] + d[1]) + (d[2] + d[3]));
;   return rsqrtf(s * inv_n + EPS_);
; DI void ffnup_tile(const Params& p, int layer, int b, int mt, int tn, bf16_t* smem) {
;     ...
;     bf16_t* dstb = (wn < 2 ? U : V) + (wn & 1) * 64 + quad * 4;
; #pragma unroll
;     for (int i = 0; i < 8; ++i) {
;       const int row = wm * 128 + i * 16 + l15, s = s0 + row;
;       const float rs = (s >= 0 && s < S_) ? rstd_from16((const float*)(p.ws + O_SSQ) + ((size_t)b * S_ + s) * 16, 1.f / 1024.f) : 0.f;
; #pragma unroll
;       for (int j = 0; j < 4; ++j) store4(dstb + row * LDU + j * 16, acc[i][j], rs);
;     }
.LrcG0_5:
	s_or_b64 exec, exec, s[98:99]
	s_waitcnt vmcnt(0)
	v_cndmask_b32_e64 v64, v249, v64, s[100:101]
.LBB0_1062:
	s_or_b64 exec, exec, s[0:1]
	v_pk_mul_f32 v[40:41], v[40:41], v[64:65] op_sel_hi:[1,0]
	v_pk_mul_f32 v[42:43], v[42:43], v[64:65] op_sel_hi:[1,0]
	v_pk_mul_f32 v[36:37], v[36:37], v[64:65] op_sel_hi:[1,0]
	v_pk_mul_f32 v[38:39], v[38:39], v[64:65] op_sel_hi:[1,0]
	v_pk_mul_f32 v[32:33], v[32:33], v[64:65] op_sel_hi:[1,0]
	v_pk_mul_f32 v[34:35], v[34:35], v[64:65] op_sel_hi:[1,0]
	v_cvt_pk_bf16_f32 v40, v40, v41
	v_cvt_pk_bf16_f32 v41, v42, v43
	v_add_u32_e32 v42, 0x5000, v117
	v_cvt_pk_bf16_f32 v36, v36, v37
	v_cvt_pk_bf16_f32 v37, v38, v39
	v_cvt_pk_bf16_f32 v32, v32, v33
	v_cvt_pk_bf16_f32 v33, v34, v35
	v_pk_mul_f32 v[44:45], v[44:45], v[64:65] op_sel_hi:[1,0]
	v_pk_mul_f32 v[46:47], v[46:47], v[64:65] op_sel_hi:[1,0]
	ds_write2_b64 v42, v[36:37], v[32:33] offset0:168 offset1:172
	v_add_u32_e32 v33, 0x60, v116
	v_cvt_pk_bf16_f32 v44, v44, v45
	v_cvt_pk_bf16_f32 v45, v46, v47
	v_cmp_gt_u32_e32 vcc, s22, v33
	v_mov_b32_e32 v32, 0
	v_mov_b32_e32 v34, 0
	ds_write2_b64 v42, v[44:45], v[40:41] offset0:160 offset1:164
	s_and_saveexec_b64 s[0:1], vcc
	s_cbranch_execz .LBB0_1064
	v_or_b32_e32 v34, s2, v33
	v_mov_b32_e32 v35, s3
	v_lshlrev_b64 v[34:35], 6, v[34:35]
	v_lshl_add_u64 v[46:47], s[8:9], 0, v[34:35]
	v_bfe_u32 v244, v46, 6, 8
	v_lshlrev_b32_e32 v244, 3, v244
	v_add_u32_e32 v244, 0x24010, v244
	v_or_b32_e32 v246, 2, v46
	ds_read_b64 v[248:249], v244
	s_waitcnt lgkmcnt(0)
	v_cmp_ne_u32_e64 s[100:101], v248, v246
	s_nop 1
	s_and_saveexec_b64 s[98:99], s[100:101]
	s_cbranch_execz .LrcG0_6
	global_load_dwordx4 v[34:37], v[46:47], off
	global_load_dwordx4 v[38:41], v[46:47], off offset:16
	global_load_dwordx4 v[42:45], v[46:47], off offset:32
	s_nop 0
	global_load_dwordx4 v[46:49], v[46:47], off offset:48
	s_waitcnt vmcnt(3)
	v_mov_b32_e32 v50, v35
	v_mov_b32_e32 v51, v36
	v_mov_b32_e32 v35, v37
	s_waitcnt vmcnt(2)
	v_mov_b32_e32 v36, v39
	v_mov_b32_e32 v37, v40
	v_mov_b32_e32 v39, v41
	v_pk_add_f32 v[34:35], v[50:51], v[34:35]
	v_pk_add_f32 v[36:37], v[36:37], v[38:39]
	v_pk_add_f32 v[34:35], v[34:35], v[34:35] op_sel:[0,1] op_sel_hi:[1,0]
	v_pk_add_f32 v[36:37], v[36:37], v[36:37] op_sel:[0,1] op_sel_hi:[1,0]
	s_waitcnt vmcnt(1)
	v_add_f32_e32 v40, v42, v43
	v_add_f32_e32 v42, v44, v45
	s_waitcnt vmcnt(0)
	v_mov_b32_e32 v41, v48
	v_mov_b32_e32 v43, v49
	v_mov_b32_e32 v35, v46
	v_mov_b32_e32 v37, v47
	v_pk_add_f32 v[38:39], v[40:41], v[42:43]
	v_pk_add_f32 v[34:35], v[34:35], v[36:37]
	s_nop 0
	v_pk_add_f32 v[34:35], v[34:35], v[38:39]
	s_nop 0
	v_add_f32_e32 v33, v34, v35
	v_fmamk_f32 v33, v33, 0x3a800000, v168
	v_mul_f32_e32 v34, 0x4b800000, v33
	v_cmp_gt_f32_e32 vcc, s24, v33
	s_nop 1
	v_cndmask_b32_e32 v33, v33, v34, vcc
	v_rsq_f32_e32 v33, v33
	s_nop 0
	v_mul_f32_e32 v34, 0x45800000, v33
	v_cndmask_b32_e32 v34, v33, v34, vcc
	s_nop 0
	v_mov_b32_e32 v247, v34
	ds_write_b64 v244, v[246:247]
.LrcG0_6:
	s_or_b64 exec, exec, s[98:99]
	s_waitcnt vmcnt(0)
	v_cndmask_b32_e64 v34, v249, v34, s[100:101]
.LBB0_1064:
	s_or_b64 exec, exec, s[0:1]
	v_pk_mul_f32 v[24:25], v[24:25], v[34:35] op_sel_hi:[1,0]
	v_pk_mul_f32 v[26:27], v[26:27], v[34:35] op_sel_hi:[1,0]
	v_pk_mul_f32 v[20:21], v[20:21], v[34:35] op_sel_hi:[1,0]
	v_pk_mul_f32 v[22:23], v[22:23], v[34:35] op_sel_hi:[1,0]
	v_pk_mul_f32 v[16:17], v[16:17], v[34:35] op_sel_hi:[1,0]
	v_pk_mul_f32 v[18:19], v[18:19], v[34:35] op_sel_hi:[1,0]
	v_cvt_pk_bf16_f32 v24, v24, v25
	v_cvt_pk_bf16_f32 v25, v26, v27
	v_add_u32_e32 v26, 0x6000, v117
	v_cvt_pk_bf16_f32 v20, v20, v21
	v_cvt_pk_bf16_f32 v21, v22, v23
	v_cvt_pk_bf16_f32 v16, v16, v17
	v_cvt_pk_bf16_f32 v17, v18, v19
	v_pk_mul_f32 v[28:29], v[28:29], v[34:35] op_sel_hi:[1,0]
	v_pk_mul_f32 v[30:31], v[30:31], v[34:35] op_sel_hi:[1,0]
	ds_write2_b64 v26, v[20:21], v[16:17] offset0:200 offset1:204
	v_add_u32_e32 v16, 0x70, v116
	v_cvt_pk_bf16_f32 v28, v28, v29
	v_cvt_pk_bf16_f32 v29, v30, v31
	v_cmp_gt_u32_e32 vcc, s22, v16
	ds_write2_b64 v26, v[28:29], v[24:25] offset0:192 offset1:196
	s_and_saveexec_b64 s[0:1], vcc
	s_cbranch_execz .LBB0_1066
	v_or_b32_e32 v16, s2, v16
	v_mov_b32_e32 v17, s3
	v_lshlrev_b64 v[16:17], 6, v[16:17]
	v_lshl_add_u64 v[28:29], s[8:9], 0, v[16:17]
	v_bfe_u32 v244, v28, 6, 8
	v_lshlrev_b32_e32 v244, 3, v244
	v_add_u32_e32 v244, 0x24010, v244
	v_or_b32_e32 v246, 2, v28
	ds_read_b64 v[248:249], v244
	s_waitcnt lgkmcnt(0)
	v_cmp_ne_u32_e64 s[100:101], v248, v246
	s_nop 1
	s_and_saveexec_b64 s[98:99], s[100:101]
	s_cbranch_execz .LrcG0_7
	global_load_dwordx4 v[16:19], v[28:29], off
	global_load_dwordx4 v[20:23], v[28:29], off offset:16
	global_load_dwordx4 v[24:27], v[28:29], off offset:32
	s_nop 0
	global_load_dwordx4 v[28:31], v[28:29], off offset:48
	s_waitcnt vmcnt(3)
	v_mov_b32_e32 v32, v17
	v_mov_b32_e32 v33, v18
	v_mov_b32_e32 v17, v19
	s_waitcnt vmcnt(2)
	v_mov_b32_e32 v18, v21
	v_mov_b32_e32 v19, v22
	v_mov_b32_e32 v21, v23
	v_pk_add_f32 v[16:17], v[32:33], v[16:17]
	v_pk_add_f32 v[18:19], v[18:19], v[20:21]
	v_pk_add_f32 v[16:17], v[16:17], v[16:17] op_sel:[0,1] op_sel_hi:[1,0]
	v_pk_add_f32 v[18:19], v[18:19], v[18:19] op_sel:[0,1] op_sel_hi:[1,0]
	s_waitcnt vmcnt(1)
	v_add_f32_e32 v22, v24, v25
	v_add_f32_e32 v24, v26, v27
	s_waitcnt vmcnt(0)
	v_mov_b32_e32 v23, v30
	v_mov_b32_e32 v25, v31
	v_mov_b32_e32 v17, v28
	v_mov_b32_e32 v19, v29
	v_pk_add_f32 v[20:21], v[22:23], v[24:25]
	v_pk_add_f32 v[16:17], v[16:17], v[18:19]
	s_nop 0
	v_pk_add_f32 v[16:17], v[16:17], v[20:21]
	s_nop 0
	v_add_f32_e32 v16, v16, v17
	v_fmamk_f32 v16, v16, 0x3a800000, v168
	v_mul_f32_e32 v17, 0x4b800000, v16
	v_cmp_gt_f32_e32 vcc, s24, v16
	s_nop 1
	v_cndmask_b32_e32 v16, v16, v17, vcc
	v_rsq_f32_e32 v16, v16
	s_nop 0
	v_mul_f32_e32 v17, 0x45800000, v16
	v_cndmask_b32_e32 v32, v16, v17, vcc
	s_nop 0
	v_mov_b32_e32 v247, v32
	ds_write_b64 v244, v[246:247]
.LrcG0_7:
	s_or_b64 exec, exec, s[98:99]
	s_waitcnt vmcnt(0)
	v_cndmask_b32_e64 v32, v249, v32, s[100:101]

; DI void stage4(bf16_t* stg, int row, int col, const f32x4& v, float s) { *(u32x2*)(stg + row * STG_LD + col) = (u32x2){pk2(v[0] * s, v[1] * s), pk2(v[2] * s, v[3] * s)}; }
; DI float rstd_from16(const float* p, float inv_n) {
;   const f32x4 a = *(const f32x4*)p, b = *(const f32x4*)(p + 4), c = *(const f32x4*)(p + 8), d = *(const f32x4*)(p + 12);
;   const float s = ((a[0] + a[1]) + (a[2] + a[3])) + ((b[0] + b[1]) + (b[2] + b[3])) + ((c[0] + c[1]) + (c[2] + c[3])) + ((d[0] + d[1]) + (d[2] + d[3]));
;   return rsqrtf(s * inv_n + EPS_);
; template <bool SWAP> DI void inproj_tile(const Params& p, int layer, int tm, int tn, bf16_t* smem) {
;     ...
; #pragma unroll
;       for (int i = 0; i < 8; ++i) {
;         const int row = i * 16 + l15, t = trow0 + row; const float rs = rstd_from16(ssq + (size_t)t * 16, 1.f / 1024.f) * qs;
;         if (kind == 1) {
;           const float* rp = (const float*)(p.ws + O_ROPE8) + (size_t)t * 16 + (quad & 1) * 8;
;           f32x4 v, o;
; #pragma unroll
;           for (int r = 0; r < 4; ++r) { v[r] = acc[i][0][r] * rs; o[r] = __shfl_xor(v[r], 32); }
; #pragma unroll
;           for (int r = 0; r < 4; ++r) { const float cs = rp[2 * r], sn = rp[2 * r + 1]; v[r] = quad < 2 ? v[r] * cs - o[r] * sn : v[r] * cs + o[r] * sn; }
;           stage4(stg, row, quad * 4, v, 1.f);
;         } else stage4(stg, row, quad * 4, acc[i][0], rs);
; #pragma unroll
;         for (int j = 1; j < 4; ++j) stage4(stg, row, j * 16 + quad * 4, acc[i][j], rs);
.LBB0_1237:
	s_or_b64 exec, exec, s[0:1]
	v_or_b32_e32 v138, v147, v146
	v_ashrrev_i32_e32 v139, 31, v138
	v_lshlrev_b64 v[136:137], 6, v[138:139]
	v_lshl_add_u64 v[136:137], s[6:7], 0, v[136:137]
	s_xor_b64 s[30:31], s[2:3], -1
	v_cmp_gt_u32_e32 vcc, 32, v145
	v_bfe_u32 v244, v136, 6, 8
	v_lshlrev_b32_e32 v244, 3, v244
	v_add_u32_e32 v244, 0x24010, v244
	v_or_b32_e32 v246, 3, v136
	ds_read_b64 v[248:249], v244
	s_waitcnt lgkmcnt(0)
	v_cmp_ne_u32_e64 s[100:101], v248, v246
	s_nop 1
	s_and_saveexec_b64 s[98:99], s[100:101]
	s_cbranch_execz .LrcA1_0
	global_load_dwordx4 v[140:143], v[136:137], off offset:48
	global_load_dwordx4 v[148:151], v[136:137], off offset:32
	global_load_dwordx4 v[152:155], v[136:137], off offset:16
	global_load_dwordx4 v[156:159], v[136:137], off
	s_waitcnt vmcnt(2)
	v_add_f32_e32 v148, v148, v149
	v_add_f32_e32 v150, v150, v151
	s_waitcnt vmcnt(0)
	v_mov_b32_e32 v136, v157
	v_mov_b32_e32 v137, v158
	v_mov_b32_e32 v157, v159
	v_pk_add_f32 v[136:137], v[136:137], v[156:157]
	v_mov_b32_e32 v156, v153
	v_mov_b32_e32 v157, v154
	v_mov_b32_e32 v153, v155
	v_pk_add_f32 v[152:153], v[156:157], v[152:153]
	v_pk_add_f32 v[136:137], v[136:137], v[136:137] op_sel:[0,1] op_sel_hi:[1,0]
	v_pk_add_f32 v[152:153], v[152:153], v[152:153] op_sel:[0,1] op_sel_hi:[1,0]
	v_mov_b32_e32 v137, v140
	v_mov_b32_e32 v153, v141
	v_mov_b32_e32 v149, v142
	v_mov_b32_e32 v151, v143
	v_pk_add_f32 v[136:137], v[136:137], v[152:153]
	v_pk_add_f32 v[140:141], v[148:149], v[150:151]
	s_nop 0
	v_pk_add_f32 v[136:137], v[136:137], v[140:141]
	s_nop 0
	v_add_f32_e32 v136, v136, v137
	v_fmamk_f32 v136, v136, 0x3a800000, v170
	v_cmp_gt_f32_e64 s[0:1], s43, v136
	v_mul_f32_e32 v137, 0x4b800000, v136
	s_nop 0
	v_cndmask_b32_e64 v136, v136, v137, s[0:1]
	v_rsq_f32_e32 v136, v136
	s_nop 0
	v_mul_f32_e32 v137, 0x45800000, v136
	v_cndmask_b32_e64 v136, v136, v137, s[0:1]
	s_nop 0
	v_mov_b32_e32 v247, v136
	ds_write_b64 v244, v[246:247]
.LrcA1_0:
	s_or_b64 exec, exec, s[98:99]
	s_waitcnt vmcnt(0)
	v_cndmask_b32_e64 v136, v249, v136, s[100:101]
	v_mul_f32_e32 v136, v131, v136
	s_and_saveexec_b64 s[0:1], s[30:31]
	s_xor_b64 s[0:1], exec, s[0:1]
	v_pk_mul_f32 v[140:141], v[124:125], v[136:137] op_sel_hi:[1,0]
	v_pk_mul_f32 v[142:143], v[126:127], v[136:137] op_sel_hi:[1,0]
	v_cvt_pk_bf16_f32 v140, v140, v141
	s_or_saveexec_b64 s[2:3], s[0:1]
	v_lshlrev_b32_e32 v149, 3, v144
	v_and_b32_e32 v141, 8, v149
	v_lshlrev_b64 v[138:139], 4, v[138:139]
	v_lshlrev_b32_e32 v160, 2, v141
	s_xor_b64 exec, exec, s[2:3]
	s_cbranch_execz .LBB0_1241
	v_readlane_b32 s0, v240, 26
	v_readlane_b32 s1, v240, 27
	v_pk_mul_f32 v[154:155], v[124:125], v[136:137] op_sel_hi:[1,0]
	s_nop 0
	v_lshl_add_u64 v[140:141], v[138:139], 2, s[0:1]
	v_cmp_lt_i32_e64 s[0:1], v222, v223
	v_lshl_add_u64 v[150:151], v[140:141], 0, v[160:161]
	s_nop 0
	v_cndmask_b32_e64 v142, v221, v222, s[0:1]
	v_lshlrev_b32_e32 v148, 2, v142
	global_load_dwordx4 v[140:143], v[150:151], off offset:16
	s_nop 0
	global_load_dwordx4 v[150:153], v[150:151], off
	ds_bpermute_b32 v156, v148, v154
	ds_bpermute_b32 v157, v148, v155
	s_waitcnt vmcnt(0)
	v_mov_b32_e32 v159, v152
	v_mov_b32_e32 v152, v151
	v_mov_b32_e32 v158, v150
	s_waitcnt lgkmcnt(0)
	v_pk_mul_f32 v[150:151], v[152:153], v[156:157]
	v_pk_mul_f32 v[152:153], v[126:127], v[136:137] op_sel_hi:[1,0]
	v_cndmask_b32_e64 v151, v151, -v151, vcc
	v_cndmask_b32_e64 v150, v150, -v150, vcc
	v_pk_fma_f32 v[150:151], v[154:155], v[158:159], v[150:151]
	ds_bpermute_b32 v154, v148, v152
	ds_bpermute_b32 v155, v148, v153
	v_mov_b32_e32 v157, v142
	v_mov_b32_e32 v142, v141
	v_mov_b32_e32 v156, v140
	s_waitcnt lgkmcnt(0)
	v_pk_mul_f32 v[140:141], v[142:143], v[154:155]
	s_nop 0
	v_cndmask_b32_e64 v141, v141, -v141, vcc
	v_cndmask_b32_e64 v140, v140, -v140, vcc
	v_pk_fma_f32 v[142:143], v[152:153], v[156:157], v[140:141]
	v_cvt_pk_bf16_f32 v140, v150, v151

; DI void stage4(bf16_t* stg, int row, int col, const f32x4& v, float s) { *(u32x2*)(stg + row * STG_LD + col) = (u32x2){pk2(v[0] * s, v[1] * s), pk2(v[2] * s, v[3] * s)}; }
; DI float rstd_from16(const float* p, float inv_n) {
;   const f32x4 a = *(const f32x4*)p, b = *(const f32x4*)(p + 4), c = *(const f32x4*)(p + 8), d = *(const f32x4*)(p + 12);
;   const float s = ((a[0] + a[1]) + (a[2] + a[3])) + ((b[0] + b[1]) + (b[2] + b[3])) + ((c[0] + c[1]) + (c[2] + c[3])) + ((d[0] + d[1]) + (d[2] + d[3]));
;   return rsqrtf(s * inv_n + EPS_);
; template <bool SWAP> DI void inproj_tile(const Params& p, int layer, int tm, int tn, bf16_t* smem) {
;     ...
; #pragma unroll
;       for (int i = 0; i < 8; ++i) {
;         const int row = i * 16 + l15, t = trow0 + row; const float rs = rstd_from16(ssq + (size_t)t * 16, 1.f / 1024.f) * qs;
;         if (kind == 1) {
;           const float* rp = (const float*)(p.ws + O_ROPE8) + (size_t)t * 16 + (quad & 1) * 8;
;           f32x4 v, o;
; #pragma unroll
;           for (int r = 0; r < 4; ++r) { v[r] = acc[i][0][r] * rs; o[r] = __shfl_xor(v[r], 32); }
; #pragma unroll
;           for (int r = 0; r < 4; ++r) { const float cs = rp[2 * r], sn = rp[2 * r + 1]; v[r] = quad < 2 ? v[r] * cs - o[r] * sn : v[r] * cs + o[r] * sn; }
;           stage4(stg, row, quad * 4, v, 1.f);
;         } else stage4(stg, row, quad * 4, acc[i][0], rs);
; #pragma unroll
;         for (int j = 1; j < 4; ++j) stage4(stg, row, j * 16 + quad * 4, acc[i][j], rs);
.LBB0_1244:
	s_or_b64 exec, exec, s[34:35]
	v_or3_b32 v138, v146, v147, 16
	v_ashrrev_i32_e32 v139, 31, v138
	s_waitcnt lgkmcnt(0)
	v_lshlrev_b64 v[136:137], 6, v[138:139]
	v_lshl_add_u64 v[136:137], s[6:7], 0, v[136:137]
	v_bfe_u32 v244, v136, 6, 8
	v_lshlrev_b32_e32 v244, 3, v244
	v_add_u32_e32 v244, 0x24010, v244
	v_or_b32_e32 v246, 3, v136
	ds_read_b64 v[248:249], v244
	s_waitcnt lgkmcnt(0)
	v_cmp_ne_u32_e64 s[100:101], v248, v246
	s_nop 1
	s_and_saveexec_b64 s[98:99], s[100:101]
	s_cbranch_execz .LrcA1_1
	global_load_dwordx4 v[140:143], v[136:137], off offset:48
	global_load_dwordx4 v[152:155], v[136:137], off offset:32
	global_load_dwordx4 v[156:159], v[136:137], off offset:16
	global_load_dwordx4 v[162:165], v[136:137], off
	s_waitcnt vmcnt(2)
	v_add_f32_e32 v152, v152, v153
	v_add_f32_e32 v154, v154, v155
	s_waitcnt vmcnt(0)
	v_mov_b32_e32 v136, v163
	v_mov_b32_e32 v137, v164
	v_mov_b32_e32 v163, v165
	v_pk_add_f32 v[136:137], v[136:137], v[162:163]
	v_mov_b32_e32 v162, v157
	v_mov_b32_e32 v163, v158
	v_mov_b32_e32 v157, v159
	v_pk_add_f32 v[156:157], v[162:163], v[156:157]
	v_pk_add_f32 v[136:137], v[136:137], v[136:137] op_sel:[0,1] op_sel_hi:[1,0]
	v_pk_add_f32 v[156:157], v[156:157], v[156:157] op_sel:[0,1] op_sel_hi:[1,0]
	v_mov_b32_e32 v137, v140
	v_mov_b32_e32 v157, v141
	v_mov_b32_e32 v153, v142
	v_mov_b32_e32 v155, v143
	v_pk_add_f32 v[136:137], v[136:137], v[156:157]
	v_pk_add_f32 v[140:141], v[152:153], v[154:155]
	s_nop 0
	v_pk_add_f32 v[136:137], v[136:137], v[140:141]
	s_nop 0
	v_add_f32_e32 v136, v136, v137
	v_fmamk_f32 v136, v136, 0x3a800000, v170
	v_cmp_gt_f32_e64 s[2:3], s43, v136
	v_mul_f32_e32 v137, 0x4b800000, v136
	s_nop 0
	v_cndmask_b32_e64 v136, v136, v137, s[2:3]
	v_rsq_f32_e32 v136, v136
	s_nop 0
	v_mul_f32_e32 v137, 0x45800000, v136
	v_cndmask_b32_e64 v136, v136, v137, s[2:3]
	s_nop 0
	v_mov_b32_e32 v247, v136
	ds_write_b64 v244, v[246:247]
.LrcA1_1:
	s_or_b64 exec, exec, s[98:99]
	s_waitcnt vmcnt(0)
	v_cndmask_b32_e64 v136, v249, v136, s[100:101]
	v_mul_f32_e32 v136, v131, v136
	s_and_saveexec_b64 s[2:3], s[30:31]
	s_xor_b64 s[2:3], exec, s[2:3]
	v_pk_mul_f32 v[140:141], v[108:109], v[136:137] op_sel_hi:[1,0]
	v_pk_mul_f32 v[142:143], v[110:111], v[136:137] op_sel_hi:[1,0]
	v_cvt_pk_bf16_f32 v140, v140, v141
	s_or_saveexec_b64 s[34:35], s[2:3]
	v_lshlrev_b64 v[138:139], 4, v[138:139]
	s_xor_b64 exec, exec, s[34:35]
	s_cbranch_execz .LBB0_1248
	v_readlane_b32 s2, v240, 26
	v_readlane_b32 s3, v240, 27
	v_pk_mul_f32 v[156:157], v[108:109], v[136:137] op_sel_hi:[1,0]
	s_nop 0
	v_lshl_add_u64 v[140:141], v[138:139], 2, s[2:3]
	v_cmp_lt_i32_e64 s[2:3], v222, v223
	v_lshl_add_u64 v[152:153], v[140:141], 0, v[160:161]
	s_nop 0
	v_cndmask_b32_e64 v142, v221, v222, s[2:3]
	v_lshlrev_b32_e32 v149, 2, v142
	global_load_dwordx4 v[140:143], v[152:153], off offset:16
	s_nop 0
	global_load_dwordx4 v[152:155], v[152:153], off
	ds_bpermute_b32 v158, v149, v156
	ds_bpermute_b32 v159, v149, v157
	s_waitcnt vmcnt(0)
	v_mov_b32_e32 v163, v154
	v_mov_b32_e32 v154, v153
	v_mov_b32_e32 v162, v152
	s_waitcnt lgkmcnt(0)
	v_pk_mul_f32 v[152:153], v[154:155], v[158:159]
	v_pk_mul_f32 v[154:155], v[110:111], v[136:137] op_sel_hi:[1,0]
	v_cndmask_b32_e64 v153, v153, -v153, vcc
	v_cndmask_b32_e64 v152, v152, -v152, vcc
	v_pk_fma_f32 v[152:153], v[156:157], v[162:163], v[152:153]
	ds_bpermute_b32 v156, v149, v154
	ds_bpermute_b32 v157, v149, v155
	v_mov_b32_e32 v159, v142
	v_mov_b32_e32 v142, v141
	v_mov_b32_e32 v158, v140
	s_waitcnt lgkmcnt(0)
	v_pk_mul_f32 v[140:141], v[142:143], v[156:157]
	s_nop 0
	v_cndmask_b32_e64 v141, v141, -v141, vcc
	v_cndmask_b32_e64 v140, v140, -v140, vcc
	v_pk_fma_f32 v[142:143], v[154:155], v[158:159], v[140:141]
	v_cvt_pk_bf16_f32 v140, v152, v153

; DI void stage4(bf16_t* stg, int row, int col, const f32x4& v, float s) { *(u32x2*)(stg + row * STG_LD + col) = (u32x2){pk2(v[0] * s, v[1] * s), pk2(v[2] * s, v[3] * s)}; }
; DI float rstd_from16(const float* p, float inv_n) {
;   const f32x4 a = *(const f32x4*)p, b = *(const f32x4*)(p + 4), c = *(const f32x4*)(p + 8), d = *(const f32x4*)(p + 12);
;   const float s = ((a[0] + a[1]) + (a[2] + a[3])) + ((b[0] + b[1]) + (b[2] + b[3])) + ((c[0] + c[1]) + (c[2] + c[3])) + ((d[0] + d[1]) + (d[2] + d[3]));
;   return rsqrtf(s * inv_n + EPS_);
; template <bool SWAP> DI void inproj_tile(const Params& p, int layer, int tm, int tn, bf16_t* smem) {
;     ...
; #pragma unroll
;       for (int i = 0; i < 8; ++i) {
;         const int row = i * 16 + l15, t = trow0 + row; const float rs = rstd_from16(ssq + (size_t)t * 16, 1.f / 1024.f) * qs;
;         if (kind == 1) {
;           const float* rp = (const float*)(p.ws + O_ROPE8) + (size_t)t * 16 + (quad & 1) * 8;
;           f32x4 v, o;
; #pragma unroll
;           for (int r = 0; r < 4; ++r) { v[r] = acc[i][0][r] * rs; o[r] = __shfl_xor(v[r], 32); }
; #pragma unroll
;           for (int r = 0; r < 4; ++r) { const float cs = rp[2 * r], sn = rp[2 * r + 1]; v[r] = quad < 2 ? v[r] * cs - o[r] * sn : v[r] * cs + o[r] * sn; }
;           stage4(stg, row, quad * 4, v, 1.f);
;         } else stage4(stg, row, quad * 4, acc[i][0], rs);
; #pragma unroll
;         for (int j = 1; j < 4; ++j) stage4(stg, row, j * 16 + quad * 4, acc[i][j], rs);
.LBB0_1251:
	s_or_b64 exec, exec, s[34:35]
	v_or3_b32 v138, v146, v147, 32
	v_ashrrev_i32_e32 v139, 31, v138
	s_waitcnt lgkmcnt(0)
	v_lshlrev_b64 v[136:137], 6, v[138:139]
	v_lshl_add_u64 v[136:137], s[6:7], 0, v[136:137]
	v_bfe_u32 v244, v136, 6, 8
	v_lshlrev_b32_e32 v244, 3, v244
	v_add_u32_e32 v244, 0x24010, v244
	v_or_b32_e32 v246, 3, v136
	ds_read_b64 v[248:249], v244
	s_waitcnt lgkmcnt(0)
	v_cmp_ne_u32_e64 s[100:101], v248, v246
	s_nop 1
	s_and_saveexec_b64 s[98:99], s[100:101]
	s_cbranch_execz .LrcA1_2
	global_load_dwordx4 v[140:143], v[136:137], off offset:48
	global_load_dwordx4 v[152:155], v[136:137], off offset:32
	global_load_dwordx4 v[156:159], v[136:137], off offset:16
	global_load_dwordx4 v[162:165], v[136:137], off
	s_waitcnt vmcnt(2)
	v_add_f32_e32 v152, v152, v153
	v_add_f32_e32 v154, v154, v155
	s_waitcnt vmcnt(0)
	v_mov_b32_e32 v136, v163
	v_mov_b32_e32 v137, v164
	v_mov_b32_e32 v163, v165
	v_pk_add_f32 v[136:137], v[136:137], v[162:163]
	v_mov_b32_e32 v162, v157
	v_mov_b32_e32 v163, v158
	v_mov_b32_e32 v157, v159
	v_pk_add_f32 v[156:157], v[162:163], v[156:157]
	v_pk_add_f32 v[136:137], v[136:137], v[136:137] op_sel:[0,1] op_sel_hi:[1,0]
	v_pk_add_f32 v[156:157], v[156:157], v[156:157] op_sel:[0,1] op_sel_hi:[1,0]
	v_mov_b32_e32 v137, v140
	v_mov_b32_e32 v157, v141
	v_mov_b32_e32 v153, v142
	v_mov_b32_e32 v155, v143
	v_pk_add_f32 v[136:137], v[136:137], v[156:157]
	v_pk_add_f32 v[140:141], v[152:153], v[154:155]
	s_nop 0
	v_pk_add_f32 v[136:137], v[136:137], v[140:141]
	s_nop 0
	v_add_f32_e32 v136, v136, v137
	v_fmamk_f32 v136, v136, 0x3a800000, v170
	v_cmp_gt_f32_e64 s[2:3], s43, v136
	v_mul_f32_e32 v137, 0x4b800000, v136
	s_nop 0
	v_cndmask_b32_e64 v136, v136, v137, s[2:3]
	v_rsq_f32_e32 v136, v136
	s_nop 0
	v_mul_f32_e32 v137, 0x45800000, v136
	v_cndmask_b32_e64 v136, v136, v137, s[2:3]
	s_nop 0
	v_mov_b32_e32 v247, v136
	ds_write_b64 v244, v[246:247]
.LrcA1_2:
	s_or_b64 exec, exec, s[98:99]
	s_waitcnt vmcnt(0)
	v_cndmask_b32_e64 v136, v249, v136, s[100:101]
	v_mul_f32_e32 v136, v131, v136
	s_and_saveexec_b64 s[2:3], s[30:31]
	s_xor_b64 s[2:3], exec, s[2:3]
	v_pk_mul_f32 v[140:141], v[92:93], v[136:137] op_sel_hi:[1,0]
	v_pk_mul_f32 v[142:143], v[94:95], v[136:137] op_sel_hi:[1,0]
	v_cvt_pk_bf16_f32 v140, v140, v141
	s_or_saveexec_b64 s[34:35], s[2:3]
	v_lshlrev_b64 v[138:139], 4, v[138:139]
	s_xor_b64 exec, exec, s[34:35]
	s_cbranch_execz .LBB0_1255
	v_readlane_b32 s2, v240, 26
	v_readlane_b32 s3, v240, 27
	v_pk_mul_f32 v[156:157], v[92:93], v[136:137] op_sel_hi:[1,0]
	s_nop 0
	v_lshl_add_u64 v[140:141], v[138:139], 2, s[2:3]
	v_cmp_lt_i32_e64 s[2:3], v222, v223
	v_lshl_add_u64 v[152:153], v[140:141], 0, v[160:161]
	s_nop 0
	v_cndmask_b32_e64 v142, v221, v222, s[2:3]
	v_lshlrev_b32_e32 v164, 2, v142
	global_load_dwordx4 v[140:143], v[152:153], off offset:16
	s_nop 0
	global_load_dwordx4 v[152:155], v[152:153], off
	ds_bpermute_b32 v158, v164, v156
	ds_bpermute_b32 v159, v164, v157
	s_waitcnt vmcnt(0)
	v_mov_b32_e32 v163, v154
	v_mov_b32_e32 v154, v153
	v_mov_b32_e32 v162, v152
	s_waitcnt lgkmcnt(0)
	v_pk_mul_f32 v[152:153], v[154:155], v[158:159]
	v_pk_mul_f32 v[154:155], v[94:95], v[136:137] op_sel_hi:[1,0]
	v_cndmask_b32_e64 v153, v153, -v153, vcc
	v_cndmask_b32_e64 v152, v152, -v152, vcc
	v_pk_fma_f32 v[152:153], v[156:157], v[162:163], v[152:153]
	ds_bpermute_b32 v156, v164, v154
	ds_bpermute_b32 v157, v164, v155
	v_mov_b32_e32 v159, v142
	v_mov_b32_e32 v142, v141
	v_mov_b32_e32 v158, v140
	s_waitcnt lgkmcnt(0)
	v_pk_mul_f32 v[140:141], v[142:143], v[156:157]
	s_nop 0
	v_cndmask_b32_e64 v141, v141, -v141, vcc
	v_cndmask_b32_e64 v140, v140, -v140, vcc
	v_pk_fma_f32 v[142:143], v[154:155], v[158:159], v[140:141]
	v_cvt_pk_bf16_f32 v140, v152, v153

; DI void stage4(bf16_t* stg, int row, int col, const f32x4& v, float s) { *(u32x2*)(stg + row * STG_LD + col) = (u32x2){pk2(v[0] * s, v[1] * s), pk2(v[2] * s, v[3] * s)}; }
; DI float rstd_from16(const float* p, float inv_n) {
;   const f32x4 a = *(const f32x4*)p, b = *(const f32x4*)(p + 4), c = *(const f32x4*)(p + 8), d = *(const f32x4*)(p + 12);
;   const float s = ((a[0] + a[1]) + (a[2] + a[3])) + ((b[0] + b[1]) + (b[2] + b[3])) + ((c[0] + c[1]) + (c[2] + c[3])) + ((d[0] + d[1]) + (d[2] + d[3]));
;   return rsqrtf(s * inv_n + EPS_);
; template <bool SWAP> DI void inproj_tile(const Params& p, int layer, int tm, int tn, bf16_t* smem) {
;     ...
; #pragma unroll
;       for (int i = 0; i < 8; ++i) {
;         const int row = i * 16 + l15, t = trow0 + row; const float rs = rstd_from16(ssq + (size_t)t * 16, 1.f / 1024.f) * qs;
;         if (kind == 1) {
;           const float* rp = (const float*)(p.ws + O_ROPE8) + (size_t)t * 16 + (quad & 1) * 8;
;           f32x4 v, o;
; #pragma unroll
;           for (int r = 0; r < 4; ++r) { v[r] = acc[i][0][r] * rs; o[r] = __shfl_xor(v[r], 32); }
; #pragma unroll
;           for (int r = 0; r < 4; ++r) { const float cs = rp[2 * r], sn = rp[2 * r + 1]; v[r] = quad < 2 ? v[r] * cs - o[r] * sn : v[r] * cs + o[r] * sn; }
;           stage4(stg, row, quad * 4, v, 1.f);
;         } else stage4(stg, row, quad * 4, acc[i][0], rs);
; #pragma unroll
;         for (int j = 1; j < 4; ++j) stage4(stg, row, j * 16 + quad * 4, acc[i][j], rs);
.LBB0_1258:
	s_or_b64 exec, exec, s[34:35]
	v_or3_b32 v138, v146, v147, 48
	v_ashrrev_i32_e32 v139, 31, v138
	s_waitcnt lgkmcnt(0)
	v_lshlrev_b64 v[136:137], 6, v[138:139]
	v_lshl_add_u64 v[136:137], s[6:7], 0, v[136:137]
	v_bfe_u32 v244, v136, 6, 8
	v_lshlrev_b32_e32 v244, 3, v244
	v_add_u32_e32 v244, 0x24010, v244
	v_or_b32_e32 v246, 3, v136
	ds_read_b64 v[248:249], v244
	s_waitcnt lgkmcnt(0)
	v_cmp_ne_u32_e64 s[100:101], v248, v246
	s_nop 1
	s_and_saveexec_b64 s[98:99], s[100:101]
	s_cbranch_execz .LrcA1_3
	global_load_dwordx4 v[140:143], v[136:137], off offset:48
	global_load_dwordx4 v[152:155], v[136:137], off offset:32
	global_load_dwordx4 v[156:159], v[136:137], off offset:16
	global_load_dwordx4 v[162:165], v[136:137], off
	s_waitcnt vmcnt(2)
	v_add_f32_e32 v152, v152, v153
	v_add_f32_e32 v154, v154, v155
	s_waitcnt vmcnt(0)
	v_mov_b32_e32 v136, v163
	v_mov_b32_e32 v137, v164
	v_mov_b32_e32 v163, v165
	v_pk_add_f32 v[136:137], v[136:137], v[162:163]
	v_mov_b32_e32 v162, v157
	v_mov_b32_e32 v163, v158
	v_mov_b32_e32 v157, v159
	v_pk_add_f32 v[156:157], v[162:163], v[156:157]
	v_pk_add_f32 v[136:137], v[136:137], v[136:137] op_sel:[0,1] op_sel_hi:[1,0]
	v_pk_add_f32 v[156:157], v[156:157], v[156:157] op_sel:[0,1] op_sel_hi:[1,0]
	v_mov_b32_e32 v137, v140
	v_mov_b32_e32 v157, v141
	v_mov_b32_e32 v153, v142
	v_mov_b32_e32 v155, v143
	v_pk_add_f32 v[136:137], v[136:137], v[156:157]
	v_pk_add_f32 v[140:141], v[152:153], v[154:155]
	s_nop 0
	v_pk_add_f32 v[136:137], v[136:137], v[140:141]
	s_nop 0
	v_add_f32_e32 v136, v136, v137
	v_fmamk_f32 v136, v136, 0x3a800000, v170
	v_cmp_gt_f32_e64 s[2:3], s43, v136
	v_mul_f32_e32 v137, 0x4b800000, v136
	s_nop 0
	v_cndmask_b32_e64 v136, v136, v137, s[2:3]
	v_rsq_f32_e32 v136, v136
	s_nop 0
	v_mul_f32_e32 v137, 0x45800000, v136
	v_cndmask_b32_e64 v136, v136, v137, s[2:3]
	s_nop 0
	v_mov_b32_e32 v247, v136
	ds_write_b64 v244, v[246:247]
.LrcA1_3:
	s_or_b64 exec, exec, s[98:99]
	s_waitcnt vmcnt(0)
	v_cndmask_b32_e64 v136, v249, v136, s[100:101]
	v_mul_f32_e32 v136, v131, v136
	s_and_saveexec_b64 s[2:3], s[30:31]
	s_xor_b64 s[2:3], exec, s[2:3]
	v_pk_mul_f32 v[140:141], v[76:77], v[136:137] op_sel_hi:[1,0]
	v_pk_mul_f32 v[142:143], v[78:79], v[136:137] op_sel_hi:[1,0]
	v_cvt_pk_bf16_f32 v140, v140, v141
	s_or_saveexec_b64 s[34:35], s[2:3]
	v_lshlrev_b64 v[138:139], 4, v[138:139]
	s_xor_b64 exec, exec, s[34:35]
	s_cbranch_execz .LBB0_1262
	v_readlane_b32 s2, v240, 26
	v_readlane_b32 s3, v240, 27
	v_pk_mul_f32 v[156:157], v[76:77], v[136:137] op_sel_hi:[1,0]
	s_nop 0
	v_lshl_add_u64 v[140:141], v[138:139], 2, s[2:3]
	v_cmp_lt_i32_e64 s[2:3], v222, v223
	v_lshl_add_u64 v[152:153], v[140:141], 0, v[160:161]
	s_nop 0
	v_cndmask_b32_e64 v142, v221, v222, s[2:3]
	v_lshlrev_b32_e32 v164, 2, v142
	global_load_dwordx4 v[140:143], v[152:153], off offset:16
	s_nop 0
	global_load_dwordx4 v[152:155], v[152:153], off
	ds_bpermute_b32 v158, v164, v156
	ds_bpermute_b32 v159, v164, v157
	s_waitcnt vmcnt(0)
	v_mov_b32_e32 v163, v154
	v_mov_b32_e32 v154, v153
	v_mov_b32_e32 v162, v152
	s_waitcnt lgkmcnt(0)
	v_pk_mul_f32 v[152:153], v[154:155], v[158:159]
	v_pk_mul_f32 v[154:155], v[78:79], v[136:137] op_sel_hi:[1,0]
	v_cndmask_b32_e64 v153, v153, -v153, vcc
	v_cndmask_b32_e64 v152, v152, -v152, vcc
	v_pk_fma_f32 v[152:153], v[156:157], v[162:163], v[152:153]
	ds_bpermute_b32 v156, v164, v154
	ds_bpermute_b32 v157, v164, v155
	v_mov_b32_e32 v159, v142
	v_mov_b32_e32 v142, v141
	v_mov_b32_e32 v158, v140
	s_waitcnt lgkmcnt(0)
	v_pk_mul_f32 v[140:141], v[142:143], v[156:157]
	s_nop 0
	v_cndmask_b32_e64 v141, v141, -v141, vcc
	v_cndmask_b32_e64 v140, v140, -v140, vcc
	v_pk_fma_f32 v[142:143], v[154:155], v[158:159], v[140:141]
	v_cvt_pk_bf16_f32 v140, v152, v153

; DI void stage4(bf16_t* stg, int row, int col, const f32x4& v, float s) { *(u32x2*)(stg + row * STG_LD + col) = (u32x2){pk2(v[0] * s, v[1] * s), pk2(v[2] * s, v[3] * s)}; }
; DI float rstd_from16(const float* p, float inv_n) {
;   const f32x4 a = *(const f32x4*)p, b = *(const f32x4*)(p + 4), c = *(const f32x4*)(p + 8), d = *(const f32x4*)(p + 12);
;   const float s = ((a[0] + a[1]) + (a[2] + a[3])) + ((b[0] + b[1]) + (b[2] + b[3])) + ((c[0] + c[1]) + (c[2] + c[3])) + ((d[0] + d[1]) + (d[2] + d[3]));
;   return rsqrtf(s * inv_n + EPS_);
; template <bool SWAP> DI void inproj_tile(const Params& p, int layer, int tm, int tn, bf16_t* smem) {
;     ...
; #pragma unroll
;       for (int i = 0; i < 8; ++i) {
;         const int row = i * 16 + l15, t = trow0 + row; const float rs = rstd_from16(ssq + (size_t)t * 16, 1.f / 1024.f) * qs;
;         if (kind == 1) {
;           const float* rp = (const float*)(p.ws + O_ROPE8) + (size_t)t * 16 + (quad & 1) * 8;
;           f32x4 v, o;
; #pragma unroll
;           for (int r = 0; r < 4; ++r) { v[r] = acc[i][0][r] * rs; o[r] = __shfl_xor(v[r], 32); }
; #pragma unroll
;           for (int r = 0; r < 4; ++r) { const float cs = rp[2 * r], sn = rp[2 * r + 1]; v[r] = quad < 2 ? v[r] * cs - o[r] * sn : v[r] * cs + o[r] * sn; }
;           stage4(stg, row, quad * 4, v, 1.f);
;         } else stage4(stg, row, quad * 4, acc[i][0], rs);
; #pragma unroll
;         for (int j = 1; j < 4; ++j) stage4(stg, row, j * 16 + quad * 4, acc[i][j], rs);
.LBB0_1265:
	s_or_b64 exec, exec, s[34:35]
	v_or3_b32 v138, v146, v147, 64
	v_ashrrev_i32_e32 v139, 31, v138
	s_waitcnt lgkmcnt(0)
	v_lshlrev_b64 v[136:137], 6, v[138:139]
	v_lshl_add_u64 v[136:137], s[6:7], 0, v[136:137]
	v_bfe_u32 v244, v136, 6, 8
	v_lshlrev_b32_e32 v244, 3, v244
	v_add_u32_e32 v244, 0x24010, v244
	v_or_b32_e32 v246, 3, v136
	ds_read_b64 v[248:249], v244
	s_waitcnt lgkmcnt(0)
	v_cmp_ne_u32_e64 s[100:101], v248, v246
	s_nop 1
	s_and_saveexec_b64 s[98:99], s[100:101]
	s_cbranch_execz .LrcA1_4
	global_load_dwordx4 v[140:143], v[136:137], off offset:48
	global_load_dwordx4 v[152:155], v[136:137], off offset:32
	global_load_dwordx4 v[156:159], v[136:137], off offset:16
	global_load_dwordx4 v[162:165], v[136:137], off
	s_waitcnt vmcnt(2)
	v_add_f32_e32 v152, v152, v153
	v_add_f32_e32 v154, v154, v155
	s_waitcnt vmcnt(0)
	v_mov_b32_e32 v136, v163
	v_mov_b32_e32 v137, v164
	v_mov_b32_e32 v163, v165
	v_pk_add_f32 v[136:137], v[136:137], v[162:163]
	v_mov_b32_e32 v162, v157
	v_mov_b32_e32 v163, v158
	v_mov_b32_e32 v157, v159
	v_pk_add_f32 v[156:157], v[162:163], v[156:157]
	v_pk_add_f32 v[136:137], v[136:137], v[136:137] op_sel:[0,1] op_sel_hi:[1,0]
	v_pk_add_f32 v[156:157], v[156:157], v[156:157] op_sel:[0,1] op_sel_hi:[1,0]
	v_mov_b32_e32 v137, v140
	v_mov_b32_e32 v157, v141
	v_mov_b32_e32 v153, v142
	v_mov_b32_e32 v155, v143
	v_pk_add_f32 v[136:137], v[136:137], v[156:157]
	v_pk_add_f32 v[140:141], v[152:153], v[154:155]
	s_nop 0
	v_pk_add_f32 v[136:137], v[136:137], v[140:141]
	s_nop 0
	v_add_f32_e32 v136, v136, v137
	v_fmamk_f32 v136, v136, 0x3a800000, v170
	v_cmp_gt_f32_e64 s[2:3], s43, v136
	v_mul_f32_e32 v137, 0x4b800000, v136
	s_nop 0
	v_cndmask_b32_e64 v136, v136, v137, s[2:3]
	v_rsq_f32_e32 v136, v136
	s_nop 0
	v_mul_f32_e32 v137, 0x45800000, v136
	v_cndmask_b32_e64 v136, v136, v137, s[2:3]
	s_nop 0
	v_mov_b32_e32 v247, v136
	ds_write_b64 v244, v[246:247]
.LrcA1_4:
	s_or_b64 exec, exec, s[98:99]
	s_waitcnt vmcnt(0)
	v_cndmask_b32_e64 v136, v249, v136, s[100:101]
	v_mul_f32_e32 v136, v131, v136
	s_and_saveexec_b64 s[2:3], s[30:31]
	s_xor_b64 s[2:3], exec, s[2:3]
	v_pk_mul_f32 v[140:141], v[60:61], v[136:137] op_sel_hi:[1,0]
	v_pk_mul_f32 v[142:143], v[62:63], v[136:137] op_sel_hi:[1,0]
	v_cvt_pk_bf16_f32 v140, v140, v141
	s_or_saveexec_b64 s[34:35], s[2:3]
	v_lshlrev_b64 v[138:139], 4, v[138:139]
	s_xor_b64 exec, exec, s[34:35]
	s_cbranch_execz .LBB0_1269
	v_readlane_b32 s2, v240, 26
	v_readlane_b32 s3, v240, 27
	v_pk_mul_f32 v[156:157], v[60:61], v[136:137] op_sel_hi:[1,0]
	s_nop 0
	v_lshl_add_u64 v[140:141], v[138:139], 2, s[2:3]
	v_cmp_lt_i32_e64 s[2:3], v222, v223
	v_lshl_add_u64 v[152:153], v[140:141], 0, v[160:161]
	s_nop 0
	v_cndmask_b32_e64 v142, v221, v222, s[2:3]
	v_lshlrev_b32_e32 v164, 2, v142
	global_load_dwordx4 v[140:143], v[152:153], off offset:16
	s_nop 0
	global_load_dwordx4 v[152:155], v[152:153], off
	ds_bpermute_b32 v158, v164, v156
	ds_bpermute_b32 v159, v164, v157
	s_waitcnt vmcnt(0)
	v_mov_b32_e32 v163, v154
	v_mov_b32_e32 v154, v153
	v_mov_b32_e32 v162, v152
	s_waitcnt lgkmcnt(0)
	v_pk_mul_f32 v[152:153], v[154:155], v[158:159]
	v_pk_mul_f32 v[154:155], v[62:63], v[136:137] op_sel_hi:[1,0]
	v_cndmask_b32_e64 v153, v153, -v153, vcc
	v_cndmask_b32_e64 v152, v152, -v152, vcc
	v_pk_fma_f32 v[152:153], v[156:157], v[162:163], v[152:153]
	ds_bpermute_b32 v156, v164, v154
	ds_bpermute_b32 v157, v164, v155
	v_mov_b32_e32 v159, v142
	v_mov_b32_e32 v142, v141
	v_mov_b32_e32 v158, v140
	s_waitcnt lgkmcnt(0)
	v_pk_mul_f32 v[140:141], v[142:143], v[156:157]
	s_nop 0
	v_cndmask_b32_e64 v141, v141, -v141, vcc
	v_cndmask_b32_e64 v140, v140, -v140, vcc
	v_pk_fma_f32 v[142:143], v[154:155], v[158:159], v[140:141]
	v_cvt_pk_bf16_f32 v140, v152, v153

; DI void stage4(bf16_t* stg, int row, int col, const f32x4& v, float s) { *(u32x2*)(stg + row * STG_LD + col) = (u32x2){pk2(v[0] * s, v[1] * s), pk2(v[2] * s, v[3] * s)}; }
; DI float rstd_from16(const float* p, float inv_n) {
;   const f32x4 a = *(const f32x4*)p, b = *(const f32x4*)(p + 4), c = *(const f32x4*)(p + 8), d = *(const f32x4*)(p + 12);
;   const float s = ((a[0] + a[1]) + (a[2] + a[3])) + ((b[0] + b[1]) + (b[2] + b[3])) + ((c[0] + c[1]) + (c[2] + c[3])) + ((d[0] + d[1]) + (d[2] + d[3]));
;   return rsqrtf(s * inv_n + EPS_);
; template <bool SWAP> DI void inproj_tile(const Params& p, int layer, int tm, int tn, bf16_t* smem) {
;     ...
; #pragma unroll
;       for (int i = 0; i < 8; ++i) {
;         const int row = i * 16 + l15, t = trow0 + row; const float rs = rstd_from16(ssq + (size_t)t * 16, 1.f / 1024.f) * qs;
;         if (kind == 1) {
;           const float* rp = (const float*)(p.ws + O_ROPE8) + (size_t)t * 16 + (quad & 1) * 8;
;           f32x4 v, o;
; #pragma unroll
;           for (int r = 0; r < 4; ++r) { v[r] = acc[i][0][r] * rs; o[r] = __shfl_xor(v[r], 32); }
; #pragma unroll
;           for (int r = 0; r < 4; ++r) { const float cs = rp[2 * r], sn = rp[2 * r + 1]; v[r] = quad < 2 ? v[r] * cs - o[r] * sn : v[r] * cs + o[r] * sn; }
;           stage4(stg, row, quad * 4, v, 1.f);
;         } else stage4(stg, row, quad * 4, acc[i][0], rs);
; #pragma unroll
;         for (int j = 1; j < 4; ++j) stage4(stg, row, j * 16 + quad * 4, acc[i][j], rs);
.LBB0_1272:
	s_or_b64 exec, exec, s[34:35]
	s_movk_i32 s2, 0x50
	v_or3_b32 v138, v146, v147, s2
	v_ashrrev_i32_e32 v139, 31, v138
	s_waitcnt lgkmcnt(0)
	v_lshlrev_b64 v[136:137], 6, v[138:139]
	v_lshl_add_u64 v[136:137], s[6:7], 0, v[136:137]
	v_bfe_u32 v244, v136, 6, 8
	v_lshlrev_b32_e32 v244, 3, v244
	v_add_u32_e32 v244, 0x24010, v244
	v_or_b32_e32 v246, 3, v136
	ds_read_b64 v[248:249], v244
	s_waitcnt lgkmcnt(0)
	v_cmp_ne_u32_e64 s[100:101], v248, v246
	s_nop 1
	s_and_saveexec_b64 s[98:99], s[100:101]
	s_cbranch_execz .LrcA1_5
	global_load_dwordx4 v[140:143], v[136:137], off offset:48
	global_load_dwordx4 v[152:155], v[136:137], off offset:32
	global_load_dwordx4 v[156:159], v[136:137], off offset:16
	global_load_dwordx4 v[162:165], v[136:137], off
	s_waitcnt vmcnt(2)
	v_add_f32_e32 v152, v152, v153
	v_add_f32_e32 v154, v154, v155
	s_waitcnt vmcnt(0)
	v_mov_b32_e32 v136, v163
	v_mov_b32_e32 v137, v164
	v_mov_b32_e32 v163, v165
	v_pk_add_f32 v[136:137], v[136:137], v[162:163]
	v_mov_b32_e32 v162, v157
	v_mov_b32_e32 v163, v158
	v_mov_b32_e32 v157, v159
	v_pk_add_f32 v[156:157], v[162:163], v[156:157]
	v_pk_add_f32 v[136:137], v[136:137], v[136:137] op_sel:[0,1] op_sel_hi:[1,0]
	v_pk_add_f32 v[156:157], v[156:157], v[156:157] op_sel:[0,1] op_sel_hi:[1,0]
	v_mov_b32_e32 v137, v140
	v_mov_b32_e32 v157, v141
	v_mov_b32_e32 v153, v142
	v_mov_b32_e32 v155, v143
	v_pk_add_f32 v[136:137], v[136:137], v[156:157]
	v_pk_add_f32 v[140:141], v[152:153], v[154:155]
	s_nop 0
	v_pk_add_f32 v[136:137], v[136:137], v[140:141]
	s_nop 0
	v_add_f32_e32 v136, v136, v137
	v_fmamk_f32 v136, v136, 0x3a800000, v170
	v_cmp_gt_f32_e64 s[2:3], s43, v136
	v_mul_f32_e32 v137, 0x4b800000, v136
	s_nop 0
	v_cndmask_b32_e64 v136, v136, v137, s[2:3]
	v_rsq_f32_e32 v136, v136
	s_nop 0
	v_mul_f32_e32 v137, 0x45800000, v136
	v_cndmask_b32_e64 v136, v136, v137, s[2:3]
	s_nop 0
	v_mov_b32_e32 v247, v136
	ds_write_b64 v244, v[246:247]
.LrcA1_5:
	s_or_b64 exec, exec, s[98:99]
	s_waitcnt vmcnt(0)
	v_cndmask_b32_e64 v136, v249, v136, s[100:101]
	v_mul_f32_e32 v136, v131, v136
	s_and_saveexec_b64 s[2:3], s[30:31]
	s_xor_b64 s[2:3], exec, s[2:3]
	v_pk_mul_f32 v[140:141], v[44:45], v[136:137] op_sel_hi:[1,0]
	v_pk_mul_f32 v[142:143], v[46:47], v[136:137] op_sel_hi:[1,0]
	v_cvt_pk_bf16_f32 v140, v140, v141
	s_or_saveexec_b64 s[34:35], s[2:3]
	v_lshlrev_b64 v[138:139], 4, v[138:139]
	s_xor_b64 exec, exec, s[34:35]
	s_cbranch_execz .LBB0_1276
	v_readlane_b32 s2, v240, 26
	v_readlane_b32 s3, v240, 27
	v_pk_mul_f32 v[156:157], v[44:45], v[136:137] op_sel_hi:[1,0]
	s_nop 0
	v_lshl_add_u64 v[140:141], v[138:139], 2, s[2:3]
	v_cmp_lt_i32_e64 s[2:3], v222, v223
	v_lshl_add_u64 v[152:153], v[140:141], 0, v[160:161]
	s_nop 0
	v_cndmask_b32_e64 v142, v221, v222, s[2:3]
	v_lshlrev_b32_e32 v164, 2, v142
	global_load_dwordx4 v[140:143], v[152:153], off offset:16
	s_nop 0
	global_load_dwordx4 v[152:155], v[152:153], off
	ds_bpermute_b32 v158, v164, v156
	ds_bpermute_b32 v159, v164, v157
	s_waitcnt vmcnt(0)
	v_mov_b32_e32 v163, v154
	v_mov_b32_e32 v154, v153
	v_mov_b32_e32 v162, v152
	s_waitcnt lgkmcnt(0)
	v_pk_mul_f32 v[152:153], v[154:155], v[158:159]
	v_pk_mul_f32 v[154:155], v[46:47], v[136:137] op_sel_hi:[1,0]
	v_cndmask_b32_e64 v153, v153, -v153, vcc
	v_cndmask_b32_e64 v152, v152, -v152, vcc
	v_pk_fma_f32 v[152:153], v[156:157], v[162:163], v[152:153]
	ds_bpermute_b32 v156, v164, v154
	ds_bpermute_b32 v157, v164, v155
	v_mov_b32_e32 v159, v142
	v_mov_b32_e32 v142, v141
	v_mov_b32_e32 v158, v140
	s_waitcnt lgkmcnt(0)
	v_pk_mul_f32 v[140:141], v[142:143], v[156:157]
	s_nop 0
	v_cndmask_b32_e64 v141, v141, -v141, vcc
	v_cndmask_b32_e64 v140, v140, -v140, vcc
	v_pk_fma_f32 v[142:143], v[154:155], v[158:159], v[140:141]
	v_cvt_pk_bf16_f32 v140, v152, v153

; DI void stage4(bf16_t* stg, int row, int col, const f32x4& v, float s) { *(u32x2*)(stg + row * STG_LD + col) = (u32x2){pk2(v[0] * s, v[1] * s), pk2(v[2] * s, v[3] * s)}; }
; DI float rstd_from16(const float* p, float inv_n) {
;   const f32x4 a = *(const f32x4*)p, b = *(const f32x4*)(p + 4), c = *(const f32x4*)(p + 8), d = *(const f32x4*)(p + 12);
;   const float s = ((a[0] + a[1]) + (a[2] + a[3])) + ((b[0] + b[1]) + (b[2] + b[3])) + ((c[0] + c[1]) + (c[2] + c[3])) + ((d[0] + d[1]) + (d[2] + d[3]));
;   return rsqrtf(s * inv_n + EPS_);
; template <bool SWAP> DI void inproj_tile(const Params& p, int layer, int tm, int tn, bf16_t* smem) {
;     ...
; #pragma unroll
;       for (int i = 0; i < 8; ++i) {
;         const int row = i * 16 + l15, t = trow0 + row; const float rs = rstd_from16(ssq + (size_t)t * 16, 1.f / 1024.f) * qs;
;         if (kind == 1) {
;           const float* rp = (const float*)(p.ws + O_ROPE8) + (size_t)t * 16 + (quad & 1) * 8;
;           f32x4 v, o;
; #pragma unroll
;           for (int r = 0; r < 4; ++r) { v[r] = acc[i][0][r] * rs; o[r] = __shfl_xor(v[r], 32); }
; #pragma unroll
;           for (int r = 0; r < 4; ++r) { const float cs = rp[2 * r], sn = rp[2 * r + 1]; v[r] = quad < 2 ? v[r] * cs - o[r] * sn : v[r] * cs + o[r] * sn; }
;           stage4(stg, row, quad * 4, v, 1.f);
;         } else stage4(stg, row, quad * 4, acc[i][0], rs);
; #pragma unroll
;         for (int j = 1; j < 4; ++j) stage4(stg, row, j * 16 + quad * 4, acc[i][j], rs);
.LBB0_1279:
	s_or_b64 exec, exec, s[34:35]
	v_or3_b32 v138, v146, v147, s45
	v_ashrrev_i32_e32 v139, 31, v138
	s_waitcnt lgkmcnt(0)
	v_lshlrev_b64 v[136:137], 6, v[138:139]
	v_lshl_add_u64 v[136:137], s[6:7], 0, v[136:137]
	v_bfe_u32 v244, v136, 6, 8
	v_lshlrev_b32_e32 v244, 3, v244
	v_add_u32_e32 v244, 0x24010, v244
	v_or_b32_e32 v246, 3, v136
	ds_read_b64 v[248:249], v244
	s_waitcnt lgkmcnt(0)
	v_cmp_ne_u32_e64 s[100:101], v248, v246
	s_nop 1
	s_and_saveexec_b64 s[98:99], s[100:101]
	s_cbranch_execz .LrcA1_6
	global_load_dwordx4 v[140:143], v[136:137], off offset:48
	global_load_dwordx4 v[152:155], v[136:137], off offset:32
	global_load_dwordx4 v[156:159], v[136:137], off offset:16
	global_load_dwordx4 v[162:165], v[136:137], off
	s_waitcnt vmcnt(2)
	v_add_f32_e32 v152, v152, v153
	v_add_f32_e32 v154, v154, v155
	s_waitcnt vmcnt(0)
	v_mov_b32_e32 v136, v163
	v_mov_b32_e32 v137, v164
	v_mov_b32_e32 v163, v165
	v_pk_add_f32 v[136:137], v[136:137], v[162:163]
	v_mov_b32_e32 v162, v157
	v_mov_b32_e32 v163, v158
	v_mov_b32_e32 v157, v159
	v_pk_add_f32 v[156:157], v[162:163], v[156:157]
	v_pk_add_f32 v[136:137], v[136:137], v[136:137] op_sel:[0,1] op_sel_hi:[1,0]
	v_pk_add_f32 v[156:157], v[156:157], v[156:157] op_sel:[0,1] op_sel_hi:[1,0]
	v_mov_b32_e32 v137, v140
	v_mov_b32_e32 v157, v141
	v_mov_b32_e32 v153, v142
	v_mov_b32_e32 v155, v143
	v_pk_add_f32 v[136:137], v[136:137], v[156:157]
	v_pk_add_f32 v[140:141], v[152:153], v[154:155]
	s_nop 0
	v_pk_add_f32 v[136:137], v[136:137], v[140:141]
	s_nop 0
	v_add_f32_e32 v136, v136, v137
	v_fmamk_f32 v136, v136, 0x3a800000, v170
	v_cmp_gt_f32_e64 s[2:3], s43, v136
	v_mul_f32_e32 v137, 0x4b800000, v136
	s_nop 0
	v_cndmask_b32_e64 v136, v136, v137, s[2:3]
	v_rsq_f32_e32 v136, v136
	s_nop 0
	v_mul_f32_e32 v137, 0x45800000, v136
	v_cndmask_b32_e64 v136, v136, v137, s[2:3]
	s_nop 0
	v_mov_b32_e32 v247, v136
	ds_write_b64 v244, v[246:247]
.LrcA1_6:
	s_or_b64 exec, exec, s[98:99]
	s_waitcnt vmcnt(0)
	v_cndmask_b32_e64 v136, v249, v136, s[100:101]
	v_mul_f32_e32 v136, v131, v136
	s_and_saveexec_b64 s[2:3], s[30:31]
	s_xor_b64 s[2:3], exec, s[2:3]
	v_pk_mul_f32 v[140:141], v[28:29], v[136:137] op_sel_hi:[1,0]
	v_pk_mul_f32 v[142:143], v[30:31], v[136:137] op_sel_hi:[1,0]
	v_cvt_pk_bf16_f32 v140, v140, v141
	s_or_saveexec_b64 s[34:35], s[2:3]
	v_lshlrev_b64 v[138:139], 4, v[138:139]
	s_xor_b64 exec, exec, s[34:35]
	s_cbranch_execz .LBB0_1283
	v_readlane_b32 s2, v240, 26
	v_readlane_b32 s3, v240, 27
	v_pk_mul_f32 v[156:157], v[28:29], v[136:137] op_sel_hi:[1,0]
	s_nop 0
	v_lshl_add_u64 v[140:141], v[138:139], 2, s[2:3]
	v_cmp_lt_i32_e64 s[2:3], v222, v223
	v_lshl_add_u64 v[152:153], v[140:141], 0, v[160:161]
	s_nop 0
	v_cndmask_b32_e64 v142, v221, v222, s[2:3]
	v_lshlrev_b32_e32 v164, 2, v142
	global_load_dwordx4 v[140:143], v[152:153], off offset:16
	s_nop 0
	global_load_dwordx4 v[152:155], v[152:153], off
	ds_bpermute_b32 v158, v164, v156
	ds_bpermute_b32 v159, v164, v157
	s_waitcnt vmcnt(0)
	v_mov_b32_e32 v163, v154
	v_mov_b32_e32 v154, v153
	v_mov_b32_e32 v162, v152
	s_waitcnt lgkmcnt(0)
	v_pk_mul_f32 v[152:153], v[154:155], v[158:159]
	v_pk_mul_f32 v[154:155], v[30:31], v[136:137] op_sel_hi:[1,0]
	v_cndmask_b32_e64 v153, v153, -v153, vcc
	v_cndmask_b32_e64 v152, v152, -v152, vcc
	v_pk_fma_f32 v[152:153], v[156:157], v[162:163], v[152:153]
	ds_bpermute_b32 v156, v164, v154
	ds_bpermute_b32 v157, v164, v155
	v_mov_b32_e32 v159, v142
	v_mov_b32_e32 v142, v141
	v_mov_b32_e32 v158, v140
	s_waitcnt lgkmcnt(0)
	v_pk_mul_f32 v[140:141], v[142:143], v[156:157]
	s_nop 0
	v_cndmask_b32_e64 v141, v141, -v141, vcc
	v_cndmask_b32_e64 v140, v140, -v140, vcc
	v_pk_fma_f32 v[142:143], v[154:155], v[158:159], v[140:141]
	v_cvt_pk_bf16_f32 v140, v152, v153

; DI void stage4(bf16_t* stg, int row, int col, const f32x4& v, float s) { *(u32x2*)(stg + row * STG_LD + col) = (u32x2){pk2(v[0] * s, v[1] * s), pk2(v[2] * s, v[3] * s)}; }
; DI float rstd_from16(const float* p, float inv_n) {
;   const f32x4 a = *(const f32x4*)p, b = *(const f32x4*)(p + 4), c = *(const f32x4*)(p + 8), d = *(const f32x4*)(p + 12);
;   const float s = ((a[0] + a[1]) + (a[2] + a[3])) + ((b[0] + b[1]) + (b[2] + b[3])) + ((c[0] + c[1]) + (c[2] + c[3])) + ((d[0] + d[1]) + (d[2] + d[3]));
;   return rsqrtf(s * inv_n + EPS_);
; template <bool SWAP> DI void inproj_tile(const Params& p, int layer, int tm, int tn, bf16_t* smem) {
;     ...
; #pragma unroll
;       for (int i = 0; i < 8; ++i) {
;         const int row = i * 16 + l15, t = trow0 + row; const float rs = rstd_from16(ssq + (size_t)t * 16, 1.f / 1024.f) * qs;
;         if (kind == 1) {
;           const float* rp = (const float*)(p.ws + O_ROPE8) + (size_t)t * 16 + (quad & 1) * 8;
;           f32x4 v, o;
; #pragma unroll
;           for (int r = 0; r < 4; ++r) { v[r] = acc[i][0][r] * rs; o[r] = __shfl_xor(v[r], 32); }
; #pragma unroll
;           for (int r = 0; r < 4; ++r) { const float cs = rp[2 * r], sn = rp[2 * r + 1]; v[r] = quad < 2 ? v[r] * cs - o[r] * sn : v[r] * cs + o[r] * sn; }
;           stage4(stg, row, quad * 4, v, 1.f);
;         } else stage4(stg, row, quad * 4, acc[i][0], rs);
; #pragma unroll
;         for (int j = 1; j < 4; ++j) stage4(stg, row, j * 16 + quad * 4, acc[i][j], rs);
.LBB0_1286:
	s_or_b64 exec, exec, s[34:35]
	s_movk_i32 s2, 0x70
	v_or3_b32 v138, v146, v147, s2
	v_ashrrev_i32_e32 v139, 31, v138
	s_waitcnt lgkmcnt(0)
	v_lshlrev_b64 v[136:137], 6, v[138:139]
	v_lshl_add_u64 v[136:137], s[6:7], 0, v[136:137]
	v_bfe_u32 v244, v136, 6, 8
	v_lshlrev_b32_e32 v244, 3, v244
	v_add_u32_e32 v244, 0x24010, v244
	v_or_b32_e32 v246, 3, v136
	ds_read_b64 v[248:249], v244
	s_waitcnt lgkmcnt(0)
	v_cmp_ne_u32_e64 s[100:101], v248, v246
	s_nop 1
	s_and_saveexec_b64 s[98:99], s[100:101]
	s_cbranch_execz .LrcA1_7
	global_load_dwordx4 v[140:143], v[136:137], off offset:48
	global_load_dwordx4 v[150:153], v[136:137], off offset:32
	global_load_dwordx4 v[154:157], v[136:137], off offset:16
	global_load_dwordx4 v[162:165], v[136:137], off
	s_waitcnt vmcnt(2)
	v_add_f32_e32 v150, v150, v151
	s_waitcnt vmcnt(1)
	v_mov_b32_e32 v158, v155
	s_waitcnt vmcnt(0)
	v_mov_b32_e32 v136, v163
	v_mov_b32_e32 v137, v164
	v_mov_b32_e32 v163, v165
	v_mov_b32_e32 v159, v156
	v_mov_b32_e32 v155, v157
	v_pk_add_f32 v[136:137], v[136:137], v[162:163]
	v_pk_add_f32 v[154:155], v[158:159], v[154:155]
	v_pk_add_f32 v[136:137], v[136:137], v[136:137] op_sel:[0,1] op_sel_hi:[1,0]
	v_pk_add_f32 v[154:155], v[154:155], v[154:155] op_sel:[0,1] op_sel_hi:[1,0]
	v_add_f32_e32 v152, v152, v153
	v_mov_b32_e32 v137, v140
	v_mov_b32_e32 v155, v141
	v_mov_b32_e32 v151, v142
	v_mov_b32_e32 v153, v143
	v_pk_add_f32 v[136:137], v[136:137], v[154:155]
	v_pk_add_f32 v[140:141], v[150:151], v[152:153]
	s_nop 0
	v_pk_add_f32 v[136:137], v[136:137], v[140:141]
	s_nop 0
	v_add_f32_e32 v136, v136, v137
	v_fmamk_f32 v136, v136, 0x3a800000, v170
	v_cmp_gt_f32_e64 s[2:3], s43, v136
	v_mul_f32_e32 v137, 0x4b800000, v136
	s_nop 0
	v_cndmask_b32_e64 v136, v136, v137, s[2:3]
	v_rsq_f32_e32 v136, v136
	s_nop 0
	v_mul_f32_e32 v137, 0x45800000, v136
	v_cndmask_b32_e64 v136, v136, v137, s[2:3]
	s_nop 0
	v_mov_b32_e32 v247, v136
	ds_write_b64 v244, v[246:247]
.LrcA1_7:
	s_or_b64 exec, exec, s[98:99]
	s_waitcnt vmcnt(0)
	v_cndmask_b32_e64 v136, v249, v136, s[100:101]
	v_mul_f32_e32 v136, v131, v136
	s_and_saveexec_b64 s[2:3], s[30:31]
	s_xor_b64 s[2:3], exec, s[2:3]
	v_pk_mul_f32 v[140:141], v[12:13], v[136:137] op_sel_hi:[1,0]
	v_pk_mul_f32 v[142:143], v[14:15], v[136:137] op_sel_hi:[1,0]
	v_cvt_pk_bf16_f32 v140, v140, v141
	s_or_saveexec_b64 s[30:31], s[2:3]
	v_lshlrev_b64 v[138:139], 4, v[138:139]
	s_xor_b64 exec, exec, s[30:31]
	s_cbranch_execz .LBB0_1290
	v_readlane_b32 s2, v240, 26
	v_readlane_b32 s3, v240, 27
	v_pk_mul_f32 v[154:155], v[12:13], v[136:137] op_sel_hi:[1,0]
	s_nop 0
	v_lshl_add_u64 v[140:141], v[138:139], 2, s[2:3]
	v_lshl_add_u64 v[150:151], v[140:141], 0, v[160:161]
	global_load_dwordx4 v[140:143], v[150:151], off offset:16
	s_nop 0
	global_load_dwordx4 v[150:153], v[150:151], off
	v_cmp_lt_i32_e64 s[2:3], v222, v223
	s_waitcnt vmcnt(0)
	v_mov_b32_e32 v159, v152
	v_cndmask_b32_e64 v131, v221, v222, s[2:3]
	v_lshlrev_b32_e32 v131, 2, v131
	ds_bpermute_b32 v156, v131, v154
	ds_bpermute_b32 v157, v131, v155
	v_mov_b32_e32 v152, v151
	v_mov_b32_e32 v158, v150
	s_waitcnt lgkmcnt(0)
	v_pk_mul_f32 v[150:151], v[152:153], v[156:157]
	s_nop 0
	v_cndmask_b32_e64 v151, v151, -v151, vcc
	v_cndmask_b32_e64 v150, v150, -v150, vcc
	v_pk_mul_f32 v[152:153], v[14:15], v[136:137] op_sel_hi:[1,0]
	v_pk_fma_f32 v[150:151], v[154:155], v[158:159], v[150:151]
	ds_bpermute_b32 v154, v131, v152
	ds_bpermute_b32 v155, v131, v153
	v_mov_b32_e32 v157, v142
	v_mov_b32_e32 v142, v141
	v_mov_b32_e32 v156, v140
	s_waitcnt lgkmcnt(0)
	v_pk_mul_f32 v[140:141], v[142:143], v[154:155]
	s_nop 0
	v_cndmask_b32_e64 v141, v141, -v141, vcc
	v_cndmask_b32_e64 v140, v140, -v140, vcc
	v_pk_fma_f32 v[142:143], v[152:153], v[156:157], v[140:141]
	v_cvt_pk_bf16_f32 v140, v150, v151

; DI float sigmoidf_(float x) { return 1.f / (1.f + __expf(-x)); }
; DI float rstd_from16(const float* p, float inv_n) {
;   const f32x4 a = *(const f32x4*)p, b = *(const f32x4*)(p + 4), c = *(const f32x4*)(p + 8), d = *(const f32x4*)(p + 12);
;   const float s = ((a[0] + a[1]) + (a[2] + a[3])) + ((b[0] + b[1]) + (b[2] + b[3])) + ((c[0] + c[1]) + (c[2] + c[3])) + ((d[0] + d[1]) + (d[2] + d[3]));
;   return rsqrtf(s * inv_n + EPS_);
; template <bool SWAP> DI void inproj_tile(const Params& p, int layer, int tm, int tn, bf16_t* smem) {
;     ...
;       for (int i = 0; i < 8; ++i) {
;         const int t = trow0 + i * 16 + l15; const float rs = rstd_from16(ssq + (size_t)t * 16, 1.f / 1024.f);
;         float* gt = (float*)(p.ws + O_GATES) + (size_t)t * 24; float* lf = (float*)(p.ws + O_LOGF) + (size_t)t * 8;
; #pragma unroll
;         for (int r = 0; r < 4; ++r) gt[quad * 4 + r] = sigmoidf_(acc[i][0][r] * rs);
;         if (quad < 2) {
; #pragma unroll
;           for (int r = 0; r < 4; ++r) gt[16 + quad * 4 + r] = sigmoidf_(acc[i][1][r] * rs);
.LBB0_1294:
	s_or_b64 exec, exec, s[26:27]
	s_and_saveexec_b64 s[0:1], s[4:5]
	s_xor_b64 s[0:1], exec, s[0:1]
	s_cbranch_execz .LBB0_1328
	v_or_b32_e32 v128, v147, v146
	v_ashrrev_i32_e32 v129, 31, v128
	v_lshlrev_b64 v[132:133], 6, v[128:129]
	v_lshl_add_u64 v[146:147], s[6:7], 0, v[132:133]
	v_readlane_b32 s2, v240, 35
	v_readlane_b32 s3, v240, 36
	v_lshlrev_b32_e32 v131, 2, v144
	v_lshlrev_b32_e32 v160, 4, v144
	v_cmp_lt_u32_e64 s[4:5], 31, v145
	v_bfe_u32 v244, v146, 6, 8
	v_lshlrev_b32_e32 v244, 3, v244
	v_add_u32_e32 v244, 0x24010, v244
	v_or_b32_e32 v246, 3, v146
	ds_read_b64 v[248:249], v244
	s_waitcnt lgkmcnt(0)
	v_cmp_ne_u32_e64 s[100:101], v248, v246
	s_nop 1
	s_and_saveexec_b64 s[98:99], s[100:101]
	s_cbranch_execz .LrcA1_8
	global_load_dwordx4 v[132:135], v[146:147], off offset:48
	global_load_dwordx4 v[136:139], v[146:147], off offset:32
	global_load_dwordx4 v[140:143], v[146:147], off offset:16
	s_nop 0
	global_load_dwordx4 v[146:149], v[146:147], off
	s_waitcnt vmcnt(2)
	v_add_f32_e32 v136, v136, v137
	v_add_f32_e32 v138, v138, v139
	s_waitcnt vmcnt(0)
	v_mov_b32_e32 v150, v147
	v_mov_b32_e32 v151, v148
	v_mov_b32_e32 v147, v149
	v_mov_b32_e32 v148, v141
	v_mov_b32_e32 v149, v142
	v_mov_b32_e32 v141, v143
	v_pk_add_f32 v[146:147], v[150:151], v[146:147]
	v_pk_add_f32 v[140:141], v[148:149], v[140:141]
	v_pk_add_f32 v[146:147], v[146:147], v[146:147] op_sel:[0,1] op_sel_hi:[1,0]
	v_pk_add_f32 v[140:141], v[140:141], v[140:141] op_sel:[0,1] op_sel_hi:[1,0]
	v_mov_b32_e32 v147, v132
	v_mov_b32_e32 v141, v133
	v_mov_b32_e32 v137, v134
	v_mov_b32_e32 v139, v135
	v_pk_add_f32 v[132:133], v[146:147], v[140:141]
	v_pk_add_f32 v[134:135], v[136:137], v[138:139]
	s_nop 0
	v_pk_add_f32 v[132:133], v[132:133], v[134:135]
	s_nop 0
	v_add_f32_e32 v130, v132, v133
	v_fmamk_f32 v130, v130, 0x3a800000, v170
	v_cmp_gt_f32_e32 vcc, s43, v130
	v_mul_f32_e32 v132, 0x4b800000, v130
	s_nop 0
	v_cndmask_b32_e32 v130, v130, v132, vcc
	v_rsq_f32_e32 v130, v130
	s_nop 0
	v_mul_f32_e32 v132, 0x45800000, v130
	v_cndmask_b32_e32 v130, v130, v132, vcc
	s_nop 0
	v_mov_b32_e32 v247, v130
	ds_write_b64 v244, v[246:247]
.LrcA1_8:
	s_or_b64 exec, exec, s[98:99]
	s_waitcnt vmcnt(0)
	v_cndmask_b32_e64 v130, v249, v130, s[100:101]
	v_mul_f32_e32 v124, v124, v130
	v_mul_f32_e32 v125, v125, v130
	v_mul_f32_e32 v124, 0xbfb8aa3b, v124
	v_mul_f32_e32 v125, 0xbfb8aa3b, v125
	v_exp_f32_e32 v124, v124
	v_exp_f32_e32 v125, v125
	v_mov_b64_e32 v[132:133], s[2:3]
	v_mad_i64_i32 v[134:135], s[2:3], v128, s45, v[132:133]
	v_pk_add_f32 v[124:125], v[124:125], 1.0 op_sel_hi:[1,0]
	v_lshlrev_b64 v[132:133], 5, v[128:129]
	v_div_scale_f32 v129, s[2:3], v125, v125, 1.0
	v_rcp_f32_e32 v136, v129
	v_mul_f32_e32 v126, v126, v130
	v_mul_f32_e32 v127, v127, v130
	v_mul_f32_e32 v126, 0xbfb8aa3b, v126
	v_fma_f32 v137, -v129, v136, 1.0
	v_fmac_f32_e32 v136, v137, v136
	v_div_scale_f32 v137, vcc, 1.0, v125, 1.0
	v_mul_f32_e32 v138, v137, v136
	v_fma_f32 v139, -v129, v138, v137
	v_fmac_f32_e32 v138, v139, v136
	v_fma_f32 v129, -v129, v138, v137
	v_div_fmas_f32 v129, v129, v136, v138
	v_div_fixup_f32 v125, v129, v125, 1.0
	v_div_scale_f32 v129, s[2:3], v124, v124, 1.0
	v_rcp_f32_e32 v136, v129
	v_mul_f32_e32 v127, 0xbfb8aa3b, v127
	v_exp_f32_e32 v126, v126
	v_exp_f32_e32 v127, v127
	v_fma_f32 v137, -v129, v136, 1.0
	v_fmac_f32_e32 v136, v137, v136
	v_div_scale_f32 v137, vcc, 1.0, v124, 1.0
	v_mul_f32_e32 v138, v137, v136
	v_fma_f32 v139, -v129, v138, v137
	v_fmac_f32_e32 v138, v139, v136
	v_fma_f32 v129, -v129, v138, v137
	v_div_fmas_f32 v129, v129, v136, v138
	v_pk_add_f32 v[126:127], v[126:127], 1.0 op_sel_hi:[1,0]
	v_div_fixup_f32 v124, v129, v124, 1.0
	v_div_scale_f32 v129, s[2:3], v127, v127, 1.0
	v_rcp_f32_e32 v136, v129
	v_lshl_add_u64 v[134:135], v[134:135], 0, v[160:161]
	v_lshlrev_b32_e32 v160, 2, v131
	v_fma_f32 v137, -v129, v136, 1.0
	v_fmac_f32_e32 v136, v137, v136
	v_div_scale_f32 v137, vcc, 1.0, v127, 1.0
	v_mul_f32_e32 v138, v137, v136
	v_fma_f32 v139, -v129, v138, v137
	v_fmac_f32_e32 v138, v139, v136
	v_fma_f32 v129, -v129, v138, v137
	v_div_fmas_f32 v129, v129, v136, v138
	v_div_fixup_f32 v127, v129, v127, 1.0
	v_div_scale_f32 v129, s[2:3], v126, v126, 1.0
	v_rcp_f32_e32 v136, v129
	s_nop 0
	v_fma_f32 v137, -v129, v136, 1.0
	v_fmac_f32_e32 v136, v137, v136
	v_div_scale_f32 v137, vcc, 1.0, v126, 1.0
	v_mul_f32_e32 v138, v137, v136
	v_fma_f32 v139, -v129, v138, v137
	v_fmac_f32_e32 v138, v139, v136
	v_fma_f32 v129, -v129, v138, v137
	v_div_fmas_f32 v129, v129, v136, v138
	v_div_fixup_f32 v126, v129, v126, 1.0
	global_store_dwordx4 v[134:135], v[124:127], off
	s_and_saveexec_b64 s[2:3], s[4:5]
	s_xor_b64 s[2:3], exec, s[2:3]
	s_cbranch_execz .LBB0_1297
; template <bool SWAP> DI void inproj_tile(const Params& p, int layer, int tm, int tn, bf16_t* smem) {
;     ...
;         } else {
; #pragma unroll
;           for (int r = 0; r < 4; ++r) { const int h = (quad - 2) * 4 + r; const float xx = acc[i][1][r] * rs + p.b_forget[layer * 8 + h]; lf[h] = fminf(xx, 0.f) - log1pf(__expf(-fabsf(xx))); }
;         }
	v_readlane_b32 s52, v241, 8
	v_readlane_b32 s60, v241, 16
	v_readlane_b32 s61, v241, 17
	v_lshl_add_u64 v[124:125], s[8:9], 0, v[132:133]
	v_lshl_add_u64 v[124:125], v[124:125], 0, v[160:161]
	v_readlane_b32 s53, v241, 9
	v_readlane_b32 s54, v241, 10
	v_readlane_b32 s55, v241, 11
	global_load_dword v126, v160, s[60:61]
	v_readlane_b32 s56, v241, 12
	v_readlane_b32 s57, v241, 13
	v_readlane_b32 s58, v241, 14
	v_readlane_b32 s59, v241, 15
	v_readlane_b32 s62, v241, 18
	v_readlane_b32 s63, v241, 19
	v_readlane_b32 s64, v241, 20
	v_readlane_b32 s65, v241, 21
	v_readlane_b32 s66, v241, 22
	v_readlane_b32 s67, v241, 23
	s_waitcnt vmcnt(0)
	v_fmac_f32_e32 v126, v120, v130
	v_min_f32_e32 v129, 0, v126
	v_mul_f32_e64 v126, |v126|, s46
	v_exp_f32_e32 v134, v126
	s_nop 0
	v_add_f32_e32 v135, 1.0, v134
	v_add_f32_e32 v126, -1.0, v135
	v_sub_f32_e32 v127, v126, v135
	v_add_f32_e32 v127, 1.0, v127
	v_sub_f32_e32 v126, v134, v126
	v_add_f32_e32 v136, v126, v127
	v_frexp_mant_f32_e32 v126, v135
	v_cmp_gt_f32_e32 vcc, s47, v126
	v_cvt_f64_f32_e32 v[126:127], v135
	v_frexp_exp_i32_f64_e32 v126, v[126:127]
	v_subbrev_co_u32_e32 v126, vcc, 0, v126, vcc
	v_sub_u32_e32 v127, 0, v126
	v_ldexp_f32 v135, v135, v127
	v_ldexp_f32 v127, v136, v127
	v_add_f32_e32 v136, -1.0, v135
	v_add_f32_e32 v137, 1.0, v136
	v_sub_f32_e32 v137, v135, v137
	v_add_f32_e32 v137, v127, v137
	v_add_f32_e32 v138, v136, v137
	v_sub_f32_e32 v136, v138, v136
	v_sub_f32_e32 v136, v137, v136
	v_add_f32_e32 v137, 1.0, v135
	v_add_f32_e32 v139, -1.0, v137
	v_sub_f32_e32 v135, v135, v139
	v_add_f32_e32 v127, v127, v135
	v_add_f32_e32 v135, v137, v127
	v_sub_f32_e32 v137, v135, v137
	v_sub_f32_e32 v127, v127, v137
	v_rcp_f32_e32 v137, v135
	v_cvt_f32_i32_e32 v126, v126
	v_cmp_neq_f32_e32 vcc, s49, v134
	v_mul_f32_e32 v139, v138, v137
	v_mul_f32_e32 v140, v135, v139
	v_fma_f32 v141, v139, v135, -v140
	v_fmac_f32_e32 v141, v139, v127
	v_add_f32_e32 v142, v140, v141
	v_sub_f32_e32 v143, v138, v142
	v_sub_f32_e32 v138, v138, v143
	v_sub_f32_e32 v140, v142, v140
	v_sub_f32_e32 v138, v138, v142
	v_add_f32_e32 v136, v136, v138
	v_sub_f32_e32 v138, v140, v141
	v_add_f32_e32 v136, v138, v136
	v_add_f32_e32 v138, v143, v136
	v_mul_f32_e32 v140, v137, v138
	v_mul_f32_e32 v141, v135, v140
	v_fma_f32 v135, v140, v135, -v141
	v_fmac_f32_e32 v135, v140, v127
	v_sub_f32_e32 v127, v143, v138
	v_add_f32_e32 v127, v136, v127
	v_add_f32_e32 v136, v141, v135
	v_sub_f32_e32 v142, v138, v136
	v_sub_f32_e32 v138, v138, v142
	v_sub_f32_e32 v141, v136, v141
	v_sub_f32_e32 v136, v138, v136
	v_add_f32_e32 v127, v127, v136
	v_sub_f32_e32 v135, v141, v135
	v_add_f32_e32 v127, v135, v127
	v_add_f32_e32 v135, v139, v140
	v_add_f32_e32 v127, v142, v127
	v_sub_f32_e32 v136, v135, v139
	v_mul_f32_e32 v127, v137, v127
	v_sub_f32_e32 v136, v140, v136
	v_add_f32_e32 v127, v136, v127
	v_mul_f32_e32 v139, 0x3f317218, v126
	v_add_f32_e32 v136, v135, v127
	v_fma_f32 v140, v126, s48, -v139
	v_mul_f32_e32 v137, v136, v136
	v_fmac_f32_e32 v140, 0xb102e308, v126
	v_sub_f32_e32 v126, v136, v135
	v_fmamk_f32 v138, v137, 0x3e9b6dac, v171
	v_sub_f32_e32 v126, v127, v126
	v_add_f32_e32 v127, v139, v140
	v_fmaak_f32 v138, v137, v138, 0x3f2aaada
	v_sub_f32_e32 v135, v127, v139
	v_ldexp_f32 v139, v136, 1
	v_mul_f32_e32 v136, v136, v137
	v_mul_f32_e32 v136, v136, v138
	v_add_f32_e32 v137, v139, v136
	v_sub_f32_e32 v138, v137, v139
	v_ldexp_f32 v126, v126, 1
	v_sub_f32_e32 v136, v136, v138
	v_add_f32_e32 v126, v126, v136
	v_add_f32_e32 v136, v137, v126
	v_sub_f32_e32 v137, v136, v137
	v_sub_f32_e32 v126, v126, v137
	v_add_f32_e32 v137, v127, v136
	v_sub_f32_e32 v138, v137, v127
	v_sub_f32_e32 v139, v137, v138
	v_sub_f32_e32 v135, v140, v135
	v_sub_f32_e32 v127, v127, v139
	v_sub_f32_e32 v136, v136, v138
	v_add_f32_e32 v127, v136, v127
	v_add_f32_e32 v136, v135, v126
	v_sub_f32_e32 v138, v136, v135
	v_sub_f32_e32 v139, v136, v138
	v_sub_f32_e32 v135, v135, v139
	v_sub_f32_e32 v126, v126, v138
	v_add_f32_e32 v127, v136, v127
	v_add_f32_e32 v126, v126, v135
	v_add_f32_e32 v135, v137, v127
	v_sub_f32_e32 v136, v135, v137
	v_sub_f32_e32 v127, v127, v136
	v_add_f32_e32 v126, v126, v127
	v_add_f32_e32 v126, v135, v126
	v_cndmask_b32_e32 v126, v178, v126, vcc
	v_cmp_ngt_f32_e32 vcc, -1.0, v134
	s_nop 1
	v_cndmask_b32_e32 v126, v179, v126, vcc
	v_cmp_neq_f32_e32 vcc, -1.0, v134
	s_nop 1
	v_cndmask_b32_e32 v126, v180, v126, vcc
	v_cmp_lt_f32_e64 vcc, |v134|, s50
	s_nop 1
	v_cndmask_b32_e32 v126, v126, v134, vcc
	v_sub_f32_e32 v126, v129, v126
	global_store_dword v[124:125], v126, off offset:-32
	global_load_dword v127, v160, s[60:61] offset:4
	s_waitcnt vmcnt(0)
; template <bool SWAP> DI void inproj_tile(const Params& p, int layer, int tm, int tn, bf16_t* smem) {
;     ...
;         } else {
; #pragma unroll
;           for (int r = 0; r < 4; ++r) { const int h = (quad - 2) * 4 + r; const float xx = acc[i][1][r] * rs + p.b_forget[layer * 8 + h]; lf[h] = fminf(xx, 0.f) - log1pf(__expf(-fabsf(xx))); }
;         }
	v_fmac_f32_e32 v127, v121, v130
	v_min_f32_e32 v126, 0, v127
	v_mul_f32_e64 v127, |v127|, s46
	v_exp_f32_e32 v127, v127
	s_nop 0
	v_add_f32_e32 v129, 1.0, v127
	v_add_f32_e32 v134, -1.0, v129
	v_sub_f32_e32 v135, v134, v129
	v_add_f32_e32 v135, 1.0, v135
	v_sub_f32_e32 v134, v127, v134
	v_add_f32_e32 v136, v134, v135
	v_frexp_mant_f32_e32 v134, v129
	v_cmp_gt_f32_e32 vcc, s47, v134
	v_cvt_f64_f32_e32 v[134:135], v129
	v_frexp_exp_i32_f64_e32 v134, v[134:135]
	v_subbrev_co_u32_e32 v134, vcc, 0, v134, vcc
	v_sub_u32_e32 v135, 0, v134
	v_ldexp_f32 v129, v129, v135
	v_ldexp_f32 v135, v136, v135
	v_add_f32_e32 v136, -1.0, v129
	v_add_f32_e32 v137, 1.0, v136
	v_sub_f32_e32 v137, v129, v137
	v_add_f32_e32 v137, v135, v137
	v_add_f32_e32 v138, v136, v137
	v_sub_f32_e32 v136, v138, v136
	v_sub_f32_e32 v136, v137, v136
	v_add_f32_e32 v137, 1.0, v129
	v_add_f32_e32 v139, -1.0, v137
	v_sub_f32_e32 v129, v129, v139
	v_add_f32_e32 v129, v135, v129
	v_add_f32_e32 v135, v137, v129
	v_sub_f32_e32 v137, v135, v137
	v_sub_f32_e32 v129, v129, v137
	v_rcp_f32_e32 v137, v135
	v_cvt_f32_i32_e32 v134, v134
	v_cmp_neq_f32_e32 vcc, s49, v127
	v_mul_f32_e32 v139, v138, v137
	v_mul_f32_e32 v140, v135, v139
	v_fma_f32 v141, v139, v135, -v140
	v_fmac_f32_e32 v141, v139, v129
	v_add_f32_e32 v142, v140, v141
	v_sub_f32_e32 v143, v138, v142
	v_sub_f32_e32 v138, v138, v143
	v_sub_f32_e32 v140, v142, v140
	v_sub_f32_e32 v138, v138, v142
	v_add_f32_e32 v136, v136, v138
	v_sub_f32_e32 v138, v140, v141
	v_add_f32_e32 v136, v138, v136
	v_add_f32_e32 v138, v143, v136
	v_mul_f32_e32 v140, v137, v138
	v_mul_f32_e32 v141, v135, v140
	v_fma_f32 v135, v140, v135, -v141
	v_fmac_f32_e32 v135, v140, v129
	v_sub_f32_e32 v129, v143, v138
	v_add_f32_e32 v129, v136, v129
	v_add_f32_e32 v136, v141, v135
	v_sub_f32_e32 v142, v138, v136
	v_sub_f32_e32 v138, v138, v142
	v_sub_f32_e32 v141, v136, v141
	v_sub_f32_e32 v136, v138, v136
	v_add_f32_e32 v129, v129, v136
	v_sub_f32_e32 v135, v141, v135
	v_add_f32_e32 v129, v135, v129
	v_add_f32_e32 v135, v139, v140
	v_add_f32_e32 v129, v142, v129
	v_sub_f32_e32 v136, v135, v139
	v_mul_f32_e32 v129, v137, v129
	v_sub_f32_e32 v136, v140, v136
	v_add_f32_e32 v129, v136, v129
	v_mul_f32_e32 v139, 0x3f317218, v134
	v_add_f32_e32 v136, v135, v129
	v_fma_f32 v140, v134, s48, -v139
	v_mul_f32_e32 v137, v136, v136
	v_fmac_f32_e32 v140, 0xb102e308, v134
	v_sub_f32_e32 v134, v136, v135
	v_fmamk_f32 v138, v137, 0x3e9b6dac, v171
	v_sub_f32_e32 v129, v129, v134
	v_add_f32_e32 v134, v139, v140
	v_fmaak_f32 v138, v137, v138, 0x3f2aaada
	v_sub_f32_e32 v135, v134, v139
	v_ldexp_f32 v139, v136, 1
	v_mul_f32_e32 v136, v136, v137
	v_mul_f32_e32 v136, v136, v138
	v_add_f32_e32 v137, v139, v136
	v_sub_f32_e32 v138, v137, v139
	v_ldexp_f32 v129, v129, 1
	v_sub_f32_e32 v136, v136, v138
	v_add_f32_e32 v129, v129, v136
	v_add_f32_e32 v136, v137, v129
	v_sub_f32_e32 v137, v136, v137
	v_sub_f32_e32 v129, v129, v137
	v_add_f32_e32 v137, v134, v136
	v_sub_f32_e32 v138, v137, v134
	v_sub_f32_e32 v139, v137, v138
	v_sub_f32_e32 v135, v140, v135
	v_sub_f32_e32 v134, v134, v139
	v_sub_f32_e32 v136, v136, v138
	v_add_f32_e32 v134, v136, v134
	v_add_f32_e32 v136, v135, v129
	v_sub_f32_e32 v138, v136, v135
	v_sub_f32_e32 v139, v136, v138
	v_sub_f32_e32 v135, v135, v139
	v_sub_f32_e32 v129, v129, v138
	v_add_f32_e32 v134, v136, v134
	v_add_f32_e32 v129, v129, v135
	v_add_f32_e32 v135, v137, v134
	v_sub_f32_e32 v136, v135, v137
	v_sub_f32_e32 v134, v134, v136
	v_add_f32_e32 v129, v129, v134
	v_add_f32_e32 v129, v135, v129
	v_cndmask_b32_e32 v129, v178, v129, vcc
	v_cmp_ngt_f32_e32 vcc, -1.0, v127
	s_nop 1
	v_cndmask_b32_e32 v129, v179, v129, vcc
	v_cmp_neq_f32_e32 vcc, -1.0, v127
	s_nop 1
	v_cndmask_b32_e32 v129, v180, v129, vcc
	v_cmp_lt_f32_e64 vcc, |v127|, s50
	s_nop 1
	v_cndmask_b32_e32 v127, v129, v127, vcc
	v_sub_f32_e32 v126, v126, v127
	global_store_dword v[124:125], v126, off offset:-28
	global_load_dword v127, v160, s[60:61] offset:8
	s_waitcnt vmcnt(0)
	v_fmac_f32_e32 v127, v122, v130
	v_min_f32_e32 v126, 0, v127
	v_mul_f32_e64 v127, |v127|, s46
	v_exp_f32_e32 v127, v127
	s_nop 0
	v_add_f32_e32 v129, 1.0, v127
	v_add_f32_e32 v134, -1.0, v129
	v_sub_f32_e32 v135, v134, v129
	v_add_f32_e32 v135, 1.0, v135
	v_sub_f32_e32 v134, v127, v134
	v_add_f32_e32 v136, v134, v135
	v_frexp_mant_f32_e32 v134, v129
	v_cmp_gt_f32_e32 vcc, s47, v134
	v_cvt_f64_f32_e32 v[134:135], v129
	v_frexp_exp_i32_f64_e32 v134, v[134:135]
	v_subbrev_co_u32_e32 v134, vcc, 0, v134, vcc
	v_sub_u32_e32 v135, 0, v134
	v_ldexp_f32 v129, v129, v135
	v_ldexp_f32 v135, v136, v135
	v_add_f32_e32 v136, -1.0, v129
	v_add_f32_e32 v137, 1.0, v136
	v_sub_f32_e32 v137, v129, v137
	v_add_f32_e32 v137, v135, v137
	v_add_f32_e32 v138, v136, v137
	v_sub_f32_e32 v136, v138, v136
	v_sub_f32_e32 v136, v137, v136
	v_add_f32_e32 v137, 1.0, v129
	v_add_f32_e32 v139, -1.0, v137
	v_sub_f32_e32 v129, v129, v139
	v_add_f32_e32 v129, v135, v129
	v_add_f32_e32 v135, v137, v129
	v_sub_f32_e32 v137, v135, v137
	v_sub_f32_e32 v129, v129, v137
	v_rcp_f32_e32 v137, v135
	v_cvt_f32_i32_e32 v134, v134
	v_cmp_neq_f32_e32 vcc, s49, v127
	v_mul_f32_e32 v139, v138, v137
	v_mul_f32_e32 v140, v135, v139
	v_fma_f32 v141, v139, v135, -v140
	v_fmac_f32_e32 v141, v139, v129
	v_add_f32_e32 v142, v140, v141
	v_sub_f32_e32 v143, v138, v142
	v_sub_f32_e32 v138, v138, v143
	v_sub_f32_e32 v140, v142, v140
	v_sub_f32_e32 v138, v138, v142
	v_add_f32_e32 v136, v136, v138
	v_sub_f32_e32 v138, v140, v141
	v_add_f32_e32 v136, v138, v136
	v_add_f32_e32 v138, v143, v136
	v_mul_f32_e32 v140, v137, v138
	v_mul_f32_e32 v141, v135, v140
	v_fma_f32 v135, v140, v135, -v141
; template <bool SWAP> DI void inproj_tile(const Params& p, int layer, int tm, int tn, bf16_t* smem) {
;     ...
;         } else {
; #pragma unroll
;           for (int r = 0; r < 4; ++r) { const int h = (quad - 2) * 4 + r; const float xx = acc[i][1][r] * rs + p.b_forget[layer * 8 + h]; lf[h] = fminf(xx, 0.f) - log1pf(__expf(-fabsf(xx))); }
;         }
	v_fmac_f32_e32 v135, v140, v129
	v_sub_f32_e32 v129, v143, v138
	v_add_f32_e32 v129, v136, v129
	v_add_f32_e32 v136, v141, v135
	v_sub_f32_e32 v142, v138, v136
	v_sub_f32_e32 v138, v138, v142
	v_sub_f32_e32 v141, v136, v141
	v_sub_f32_e32 v136, v138, v136
	v_add_f32_e32 v129, v129, v136
	v_sub_f32_e32 v135, v141, v135
	v_add_f32_e32 v129, v135, v129
	v_add_f32_e32 v135, v139, v140
	v_add_f32_e32 v129, v142, v129
	v_sub_f32_e32 v136, v135, v139
	v_mul_f32_e32 v129, v137, v129
	v_sub_f32_e32 v136, v140, v136
	v_add_f32_e32 v129, v136, v129
	v_mul_f32_e32 v139, 0x3f317218, v134
	v_add_f32_e32 v136, v135, v129
	v_fma_f32 v140, v134, s48, -v139
	v_mul_f32_e32 v137, v136, v136
	v_fmac_f32_e32 v140, 0xb102e308, v134
	v_sub_f32_e32 v134, v136, v135
	v_fmamk_f32 v138, v137, 0x3e9b6dac, v171
	v_sub_f32_e32 v129, v129, v134
	v_add_f32_e32 v134, v139, v140
	v_fmaak_f32 v138, v137, v138, 0x3f2aaada
	v_sub_f32_e32 v135, v134, v139
	v_ldexp_f32 v139, v136, 1
	v_mul_f32_e32 v136, v136, v137
	v_mul_f32_e32 v136, v136, v138
	v_add_f32_e32 v137, v139, v136
	v_sub_f32_e32 v138, v137, v139
	v_ldexp_f32 v129, v129, 1
	v_sub_f32_e32 v136, v136, v138
	v_add_f32_e32 v129, v129, v136
	v_add_f32_e32 v136, v137, v129
	v_sub_f32_e32 v137, v136, v137
	v_sub_f32_e32 v129, v129, v137
	v_add_f32_e32 v137, v134, v136
	v_sub_f32_e32 v138, v137, v134
	v_sub_f32_e32 v139, v137, v138
	v_sub_f32_e32 v135, v140, v135
	v_sub_f32_e32 v134, v134, v139
	v_sub_f32_e32 v136, v136, v138
	v_add_f32_e32 v134, v136, v134
	v_add_f32_e32 v136, v135, v129
	v_sub_f32_e32 v138, v136, v135
	v_sub_f32_e32 v139, v136, v138
	v_sub_f32_e32 v135, v135, v139
	v_sub_f32_e32 v129, v129, v138
	v_add_f32_e32 v134, v136, v134
	v_add_f32_e32 v129, v129, v135
	v_add_f32_e32 v135, v137, v134
	v_sub_f32_e32 v136, v135, v137
	v_sub_f32_e32 v134, v134, v136
	v_add_f32_e32 v129, v129, v134
	v_add_f32_e32 v129, v135, v129
	v_cndmask_b32_e32 v129, v178, v129, vcc
	v_cmp_ngt_f32_e32 vcc, -1.0, v127
	s_nop 1
	v_cndmask_b32_e32 v129, v179, v129, vcc
	v_cmp_neq_f32_e32 vcc, -1.0, v127
	s_nop 1
	v_cndmask_b32_e32 v129, v180, v129, vcc
	v_cmp_lt_f32_e64 vcc, |v127|, s50
	s_nop 1
	v_cndmask_b32_e32 v127, v129, v127, vcc
	v_sub_f32_e32 v126, v126, v127
	global_store_dword v[124:125], v126, off offset:-24
	global_load_dword v127, v160, s[60:61] offset:12
	s_waitcnt vmcnt(0)
	v_fmac_f32_e32 v127, v123, v130
	v_min_f32_e32 v126, 0, v127
	v_mul_f32_e64 v127, |v127|, s46
	v_exp_f32_e32 v127, v127
	s_nop 0
	v_add_f32_e32 v129, 1.0, v127
	v_add_f32_e32 v134, -1.0, v129
	v_sub_f32_e32 v135, v134, v129
	v_add_f32_e32 v135, 1.0, v135
	v_sub_f32_e32 v134, v127, v134
	v_add_f32_e32 v136, v134, v135
	v_frexp_mant_f32_e32 v134, v129
	v_cmp_gt_f32_e32 vcc, s47, v134
	v_cvt_f64_f32_e32 v[134:135], v129
	v_frexp_exp_i32_f64_e32 v134, v[134:135]
	v_subbrev_co_u32_e32 v134, vcc, 0, v134, vcc
	v_sub_u32_e32 v135, 0, v134
	v_ldexp_f32 v129, v129, v135
	v_ldexp_f32 v135, v136, v135
	v_add_f32_e32 v136, -1.0, v129
	v_add_f32_e32 v137, 1.0, v136
	v_sub_f32_e32 v137, v129, v137
	v_add_f32_e32 v137, v135, v137
	v_add_f32_e32 v138, v136, v137
	v_sub_f32_e32 v136, v138, v136
	v_sub_f32_e32 v136, v137, v136
	v_add_f32_e32 v137, 1.0, v129
	v_add_f32_e32 v139, -1.0, v137
	v_sub_f32_e32 v129, v129, v139
	v_add_f32_e32 v129, v135, v129
	v_add_f32_e32 v135, v137, v129
	v_sub_f32_e32 v137, v135, v137
	v_sub_f32_e32 v129, v129, v137
	v_rcp_f32_e32 v137, v135
	v_cvt_f32_i32_e32 v134, v134
	v_cmp_neq_f32_e32 vcc, s49, v127
	v_mul_f32_e32 v139, v138, v137
	v_mul_f32_e32 v140, v135, v139
	v_fma_f32 v141, v139, v135, -v140
	v_fmac_f32_e32 v141, v139, v129
	v_add_f32_e32 v142, v140, v141
	v_sub_f32_e32 v143, v138, v142
	v_sub_f32_e32 v138, v138, v143
	v_sub_f32_e32 v140, v142, v140
	v_sub_f32_e32 v138, v138, v142
	v_add_f32_e32 v136, v136, v138
	v_sub_f32_e32 v138, v140, v141
	v_add_f32_e32 v136, v138, v136
	v_add_f32_e32 v138, v143, v136
	v_mul_f32_e32 v140, v137, v138
	v_mul_f32_e32 v141, v135, v140
	v_fma_f32 v135, v140, v135, -v141
	v_fmac_f32_e32 v135, v140, v129
	v_sub_f32_e32 v129, v143, v138
	v_add_f32_e32 v129, v136, v129
	v_add_f32_e32 v136, v141, v135
	v_sub_f32_e32 v142, v138, v136
	v_sub_f32_e32 v138, v138, v142
	v_sub_f32_e32 v141, v136, v141
	v_sub_f32_e32 v136, v138, v136
	v_add_f32_e32 v129, v129, v136
	v_sub_f32_e32 v135, v141, v135
	v_add_f32_e32 v129, v135, v129
	v_add_f32_e32 v135, v139, v140
	v_add_f32_e32 v129, v142, v129
	v_sub_f32_e32 v136, v135, v139
	v_mul_f32_e32 v129, v137, v129
	v_sub_f32_e32 v136, v140, v136
	v_add_f32_e32 v129, v136, v129
	v_mul_f32_e32 v139, 0x3f317218, v134
	v_add_f32_e32 v136, v135, v129
	v_fma_f32 v140, v134, s48, -v139
	v_mul_f32_e32 v137, v136, v136
	v_fmac_f32_e32 v140, 0xb102e308, v134
	v_sub_f32_e32 v134, v136, v135
	v_fmamk_f32 v138, v137, 0x3e9b6dac, v171
	v_sub_f32_e32 v129, v129, v134
	v_add_f32_e32 v134, v139, v140
	v_fmaak_f32 v138, v137, v138, 0x3f2aaada
	v_sub_f32_e32 v135, v134, v139
	v_ldexp_f32 v139, v136, 1
	v_mul_f32_e32 v136, v136, v137
	v_mul_f32_e32 v136, v136, v138
	v_add_f32_e32 v137, v139, v136
	v_sub_f32_e32 v138, v137, v139
	v_ldexp_f32 v129, v129, 1
	v_sub_f32_e32 v136, v136, v138
	v_add_f32_e32 v129, v129, v136
	v_add_f32_e32 v136, v137, v129
	v_sub_f32_e32 v137, v136, v137
	v_sub_f32_e32 v129, v129, v137
	v_add_f32_e32 v137, v134, v136
	v_sub_f32_e32 v138, v137, v134
	v_sub_f32_e32 v139, v137, v138
	v_sub_f32_e32 v135, v140, v135
	v_sub_f32_e32 v134, v134, v139
	v_sub_f32_e32 v136, v136, v138
	v_add_f32_e32 v134, v136, v134
	v_add_f32_e32 v136, v135, v129
	v_sub_f32_e32 v138, v136, v135
	v_sub_f32_e32 v139, v136, v138
	v_sub_f32_e32 v135, v135, v139
	v_sub_f32_e32 v129, v129, v138
	v_add_f32_e32 v134, v136, v134
	v_add_f32_e32 v129, v129, v135
	v_add_f32_e32 v135, v137, v134
	v_sub_f32_e32 v136, v135, v137
	v_sub_f32_e32 v134, v134, v136
	v_add_f32_e32 v129, v129, v134
	v_add_f32_e32 v129, v135, v129
	v_cndmask_b32_e32 v129, v178, v129, vcc
	v_cmp_ngt_f32_e32 vcc, -1.0, v127
	s_nop 1
	v_cndmask_b32_e32 v129, v179, v129, vcc
	v_cmp_neq_f32_e32 vcc, -1.0, v127
	s_nop 1
	v_cndmask_b32_e32 v129, v180, v129, vcc
	v_cmp_lt_f32_e64 vcc, |v127|, s50
	s_nop 1
	v_cndmask_b32_e32 v127, v129, v127, vcc
	v_sub_f32_e32 v126, v126, v127
	global_store_dword v[124:125], v126, off offset:-20

; DI unsigned pk2(float lo, float hi) { f32x2 v = {lo, hi}; return __builtin_bit_cast(unsigned, __builtin_convertvector(v, bfx2)); }
; DI float sigmoidf_(float x) { return 1.f / (1.f + __expf(-x)); }
; template <bool SWAP> DI void inproj_tile(const Params& p, int layer, int tm, int tn, bf16_t* smem) {
;     ...
;       for (int i = 0; i < 8; ++i) {
;         const int t = trow0 + i * 16 + l15; const float rs = rstd_from16(ssq + (size_t)t * 16, 1.f / 1024.f);
;         float* gt = (float*)(p.ws + O_GATES) + (size_t)t * 24; float* lf = (float*)(p.ws + O_LOGF) + (size_t)t * 8;
; #pragma unroll
;         for (int r = 0; r < 4; ++r) gt[quad * 4 + r] = sigmoidf_(acc[i][0][r] * rs);
;     ...
;         const float* rp = (const float*)(p.ws + O_ROPE16) + (size_t)t * 32 + quad * 8; float o1[4], o2[4];
; #pragma unroll
;         for (int r = 0; r < 4; ++r) { const float cs = rp[2 * r], sn = rp[2 * r + 1], x1 = acc[i][2][r] * rs, x2 = acc[i][3][r] * rs; o1[r] = x1 * cs - x2 * sn; o2[r] = x2 * cs + x1 * sn; }
;         bf16_t* kp = (bf16_t*)(p.ws + O_MLAKPE) + (size_t)t * 32 + quad * 4;
;         *(u32x2*)kp = (u32x2){pk2(o1[0], o1[1]), pk2(o1[2], o1[3])}; *(u32x2*)(kp + 16) = (u32x2){pk2(o2[0], o2[1]), pk2(o2[2], o2[3])};
.LBB0_1299:
	s_or_b64 exec, exec, s[2:3]
	s_nop 0
	v_lshl_add_u64 v[120:121], v[132:133], 2, s[10:11]
	v_lshlrev_b32_e32 v122, 5, v144
	v_mov_b32_e32 v123, v161
	v_lshl_add_u64 v[124:125], v[120:121], 0, v[122:123]
	global_load_dwordx4 v[120:123], v[124:125], off offset:16
	s_nop 0
	global_load_dwordx4 v[124:127], v[124:125], off
	v_pk_mul_f32 v[112:113], v[112:113], v[130:131] op_sel_hi:[1,0]
	v_pk_mul_f32 v[116:117], v[116:117], v[130:131] op_sel_hi:[1,0]
	v_readlane_b32 s2, v240, 32
	v_readlane_b32 s3, v240, 33
	s_waitcnt vmcnt(0)
	v_mov_b32_e32 v135, v126
	v_mov_b32_e32 v126, v125
	v_mov_b32_e32 v134, v124
	v_pk_mul_f32 v[124:125], v[112:113], v[126:127]
	s_nop 0
	v_pk_fma_f32 v[124:125], v[116:117], v[134:135], v[124:125] neg_lo:[0,0,1] neg_hi:[0,0,1]
	v_pk_mul_f32 v[116:117], v[116:117], v[126:127]
	v_or_b32_e32 v126, 16, v128
	v_pk_fma_f32 v[116:117], v[112:113], v[134:135], v[116:117]
	v_pk_mul_f32 v[112:113], v[114:115], v[130:131] op_sel_hi:[1,0]
	v_pk_mul_f32 v[114:115], v[118:119], v[130:131] op_sel_hi:[1,0]
	v_mov_b32_e32 v119, v122
	v_mov_b32_e32 v122, v121
	v_mov_b32_e32 v118, v120
	v_pk_mul_f32 v[120:121], v[112:113], v[122:123]
	v_ashrrev_i32_e32 v127, 31, v126
	v_pk_fma_f32 v[120:121], v[114:115], v[118:119], v[120:121] neg_lo:[0,0,1] neg_hi:[0,0,1]
	v_pk_mul_f32 v[114:115], v[114:115], v[122:123]
	v_cvt_pk_bf16_f32 v122, v124, v125
	v_pk_fma_f32 v[114:115], v[112:113], v[118:119], v[114:115]
	v_lshl_add_u64 v[118:119], v[132:133], 1, s[2:3]
	v_lshlrev_b32_e32 v112, 1, v131
	v_mov_b32_e32 v113, v161
	v_lshl_add_u64 v[118:119], v[118:119], 0, v[112:113]
	v_cvt_pk_bf16_f32 v123, v120, v121
	v_cvt_pk_bf16_f32 v116, v116, v117
	v_cvt_pk_bf16_f32 v117, v114, v115
	v_lshlrev_b64 v[114:115], 6, v[126:127]
	global_store_dwordx2 v[118:119], v[122:123], off
	global_store_dwordx2 v[118:119], v[116:117], off offset:32
	v_lshl_add_u64 v[130:131], s[6:7], 0, v[114:115]
	v_bfe_u32 v244, v130, 6, 8
	v_lshlrev_b32_e32 v244, 3, v244
	v_add_u32_e32 v244, 0x24010, v244
	v_or_b32_e32 v246, 3, v130
	ds_read_b64 v[248:249], v244
	s_waitcnt lgkmcnt(0)
	v_cmp_ne_u32_e64 s[100:101], v248, v246
	s_nop 1
	s_and_saveexec_b64 s[98:99], s[100:101]
	s_cbranch_execz .LrcA1_9
	global_load_dwordx4 v[114:117], v[130:131], off offset:48
	global_load_dwordx4 v[118:121], v[130:131], off offset:32
	global_load_dwordx4 v[122:125], v[130:131], off offset:16
	s_nop 0
	global_load_dwordx4 v[130:133], v[130:131], off
	s_waitcnt vmcnt(2)
	v_add_f32_e32 v118, v118, v119
	v_add_f32_e32 v120, v120, v121
	s_waitcnt vmcnt(0)
	v_mov_b32_e32 v134, v131
	v_mov_b32_e32 v135, v132
	v_mov_b32_e32 v131, v133
	v_mov_b32_e32 v132, v123
	v_mov_b32_e32 v133, v124
	v_mov_b32_e32 v123, v125
	v_pk_add_f32 v[130:131], v[134:135], v[130:131]
	v_pk_add_f32 v[122:123], v[132:133], v[122:123]
	v_pk_add_f32 v[130:131], v[130:131], v[130:131] op_sel:[0,1] op_sel_hi:[1,0]
	v_pk_add_f32 v[122:123], v[122:123], v[122:123] op_sel:[0,1] op_sel_hi:[1,0]
	v_mov_b32_e32 v131, v114
	v_mov_b32_e32 v123, v115
	v_mov_b32_e32 v119, v116
	v_mov_b32_e32 v121, v117
	v_pk_add_f32 v[114:115], v[130:131], v[122:123]
	v_pk_add_f32 v[116:117], v[118:119], v[120:121]
	s_nop 0
	v_pk_add_f32 v[114:115], v[114:115], v[116:117]
	v_add_f32_e32 v113, v114, v115
	v_fmamk_f32 v113, v113, 0x3a800000, v170
	v_cmp_gt_f32_e32 vcc, s43, v113
	v_mul_f32_e32 v114, 0x4b800000, v113
	v_cndmask_b32_e32 v113, v113, v114, vcc
	v_rsq_f32_e32 v113, v113
	v_mul_f32_e32 v114, 0x45800000, v113
	v_cndmask_b32_e32 v114, v113, v114, vcc
	s_nop 0
	v_mov_b32_e32 v247, v114
	ds_write_b64 v244, v[246:247]
.LrcA1_9:
	s_or_b64 exec, exec, s[98:99]
	s_waitcnt vmcnt(0)
	v_cndmask_b32_e64 v114, v249, v114, s[100:101]
	v_readlane_b32 s2, v240, 35
	v_readlane_b32 s3, v240, 36
	v_mov_b64_e32 v[116:117], s[2:3]
	v_mad_i64_i32 v[118:119], s[2:3], v126, s45, v[116:117]
	v_lshlrev_b64 v[116:117], 5, v[126:127]
	v_lshl_add_u64 v[118:119], v[118:119], 0, v[160:161]
	v_mul_f32_e32 v108, v108, v114
	v_mul_f32_e32 v109, v109, v114
	v_mul_f32_e32 v108, 0xbfb8aa3b, v108
	v_mul_f32_e32 v109, 0xbfb8aa3b, v109
	v_exp_f32_e32 v108, v108
	v_exp_f32_e32 v109, v109
	v_mul_f32_e32 v110, v110, v114
	v_mul_f32_e32 v111, v111, v114
	v_mul_f32_e32 v110, 0xbfb8aa3b, v110
	v_pk_add_f32 v[108:109], v[108:109], 1.0 op_sel_hi:[1,0]
	v_mul_f32_e32 v111, 0xbfb8aa3b, v111
	v_div_scale_f32 v113, s[2:3], v109, v109, 1.0
	v_rcp_f32_e32 v115, v113
	v_exp_f32_e32 v110, v110
	v_exp_f32_e32 v111, v111
	v_fma_f32 v120, -v113, v115, 1.0
	v_fmac_f32_e32 v115, v120, v115
	v_div_scale_f32 v120, vcc, 1.0, v109, 1.0
	v_mul_f32_e32 v121, v120, v115
	v_fma_f32 v122, -v113, v121, v120
	v_fmac_f32_e32 v121, v122, v115
	v_fma_f32 v113, -v113, v121, v120
	v_div_fmas_f32 v113, v113, v115, v121
	v_div_fixup_f32 v109, v113, v109, 1.0
	v_div_scale_f32 v113, s[2:3], v108, v108, 1.0
	v_rcp_f32_e32 v115, v113
	v_pk_add_f32 v[110:111], v[110:111], 1.0 op_sel_hi:[1,0]
	v_fma_f32 v120, -v113, v115, 1.0
	v_fmac_f32_e32 v115, v120, v115
	v_div_scale_f32 v120, vcc, 1.0, v108, 1.0
	v_mul_f32_e32 v121, v120, v115
	v_fma_f32 v122, -v113, v121, v120
	v_fmac_f32_e32 v121, v122, v115
	v_fma_f32 v113, -v113, v121, v120
	v_div_fmas_f32 v113, v113, v115, v121
	v_div_fixup_f32 v108, v113, v108, 1.0
	v_div_scale_f32 v113, s[2:3], v111, v111, 1.0
	v_rcp_f32_e32 v115, v113
	s_nop 0
	v_fma_f32 v120, -v113, v115, 1.0
	v_fmac_f32_e32 v115, v120, v115
	v_div_scale_f32 v120, vcc, 1.0, v111, 1.0
	v_mul_f32_e32 v121, v120, v115
	v_fma_f32 v122, -v113, v121, v120
	v_fmac_f32_e32 v121, v122, v115
	v_fma_f32 v113, -v113, v121, v120
	v_div_fmas_f32 v113, v113, v115, v121
	v_div_fixup_f32 v111, v113, v111, 1.0
	v_div_scale_f32 v113, s[2:3], v110, v110, 1.0
	v_rcp_f32_e32 v115, v113
	s_nop 0
	v_fma_f32 v120, -v113, v115, 1.0
	v_fmac_f32_e32 v115, v120, v115
	v_div_scale_f32 v120, vcc, 1.0, v110, 1.0
	v_mul_f32_e32 v121, v120, v115
	v_fma_f32 v122, -v113, v121, v120
	v_fmac_f32_e32 v121, v122, v115
	v_fma_f32 v113, -v113, v121, v120
	v_div_fmas_f32 v113, v113, v115, v121
	v_div_fixup_f32 v110, v113, v110, 1.0
	global_store_dwordx4 v[118:119], v[108:111], off
	s_and_saveexec_b64 s[2:3], s[4:5]
	s_xor_b64 s[2:3], exec, s[2:3]
	s_cbranch_execz .LBB0_1301
; template <bool SWAP> DI void inproj_tile(const Params& p, int layer, int tm, int tn, bf16_t* smem) {
;     ...
;         } else {
; #pragma unroll
;           for (int r = 0; r < 4; ++r) { const int h = (quad - 2) * 4 + r; const float xx = acc[i][1][r] * rs + p.b_forget[layer * 8 + h]; lf[h] = fminf(xx, 0.f) - log1pf(__expf(-fabsf(xx))); }
;         }
	v_readlane_b32 s52, v241, 8
	v_readlane_b32 s60, v241, 16
	v_readlane_b32 s61, v241, 17
	v_lshl_add_u64 v[108:109], s[8:9], 0, v[116:117]
	v_lshl_add_u64 v[108:109], v[108:109], 0, v[160:161]
	v_readlane_b32 s53, v241, 9
	v_readlane_b32 s54, v241, 10
	v_readlane_b32 s55, v241, 11
	global_load_dword v110, v160, s[60:61]
	v_readlane_b32 s56, v241, 12
	v_readlane_b32 s57, v241, 13
	v_readlane_b32 s58, v241, 14
	v_readlane_b32 s59, v241, 15
	v_readlane_b32 s62, v241, 18
	v_readlane_b32 s63, v241, 19
	v_readlane_b32 s64, v241, 20
	v_readlane_b32 s65, v241, 21
	v_readlane_b32 s66, v241, 22
	v_readlane_b32 s67, v241, 23
	s_waitcnt vmcnt(0)
	v_fmac_f32_e32 v110, v104, v114
	v_min_f32_e32 v113, 0, v110
	v_mul_f32_e64 v110, |v110|, s46
	v_exp_f32_e32 v115, v110
	s_nop 0
	v_add_f32_e32 v118, 1.0, v115
	v_add_f32_e32 v110, -1.0, v118
	v_sub_f32_e32 v111, v110, v118
	v_add_f32_e32 v111, 1.0, v111
	v_sub_f32_e32 v110, v115, v110
	v_add_f32_e32 v119, v110, v111
	v_frexp_mant_f32_e32 v110, v118
	v_cmp_gt_f32_e32 vcc, s47, v110
	v_cvt_f64_f32_e32 v[110:111], v118
	v_frexp_exp_i32_f64_e32 v110, v[110:111]
	v_subbrev_co_u32_e32 v110, vcc, 0, v110, vcc
	v_sub_u32_e32 v111, 0, v110
	v_ldexp_f32 v118, v118, v111
	v_ldexp_f32 v111, v119, v111
	v_add_f32_e32 v119, -1.0, v118
	v_add_f32_e32 v120, 1.0, v119
	v_sub_f32_e32 v120, v118, v120
	v_add_f32_e32 v120, v111, v120
	v_add_f32_e32 v121, v119, v120
	v_sub_f32_e32 v119, v121, v119
	v_sub_f32_e32 v119, v120, v119
	v_add_f32_e32 v120, 1.0, v118
	v_add_f32_e32 v122, -1.0, v120
	v_sub_f32_e32 v118, v118, v122
	v_add_f32_e32 v111, v111, v118
	v_add_f32_e32 v118, v120, v111
	v_sub_f32_e32 v120, v118, v120
	v_sub_f32_e32 v111, v111, v120
	v_rcp_f32_e32 v120, v118
	v_cvt_f32_i32_e32 v110, v110
	v_cmp_neq_f32_e32 vcc, s49, v115
	v_mul_f32_e32 v122, v121, v120
	v_mul_f32_e32 v123, v118, v122
	v_fma_f32 v124, v122, v118, -v123
	v_fmac_f32_e32 v124, v122, v111
	v_add_f32_e32 v125, v123, v124
	v_sub_f32_e32 v126, v121, v125
	v_sub_f32_e32 v121, v121, v126
	v_sub_f32_e32 v123, v125, v123
	v_sub_f32_e32 v121, v121, v125
	v_add_f32_e32 v119, v119, v121
	v_sub_f32_e32 v121, v123, v124
	v_add_f32_e32 v119, v121, v119
	v_add_f32_e32 v121, v126, v119
	v_mul_f32_e32 v123, v120, v121
	v_mul_f32_e32 v124, v118, v123
	v_fma_f32 v118, v123, v118, -v124
	v_fmac_f32_e32 v118, v123, v111
	v_sub_f32_e32 v111, v126, v121
	v_add_f32_e32 v111, v119, v111
	v_add_f32_e32 v119, v124, v118
	v_sub_f32_e32 v125, v121, v119
	v_sub_f32_e32 v121, v121, v125
	v_sub_f32_e32 v124, v119, v124
	v_sub_f32_e32 v119, v121, v119
	v_add_f32_e32 v111, v111, v119
	v_sub_f32_e32 v118, v124, v118
	v_add_f32_e32 v111, v118, v111
	v_add_f32_e32 v118, v122, v123
	v_add_f32_e32 v111, v125, v111
	v_sub_f32_e32 v119, v118, v122
	v_mul_f32_e32 v111, v120, v111
	v_sub_f32_e32 v119, v123, v119
	v_add_f32_e32 v111, v119, v111
	v_mul_f32_e32 v122, 0x3f317218, v110
	v_add_f32_e32 v119, v118, v111
	v_fma_f32 v123, v110, s48, -v122
	v_mul_f32_e32 v120, v119, v119
	v_fmac_f32_e32 v123, 0xb102e308, v110
	v_sub_f32_e32 v110, v119, v118
	v_fmamk_f32 v121, v120, 0x3e9b6dac, v171
	v_sub_f32_e32 v110, v111, v110
	v_add_f32_e32 v111, v122, v123
	v_fmaak_f32 v121, v120, v121, 0x3f2aaada
	v_sub_f32_e32 v118, v111, v122
	v_ldexp_f32 v122, v119, 1
	v_mul_f32_e32 v119, v119, v120
	v_mul_f32_e32 v119, v119, v121
	v_add_f32_e32 v120, v122, v119
	v_sub_f32_e32 v121, v120, v122
	v_ldexp_f32 v110, v110, 1
	v_sub_f32_e32 v119, v119, v121
	v_add_f32_e32 v110, v110, v119
	v_add_f32_e32 v119, v120, v110
	v_sub_f32_e32 v120, v119, v120
	v_sub_f32_e32 v110, v110, v120
	v_add_f32_e32 v120, v111, v119
	v_sub_f32_e32 v121, v120, v111
	v_sub_f32_e32 v122, v120, v121
	v_sub_f32_e32 v118, v123, v118
	v_sub_f32_e32 v111, v111, v122
	v_sub_f32_e32 v119, v119, v121
	v_add_f32_e32 v111, v119, v111
	v_add_f32_e32 v119, v118, v110
	v_sub_f32_e32 v121, v119, v118
	v_sub_f32_e32 v122, v119, v121
	v_sub_f32_e32 v118, v118, v122
	v_sub_f32_e32 v110, v110, v121
	v_add_f32_e32 v111, v119, v111
	v_add_f32_e32 v110, v110, v118
	v_add_f32_e32 v118, v120, v111
	v_sub_f32_e32 v119, v118, v120
	v_sub_f32_e32 v111, v111, v119
	v_add_f32_e32 v110, v110, v111
	v_add_f32_e32 v110, v118, v110
	v_cndmask_b32_e32 v110, v178, v110, vcc
	v_cmp_ngt_f32_e32 vcc, -1.0, v115
	s_nop 1
	v_cndmask_b32_e32 v110, v179, v110, vcc
	v_cmp_neq_f32_e32 vcc, -1.0, v115
	s_nop 1
	v_cndmask_b32_e32 v110, v180, v110, vcc
	v_cmp_lt_f32_e64 vcc, |v115|, s50
	s_nop 1
	v_cndmask_b32_e32 v110, v110, v115, vcc
	v_sub_f32_e32 v110, v113, v110
	global_store_dword v[108:109], v110, off offset:-32
	global_load_dword v111, v160, s[60:61] offset:4
	s_waitcnt vmcnt(0)
; template <bool SWAP> DI void inproj_tile(const Params& p, int layer, int tm, int tn, bf16_t* smem) {
;     ...
;         } else {
; #pragma unroll
;           for (int r = 0; r < 4; ++r) { const int h = (quad - 2) * 4 + r; const float xx = acc[i][1][r] * rs + p.b_forget[layer * 8 + h]; lf[h] = fminf(xx, 0.f) - log1pf(__expf(-fabsf(xx))); }
;         }
	v_fmac_f32_e32 v111, v105, v114
	v_min_f32_e32 v110, 0, v111
	v_mul_f32_e64 v111, |v111|, s46
	v_exp_f32_e32 v111, v111
	s_nop 0
	v_add_f32_e32 v113, 1.0, v111
	v_add_f32_e32 v115, -1.0, v113
	v_sub_f32_e32 v118, v115, v113
	v_add_f32_e32 v118, 1.0, v118
	v_sub_f32_e32 v115, v111, v115
	v_add_f32_e32 v115, v115, v118
	v_frexp_mant_f32_e32 v118, v113
	v_cmp_gt_f32_e32 vcc, s47, v118
	v_cvt_f64_f32_e32 v[118:119], v113
	v_frexp_exp_i32_f64_e32 v118, v[118:119]
	v_subbrev_co_u32_e32 v118, vcc, 0, v118, vcc
	v_sub_u32_e32 v119, 0, v118
	v_ldexp_f32 v113, v113, v119
	v_ldexp_f32 v115, v115, v119
	v_add_f32_e32 v119, -1.0, v113
	v_add_f32_e32 v120, 1.0, v119
	v_sub_f32_e32 v120, v113, v120
	v_add_f32_e32 v120, v115, v120
	v_add_f32_e32 v121, v119, v120
	v_sub_f32_e32 v119, v121, v119
	v_sub_f32_e32 v119, v120, v119
	v_add_f32_e32 v120, 1.0, v113
	v_add_f32_e32 v122, -1.0, v120
	v_sub_f32_e32 v113, v113, v122
	v_add_f32_e32 v113, v115, v113
	v_add_f32_e32 v115, v120, v113
	v_sub_f32_e32 v120, v115, v120
	v_sub_f32_e32 v113, v113, v120
	v_rcp_f32_e32 v120, v115
	v_cvt_f32_i32_e32 v118, v118
	v_cmp_neq_f32_e32 vcc, s49, v111
	v_mul_f32_e32 v122, v121, v120
	v_mul_f32_e32 v123, v115, v122
	v_fma_f32 v124, v122, v115, -v123
	v_fmac_f32_e32 v124, v122, v113
	v_add_f32_e32 v125, v123, v124
	v_sub_f32_e32 v126, v121, v125
	v_sub_f32_e32 v121, v121, v126
	v_sub_f32_e32 v123, v125, v123
	v_sub_f32_e32 v121, v121, v125
	v_add_f32_e32 v119, v119, v121
	v_sub_f32_e32 v121, v123, v124
	v_add_f32_e32 v119, v121, v119
	v_add_f32_e32 v121, v126, v119
	v_mul_f32_e32 v123, v120, v121
	v_mul_f32_e32 v124, v115, v123
	v_fma_f32 v115, v123, v115, -v124
	v_fmac_f32_e32 v115, v123, v113
	v_sub_f32_e32 v113, v126, v121
	v_add_f32_e32 v113, v119, v113
	v_add_f32_e32 v119, v124, v115
	v_sub_f32_e32 v125, v121, v119
	v_sub_f32_e32 v121, v121, v125
	v_sub_f32_e32 v124, v119, v124
	v_sub_f32_e32 v119, v121, v119
	v_add_f32_e32 v113, v113, v119
	v_sub_f32_e32 v115, v124, v115
	v_add_f32_e32 v113, v115, v113
	v_add_f32_e32 v115, v122, v123
	v_add_f32_e32 v113, v125, v113
	v_sub_f32_e32 v119, v115, v122
	v_mul_f32_e32 v113, v120, v113
	v_sub_f32_e32 v119, v123, v119
	v_add_f32_e32 v113, v119, v113
	v_mul_f32_e32 v122, 0x3f317218, v118
	v_add_f32_e32 v119, v115, v113
	v_fma_f32 v123, v118, s48, -v122
	v_mul_f32_e32 v120, v119, v119
	v_fmac_f32_e32 v123, 0xb102e308, v118
	v_sub_f32_e32 v115, v119, v115
	v_fmamk_f32 v121, v120, 0x3e9b6dac, v171
	v_sub_f32_e32 v113, v113, v115
	v_add_f32_e32 v115, v122, v123
	v_fmaak_f32 v121, v120, v121, 0x3f2aaada
	v_sub_f32_e32 v118, v115, v122
	v_ldexp_f32 v122, v119, 1
	v_mul_f32_e32 v119, v119, v120
	v_mul_f32_e32 v119, v119, v121
	v_add_f32_e32 v120, v122, v119
	v_sub_f32_e32 v121, v120, v122
	v_ldexp_f32 v113, v113, 1
	v_sub_f32_e32 v119, v119, v121
	v_add_f32_e32 v113, v113, v119
	v_add_f32_e32 v119, v120, v113
	v_sub_f32_e32 v120, v119, v120
	v_sub_f32_e32 v113, v113, v120
	v_add_f32_e32 v120, v115, v119
	v_sub_f32_e32 v121, v120, v115
	v_sub_f32_e32 v122, v120, v121
	v_sub_f32_e32 v118, v123, v118
	v_sub_f32_e32 v115, v115, v122
	v_sub_f32_e32 v119, v119, v121
	v_add_f32_e32 v115, v119, v115
	v_add_f32_e32 v119, v118, v113
	v_sub_f32_e32 v121, v119, v118
	v_sub_f32_e32 v122, v119, v121
	v_sub_f32_e32 v118, v118, v122
	v_sub_f32_e32 v113, v113, v121
	v_add_f32_e32 v115, v119, v115
	v_add_f32_e32 v113, v113, v118
	v_add_f32_e32 v118, v120, v115
	v_sub_f32_e32 v119, v118, v120
	v_sub_f32_e32 v115, v115, v119
	v_add_f32_e32 v113, v113, v115
	v_add_f32_e32 v113, v118, v113
	v_cndmask_b32_e32 v113, v178, v113, vcc
	v_cmp_ngt_f32_e32 vcc, -1.0, v111
	s_nop 1
	v_cndmask_b32_e32 v113, v179, v113, vcc
	v_cmp_neq_f32_e32 vcc, -1.0, v111
	s_nop 1
	v_cndmask_b32_e32 v113, v180, v113, vcc
	v_cmp_lt_f32_e64 vcc, |v111|, s50
	s_nop 1
	v_cndmask_b32_e32 v111, v113, v111, vcc
	v_sub_f32_e32 v110, v110, v111
	global_store_dword v[108:109], v110, off offset:-28
	global_load_dword v111, v160, s[60:61] offset:8
	s_waitcnt vmcnt(0)
	v_fmac_f32_e32 v111, v106, v114
	v_min_f32_e32 v110, 0, v111
	v_mul_f32_e64 v111, |v111|, s46
	v_exp_f32_e32 v111, v111
	s_nop 0
	v_add_f32_e32 v113, 1.0, v111
	v_add_f32_e32 v115, -1.0, v113
	v_sub_f32_e32 v118, v115, v113
	v_add_f32_e32 v118, 1.0, v118
	v_sub_f32_e32 v115, v111, v115
	v_add_f32_e32 v115, v115, v118
	v_frexp_mant_f32_e32 v118, v113
	v_cmp_gt_f32_e32 vcc, s47, v118
	v_cvt_f64_f32_e32 v[118:119], v113
	v_frexp_exp_i32_f64_e32 v118, v[118:119]
	v_subbrev_co_u32_e32 v118, vcc, 0, v118, vcc
	v_sub_u32_e32 v119, 0, v118
	v_ldexp_f32 v113, v113, v119
	v_ldexp_f32 v115, v115, v119
	v_add_f32_e32 v119, -1.0, v113
	v_add_f32_e32 v120, 1.0, v119
	v_sub_f32_e32 v120, v113, v120
	v_add_f32_e32 v120, v115, v120
	v_add_f32_e32 v121, v119, v120
	v_sub_f32_e32 v119, v121, v119
	v_sub_f32_e32 v119, v120, v119
	v_add_f32_e32 v120, 1.0, v113
	v_add_f32_e32 v122, -1.0, v120
	v_sub_f32_e32 v113, v113, v122
	v_add_f32_e32 v113, v115, v113
	v_add_f32_e32 v115, v120, v113
	v_sub_f32_e32 v120, v115, v120
	v_sub_f32_e32 v113, v113, v120
	v_rcp_f32_e32 v120, v115
	v_cvt_f32_i32_e32 v118, v118
	v_cmp_neq_f32_e32 vcc, s49, v111
	v_mul_f32_e32 v122, v121, v120
	v_mul_f32_e32 v123, v115, v122
	v_fma_f32 v124, v122, v115, -v123
	v_fmac_f32_e32 v124, v122, v113
	v_add_f32_e32 v125, v123, v124
	v_sub_f32_e32 v126, v121, v125
	v_sub_f32_e32 v121, v121, v126
	v_sub_f32_e32 v123, v125, v123
	v_sub_f32_e32 v121, v121, v125
	v_add_f32_e32 v119, v119, v121
	v_sub_f32_e32 v121, v123, v124
	v_add_f32_e32 v119, v121, v119
	v_add_f32_e32 v121, v126, v119
	v_mul_f32_e32 v123, v120, v121
	v_mul_f32_e32 v124, v115, v123
	v_fma_f32 v115, v123, v115, -v124
; template <bool SWAP> DI void inproj_tile(const Params& p, int layer, int tm, int tn, bf16_t* smem) {
;     ...
;         } else {
; #pragma unroll
;           for (int r = 0; r < 4; ++r) { const int h = (quad - 2) * 4 + r; const float xx = acc[i][1][r] * rs + p.b_forget[layer * 8 + h]; lf[h] = fminf(xx, 0.f) - log1pf(__expf(-fabsf(xx))); }
;         }
	v_fmac_f32_e32 v115, v123, v113
	v_sub_f32_e32 v113, v126, v121
	v_add_f32_e32 v113, v119, v113
	v_add_f32_e32 v119, v124, v115
	v_sub_f32_e32 v125, v121, v119
	v_sub_f32_e32 v121, v121, v125
	v_sub_f32_e32 v124, v119, v124
	v_sub_f32_e32 v119, v121, v119
	v_add_f32_e32 v113, v113, v119
	v_sub_f32_e32 v115, v124, v115
	v_add_f32_e32 v113, v115, v113
	v_add_f32_e32 v115, v122, v123
	v_add_f32_e32 v113, v125, v113
	v_sub_f32_e32 v119, v115, v122
	v_mul_f32_e32 v113, v120, v113
	v_sub_f32_e32 v119, v123, v119
	v_add_f32_e32 v113, v119, v113
	v_mul_f32_e32 v122, 0x3f317218, v118
	v_add_f32_e32 v119, v115, v113
	v_fma_f32 v123, v118, s48, -v122
	v_mul_f32_e32 v120, v119, v119
	v_fmac_f32_e32 v123, 0xb102e308, v118
	v_sub_f32_e32 v115, v119, v115
	v_fmamk_f32 v121, v120, 0x3e9b6dac, v171
	v_sub_f32_e32 v113, v113, v115
	v_add_f32_e32 v115, v122, v123
	v_fmaak_f32 v121, v120, v121, 0x3f2aaada
	v_sub_f32_e32 v118, v115, v122
	v_ldexp_f32 v122, v119, 1
	v_mul_f32_e32 v119, v119, v120
	v_mul_f32_e32 v119, v119, v121
	v_add_f32_e32 v120, v122, v119
	v_sub_f32_e32 v121, v120, v122
	v_ldexp_f32 v113, v113, 1
	v_sub_f32_e32 v119, v119, v121
	v_add_f32_e32 v113, v113, v119
	v_add_f32_e32 v119, v120, v113
	v_sub_f32_e32 v120, v119, v120
	v_sub_f32_e32 v113, v113, v120
	v_add_f32_e32 v120, v115, v119
	v_sub_f32_e32 v121, v120, v115
	v_sub_f32_e32 v122, v120, v121
	v_sub_f32_e32 v118, v123, v118
	v_sub_f32_e32 v115, v115, v122
	v_sub_f32_e32 v119, v119, v121
	v_add_f32_e32 v115, v119, v115
	v_add_f32_e32 v119, v118, v113
	v_sub_f32_e32 v121, v119, v118
	v_sub_f32_e32 v122, v119, v121
	v_sub_f32_e32 v118, v118, v122
	v_sub_f32_e32 v113, v113, v121
	v_add_f32_e32 v115, v119, v115
	v_add_f32_e32 v113, v113, v118
	v_add_f32_e32 v118, v120, v115
	v_sub_f32_e32 v119, v118, v120
	v_sub_f32_e32 v115, v115, v119
	v_add_f32_e32 v113, v113, v115
	v_add_f32_e32 v113, v118, v113
	v_cndmask_b32_e32 v113, v178, v113, vcc
	v_cmp_ngt_f32_e32 vcc, -1.0, v111
	s_nop 1
	v_cndmask_b32_e32 v113, v179, v113, vcc
	v_cmp_neq_f32_e32 vcc, -1.0, v111
	s_nop 1
	v_cndmask_b32_e32 v113, v180, v113, vcc
	v_cmp_lt_f32_e64 vcc, |v111|, s50
	s_nop 1
	v_cndmask_b32_e32 v111, v113, v111, vcc
	v_sub_f32_e32 v110, v110, v111
	global_store_dword v[108:109], v110, off offset:-24
	global_load_dword v111, v160, s[60:61] offset:12
	s_waitcnt vmcnt(0)
	v_fmac_f32_e32 v111, v107, v114
	v_min_f32_e32 v110, 0, v111
	v_mul_f32_e64 v111, |v111|, s46
	v_exp_f32_e32 v111, v111
	s_nop 0
	v_add_f32_e32 v113, 1.0, v111
	v_add_f32_e32 v115, -1.0, v113
	v_sub_f32_e32 v118, v115, v113
	v_add_f32_e32 v118, 1.0, v118
	v_sub_f32_e32 v115, v111, v115
	v_add_f32_e32 v115, v115, v118
	v_frexp_mant_f32_e32 v118, v113
	v_cmp_gt_f32_e32 vcc, s47, v118
	v_cvt_f64_f32_e32 v[118:119], v113
	v_frexp_exp_i32_f64_e32 v118, v[118:119]
	v_subbrev_co_u32_e32 v118, vcc, 0, v118, vcc
	v_sub_u32_e32 v119, 0, v118
	v_ldexp_f32 v113, v113, v119
	v_ldexp_f32 v115, v115, v119
	v_add_f32_e32 v119, -1.0, v113
	v_add_f32_e32 v120, 1.0, v119
	v_sub_f32_e32 v120, v113, v120
	v_add_f32_e32 v120, v115, v120
	v_add_f32_e32 v121, v119, v120
	v_sub_f32_e32 v119, v121, v119
	v_sub_f32_e32 v119, v120, v119
	v_add_f32_e32 v120, 1.0, v113
	v_add_f32_e32 v122, -1.0, v120
	v_sub_f32_e32 v113, v113, v122
	v_add_f32_e32 v113, v115, v113
	v_add_f32_e32 v115, v120, v113
	v_sub_f32_e32 v120, v115, v120
	v_sub_f32_e32 v113, v113, v120
	v_rcp_f32_e32 v120, v115
	v_cvt_f32_i32_e32 v118, v118
	v_cmp_neq_f32_e32 vcc, s49, v111
	v_mul_f32_e32 v122, v121, v120
	v_mul_f32_e32 v123, v115, v122
	v_fma_f32 v124, v122, v115, -v123
	v_fmac_f32_e32 v124, v122, v113
	v_add_f32_e32 v125, v123, v124
	v_sub_f32_e32 v126, v121, v125
	v_sub_f32_e32 v121, v121, v126
	v_sub_f32_e32 v123, v125, v123
	v_sub_f32_e32 v121, v121, v125
	v_add_f32_e32 v119, v119, v121
	v_sub_f32_e32 v121, v123, v124
	v_add_f32_e32 v119, v121, v119
	v_add_f32_e32 v121, v126, v119
	v_mul_f32_e32 v123, v120, v121
	v_mul_f32_e32 v124, v115, v123
	v_fma_f32 v115, v123, v115, -v124
	v_fmac_f32_e32 v115, v123, v113
	v_sub_f32_e32 v113, v126, v121
	v_add_f32_e32 v113, v119, v113
	v_add_f32_e32 v119, v124, v115
	v_sub_f32_e32 v125, v121, v119
	v_sub_f32_e32 v121, v121, v125
	v_sub_f32_e32 v124, v119, v124
	v_sub_f32_e32 v119, v121, v119
	v_add_f32_e32 v113, v113, v119
	v_sub_f32_e32 v115, v124, v115
	v_add_f32_e32 v113, v115, v113
	v_add_f32_e32 v115, v122, v123
	v_add_f32_e32 v113, v125, v113
	v_sub_f32_e32 v119, v115, v122
	v_mul_f32_e32 v113, v120, v113
	v_sub_f32_e32 v119, v123, v119
	v_add_f32_e32 v113, v119, v113
	v_mul_f32_e32 v122, 0x3f317218, v118
	v_add_f32_e32 v119, v115, v113
	v_fma_f32 v123, v118, s48, -v122
	v_mul_f32_e32 v120, v119, v119
	v_fmac_f32_e32 v123, 0xb102e308, v118
	v_sub_f32_e32 v115, v119, v115
	v_fmamk_f32 v121, v120, 0x3e9b6dac, v171
	v_sub_f32_e32 v113, v113, v115
	v_add_f32_e32 v115, v122, v123
	v_fmaak_f32 v121, v120, v121, 0x3f2aaada
	v_sub_f32_e32 v118, v115, v122
	v_ldexp_f32 v122, v119, 1
	v_mul_f32_e32 v119, v119, v120
	v_mul_f32_e32 v119, v119, v121
	v_add_f32_e32 v120, v122, v119
	v_sub_f32_e32 v121, v120, v122
	v_ldexp_f32 v113, v113, 1
	v_sub_f32_e32 v119, v119, v121
	v_add_f32_e32 v113, v113, v119
	v_add_f32_e32 v119, v120, v113
	v_sub_f32_e32 v120, v119, v120
	v_sub_f32_e32 v113, v113, v120
	v_add_f32_e32 v120, v115, v119
	v_sub_f32_e32 v121, v120, v115
	v_sub_f32_e32 v122, v120, v121
	v_sub_f32_e32 v118, v123, v118
	v_sub_f32_e32 v115, v115, v122
	v_sub_f32_e32 v119, v119, v121
	v_add_f32_e32 v115, v119, v115
	v_add_f32_e32 v119, v118, v113
	v_sub_f32_e32 v121, v119, v118
	v_sub_f32_e32 v122, v119, v121
	v_sub_f32_e32 v118, v118, v122
	v_sub_f32_e32 v113, v113, v121
	v_add_f32_e32 v115, v119, v115
	v_add_f32_e32 v113, v113, v118
	v_add_f32_e32 v118, v120, v115
	v_sub_f32_e32 v119, v118, v120
	v_sub_f32_e32 v115, v115, v119
	v_add_f32_e32 v113, v113, v115
	v_add_f32_e32 v113, v118, v113
	v_cndmask_b32_e32 v113, v178, v113, vcc
	v_cmp_ngt_f32_e32 vcc, -1.0, v111
	s_nop 1
	v_cndmask_b32_e32 v113, v179, v113, vcc
	v_cmp_neq_f32_e32 vcc, -1.0, v111
	s_nop 1
	v_cndmask_b32_e32 v113, v180, v113, vcc
	v_cmp_lt_f32_e64 vcc, |v111|, s50
	s_nop 1
	v_cndmask_b32_e32 v111, v113, v111, vcc
	v_sub_f32_e32 v110, v110, v111
	global_store_dword v[108:109], v110, off offset:-20

; DI unsigned pk2(float lo, float hi) { f32x2 v = {lo, hi}; return __builtin_bit_cast(unsigned, __builtin_convertvector(v, bfx2)); }
; DI float sigmoidf_(float x) { return 1.f / (1.f + __expf(-x)); }
; template <bool SWAP> DI void inproj_tile(const Params& p, int layer, int tm, int tn, bf16_t* smem) {
;     ...
;       for (int i = 0; i < 8; ++i) {
;         const int t = trow0 + i * 16 + l15; const float rs = rstd_from16(ssq + (size_t)t * 16, 1.f / 1024.f);
;         float* gt = (float*)(p.ws + O_GATES) + (size_t)t * 24; float* lf = (float*)(p.ws + O_LOGF) + (size_t)t * 8;
; #pragma unroll
;         for (int r = 0; r < 4; ++r) gt[quad * 4 + r] = sigmoidf_(acc[i][0][r] * rs);
;     ...
;         const float* rp = (const float*)(p.ws + O_ROPE16) + (size_t)t * 32 + quad * 8; float o1[4], o2[4];
; #pragma unroll
;         for (int r = 0; r < 4; ++r) { const float cs = rp[2 * r], sn = rp[2 * r + 1], x1 = acc[i][2][r] * rs, x2 = acc[i][3][r] * rs; o1[r] = x1 * cs - x2 * sn; o2[r] = x2 * cs + x1 * sn; }
;         bf16_t* kp = (bf16_t*)(p.ws + O_MLAKPE) + (size_t)t * 32 + quad * 4;
;         *(u32x2*)kp = (u32x2){pk2(o1[0], o1[1]), pk2(o1[2], o1[3])}; *(u32x2*)(kp + 16) = (u32x2){pk2(o2[0], o2[1]), pk2(o2[2], o2[3])};
.LBB0_1303:
	s_or_b64 exec, exec, s[2:3]
	s_nop 0
	v_lshlrev_b32_e32 v104, 3, v144
	v_lshl_add_u64 v[106:107], v[116:117], 2, s[10:11]
	v_lshlrev_b32_e32 v104, 2, v104
	v_mov_b32_e32 v105, v161
	v_lshl_add_u64 v[110:111], v[106:107], 0, v[104:105]
	global_load_dwordx4 v[106:109], v[110:111], off offset:16
	global_load_dwordx4 v[118:121], v[110:111], off
	v_pk_mul_f32 v[96:97], v[96:97], v[114:115] op_sel_hi:[1,0]
	v_pk_mul_f32 v[100:101], v[100:101], v[114:115] op_sel_hi:[1,0]
	v_pk_mul_f32 v[98:99], v[98:99], v[114:115] op_sel_hi:[1,0]
	v_readlane_b32 s2, v240, 32
	v_readlane_b32 s3, v240, 33
	v_mov_b32_e32 v113, v161
	s_waitcnt vmcnt(0)
	v_mov_b32_e32 v111, v120
	v_mov_b32_e32 v120, v119
	v_mov_b32_e32 v110, v118
	v_pk_mul_f32 v[118:119], v[96:97], v[120:121]
	s_nop 0
	v_pk_fma_f32 v[118:119], v[100:101], v[110:111], v[118:119] neg_lo:[0,0,1] neg_hi:[0,0,1]
	v_pk_mul_f32 v[100:101], v[100:101], v[120:121]
	s_nop 0
	v_pk_fma_f32 v[96:97], v[96:97], v[110:111], v[100:101]
	v_pk_mul_f32 v[100:101], v[102:103], v[114:115] op_sel_hi:[1,0]
	v_mov_b32_e32 v103, v108
	v_mov_b32_e32 v108, v107
	v_mov_b32_e32 v102, v106
	v_pk_mul_f32 v[106:107], v[98:99], v[108:109]
	v_or_b32_e32 v110, 32, v128
	v_pk_fma_f32 v[106:107], v[100:101], v[102:103], v[106:107] neg_lo:[0,0,1] neg_hi:[0,0,1]
	v_pk_mul_f32 v[100:101], v[100:101], v[108:109]
	v_cvt_pk_bf16_f32 v96, v96, v97
	v_pk_fma_f32 v[98:99], v[98:99], v[102:103], v[100:101]
	v_lshl_add_u64 v[100:101], v[116:117], 1, s[2:3]
	v_lshl_add_u64 v[100:101], v[100:101], 0, v[112:113]
	v_cvt_pk_bf16_f32 v97, v98, v99
	v_ashrrev_i32_e32 v111, 31, v110
	v_cvt_pk_bf16_f32 v102, v118, v119
	v_cvt_pk_bf16_f32 v103, v106, v107
	global_store_dwordx2 v[100:101], v[96:97], off offset:32
	v_lshlrev_b64 v[96:97], 6, v[110:111]
	global_store_dwordx2 v[100:101], v[102:103], off
	v_lshl_add_u64 v[114:115], s[6:7], 0, v[96:97]
	v_bfe_u32 v244, v114, 6, 8
	v_lshlrev_b32_e32 v244, 3, v244
	v_add_u32_e32 v244, 0x24010, v244
	v_or_b32_e32 v246, 3, v114
	ds_read_b64 v[248:249], v244
	s_waitcnt lgkmcnt(0)
	v_cmp_ne_u32_e64 s[100:101], v248, v246
	s_nop 1
	s_and_saveexec_b64 s[98:99], s[100:101]
	s_cbranch_execz .LrcA1_10
	global_load_dwordx4 v[96:99], v[114:115], off offset:48
	global_load_dwordx4 v[100:103], v[114:115], off offset:32
	global_load_dwordx4 v[106:109], v[114:115], off offset:16
	s_nop 0
	global_load_dwordx4 v[114:117], v[114:115], off
	s_waitcnt vmcnt(2)
	v_add_f32_e32 v100, v100, v101
	v_add_f32_e32 v102, v102, v103
	s_waitcnt vmcnt(0)
	v_mov_b32_e32 v118, v115
	v_mov_b32_e32 v119, v116
	v_mov_b32_e32 v115, v117
	v_mov_b32_e32 v116, v107
	v_mov_b32_e32 v117, v108
	v_mov_b32_e32 v107, v109
	v_pk_add_f32 v[114:115], v[118:119], v[114:115]
	v_pk_add_f32 v[106:107], v[116:117], v[106:107]
	v_pk_add_f32 v[114:115], v[114:115], v[114:115] op_sel:[0,1] op_sel_hi:[1,0]
	v_pk_add_f32 v[106:107], v[106:107], v[106:107] op_sel:[0,1] op_sel_hi:[1,0]
	v_mov_b32_e32 v115, v96
	v_mov_b32_e32 v107, v97
	v_mov_b32_e32 v101, v98
	v_mov_b32_e32 v103, v99
	v_pk_add_f32 v[96:97], v[114:115], v[106:107]
	v_pk_add_f32 v[98:99], v[100:101], v[102:103]
	s_nop 0
	v_pk_add_f32 v[96:97], v[96:97], v[98:99]
	v_add_f32_e32 v96, v96, v97
	v_fmamk_f32 v96, v96, 0x3a800000, v170
	v_cmp_gt_f32_e32 vcc, s43, v96
	v_mul_f32_e32 v97, 0x4b800000, v96
	v_cndmask_b32_e32 v96, v96, v97, vcc
	v_rsq_f32_e32 v96, v96
	v_mul_f32_e32 v97, 0x45800000, v96
	v_cndmask_b32_e32 v96, v96, v97, vcc
	s_nop 0
	v_mov_b32_e32 v247, v96
	ds_write_b64 v244, v[246:247]
.LrcA1_10:
	s_or_b64 exec, exec, s[98:99]
	s_waitcnt vmcnt(0)
	v_cndmask_b32_e64 v96, v249, v96, s[100:101]
	v_readlane_b32 s2, v240, 35
	v_readlane_b32 s3, v240, 36
	v_mov_b64_e32 v[98:99], s[2:3]
	v_mad_i64_i32 v[100:101], s[2:3], v110, s45, v[98:99]
	v_lshlrev_b64 v[98:99], 5, v[110:111]
	v_lshl_add_u64 v[100:101], v[100:101], 0, v[160:161]
	v_mul_f32_e32 v92, v92, v96
	v_mul_f32_e32 v93, v93, v96
	v_mul_f32_e32 v92, 0xbfb8aa3b, v92
	v_mul_f32_e32 v93, 0xbfb8aa3b, v93
	v_exp_f32_e32 v92, v92
	v_exp_f32_e32 v93, v93
	v_mul_f32_e32 v94, v94, v96
	v_mul_f32_e32 v95, v95, v96
	v_mul_f32_e32 v94, 0xbfb8aa3b, v94
	v_pk_add_f32 v[92:93], v[92:93], 1.0 op_sel_hi:[1,0]
	v_mul_f32_e32 v95, 0xbfb8aa3b, v95
	v_div_scale_f32 v97, s[2:3], v93, v93, 1.0
	v_rcp_f32_e32 v102, v97
	v_exp_f32_e32 v94, v94
	v_exp_f32_e32 v95, v95
	v_fma_f32 v103, -v97, v102, 1.0
	v_fmac_f32_e32 v102, v103, v102
	v_div_scale_f32 v103, vcc, 1.0, v93, 1.0
	v_mul_f32_e32 v105, v103, v102
	v_fma_f32 v106, -v97, v105, v103
	v_fmac_f32_e32 v105, v106, v102
	v_fma_f32 v97, -v97, v105, v103
	v_div_fmas_f32 v97, v97, v102, v105
	v_div_fixup_f32 v93, v97, v93, 1.0
	v_div_scale_f32 v97, s[2:3], v92, v92, 1.0
	v_rcp_f32_e32 v102, v97
	v_pk_add_f32 v[94:95], v[94:95], 1.0 op_sel_hi:[1,0]
	v_fma_f32 v103, -v97, v102, 1.0
	v_fmac_f32_e32 v102, v103, v102
	v_div_scale_f32 v103, vcc, 1.0, v92, 1.0
	v_mul_f32_e32 v105, v103, v102
	v_fma_f32 v106, -v97, v105, v103
	v_fmac_f32_e32 v105, v106, v102
	v_fma_f32 v97, -v97, v105, v103
	v_div_fmas_f32 v97, v97, v102, v105
	v_div_fixup_f32 v92, v97, v92, 1.0
	v_div_scale_f32 v97, s[2:3], v95, v95, 1.0
	v_rcp_f32_e32 v102, v97
	s_nop 0
	v_fma_f32 v103, -v97, v102, 1.0
	v_fmac_f32_e32 v102, v103, v102
	v_div_scale_f32 v103, vcc, 1.0, v95, 1.0
	v_mul_f32_e32 v105, v103, v102
	v_fma_f32 v106, -v97, v105, v103
	v_fmac_f32_e32 v105, v106, v102
	v_fma_f32 v97, -v97, v105, v103
	v_div_fmas_f32 v97, v97, v102, v105
	v_div_fixup_f32 v95, v97, v95, 1.0
	v_div_scale_f32 v97, s[2:3], v94, v94, 1.0
	v_rcp_f32_e32 v102, v97
	s_nop 0
	v_fma_f32 v103, -v97, v102, 1.0
	v_fmac_f32_e32 v102, v103, v102
	v_div_scale_f32 v103, vcc, 1.0, v94, 1.0
	v_mul_f32_e32 v105, v103, v102
	v_fma_f32 v106, -v97, v105, v103
	v_fmac_f32_e32 v105, v106, v102
	v_fma_f32 v97, -v97, v105, v103
	v_div_fmas_f32 v97, v97, v102, v105
	v_div_fixup_f32 v94, v97, v94, 1.0
	global_store_dwordx4 v[100:101], v[92:95], off
	s_and_saveexec_b64 s[2:3], s[4:5]
	s_xor_b64 s[2:3], exec, s[2:3]
	s_cbranch_execz .LBB0_1305
; template <bool SWAP> DI void inproj_tile(const Params& p, int layer, int tm, int tn, bf16_t* smem) {
;     ...
;         } else {
; #pragma unroll
;           for (int r = 0; r < 4; ++r) { const int h = (quad - 2) * 4 + r; const float xx = acc[i][1][r] * rs + p.b_forget[layer * 8 + h]; lf[h] = fminf(xx, 0.f) - log1pf(__expf(-fabsf(xx))); }
;         }
	v_readlane_b32 s52, v241, 8
	v_readlane_b32 s60, v241, 16
	v_readlane_b32 s61, v241, 17
	v_lshl_add_u64 v[92:93], s[8:9], 0, v[98:99]
	v_lshl_add_u64 v[92:93], v[92:93], 0, v[160:161]
	v_readlane_b32 s53, v241, 9
	v_readlane_b32 s54, v241, 10
	v_readlane_b32 s55, v241, 11
	global_load_dword v94, v160, s[60:61]
	v_readlane_b32 s56, v241, 12
	v_readlane_b32 s57, v241, 13
	v_readlane_b32 s58, v241, 14
	v_readlane_b32 s59, v241, 15
	v_readlane_b32 s62, v241, 18
	v_readlane_b32 s63, v241, 19
	v_readlane_b32 s64, v241, 20
	v_readlane_b32 s65, v241, 21
	v_readlane_b32 s66, v241, 22
	v_readlane_b32 s67, v241, 23
	s_waitcnt vmcnt(0)
	v_fmac_f32_e32 v94, v88, v96
	v_min_f32_e32 v97, 0, v94
	v_mul_f32_e64 v94, |v94|, s46
	v_exp_f32_e32 v100, v94
	s_nop 0
	v_add_f32_e32 v101, 1.0, v100
	v_add_f32_e32 v94, -1.0, v101
	v_sub_f32_e32 v95, v94, v101
	v_add_f32_e32 v95, 1.0, v95
	v_sub_f32_e32 v94, v100, v94
	v_add_f32_e32 v102, v94, v95
	v_frexp_mant_f32_e32 v94, v101
	v_cmp_gt_f32_e32 vcc, s47, v94
	v_cvt_f64_f32_e32 v[94:95], v101
	v_frexp_exp_i32_f64_e32 v94, v[94:95]
	v_subbrev_co_u32_e32 v94, vcc, 0, v94, vcc
	v_sub_u32_e32 v95, 0, v94
	v_ldexp_f32 v101, v101, v95
	v_ldexp_f32 v95, v102, v95
	v_add_f32_e32 v102, -1.0, v101
	v_add_f32_e32 v103, 1.0, v102
	v_sub_f32_e32 v103, v101, v103
	v_add_f32_e32 v103, v95, v103
	v_add_f32_e32 v105, v102, v103
	v_sub_f32_e32 v102, v105, v102
	v_sub_f32_e32 v102, v103, v102
	v_add_f32_e32 v103, 1.0, v101
	v_add_f32_e32 v106, -1.0, v103
	v_sub_f32_e32 v101, v101, v106
	v_add_f32_e32 v95, v95, v101
	v_add_f32_e32 v101, v103, v95
	v_sub_f32_e32 v103, v101, v103
	v_sub_f32_e32 v95, v95, v103
	v_rcp_f32_e32 v103, v101
	v_cvt_f32_i32_e32 v94, v94
	v_cmp_neq_f32_e32 vcc, s49, v100
	v_mul_f32_e32 v106, v105, v103
	v_mul_f32_e32 v107, v101, v106
	v_fma_f32 v108, v106, v101, -v107
	v_fmac_f32_e32 v108, v106, v95
	v_add_f32_e32 v109, v107, v108
	v_sub_f32_e32 v110, v105, v109
	v_sub_f32_e32 v105, v105, v110
	v_sub_f32_e32 v107, v109, v107
	v_sub_f32_e32 v105, v105, v109
	v_add_f32_e32 v102, v102, v105
	v_sub_f32_e32 v105, v107, v108
	v_add_f32_e32 v102, v105, v102
	v_add_f32_e32 v105, v110, v102
	v_mul_f32_e32 v107, v103, v105
	v_mul_f32_e32 v108, v101, v107
	v_fma_f32 v101, v107, v101, -v108
	v_fmac_f32_e32 v101, v107, v95
	v_sub_f32_e32 v95, v110, v105
	v_add_f32_e32 v95, v102, v95
	v_add_f32_e32 v102, v108, v101
	v_sub_f32_e32 v109, v105, v102
	v_sub_f32_e32 v105, v105, v109
	v_sub_f32_e32 v108, v102, v108
	v_sub_f32_e32 v102, v105, v102
	v_add_f32_e32 v95, v95, v102
	v_sub_f32_e32 v101, v108, v101
	v_add_f32_e32 v95, v101, v95
	v_add_f32_e32 v101, v106, v107
	v_add_f32_e32 v95, v109, v95
	v_sub_f32_e32 v102, v101, v106
	v_mul_f32_e32 v95, v103, v95
	v_sub_f32_e32 v102, v107, v102
	v_add_f32_e32 v95, v102, v95
	v_mul_f32_e32 v106, 0x3f317218, v94
	v_add_f32_e32 v102, v101, v95
	v_fma_f32 v107, v94, s48, -v106
	v_mul_f32_e32 v103, v102, v102
	v_fmac_f32_e32 v107, 0xb102e308, v94
	v_sub_f32_e32 v94, v102, v101
	v_fmamk_f32 v105, v103, 0x3e9b6dac, v171
	v_sub_f32_e32 v94, v95, v94
	v_add_f32_e32 v95, v106, v107
	v_fmaak_f32 v105, v103, v105, 0x3f2aaada
	v_sub_f32_e32 v101, v95, v106
	v_ldexp_f32 v106, v102, 1
	v_mul_f32_e32 v102, v102, v103
	v_mul_f32_e32 v102, v102, v105
	v_add_f32_e32 v103, v106, v102
	v_sub_f32_e32 v105, v103, v106
	v_ldexp_f32 v94, v94, 1
	v_sub_f32_e32 v102, v102, v105
	v_add_f32_e32 v94, v94, v102
	v_add_f32_e32 v102, v103, v94
	v_sub_f32_e32 v103, v102, v103
	v_sub_f32_e32 v94, v94, v103
	v_add_f32_e32 v103, v95, v102
	v_sub_f32_e32 v105, v103, v95
	v_sub_f32_e32 v106, v103, v105
	v_sub_f32_e32 v101, v107, v101
	v_sub_f32_e32 v95, v95, v106
	v_sub_f32_e32 v102, v102, v105
	v_add_f32_e32 v95, v102, v95
	v_add_f32_e32 v102, v101, v94
	v_sub_f32_e32 v105, v102, v101
	v_sub_f32_e32 v106, v102, v105
	v_sub_f32_e32 v101, v101, v106
	v_sub_f32_e32 v94, v94, v105
	v_add_f32_e32 v95, v102, v95
	v_add_f32_e32 v94, v94, v101
	v_add_f32_e32 v101, v103, v95
	v_sub_f32_e32 v102, v101, v103
	v_sub_f32_e32 v95, v95, v102
	v_add_f32_e32 v94, v94, v95
	v_add_f32_e32 v94, v101, v94
	v_cndmask_b32_e32 v94, v178, v94, vcc
	v_cmp_ngt_f32_e32 vcc, -1.0, v100
	s_nop 1
	v_cndmask_b32_e32 v94, v179, v94, vcc
	v_cmp_neq_f32_e32 vcc, -1.0, v100
	s_nop 1
	v_cndmask_b32_e32 v94, v180, v94, vcc
	v_cmp_lt_f32_e64 vcc, |v100|, s50
	s_nop 1
	v_cndmask_b32_e32 v94, v94, v100, vcc
	v_sub_f32_e32 v94, v97, v94
	global_store_dword v[92:93], v94, off offset:-32
	global_load_dword v95, v160, s[60:61] offset:4
	s_waitcnt vmcnt(0)
; template <bool SWAP> DI void inproj_tile(const Params& p, int layer, int tm, int tn, bf16_t* smem) {
;     ...
;         } else {
; #pragma unroll
;           for (int r = 0; r < 4; ++r) { const int h = (quad - 2) * 4 + r; const float xx = acc[i][1][r] * rs + p.b_forget[layer * 8 + h]; lf[h] = fminf(xx, 0.f) - log1pf(__expf(-fabsf(xx))); }
;         }
	v_fmac_f32_e32 v95, v89, v96
	v_min_f32_e32 v94, 0, v95
	v_mul_f32_e64 v95, |v95|, s46
	v_exp_f32_e32 v95, v95
	s_nop 0
	v_add_f32_e32 v97, 1.0, v95
	v_add_f32_e32 v100, -1.0, v97
	v_sub_f32_e32 v101, v100, v97
	v_add_f32_e32 v101, 1.0, v101
	v_sub_f32_e32 v100, v95, v100
	v_add_f32_e32 v102, v100, v101
	v_frexp_mant_f32_e32 v100, v97
	v_cmp_gt_f32_e32 vcc, s47, v100
	v_cvt_f64_f32_e32 v[100:101], v97
	v_frexp_exp_i32_f64_e32 v100, v[100:101]
	v_subbrev_co_u32_e32 v100, vcc, 0, v100, vcc
	v_sub_u32_e32 v101, 0, v100
	v_ldexp_f32 v97, v97, v101
	v_ldexp_f32 v101, v102, v101
	v_add_f32_e32 v102, -1.0, v97
	v_add_f32_e32 v103, 1.0, v102
	v_sub_f32_e32 v103, v97, v103
	v_add_f32_e32 v103, v101, v103
	v_add_f32_e32 v105, v102, v103
	v_sub_f32_e32 v102, v105, v102
	v_sub_f32_e32 v102, v103, v102
	v_add_f32_e32 v103, 1.0, v97
	v_add_f32_e32 v106, -1.0, v103
	v_sub_f32_e32 v97, v97, v106
	v_add_f32_e32 v97, v101, v97
	v_add_f32_e32 v101, v103, v97
	v_sub_f32_e32 v103, v101, v103
	v_sub_f32_e32 v97, v97, v103
	v_rcp_f32_e32 v103, v101
	v_cvt_f32_i32_e32 v100, v100
	v_cmp_neq_f32_e32 vcc, s49, v95
	v_mul_f32_e32 v106, v105, v103
	v_mul_f32_e32 v107, v101, v106
	v_fma_f32 v108, v106, v101, -v107
	v_fmac_f32_e32 v108, v106, v97
	v_add_f32_e32 v109, v107, v108
	v_sub_f32_e32 v110, v105, v109
	v_sub_f32_e32 v105, v105, v110
	v_sub_f32_e32 v107, v109, v107
	v_sub_f32_e32 v105, v105, v109
	v_add_f32_e32 v102, v102, v105
	v_sub_f32_e32 v105, v107, v108
	v_add_f32_e32 v102, v105, v102
	v_add_f32_e32 v105, v110, v102
	v_mul_f32_e32 v107, v103, v105
	v_mul_f32_e32 v108, v101, v107
	v_fma_f32 v101, v107, v101, -v108
	v_fmac_f32_e32 v101, v107, v97
	v_sub_f32_e32 v97, v110, v105
	v_add_f32_e32 v97, v102, v97
	v_add_f32_e32 v102, v108, v101
	v_sub_f32_e32 v109, v105, v102
	v_sub_f32_e32 v105, v105, v109
	v_sub_f32_e32 v108, v102, v108
	v_sub_f32_e32 v102, v105, v102
	v_add_f32_e32 v97, v97, v102
	v_sub_f32_e32 v101, v108, v101
	v_add_f32_e32 v97, v101, v97
	v_add_f32_e32 v101, v106, v107
	v_add_f32_e32 v97, v109, v97
	v_sub_f32_e32 v102, v101, v106
	v_mul_f32_e32 v97, v103, v97
	v_sub_f32_e32 v102, v107, v102
	v_add_f32_e32 v97, v102, v97
	v_mul_f32_e32 v106, 0x3f317218, v100
	v_add_f32_e32 v102, v101, v97
	v_fma_f32 v107, v100, s48, -v106
	v_mul_f32_e32 v103, v102, v102
	v_fmac_f32_e32 v107, 0xb102e308, v100
	v_sub_f32_e32 v100, v102, v101
	v_fmamk_f32 v105, v103, 0x3e9b6dac, v171
	v_sub_f32_e32 v97, v97, v100
	v_add_f32_e32 v100, v106, v107
	v_fmaak_f32 v105, v103, v105, 0x3f2aaada
	v_sub_f32_e32 v101, v100, v106
	v_ldexp_f32 v106, v102, 1
	v_mul_f32_e32 v102, v102, v103
	v_mul_f32_e32 v102, v102, v105
	v_add_f32_e32 v103, v106, v102
	v_sub_f32_e32 v105, v103, v106
	v_ldexp_f32 v97, v97, 1
	v_sub_f32_e32 v102, v102, v105
	v_add_f32_e32 v97, v97, v102
	v_add_f32_e32 v102, v103, v97
	v_sub_f32_e32 v103, v102, v103
	v_sub_f32_e32 v97, v97, v103
	v_add_f32_e32 v103, v100, v102
	v_sub_f32_e32 v105, v103, v100
	v_sub_f32_e32 v106, v103, v105
	v_sub_f32_e32 v101, v107, v101
	v_sub_f32_e32 v100, v100, v106
	v_sub_f32_e32 v102, v102, v105
	v_add_f32_e32 v100, v102, v100
	v_add_f32_e32 v102, v101, v97
	v_sub_f32_e32 v105, v102, v101
	v_sub_f32_e32 v106, v102, v105
	v_sub_f32_e32 v101, v101, v106
	v_sub_f32_e32 v97, v97, v105
	v_add_f32_e32 v100, v102, v100
	v_add_f32_e32 v97, v97, v101
	v_add_f32_e32 v101, v103, v100
	v_sub_f32_e32 v102, v101, v103
	v_sub_f32_e32 v100, v100, v102
	v_add_f32_e32 v97, v97, v100
	v_add_f32_e32 v97, v101, v97
	v_cndmask_b32_e32 v97, v178, v97, vcc
	v_cmp_ngt_f32_e32 vcc, -1.0, v95
	s_nop 1
	v_cndmask_b32_e32 v97, v179, v97, vcc
	v_cmp_neq_f32_e32 vcc, -1.0, v95
	s_nop 1
	v_cndmask_b32_e32 v97, v180, v97, vcc
	v_cmp_lt_f32_e64 vcc, |v95|, s50
	s_nop 1
	v_cndmask_b32_e32 v95, v97, v95, vcc
	v_sub_f32_e32 v94, v94, v95
	global_store_dword v[92:93], v94, off offset:-28
	global_load_dword v95, v160, s[60:61] offset:8
	s_waitcnt vmcnt(0)
	v_fmac_f32_e32 v95, v90, v96
	v_min_f32_e32 v94, 0, v95
	v_mul_f32_e64 v95, |v95|, s46
	v_exp_f32_e32 v95, v95
	s_nop 0
	v_add_f32_e32 v97, 1.0, v95
	v_add_f32_e32 v100, -1.0, v97
	v_sub_f32_e32 v101, v100, v97
	v_add_f32_e32 v101, 1.0, v101
	v_sub_f32_e32 v100, v95, v100
	v_add_f32_e32 v102, v100, v101
	v_frexp_mant_f32_e32 v100, v97
	v_cmp_gt_f32_e32 vcc, s47, v100
	v_cvt_f64_f32_e32 v[100:101], v97
	v_frexp_exp_i32_f64_e32 v100, v[100:101]
	v_subbrev_co_u32_e32 v100, vcc, 0, v100, vcc
	v_sub_u32_e32 v101, 0, v100
	v_ldexp_f32 v97, v97, v101
	v_ldexp_f32 v101, v102, v101
	v_add_f32_e32 v102, -1.0, v97
	v_add_f32_e32 v103, 1.0, v102
	v_sub_f32_e32 v103, v97, v103
	v_add_f32_e32 v103, v101, v103
	v_add_f32_e32 v105, v102, v103
	v_sub_f32_e32 v102, v105, v102
	v_sub_f32_e32 v102, v103, v102
	v_add_f32_e32 v103, 1.0, v97
	v_add_f32_e32 v106, -1.0, v103
	v_sub_f32_e32 v97, v97, v106
	v_add_f32_e32 v97, v101, v97
	v_add_f32_e32 v101, v103, v97
	v_sub_f32_e32 v103, v101, v103
	v_sub_f32_e32 v97, v97, v103
	v_rcp_f32_e32 v103, v101
	v_cvt_f32_i32_e32 v100, v100
	v_cmp_neq_f32_e32 vcc, s49, v95
	v_mul_f32_e32 v106, v105, v103
	v_mul_f32_e32 v107, v101, v106
	v_fma_f32 v108, v106, v101, -v107
	v_fmac_f32_e32 v108, v106, v97
	v_add_f32_e32 v109, v107, v108
	v_sub_f32_e32 v110, v105, v109
	v_sub_f32_e32 v105, v105, v110
	v_sub_f32_e32 v107, v109, v107
	v_sub_f32_e32 v105, v105, v109
	v_add_f32_e32 v102, v102, v105
	v_sub_f32_e32 v105, v107, v108
	v_add_f32_e32 v102, v105, v102
	v_add_f32_e32 v105, v110, v102
	v_mul_f32_e32 v107, v103, v105
	v_mul_f32_e32 v108, v101, v107
	v_fma_f32 v101, v107, v101, -v108
	v_fmac_f32_e32 v101, v107, v97
	v_sub_f32_e32 v97, v110, v105
	v_add_f32_e32 v97, v102, v97
	v_add_f32_e32 v102, v108, v101
; template <bool SWAP> DI void inproj_tile(const Params& p, int layer, int tm, int tn, bf16_t* smem) {
;     ...
;         } else {
; #pragma unroll
;           for (int r = 0; r < 4; ++r) { const int h = (quad - 2) * 4 + r; const float xx = acc[i][1][r] * rs + p.b_forget[layer * 8 + h]; lf[h] = fminf(xx, 0.f) - log1pf(__expf(-fabsf(xx))); }
;         }
	v_sub_f32_e32 v109, v105, v102
	v_sub_f32_e32 v105, v105, v109
	v_sub_f32_e32 v108, v102, v108
	v_sub_f32_e32 v102, v105, v102
	v_add_f32_e32 v97, v97, v102
	v_sub_f32_e32 v101, v108, v101
	v_add_f32_e32 v97, v101, v97
	v_add_f32_e32 v101, v106, v107
	v_add_f32_e32 v97, v109, v97
	v_sub_f32_e32 v102, v101, v106
	v_mul_f32_e32 v97, v103, v97
	v_sub_f32_e32 v102, v107, v102
	v_add_f32_e32 v97, v102, v97
	v_mul_f32_e32 v106, 0x3f317218, v100
	v_add_f32_e32 v102, v101, v97
	v_fma_f32 v107, v100, s48, -v106
	v_mul_f32_e32 v103, v102, v102
	v_fmac_f32_e32 v107, 0xb102e308, v100
	v_sub_f32_e32 v100, v102, v101
	v_fmamk_f32 v105, v103, 0x3e9b6dac, v171
	v_sub_f32_e32 v97, v97, v100
	v_add_f32_e32 v100, v106, v107
	v_fmaak_f32 v105, v103, v105, 0x3f2aaada
	v_sub_f32_e32 v101, v100, v106
	v_ldexp_f32 v106, v102, 1
	v_mul_f32_e32 v102, v102, v103
	v_mul_f32_e32 v102, v102, v105
	v_add_f32_e32 v103, v106, v102
	v_sub_f32_e32 v105, v103, v106
	v_ldexp_f32 v97, v97, 1
	v_sub_f32_e32 v102, v102, v105
	v_add_f32_e32 v97, v97, v102
	v_add_f32_e32 v102, v103, v97
	v_sub_f32_e32 v103, v102, v103
	v_sub_f32_e32 v97, v97, v103
	v_add_f32_e32 v103, v100, v102
	v_sub_f32_e32 v105, v103, v100
	v_sub_f32_e32 v106, v103, v105
	v_sub_f32_e32 v101, v107, v101
	v_sub_f32_e32 v100, v100, v106
	v_sub_f32_e32 v102, v102, v105
	v_add_f32_e32 v100, v102, v100
	v_add_f32_e32 v102, v101, v97
	v_sub_f32_e32 v105, v102, v101
	v_sub_f32_e32 v106, v102, v105
	v_sub_f32_e32 v101, v101, v106
	v_sub_f32_e32 v97, v97, v105
	v_add_f32_e32 v100, v102, v100
	v_add_f32_e32 v97, v97, v101
	v_add_f32_e32 v101, v103, v100
	v_sub_f32_e32 v102, v101, v103
	v_sub_f32_e32 v100, v100, v102
	v_add_f32_e32 v97, v97, v100
	v_add_f32_e32 v97, v101, v97
	v_cndmask_b32_e32 v97, v178, v97, vcc
	v_cmp_ngt_f32_e32 vcc, -1.0, v95
	s_nop 1
	v_cndmask_b32_e32 v97, v179, v97, vcc
	v_cmp_neq_f32_e32 vcc, -1.0, v95
	s_nop 1
	v_cndmask_b32_e32 v97, v180, v97, vcc
	v_cmp_lt_f32_e64 vcc, |v95|, s50
	s_nop 1
	v_cndmask_b32_e32 v95, v97, v95, vcc
	v_sub_f32_e32 v94, v94, v95
	global_store_dword v[92:93], v94, off offset:-24
	global_load_dword v95, v160, s[60:61] offset:12
	s_waitcnt vmcnt(0)
	v_fmac_f32_e32 v95, v91, v96
	v_min_f32_e32 v94, 0, v95
	v_mul_f32_e64 v95, |v95|, s46
	v_exp_f32_e32 v95, v95
	s_nop 0
	v_add_f32_e32 v97, 1.0, v95
	v_add_f32_e32 v100, -1.0, v97
	v_sub_f32_e32 v101, v100, v97
	v_add_f32_e32 v101, 1.0, v101
	v_sub_f32_e32 v100, v95, v100
	v_add_f32_e32 v102, v100, v101
	v_frexp_mant_f32_e32 v100, v97
	v_cmp_gt_f32_e32 vcc, s47, v100
	v_cvt_f64_f32_e32 v[100:101], v97
	v_frexp_exp_i32_f64_e32 v100, v[100:101]
	v_subbrev_co_u32_e32 v100, vcc, 0, v100, vcc
	v_sub_u32_e32 v101, 0, v100
	v_ldexp_f32 v97, v97, v101
	v_ldexp_f32 v101, v102, v101
	v_add_f32_e32 v102, -1.0, v97
	v_add_f32_e32 v103, 1.0, v102
	v_sub_f32_e32 v103, v97, v103
	v_add_f32_e32 v103, v101, v103
	v_add_f32_e32 v105, v102, v103
	v_sub_f32_e32 v102, v105, v102
	v_sub_f32_e32 v102, v103, v102
	v_add_f32_e32 v103, 1.0, v97
	v_add_f32_e32 v106, -1.0, v103
	v_sub_f32_e32 v97, v97, v106
	v_add_f32_e32 v97, v101, v97
	v_add_f32_e32 v101, v103, v97
	v_sub_f32_e32 v103, v101, v103
	v_sub_f32_e32 v97, v97, v103
	v_rcp_f32_e32 v103, v101
	v_cvt_f32_i32_e32 v100, v100
	v_cmp_neq_f32_e32 vcc, s49, v95
	v_mul_f32_e32 v106, v105, v103
	v_mul_f32_e32 v107, v101, v106
	v_fma_f32 v108, v106, v101, -v107
	v_fmac_f32_e32 v108, v106, v97
	v_add_f32_e32 v109, v107, v108
	v_sub_f32_e32 v110, v105, v109
	v_sub_f32_e32 v105, v105, v110
	v_sub_f32_e32 v107, v109, v107
	v_sub_f32_e32 v105, v105, v109
	v_add_f32_e32 v102, v102, v105
	v_sub_f32_e32 v105, v107, v108
	v_add_f32_e32 v102, v105, v102
	v_add_f32_e32 v105, v110, v102
	v_mul_f32_e32 v107, v103, v105
	v_mul_f32_e32 v108, v101, v107
	v_fma_f32 v101, v107, v101, -v108
	v_fmac_f32_e32 v101, v107, v97
	v_sub_f32_e32 v97, v110, v105
	v_add_f32_e32 v97, v102, v97
	v_add_f32_e32 v102, v108, v101
	v_sub_f32_e32 v109, v105, v102
	v_sub_f32_e32 v105, v105, v109
	v_sub_f32_e32 v108, v102, v108
	v_sub_f32_e32 v102, v105, v102
	v_add_f32_e32 v97, v97, v102
	v_sub_f32_e32 v101, v108, v101
	v_add_f32_e32 v97, v101, v97
	v_add_f32_e32 v101, v106, v107
	v_add_f32_e32 v97, v109, v97
	v_sub_f32_e32 v102, v101, v106
	v_mul_f32_e32 v97, v103, v97
	v_sub_f32_e32 v102, v107, v102
	v_add_f32_e32 v97, v102, v97
	v_mul_f32_e32 v106, 0x3f317218, v100
	v_add_f32_e32 v102, v101, v97
	v_fma_f32 v107, v100, s48, -v106
	v_mul_f32_e32 v103, v102, v102
	v_fmac_f32_e32 v107, 0xb102e308, v100
	v_sub_f32_e32 v100, v102, v101
	v_fmamk_f32 v105, v103, 0x3e9b6dac, v171
	v_sub_f32_e32 v97, v97, v100
	v_add_f32_e32 v100, v106, v107
	v_fmaak_f32 v105, v103, v105, 0x3f2aaada
	v_sub_f32_e32 v101, v100, v106
	v_ldexp_f32 v106, v102, 1
	v_mul_f32_e32 v102, v102, v103
	v_mul_f32_e32 v102, v102, v105
	v_add_f32_e32 v103, v106, v102
	v_sub_f32_e32 v105, v103, v106
	v_ldexp_f32 v97, v97, 1
	v_sub_f32_e32 v102, v102, v105
	v_add_f32_e32 v97, v97, v102
	v_add_f32_e32 v102, v103, v97
	v_sub_f32_e32 v103, v102, v103
	v_sub_f32_e32 v97, v97, v103
	v_add_f32_e32 v103, v100, v102
	v_sub_f32_e32 v105, v103, v100
	v_sub_f32_e32 v106, v103, v105
	v_sub_f32_e32 v101, v107, v101
	v_sub_f32_e32 v100, v100, v106
	v_sub_f32_e32 v102, v102, v105
	v_add_f32_e32 v100, v102, v100
	v_add_f32_e32 v102, v101, v97
	v_sub_f32_e32 v105, v102, v101
	v_sub_f32_e32 v106, v102, v105
	v_sub_f32_e32 v101, v101, v106
	v_sub_f32_e32 v97, v97, v105
	v_add_f32_e32 v100, v102, v100
	v_add_f32_e32 v97, v97, v101
	v_add_f32_e32 v101, v103, v100
	v_sub_f32_e32 v102, v101, v103
	v_sub_f32_e32 v100, v100, v102
	v_add_f32_e32 v97, v97, v100
	v_add_f32_e32 v97, v101, v97
	v_cndmask_b32_e32 v97, v178, v97, vcc
	v_cmp_ngt_f32_e32 vcc, -1.0, v95
	s_nop 1
	v_cndmask_b32_e32 v97, v179, v97, vcc
	v_cmp_neq_f32_e32 vcc, -1.0, v95
	s_nop 1
	v_cndmask_b32_e32 v97, v180, v97, vcc
	v_cmp_lt_f32_e64 vcc, |v95|, s50
	s_nop 1
	v_cndmask_b32_e32 v95, v97, v95, vcc
	v_sub_f32_e32 v94, v94, v95
	global_store_dword v[92:93], v94, off offset:-20

; DI unsigned pk2(float lo, float hi) { f32x2 v = {lo, hi}; return __builtin_bit_cast(unsigned, __builtin_convertvector(v, bfx2)); }
; DI float sigmoidf_(float x) { return 1.f / (1.f + __expf(-x)); }
; template <bool SWAP> DI void inproj_tile(const Params& p, int layer, int tm, int tn, bf16_t* smem) {
;     ...
;       for (int i = 0; i < 8; ++i) {
;         const int t = trow0 + i * 16 + l15; const float rs = rstd_from16(ssq + (size_t)t * 16, 1.f / 1024.f);
;         float* gt = (float*)(p.ws + O_GATES) + (size_t)t * 24; float* lf = (float*)(p.ws + O_LOGF) + (size_t)t * 8;
; #pragma unroll
;         for (int r = 0; r < 4; ++r) gt[quad * 4 + r] = sigmoidf_(acc[i][0][r] * rs);
;         if (quad < 2) {
; #pragma unroll
;           for (int r = 0; r < 4; ++r) gt[16 + quad * 4 + r] = sigmoidf_(acc[i][1][r] * rs);
;         } else {
; #pragma unroll
;           for (int r = 0; r < 4; ++r) { const int h = (quad - 2) * 4 + r; const float xx = acc[i][1][r] * rs + p.b_forget[layer * 8 + h]; lf[h] = fminf(xx, 0.f) - log1pf(__expf(-fabsf(xx))); }
;         }
;         const float* rp = (const float*)(p.ws + O_ROPE16) + (size_t)t * 32 + quad * 8; float o1[4], o2[4];
; #pragma unroll
;         for (int r = 0; r < 4; ++r) { const float cs = rp[2 * r], sn = rp[2 * r + 1], x1 = acc[i][2][r] * rs, x2 = acc[i][3][r] * rs; o1[r] = x1 * cs - x2 * sn; o2[r] = x2 * cs + x1 * sn; }
;         bf16_t* kp = (bf16_t*)(p.ws + O_MLAKPE) + (size_t)t * 32 + quad * 4;
;         *(u32x2*)kp = (u32x2){pk2(o1[0], o1[1]), pk2(o1[2], o1[3])}; *(u32x2*)(kp + 16) = (u32x2){pk2(o2[0], o2[1]), pk2(o2[2], o2[3])};
.LBB0_1307:
	s_or_b64 exec, exec, s[2:3]
	s_nop 0
	v_lshl_add_u64 v[88:89], v[98:99], 2, s[10:11]
	v_mov_b32_e32 v105, v161
	v_lshl_add_u64 v[92:93], v[88:89], 0, v[104:105]
	global_load_dwordx4 v[88:91], v[92:93], off offset:16
	s_nop 0
	global_load_dwordx4 v[92:95], v[92:93], off
	v_pk_mul_f32 v[80:81], v[80:81], v[96:97] op_sel_hi:[1,0]
	v_pk_mul_f32 v[84:85], v[84:85], v[96:97] op_sel_hi:[1,0]
	v_pk_mul_f32 v[82:83], v[82:83], v[96:97] op_sel_hi:[1,0]
	v_readlane_b32 s2, v240, 32
	v_readlane_b32 s3, v240, 33
	v_mov_b32_e32 v113, v161
	s_waitcnt vmcnt(0)
	v_mov_b32_e32 v101, v94
	v_mov_b32_e32 v94, v93
	v_mov_b32_e32 v100, v92
	v_pk_mul_f32 v[92:93], v[80:81], v[94:95]
	s_nop 0
	v_pk_fma_f32 v[92:93], v[84:85], v[100:101], v[92:93] neg_lo:[0,0,1] neg_hi:[0,0,1]
	v_pk_mul_f32 v[84:85], v[84:85], v[94:95]
	s_nop 0
	v_pk_fma_f32 v[80:81], v[80:81], v[100:101], v[84:85]
	v_pk_mul_f32 v[84:85], v[86:87], v[96:97] op_sel_hi:[1,0]
	v_mov_b32_e32 v87, v90
	v_mov_b32_e32 v90, v89
	v_mov_b32_e32 v86, v88
	v_pk_mul_f32 v[88:89], v[82:83], v[90:91]
	v_or_b32_e32 v96, 48, v128
	v_pk_fma_f32 v[88:89], v[84:85], v[86:87], v[88:89] neg_lo:[0,0,1] neg_hi:[0,0,1]
	v_pk_mul_f32 v[84:85], v[84:85], v[90:91]
	v_cvt_pk_bf16_f32 v80, v80, v81
	v_pk_fma_f32 v[82:83], v[82:83], v[86:87], v[84:85]
	v_lshl_add_u64 v[84:85], v[98:99], 1, s[2:3]
	v_lshl_add_u64 v[84:85], v[84:85], 0, v[112:113]
	v_cvt_pk_bf16_f32 v81, v82, v83
	v_ashrrev_i32_e32 v97, 31, v96
	v_cvt_pk_bf16_f32 v86, v92, v93
	v_cvt_pk_bf16_f32 v87, v88, v89
	global_store_dwordx2 v[84:85], v[80:81], off offset:32
	v_lshlrev_b64 v[80:81], 6, v[96:97]
	global_store_dwordx2 v[84:85], v[86:87], off
	v_lshl_add_u64 v[92:93], s[6:7], 0, v[80:81]
	v_bfe_u32 v244, v92, 6, 8
	v_lshlrev_b32_e32 v244, 3, v244
	v_add_u32_e32 v244, 0x24010, v244
	v_or_b32_e32 v246, 3, v92
	ds_read_b64 v[248:249], v244
	s_waitcnt lgkmcnt(0)
	v_cmp_ne_u32_e64 s[100:101], v248, v246
	s_nop 1
	s_and_saveexec_b64 s[98:99], s[100:101]
	s_cbranch_execz .LrcA1_11
	global_load_dwordx4 v[80:83], v[92:93], off offset:48
	global_load_dwordx4 v[84:87], v[92:93], off offset:32
	global_load_dwordx4 v[88:91], v[92:93], off offset:16
	s_nop 0
	global_load_dwordx4 v[92:95], v[92:93], off
	s_waitcnt vmcnt(2)
	v_add_f32_e32 v84, v84, v85
	v_add_f32_e32 v86, v86, v87
	s_waitcnt vmcnt(0)
	v_mov_b32_e32 v98, v93
	v_mov_b32_e32 v99, v94
	v_mov_b32_e32 v93, v95
	v_mov_b32_e32 v94, v89
	v_mov_b32_e32 v95, v90
	v_mov_b32_e32 v89, v91
	v_pk_add_f32 v[92:93], v[98:99], v[92:93]
	v_pk_add_f32 v[88:89], v[94:95], v[88:89]
	v_pk_add_f32 v[92:93], v[92:93], v[92:93] op_sel:[0,1] op_sel_hi:[1,0]
	v_pk_add_f32 v[88:89], v[88:89], v[88:89] op_sel:[0,1] op_sel_hi:[1,0]
	v_mov_b32_e32 v93, v80
	v_mov_b32_e32 v89, v81
	v_mov_b32_e32 v85, v82
	v_mov_b32_e32 v87, v83
	v_pk_add_f32 v[80:81], v[92:93], v[88:89]
	v_pk_add_f32 v[82:83], v[84:85], v[86:87]
	s_nop 0
	v_pk_add_f32 v[80:81], v[80:81], v[82:83]
	v_add_f32_e32 v80, v80, v81
	v_fmamk_f32 v80, v80, 0x3a800000, v170
	v_cmp_gt_f32_e32 vcc, s43, v80
	v_mul_f32_e32 v81, 0x4b800000, v80
	v_cndmask_b32_e32 v80, v80, v81, vcc
	v_rsq_f32_e32 v80, v80
	v_mul_f32_e32 v81, 0x45800000, v80
	v_cndmask_b32_e32 v80, v80, v81, vcc
	s_nop 0
	v_mov_b32_e32 v247, v80
	ds_write_b64 v244, v[246:247]
.LrcA1_11:
	s_or_b64 exec, exec, s[98:99]
	s_waitcnt vmcnt(0)
	v_cndmask_b32_e64 v80, v249, v80, s[100:101]
	v_readlane_b32 s2, v240, 35
	v_readlane_b32 s3, v240, 36
	v_mov_b64_e32 v[82:83], s[2:3]
	v_mad_i64_i32 v[84:85], s[2:3], v96, s45, v[82:83]
	v_lshlrev_b64 v[82:83], 5, v[96:97]
	v_lshl_add_u64 v[84:85], v[84:85], 0, v[160:161]
	v_mul_f32_e32 v76, v76, v80
	v_mul_f32_e32 v77, v77, v80
	v_mul_f32_e32 v76, 0xbfb8aa3b, v76
	v_mul_f32_e32 v77, 0xbfb8aa3b, v77
	v_exp_f32_e32 v76, v76
	v_exp_f32_e32 v77, v77
	v_mul_f32_e32 v78, v78, v80
	v_mul_f32_e32 v79, v79, v80
	v_mul_f32_e32 v78, 0xbfb8aa3b, v78
	v_pk_add_f32 v[76:77], v[76:77], 1.0 op_sel_hi:[1,0]
	v_mul_f32_e32 v79, 0xbfb8aa3b, v79
	v_div_scale_f32 v81, s[2:3], v77, v77, 1.0
	v_rcp_f32_e32 v86, v81
	v_exp_f32_e32 v78, v78
	v_exp_f32_e32 v79, v79
	v_fma_f32 v87, -v81, v86, 1.0
	v_fmac_f32_e32 v86, v87, v86
	v_div_scale_f32 v87, vcc, 1.0, v77, 1.0
	v_mul_f32_e32 v88, v87, v86
	v_fma_f32 v89, -v81, v88, v87
	v_fmac_f32_e32 v88, v89, v86
	v_fma_f32 v81, -v81, v88, v87
	v_div_fmas_f32 v81, v81, v86, v88
	v_div_fixup_f32 v77, v81, v77, 1.0
	v_div_scale_f32 v81, s[2:3], v76, v76, 1.0
	v_rcp_f32_e32 v86, v81
	v_pk_add_f32 v[78:79], v[78:79], 1.0 op_sel_hi:[1,0]
	v_fma_f32 v87, -v81, v86, 1.0
	v_fmac_f32_e32 v86, v87, v86
	v_div_scale_f32 v87, vcc, 1.0, v76, 1.0
	v_mul_f32_e32 v88, v87, v86
	v_fma_f32 v89, -v81, v88, v87
	v_fmac_f32_e32 v88, v89, v86
	v_fma_f32 v81, -v81, v88, v87
	v_div_fmas_f32 v81, v81, v86, v88
	v_div_fixup_f32 v76, v81, v76, 1.0
	v_div_scale_f32 v81, s[2:3], v79, v79, 1.0
	v_rcp_f32_e32 v86, v81
	s_nop 0
	v_fma_f32 v87, -v81, v86, 1.0
	v_fmac_f32_e32 v86, v87, v86
	v_div_scale_f32 v87, vcc, 1.0, v79, 1.0
	v_mul_f32_e32 v88, v87, v86
	v_fma_f32 v89, -v81, v88, v87
	v_fmac_f32_e32 v88, v89, v86
	v_fma_f32 v81, -v81, v88, v87
	v_div_fmas_f32 v81, v81, v86, v88
	v_div_fixup_f32 v79, v81, v79, 1.0
	v_div_scale_f32 v81, s[2:3], v78, v78, 1.0
	v_rcp_f32_e32 v86, v81
	s_nop 0
	v_fma_f32 v87, -v81, v86, 1.0
	v_fmac_f32_e32 v86, v87, v86
	v_div_scale_f32 v87, vcc, 1.0, v78, 1.0
	v_mul_f32_e32 v88, v87, v86
	v_fma_f32 v89, -v81, v88, v87
	v_fmac_f32_e32 v88, v89, v86
	v_fma_f32 v81, -v81, v88, v87
	v_div_fmas_f32 v81, v81, v86, v88
	v_div_fixup_f32 v78, v81, v78, 1.0
	global_store_dwordx4 v[84:85], v[76:79], off
	s_and_saveexec_b64 s[2:3], s[4:5]
	s_xor_b64 s[2:3], exec, s[2:3]
	s_cbranch_execz .LBB0_1309
; DI float sigmoidf_(float x) { return 1.f / (1.f + __expf(-x)); }
; template <bool SWAP> DI void inproj_tile(const Params& p, int layer, int tm, int tn, bf16_t* smem) {
;     ...
;         if (quad < 2) {
; #pragma unroll
;           for (int r = 0; r < 4; ++r) gt[16 + quad * 4 + r] = sigmoidf_(acc[i][1][r] * rs);
;         } else {
; #pragma unroll
;           for (int r = 0; r < 4; ++r) { const int h = (quad - 2) * 4 + r; const float xx = acc[i][1][r] * rs + p.b_forget[layer * 8 + h]; lf[h] = fminf(xx, 0.f) - log1pf(__expf(-fabsf(xx))); }
;         }
	v_readlane_b32 s52, v241, 8
	v_readlane_b32 s60, v241, 16
	v_readlane_b32 s61, v241, 17
	v_lshl_add_u64 v[76:77], s[8:9], 0, v[82:83]
	v_lshl_add_u64 v[76:77], v[76:77], 0, v[160:161]
	v_readlane_b32 s53, v241, 9
	v_readlane_b32 s54, v241, 10
	v_readlane_b32 s55, v241, 11
	global_load_dword v78, v160, s[60:61]
	v_readlane_b32 s56, v241, 12
	v_readlane_b32 s57, v241, 13
	v_readlane_b32 s58, v241, 14
	v_readlane_b32 s59, v241, 15
	v_readlane_b32 s62, v241, 18
	v_readlane_b32 s63, v241, 19
	v_readlane_b32 s64, v241, 20
	v_readlane_b32 s65, v241, 21
	v_readlane_b32 s66, v241, 22
	v_readlane_b32 s67, v241, 23
	s_waitcnt vmcnt(0)
	v_fmac_f32_e32 v78, v72, v80
	v_min_f32_e32 v81, 0, v78
	v_mul_f32_e64 v78, |v78|, s46
	v_exp_f32_e32 v84, v78
	s_nop 0
	v_add_f32_e32 v85, 1.0, v84
	v_add_f32_e32 v78, -1.0, v85
	v_sub_f32_e32 v79, v78, v85
	v_add_f32_e32 v79, 1.0, v79
	v_sub_f32_e32 v78, v84, v78
	v_add_f32_e32 v86, v78, v79
	v_frexp_mant_f32_e32 v78, v85
	v_cmp_gt_f32_e32 vcc, s47, v78
	v_cvt_f64_f32_e32 v[78:79], v85
	v_frexp_exp_i32_f64_e32 v78, v[78:79]
	v_subbrev_co_u32_e32 v78, vcc, 0, v78, vcc
	v_sub_u32_e32 v79, 0, v78
	v_ldexp_f32 v85, v85, v79
	v_ldexp_f32 v79, v86, v79
	v_add_f32_e32 v86, -1.0, v85
	v_add_f32_e32 v87, 1.0, v86
	v_sub_f32_e32 v87, v85, v87
	v_add_f32_e32 v87, v79, v87
	v_add_f32_e32 v88, v86, v87
	v_sub_f32_e32 v86, v88, v86
	v_sub_f32_e32 v86, v87, v86
	v_add_f32_e32 v87, 1.0, v85
	v_add_f32_e32 v89, -1.0, v87
	v_sub_f32_e32 v85, v85, v89
	v_add_f32_e32 v79, v79, v85
	v_add_f32_e32 v85, v87, v79
	v_sub_f32_e32 v87, v85, v87
	v_sub_f32_e32 v79, v79, v87
	v_rcp_f32_e32 v87, v85
	v_cvt_f32_i32_e32 v78, v78
	v_cmp_neq_f32_e32 vcc, s49, v84
	v_mul_f32_e32 v89, v88, v87
	v_mul_f32_e32 v90, v85, v89
	v_fma_f32 v91, v89, v85, -v90
	v_fmac_f32_e32 v91, v89, v79
	v_add_f32_e32 v92, v90, v91
	v_sub_f32_e32 v93, v88, v92
	v_sub_f32_e32 v88, v88, v93
	v_sub_f32_e32 v90, v92, v90
	v_sub_f32_e32 v88, v88, v92
	v_add_f32_e32 v86, v86, v88
	v_sub_f32_e32 v88, v90, v91
	v_add_f32_e32 v86, v88, v86
	v_add_f32_e32 v88, v93, v86
	v_mul_f32_e32 v90, v87, v88
	v_mul_f32_e32 v91, v85, v90
	v_fma_f32 v85, v90, v85, -v91
	v_fmac_f32_e32 v85, v90, v79
	v_sub_f32_e32 v79, v93, v88
	v_add_f32_e32 v79, v86, v79
	v_add_f32_e32 v86, v91, v85
	v_sub_f32_e32 v92, v88, v86
	v_sub_f32_e32 v88, v88, v92
	v_sub_f32_e32 v91, v86, v91
	v_sub_f32_e32 v86, v88, v86
	v_add_f32_e32 v79, v79, v86
	v_sub_f32_e32 v85, v91, v85
	v_add_f32_e32 v79, v85, v79
	v_add_f32_e32 v85, v89, v90
	v_add_f32_e32 v79, v92, v79
	v_sub_f32_e32 v86, v85, v89
	v_mul_f32_e32 v79, v87, v79
	v_sub_f32_e32 v86, v90, v86
	v_add_f32_e32 v79, v86, v79
	v_mul_f32_e32 v89, 0x3f317218, v78
	v_add_f32_e32 v86, v85, v79
	v_fma_f32 v90, v78, s48, -v89
	v_mul_f32_e32 v87, v86, v86
	v_fmac_f32_e32 v90, 0xb102e308, v78
	v_sub_f32_e32 v78, v86, v85
	v_fmamk_f32 v88, v87, 0x3e9b6dac, v171
	v_sub_f32_e32 v78, v79, v78
	v_add_f32_e32 v79, v89, v90
	v_fmaak_f32 v88, v87, v88, 0x3f2aaada
	v_sub_f32_e32 v85, v79, v89
	v_ldexp_f32 v89, v86, 1
	v_mul_f32_e32 v86, v86, v87
	v_mul_f32_e32 v86, v86, v88
	v_add_f32_e32 v87, v89, v86
	v_sub_f32_e32 v88, v87, v89
	v_ldexp_f32 v78, v78, 1
	v_sub_f32_e32 v86, v86, v88
	v_add_f32_e32 v78, v78, v86
	v_add_f32_e32 v86, v87, v78
	v_sub_f32_e32 v87, v86, v87
	v_sub_f32_e32 v78, v78, v87
	v_add_f32_e32 v87, v79, v86
	v_sub_f32_e32 v88, v87, v79
	v_sub_f32_e32 v89, v87, v88
	v_sub_f32_e32 v85, v90, v85
	v_sub_f32_e32 v79, v79, v89
	v_sub_f32_e32 v86, v86, v88
	v_add_f32_e32 v79, v86, v79
	v_add_f32_e32 v86, v85, v78
	v_sub_f32_e32 v88, v86, v85
	v_sub_f32_e32 v89, v86, v88
	v_sub_f32_e32 v85, v85, v89
	v_sub_f32_e32 v78, v78, v88
	v_add_f32_e32 v79, v86, v79
	v_add_f32_e32 v78, v78, v85
	v_add_f32_e32 v85, v87, v79
	v_sub_f32_e32 v86, v85, v87
	v_sub_f32_e32 v79, v79, v86
	v_add_f32_e32 v78, v78, v79
	v_add_f32_e32 v78, v85, v78
	v_cndmask_b32_e32 v78, v178, v78, vcc
	v_cmp_ngt_f32_e32 vcc, -1.0, v84
	s_nop 1
	v_cndmask_b32_e32 v78, v179, v78, vcc
	v_cmp_neq_f32_e32 vcc, -1.0, v84
	s_nop 1
	v_cndmask_b32_e32 v78, v180, v78, vcc
	v_cmp_lt_f32_e64 vcc, |v84|, s50
	s_nop 1
	v_cndmask_b32_e32 v78, v78, v84, vcc
	v_sub_f32_e32 v78, v81, v78
	global_store_dword v[76:77], v78, off offset:-32
	global_load_dword v79, v160, s[60:61] offset:4
	s_waitcnt vmcnt(0)
; template <bool SWAP> DI void inproj_tile(const Params& p, int layer, int tm, int tn, bf16_t* smem) {
;     ...
;         } else {
; #pragma unroll
;           for (int r = 0; r < 4; ++r) { const int h = (quad - 2) * 4 + r; const float xx = acc[i][1][r] * rs + p.b_forget[layer * 8 + h]; lf[h] = fminf(xx, 0.f) - log1pf(__expf(-fabsf(xx))); }
;         }
	v_fmac_f32_e32 v79, v73, v80
	v_min_f32_e32 v78, 0, v79
	v_mul_f32_e64 v79, |v79|, s46
	v_exp_f32_e32 v79, v79
	s_nop 0
	v_add_f32_e32 v81, 1.0, v79
	v_add_f32_e32 v84, -1.0, v81
	v_sub_f32_e32 v85, v84, v81
	v_add_f32_e32 v85, 1.0, v85
	v_sub_f32_e32 v84, v79, v84
	v_add_f32_e32 v86, v84, v85
	v_frexp_mant_f32_e32 v84, v81
	v_cmp_gt_f32_e32 vcc, s47, v84
	v_cvt_f64_f32_e32 v[84:85], v81
	v_frexp_exp_i32_f64_e32 v84, v[84:85]
	v_subbrev_co_u32_e32 v84, vcc, 0, v84, vcc
	v_sub_u32_e32 v85, 0, v84
	v_ldexp_f32 v81, v81, v85
	v_ldexp_f32 v85, v86, v85
	v_add_f32_e32 v86, -1.0, v81
	v_add_f32_e32 v87, 1.0, v86
	v_sub_f32_e32 v87, v81, v87
	v_add_f32_e32 v87, v85, v87
	v_add_f32_e32 v88, v86, v87
	v_sub_f32_e32 v86, v88, v86
	v_sub_f32_e32 v86, v87, v86
	v_add_f32_e32 v87, 1.0, v81
	v_add_f32_e32 v89, -1.0, v87
	v_sub_f32_e32 v81, v81, v89
	v_add_f32_e32 v81, v85, v81
	v_add_f32_e32 v85, v87, v81
	v_sub_f32_e32 v87, v85, v87
	v_sub_f32_e32 v81, v81, v87
	v_rcp_f32_e32 v87, v85
	v_cvt_f32_i32_e32 v84, v84
	v_cmp_neq_f32_e32 vcc, s49, v79
	v_mul_f32_e32 v89, v88, v87
	v_mul_f32_e32 v90, v85, v89
	v_fma_f32 v91, v89, v85, -v90
	v_fmac_f32_e32 v91, v89, v81
	v_add_f32_e32 v92, v90, v91
	v_sub_f32_e32 v93, v88, v92
	v_sub_f32_e32 v88, v88, v93
	v_sub_f32_e32 v90, v92, v90
	v_sub_f32_e32 v88, v88, v92
	v_add_f32_e32 v86, v86, v88
	v_sub_f32_e32 v88, v90, v91
	v_add_f32_e32 v86, v88, v86
	v_add_f32_e32 v88, v93, v86
	v_mul_f32_e32 v90, v87, v88
	v_mul_f32_e32 v91, v85, v90
	v_fma_f32 v85, v90, v85, -v91
	v_fmac_f32_e32 v85, v90, v81
	v_sub_f32_e32 v81, v93, v88
	v_add_f32_e32 v81, v86, v81
	v_add_f32_e32 v86, v91, v85
	v_sub_f32_e32 v92, v88, v86
	v_sub_f32_e32 v88, v88, v92
	v_sub_f32_e32 v91, v86, v91
	v_sub_f32_e32 v86, v88, v86
	v_add_f32_e32 v81, v81, v86
	v_sub_f32_e32 v85, v91, v85
	v_add_f32_e32 v81, v85, v81
	v_add_f32_e32 v85, v89, v90
	v_add_f32_e32 v81, v92, v81
	v_sub_f32_e32 v86, v85, v89
	v_mul_f32_e32 v81, v87, v81
	v_sub_f32_e32 v86, v90, v86
	v_add_f32_e32 v81, v86, v81
	v_mul_f32_e32 v89, 0x3f317218, v84
	v_add_f32_e32 v86, v85, v81
	v_fma_f32 v90, v84, s48, -v89
	v_mul_f32_e32 v87, v86, v86
	v_fmac_f32_e32 v90, 0xb102e308, v84
	v_sub_f32_e32 v84, v86, v85
	v_fmamk_f32 v88, v87, 0x3e9b6dac, v171
	v_sub_f32_e32 v81, v81, v84
	v_add_f32_e32 v84, v89, v90
	v_fmaak_f32 v88, v87, v88, 0x3f2aaada
	v_sub_f32_e32 v85, v84, v89
	v_ldexp_f32 v89, v86, 1
	v_mul_f32_e32 v86, v86, v87
	v_mul_f32_e32 v86, v86, v88
	v_add_f32_e32 v87, v89, v86
	v_sub_f32_e32 v88, v87, v89
	v_ldexp_f32 v81, v81, 1
	v_sub_f32_e32 v86, v86, v88
	v_add_f32_e32 v81, v81, v86
	v_add_f32_e32 v86, v87, v81
	v_sub_f32_e32 v87, v86, v87
	v_sub_f32_e32 v81, v81, v87
	v_add_f32_e32 v87, v84, v86
	v_sub_f32_e32 v88, v87, v84
	v_sub_f32_e32 v89, v87, v88
	v_sub_f32_e32 v85, v90, v85
	v_sub_f32_e32 v84, v84, v89
	v_sub_f32_e32 v86, v86, v88
	v_add_f32_e32 v84, v86, v84
	v_add_f32_e32 v86, v85, v81
	v_sub_f32_e32 v88, v86, v85
	v_sub_f32_e32 v89, v86, v88
	v_sub_f32_e32 v85, v85, v89
	v_sub_f32_e32 v81, v81, v88
	v_add_f32_e32 v84, v86, v84
	v_add_f32_e32 v81, v81, v85
	v_add_f32_e32 v85, v87, v84
	v_sub_f32_e32 v86, v85, v87
	v_sub_f32_e32 v84, v84, v86
	v_add_f32_e32 v81, v81, v84
	v_add_f32_e32 v81, v85, v81
	v_cndmask_b32_e32 v81, v178, v81, vcc
	v_cmp_ngt_f32_e32 vcc, -1.0, v79
	s_nop 1
	v_cndmask_b32_e32 v81, v179, v81, vcc
	v_cmp_neq_f32_e32 vcc, -1.0, v79
	s_nop 1
	v_cndmask_b32_e32 v81, v180, v81, vcc
	v_cmp_lt_f32_e64 vcc, |v79|, s50
	s_nop 1
	v_cndmask_b32_e32 v79, v81, v79, vcc
	v_sub_f32_e32 v78, v78, v79
	global_store_dword v[76:77], v78, off offset:-28
	global_load_dword v79, v160, s[60:61] offset:8
	s_waitcnt vmcnt(0)
	v_fmac_f32_e32 v79, v74, v80
	v_min_f32_e32 v78, 0, v79
	v_mul_f32_e64 v79, |v79|, s46
	v_exp_f32_e32 v79, v79
	s_nop 0
	v_add_f32_e32 v81, 1.0, v79
	v_add_f32_e32 v84, -1.0, v81
	v_sub_f32_e32 v85, v84, v81
	v_add_f32_e32 v85, 1.0, v85
	v_sub_f32_e32 v84, v79, v84
	v_add_f32_e32 v86, v84, v85
	v_frexp_mant_f32_e32 v84, v81
	v_cmp_gt_f32_e32 vcc, s47, v84
	v_cvt_f64_f32_e32 v[84:85], v81
	v_frexp_exp_i32_f64_e32 v84, v[84:85]
	v_subbrev_co_u32_e32 v84, vcc, 0, v84, vcc
	v_sub_u32_e32 v85, 0, v84
	v_ldexp_f32 v81, v81, v85
	v_ldexp_f32 v85, v86, v85
	v_add_f32_e32 v86, -1.0, v81
	v_add_f32_e32 v87, 1.0, v86
	v_sub_f32_e32 v87, v81, v87
	v_add_f32_e32 v87, v85, v87
	v_add_f32_e32 v88, v86, v87
	v_sub_f32_e32 v86, v88, v86
	v_sub_f32_e32 v86, v87, v86
	v_add_f32_e32 v87, 1.0, v81
	v_add_f32_e32 v89, -1.0, v87
	v_sub_f32_e32 v81, v81, v89
	v_add_f32_e32 v81, v85, v81
	v_add_f32_e32 v85, v87, v81
	v_sub_f32_e32 v87, v85, v87
	v_sub_f32_e32 v81, v81, v87
	v_rcp_f32_e32 v87, v85
	v_cvt_f32_i32_e32 v84, v84
	v_cmp_neq_f32_e32 vcc, s49, v79
	v_mul_f32_e32 v89, v88, v87
	v_mul_f32_e32 v90, v85, v89
	v_fma_f32 v91, v89, v85, -v90
	v_fmac_f32_e32 v91, v89, v81
	v_add_f32_e32 v92, v90, v91
	v_sub_f32_e32 v93, v88, v92
	v_sub_f32_e32 v88, v88, v93
	v_sub_f32_e32 v90, v92, v90
	v_sub_f32_e32 v88, v88, v92
	v_add_f32_e32 v86, v86, v88
	v_sub_f32_e32 v88, v90, v91
	v_add_f32_e32 v86, v88, v86
	v_add_f32_e32 v88, v93, v86
	v_mul_f32_e32 v90, v87, v88
	v_mul_f32_e32 v91, v85, v90
	v_fma_f32 v85, v90, v85, -v91
	v_fmac_f32_e32 v85, v90, v81
	v_sub_f32_e32 v81, v93, v88
	v_add_f32_e32 v81, v86, v81
	v_add_f32_e32 v86, v91, v85
	v_sub_f32_e32 v92, v88, v86
	v_sub_f32_e32 v88, v88, v92
	v_sub_f32_e32 v91, v86, v91
	v_sub_f32_e32 v86, v88, v86
	v_add_f32_e32 v81, v81, v86
	v_sub_f32_e32 v85, v91, v85
; template <bool SWAP> DI void inproj_tile(const Params& p, int layer, int tm, int tn, bf16_t* smem) {
;     ...
;         } else {
; #pragma unroll
;           for (int r = 0; r < 4; ++r) { const int h = (quad - 2) * 4 + r; const float xx = acc[i][1][r] * rs + p.b_forget[layer * 8 + h]; lf[h] = fminf(xx, 0.f) - log1pf(__expf(-fabsf(xx))); }
;         }
	v_add_f32_e32 v81, v85, v81
	v_add_f32_e32 v85, v89, v90
	v_add_f32_e32 v81, v92, v81
	v_sub_f32_e32 v86, v85, v89
	v_mul_f32_e32 v81, v87, v81
	v_sub_f32_e32 v86, v90, v86
	v_add_f32_e32 v81, v86, v81
	v_mul_f32_e32 v89, 0x3f317218, v84
	v_add_f32_e32 v86, v85, v81
	v_fma_f32 v90, v84, s48, -v89
	v_mul_f32_e32 v87, v86, v86
	v_fmac_f32_e32 v90, 0xb102e308, v84
	v_sub_f32_e32 v84, v86, v85
	v_fmamk_f32 v88, v87, 0x3e9b6dac, v171
	v_sub_f32_e32 v81, v81, v84
	v_add_f32_e32 v84, v89, v90
	v_fmaak_f32 v88, v87, v88, 0x3f2aaada
	v_sub_f32_e32 v85, v84, v89
	v_ldexp_f32 v89, v86, 1
	v_mul_f32_e32 v86, v86, v87
	v_mul_f32_e32 v86, v86, v88
	v_add_f32_e32 v87, v89, v86
	v_sub_f32_e32 v88, v87, v89
	v_ldexp_f32 v81, v81, 1
	v_sub_f32_e32 v86, v86, v88
	v_add_f32_e32 v81, v81, v86
	v_add_f32_e32 v86, v87, v81
	v_sub_f32_e32 v87, v86, v87
	v_sub_f32_e32 v81, v81, v87
	v_add_f32_e32 v87, v84, v86
	v_sub_f32_e32 v88, v87, v84
	v_sub_f32_e32 v89, v87, v88
	v_sub_f32_e32 v85, v90, v85
	v_sub_f32_e32 v84, v84, v89
	v_sub_f32_e32 v86, v86, v88
	v_add_f32_e32 v84, v86, v84
	v_add_f32_e32 v86, v85, v81
	v_sub_f32_e32 v88, v86, v85
	v_sub_f32_e32 v89, v86, v88
	v_sub_f32_e32 v85, v85, v89
	v_sub_f32_e32 v81, v81, v88
	v_add_f32_e32 v84, v86, v84
	v_add_f32_e32 v81, v81, v85
	v_add_f32_e32 v85, v87, v84
	v_sub_f32_e32 v86, v85, v87
	v_sub_f32_e32 v84, v84, v86
	v_add_f32_e32 v81, v81, v84
	v_add_f32_e32 v81, v85, v81
	v_cndmask_b32_e32 v81, v178, v81, vcc
	v_cmp_ngt_f32_e32 vcc, -1.0, v79
	s_nop 1
	v_cndmask_b32_e32 v81, v179, v81, vcc
	v_cmp_neq_f32_e32 vcc, -1.0, v79
	s_nop 1
	v_cndmask_b32_e32 v81, v180, v81, vcc
	v_cmp_lt_f32_e64 vcc, |v79|, s50
	s_nop 1
	v_cndmask_b32_e32 v79, v81, v79, vcc
	v_sub_f32_e32 v78, v78, v79
	global_store_dword v[76:77], v78, off offset:-24
	global_load_dword v79, v160, s[60:61] offset:12
	s_waitcnt vmcnt(0)
	v_fmac_f32_e32 v79, v75, v80
	v_min_f32_e32 v78, 0, v79
	v_mul_f32_e64 v79, |v79|, s46
	v_exp_f32_e32 v79, v79
	s_nop 0
	v_add_f32_e32 v81, 1.0, v79
	v_add_f32_e32 v84, -1.0, v81
	v_sub_f32_e32 v85, v84, v81
	v_add_f32_e32 v85, 1.0, v85
	v_sub_f32_e32 v84, v79, v84
	v_add_f32_e32 v86, v84, v85
	v_frexp_mant_f32_e32 v84, v81
	v_cmp_gt_f32_e32 vcc, s47, v84
	v_cvt_f64_f32_e32 v[84:85], v81
	v_frexp_exp_i32_f64_e32 v84, v[84:85]
	v_subbrev_co_u32_e32 v84, vcc, 0, v84, vcc
	v_sub_u32_e32 v85, 0, v84
	v_ldexp_f32 v81, v81, v85
	v_ldexp_f32 v85, v86, v85
	v_add_f32_e32 v86, -1.0, v81
	v_add_f32_e32 v87, 1.0, v86
	v_sub_f32_e32 v87, v81, v87
	v_add_f32_e32 v87, v85, v87
	v_add_f32_e32 v88, v86, v87
	v_sub_f32_e32 v86, v88, v86
	v_sub_f32_e32 v86, v87, v86
	v_add_f32_e32 v87, 1.0, v81
	v_add_f32_e32 v89, -1.0, v87
	v_sub_f32_e32 v81, v81, v89
	v_add_f32_e32 v81, v85, v81
	v_add_f32_e32 v85, v87, v81
	v_sub_f32_e32 v87, v85, v87
	v_sub_f32_e32 v81, v81, v87
	v_rcp_f32_e32 v87, v85
	v_cvt_f32_i32_e32 v84, v84
	v_cmp_neq_f32_e32 vcc, s49, v79
	v_mul_f32_e32 v89, v88, v87
	v_mul_f32_e32 v90, v85, v89
	v_fma_f32 v91, v89, v85, -v90
	v_fmac_f32_e32 v91, v89, v81
	v_add_f32_e32 v92, v90, v91
	v_sub_f32_e32 v93, v88, v92
	v_sub_f32_e32 v88, v88, v93
	v_sub_f32_e32 v90, v92, v90
	v_sub_f32_e32 v88, v88, v92
	v_add_f32_e32 v86, v86, v88
	v_sub_f32_e32 v88, v90, v91
	v_add_f32_e32 v86, v88, v86
	v_add_f32_e32 v88, v93, v86
	v_mul_f32_e32 v90, v87, v88
	v_mul_f32_e32 v91, v85, v90
	v_fma_f32 v85, v90, v85, -v91
	v_fmac_f32_e32 v85, v90, v81
	v_sub_f32_e32 v81, v93, v88
	v_add_f32_e32 v81, v86, v81
	v_add_f32_e32 v86, v91, v85
	v_sub_f32_e32 v92, v88, v86
	v_sub_f32_e32 v88, v88, v92
	v_sub_f32_e32 v91, v86, v91
	v_sub_f32_e32 v86, v88, v86
	v_add_f32_e32 v81, v81, v86
	v_sub_f32_e32 v85, v91, v85
	v_add_f32_e32 v81, v85, v81
	v_add_f32_e32 v85, v89, v90
	v_add_f32_e32 v81, v92, v81
	v_sub_f32_e32 v86, v85, v89
	v_mul_f32_e32 v81, v87, v81
	v_sub_f32_e32 v86, v90, v86
	v_add_f32_e32 v81, v86, v81
	v_mul_f32_e32 v89, 0x3f317218, v84
	v_add_f32_e32 v86, v85, v81
	v_fma_f32 v90, v84, s48, -v89
	v_mul_f32_e32 v87, v86, v86
	v_fmac_f32_e32 v90, 0xb102e308, v84
	v_sub_f32_e32 v84, v86, v85
	v_fmamk_f32 v88, v87, 0x3e9b6dac, v171
	v_sub_f32_e32 v81, v81, v84
	v_add_f32_e32 v84, v89, v90
	v_fmaak_f32 v88, v87, v88, 0x3f2aaada
	v_sub_f32_e32 v85, v84, v89
	v_ldexp_f32 v89, v86, 1
	v_mul_f32_e32 v86, v86, v87
	v_mul_f32_e32 v86, v86, v88
	v_add_f32_e32 v87, v89, v86
	v_sub_f32_e32 v88, v87, v89
	v_ldexp_f32 v81, v81, 1
	v_sub_f32_e32 v86, v86, v88
	v_add_f32_e32 v81, v81, v86
	v_add_f32_e32 v86, v87, v81
	v_sub_f32_e32 v87, v86, v87
	v_sub_f32_e32 v81, v81, v87
	v_add_f32_e32 v87, v84, v86
	v_sub_f32_e32 v88, v87, v84
	v_sub_f32_e32 v89, v87, v88
	v_sub_f32_e32 v85, v90, v85
	v_sub_f32_e32 v84, v84, v89
	v_sub_f32_e32 v86, v86, v88
	v_add_f32_e32 v84, v86, v84
	v_add_f32_e32 v86, v85, v81
	v_sub_f32_e32 v88, v86, v85
	v_sub_f32_e32 v89, v86, v88
	v_sub_f32_e32 v85, v85, v89
	v_sub_f32_e32 v81, v81, v88
	v_add_f32_e32 v84, v86, v84
	v_add_f32_e32 v81, v81, v85
	v_add_f32_e32 v85, v87, v84
	v_sub_f32_e32 v86, v85, v87
	v_sub_f32_e32 v84, v84, v86
	v_add_f32_e32 v81, v81, v84
	v_add_f32_e32 v81, v85, v81
	v_cndmask_b32_e32 v81, v178, v81, vcc
	v_cmp_ngt_f32_e32 vcc, -1.0, v79
	s_nop 1
	v_cndmask_b32_e32 v81, v179, v81, vcc
	v_cmp_neq_f32_e32 vcc, -1.0, v79
	s_nop 1
	v_cndmask_b32_e32 v81, v180, v81, vcc
	v_cmp_lt_f32_e64 vcc, |v79|, s50
	s_nop 1
	v_cndmask_b32_e32 v79, v81, v79, vcc
	v_sub_f32_e32 v78, v78, v79
	global_store_dword v[76:77], v78, off offset:-20

; DI unsigned pk2(float lo, float hi) { f32x2 v = {lo, hi}; return __builtin_bit_cast(unsigned, __builtin_convertvector(v, bfx2)); }
; DI float sigmoidf_(float x) { return 1.f / (1.f + __expf(-x)); }
; template <bool SWAP> DI void inproj_tile(const Params& p, int layer, int tm, int tn, bf16_t* smem) {
;     ...
;       for (int i = 0; i < 8; ++i) {
;         const int t = trow0 + i * 16 + l15; const float rs = rstd_from16(ssq + (size_t)t * 16, 1.f / 1024.f);
;         float* gt = (float*)(p.ws + O_GATES) + (size_t)t * 24; float* lf = (float*)(p.ws + O_LOGF) + (size_t)t * 8;
; #pragma unroll
;         for (int r = 0; r < 4; ++r) gt[quad * 4 + r] = sigmoidf_(acc[i][0][r] * rs);
;         if (quad < 2) {
; #pragma unroll
;           for (int r = 0; r < 4; ++r) gt[16 + quad * 4 + r] = sigmoidf_(acc[i][1][r] * rs);
;         } else {
; #pragma unroll
;           for (int r = 0; r < 4; ++r) { const int h = (quad - 2) * 4 + r; const float xx = acc[i][1][r] * rs + p.b_forget[layer * 8 + h]; lf[h] = fminf(xx, 0.f) - log1pf(__expf(-fabsf(xx))); }
;         }
;         const float* rp = (const float*)(p.ws + O_ROPE16) + (size_t)t * 32 + quad * 8; float o1[4], o2[4];
; #pragma unroll
;         for (int r = 0; r < 4; ++r) { const float cs = rp[2 * r], sn = rp[2 * r + 1], x1 = acc[i][2][r] * rs, x2 = acc[i][3][r] * rs; o1[r] = x1 * cs - x2 * sn; o2[r] = x2 * cs + x1 * sn; }
;         bf16_t* kp = (bf16_t*)(p.ws + O_MLAKPE) + (size_t)t * 32 + quad * 4;
;         *(u32x2*)kp = (u32x2){pk2(o1[0], o1[1]), pk2(o1[2], o1[3])}; *(u32x2*)(kp + 16) = (u32x2){pk2(o2[0], o2[1]), pk2(o2[2], o2[3])};
.LBB0_1311:
	s_or_b64 exec, exec, s[2:3]
	s_nop 0
	v_lshl_add_u64 v[72:73], v[82:83], 2, s[10:11]
	v_mov_b32_e32 v105, v161
	v_lshl_add_u64 v[76:77], v[72:73], 0, v[104:105]
	global_load_dwordx4 v[72:75], v[76:77], off offset:16
	s_nop 0
	global_load_dwordx4 v[76:79], v[76:77], off
	v_pk_mul_f32 v[64:65], v[64:65], v[80:81] op_sel_hi:[1,0]
	v_pk_mul_f32 v[68:69], v[68:69], v[80:81] op_sel_hi:[1,0]
	v_pk_mul_f32 v[66:67], v[66:67], v[80:81] op_sel_hi:[1,0]
	v_readlane_b32 s2, v240, 32
	v_readlane_b32 s3, v240, 33
	v_mov_b32_e32 v113, v161
	s_waitcnt vmcnt(0)
	v_mov_b32_e32 v85, v78
	v_mov_b32_e32 v78, v77
	v_mov_b32_e32 v84, v76
	v_pk_mul_f32 v[76:77], v[64:65], v[78:79]
	s_nop 0
	v_pk_fma_f32 v[76:77], v[68:69], v[84:85], v[76:77] neg_lo:[0,0,1] neg_hi:[0,0,1]
	v_pk_mul_f32 v[68:69], v[68:69], v[78:79]
	s_nop 0
	v_pk_fma_f32 v[64:65], v[64:65], v[84:85], v[68:69]
	v_pk_mul_f32 v[68:69], v[70:71], v[80:81] op_sel_hi:[1,0]
	v_mov_b32_e32 v71, v74
	v_mov_b32_e32 v74, v73
	v_mov_b32_e32 v70, v72
	v_pk_mul_f32 v[72:73], v[66:67], v[74:75]
	v_or_b32_e32 v80, 64, v128
	v_pk_fma_f32 v[72:73], v[68:69], v[70:71], v[72:73] neg_lo:[0,0,1] neg_hi:[0,0,1]
	v_pk_mul_f32 v[68:69], v[68:69], v[74:75]
	v_cvt_pk_bf16_f32 v64, v64, v65
	v_pk_fma_f32 v[66:67], v[66:67], v[70:71], v[68:69]
	v_lshl_add_u64 v[68:69], v[82:83], 1, s[2:3]
	v_lshl_add_u64 v[68:69], v[68:69], 0, v[112:113]
	v_cvt_pk_bf16_f32 v65, v66, v67
	v_ashrrev_i32_e32 v81, 31, v80
	v_cvt_pk_bf16_f32 v70, v76, v77
	v_cvt_pk_bf16_f32 v71, v72, v73
	global_store_dwordx2 v[68:69], v[64:65], off offset:32
	v_lshlrev_b64 v[64:65], 6, v[80:81]
	global_store_dwordx2 v[68:69], v[70:71], off
	v_lshl_add_u64 v[76:77], s[6:7], 0, v[64:65]
	v_bfe_u32 v244, v76, 6, 8
	v_lshlrev_b32_e32 v244, 3, v244
	v_add_u32_e32 v244, 0x24010, v244
	v_or_b32_e32 v246, 3, v76
	ds_read_b64 v[248:249], v244
	s_waitcnt lgkmcnt(0)
	v_cmp_ne_u32_e64 s[100:101], v248, v246
	s_nop 1
	s_and_saveexec_b64 s[98:99], s[100:101]
	s_cbranch_execz .LrcA1_12
	global_load_dwordx4 v[64:67], v[76:77], off offset:48
	global_load_dwordx4 v[68:71], v[76:77], off offset:32
	global_load_dwordx4 v[72:75], v[76:77], off offset:16
	s_nop 0
	global_load_dwordx4 v[76:79], v[76:77], off
	s_waitcnt vmcnt(2)
	v_add_f32_e32 v68, v68, v69
	v_add_f32_e32 v70, v70, v71
	s_waitcnt vmcnt(0)
	v_mov_b32_e32 v82, v77
	v_mov_b32_e32 v83, v78
	v_mov_b32_e32 v77, v79
	v_mov_b32_e32 v78, v73
	v_mov_b32_e32 v79, v74
	v_mov_b32_e32 v73, v75
	v_pk_add_f32 v[76:77], v[82:83], v[76:77]
	v_pk_add_f32 v[72:73], v[78:79], v[72:73]
	v_pk_add_f32 v[76:77], v[76:77], v[76:77] op_sel:[0,1] op_sel_hi:[1,0]
	v_pk_add_f32 v[72:73], v[72:73], v[72:73] op_sel:[0,1] op_sel_hi:[1,0]
	v_mov_b32_e32 v77, v64
	v_mov_b32_e32 v73, v65
	v_mov_b32_e32 v69, v66
	v_mov_b32_e32 v71, v67
	v_pk_add_f32 v[64:65], v[76:77], v[72:73]
	v_pk_add_f32 v[66:67], v[68:69], v[70:71]
	s_nop 0
	v_pk_add_f32 v[64:65], v[64:65], v[66:67]
	v_add_f32_e32 v64, v64, v65
	v_fmamk_f32 v64, v64, 0x3a800000, v170
	v_cmp_gt_f32_e32 vcc, s43, v64
	v_mul_f32_e32 v65, 0x4b800000, v64
	v_cndmask_b32_e32 v64, v64, v65, vcc
	v_rsq_f32_e32 v64, v64
	v_mul_f32_e32 v65, 0x45800000, v64
	v_cndmask_b32_e32 v64, v64, v65, vcc
	s_nop 0
	v_mov_b32_e32 v247, v64
	ds_write_b64 v244, v[246:247]
.LrcA1_12:
	s_or_b64 exec, exec, s[98:99]
	s_waitcnt vmcnt(0)
	v_cndmask_b32_e64 v64, v249, v64, s[100:101]
	v_readlane_b32 s2, v240, 35
	v_readlane_b32 s3, v240, 36
	v_mov_b64_e32 v[66:67], s[2:3]
	v_mad_i64_i32 v[68:69], s[2:3], v80, s45, v[66:67]
	v_lshlrev_b64 v[66:67], 5, v[80:81]
	v_lshl_add_u64 v[68:69], v[68:69], 0, v[160:161]
	v_mul_f32_e32 v60, v60, v64
	v_mul_f32_e32 v61, v61, v64
	v_mul_f32_e32 v60, 0xbfb8aa3b, v60
	v_mul_f32_e32 v61, 0xbfb8aa3b, v61
	v_exp_f32_e32 v60, v60
	v_exp_f32_e32 v61, v61
	v_mul_f32_e32 v62, v62, v64
	v_mul_f32_e32 v63, v63, v64
	v_mul_f32_e32 v62, 0xbfb8aa3b, v62
	v_pk_add_f32 v[60:61], v[60:61], 1.0 op_sel_hi:[1,0]
	v_mul_f32_e32 v63, 0xbfb8aa3b, v63
	v_div_scale_f32 v65, s[2:3], v61, v61, 1.0
	v_rcp_f32_e32 v70, v65
	v_exp_f32_e32 v62, v62
	v_exp_f32_e32 v63, v63
	v_fma_f32 v71, -v65, v70, 1.0
	v_fmac_f32_e32 v70, v71, v70
	v_div_scale_f32 v71, vcc, 1.0, v61, 1.0
	v_mul_f32_e32 v72, v71, v70
	v_fma_f32 v73, -v65, v72, v71
	v_fmac_f32_e32 v72, v73, v70
	v_fma_f32 v65, -v65, v72, v71
	v_div_fmas_f32 v65, v65, v70, v72
	v_div_fixup_f32 v61, v65, v61, 1.0
	v_div_scale_f32 v65, s[2:3], v60, v60, 1.0
	v_rcp_f32_e32 v70, v65
	v_pk_add_f32 v[62:63], v[62:63], 1.0 op_sel_hi:[1,0]
	v_fma_f32 v71, -v65, v70, 1.0
	v_fmac_f32_e32 v70, v71, v70
	v_div_scale_f32 v71, vcc, 1.0, v60, 1.0
	v_mul_f32_e32 v72, v71, v70
	v_fma_f32 v73, -v65, v72, v71
	v_fmac_f32_e32 v72, v73, v70
	v_fma_f32 v65, -v65, v72, v71
	v_div_fmas_f32 v65, v65, v70, v72
	v_div_fixup_f32 v60, v65, v60, 1.0
	v_div_scale_f32 v65, s[2:3], v63, v63, 1.0
	v_rcp_f32_e32 v70, v65
	s_nop 0
	v_fma_f32 v71, -v65, v70, 1.0
	v_fmac_f32_e32 v70, v71, v70
	v_div_scale_f32 v71, vcc, 1.0, v63, 1.0
	v_mul_f32_e32 v72, v71, v70
	v_fma_f32 v73, -v65, v72, v71
	v_fmac_f32_e32 v72, v73, v70
	v_fma_f32 v65, -v65, v72, v71
	v_div_fmas_f32 v65, v65, v70, v72
	v_div_fixup_f32 v63, v65, v63, 1.0
	v_div_scale_f32 v65, s[2:3], v62, v62, 1.0
	v_rcp_f32_e32 v70, v65
	s_nop 0
	v_fma_f32 v71, -v65, v70, 1.0
	v_fmac_f32_e32 v70, v71, v70
	v_div_scale_f32 v71, vcc, 1.0, v62, 1.0
	v_mul_f32_e32 v72, v71, v70
	v_fma_f32 v73, -v65, v72, v71
	v_fmac_f32_e32 v72, v73, v70
	v_fma_f32 v65, -v65, v72, v71
	v_div_fmas_f32 v65, v65, v70, v72
	v_div_fixup_f32 v62, v65, v62, 1.0
	global_store_dwordx4 v[68:69], v[60:63], off
	s_and_saveexec_b64 s[2:3], s[4:5]
	s_xor_b64 s[2:3], exec, s[2:3]
	s_cbranch_execz .LBB0_1313
; DI float sigmoidf_(float x) { return 1.f / (1.f + __expf(-x)); }
; template <bool SWAP> DI void inproj_tile(const Params& p, int layer, int tm, int tn, bf16_t* smem) {
;     ...
;         if (quad < 2) {
; #pragma unroll
;           for (int r = 0; r < 4; ++r) gt[16 + quad * 4 + r] = sigmoidf_(acc[i][1][r] * rs);
;         } else {
; #pragma unroll
;           for (int r = 0; r < 4; ++r) { const int h = (quad - 2) * 4 + r; const float xx = acc[i][1][r] * rs + p.b_forget[layer * 8 + h]; lf[h] = fminf(xx, 0.f) - log1pf(__expf(-fabsf(xx))); }
;         }
	v_readlane_b32 s52, v241, 8
	v_readlane_b32 s60, v241, 16
	v_readlane_b32 s61, v241, 17
	v_lshl_add_u64 v[60:61], s[8:9], 0, v[66:67]
	v_lshl_add_u64 v[60:61], v[60:61], 0, v[160:161]
	v_readlane_b32 s53, v241, 9
	v_readlane_b32 s54, v241, 10
	v_readlane_b32 s55, v241, 11
	global_load_dword v62, v160, s[60:61]
	v_readlane_b32 s56, v241, 12
	v_readlane_b32 s57, v241, 13
	v_readlane_b32 s58, v241, 14
	v_readlane_b32 s59, v241, 15
	v_readlane_b32 s62, v241, 18
	v_readlane_b32 s63, v241, 19
	v_readlane_b32 s64, v241, 20
	v_readlane_b32 s65, v241, 21
	v_readlane_b32 s66, v241, 22
	v_readlane_b32 s67, v241, 23
	s_waitcnt vmcnt(0)
	v_fmac_f32_e32 v62, v56, v64
	v_min_f32_e32 v65, 0, v62
	v_mul_f32_e64 v62, |v62|, s46
	v_exp_f32_e32 v68, v62
	s_nop 0
	v_add_f32_e32 v69, 1.0, v68
	v_add_f32_e32 v62, -1.0, v69
	v_sub_f32_e32 v63, v62, v69
	v_add_f32_e32 v63, 1.0, v63
	v_sub_f32_e32 v62, v68, v62
	v_add_f32_e32 v70, v62, v63
	v_frexp_mant_f32_e32 v62, v69
	v_cmp_gt_f32_e32 vcc, s47, v62
	v_cvt_f64_f32_e32 v[62:63], v69
	v_frexp_exp_i32_f64_e32 v62, v[62:63]
	v_subbrev_co_u32_e32 v62, vcc, 0, v62, vcc
	v_sub_u32_e32 v63, 0, v62
	v_ldexp_f32 v69, v69, v63
	v_ldexp_f32 v63, v70, v63
	v_add_f32_e32 v70, -1.0, v69
	v_add_f32_e32 v71, 1.0, v70
	v_sub_f32_e32 v71, v69, v71
	v_add_f32_e32 v71, v63, v71
	v_add_f32_e32 v72, v70, v71
	v_sub_f32_e32 v70, v72, v70
	v_sub_f32_e32 v70, v71, v70
	v_add_f32_e32 v71, 1.0, v69
	v_add_f32_e32 v73, -1.0, v71
	v_sub_f32_e32 v69, v69, v73
	v_add_f32_e32 v63, v63, v69
	v_add_f32_e32 v69, v71, v63
	v_sub_f32_e32 v71, v69, v71
	v_sub_f32_e32 v63, v63, v71
	v_rcp_f32_e32 v71, v69
	v_cvt_f32_i32_e32 v62, v62
	v_cmp_neq_f32_e32 vcc, s49, v68
	v_mul_f32_e32 v73, v72, v71
	v_mul_f32_e32 v74, v69, v73
	v_fma_f32 v75, v73, v69, -v74
	v_fmac_f32_e32 v75, v73, v63
	v_add_f32_e32 v76, v74, v75
	v_sub_f32_e32 v77, v72, v76
	v_sub_f32_e32 v72, v72, v77
	v_sub_f32_e32 v74, v76, v74
	v_sub_f32_e32 v72, v72, v76
	v_add_f32_e32 v70, v70, v72
	v_sub_f32_e32 v72, v74, v75
	v_add_f32_e32 v70, v72, v70
	v_add_f32_e32 v72, v77, v70
	v_mul_f32_e32 v74, v71, v72
	v_mul_f32_e32 v75, v69, v74
	v_fma_f32 v69, v74, v69, -v75
	v_fmac_f32_e32 v69, v74, v63
	v_sub_f32_e32 v63, v77, v72
	v_add_f32_e32 v63, v70, v63
	v_add_f32_e32 v70, v75, v69
	v_sub_f32_e32 v76, v72, v70
	v_sub_f32_e32 v72, v72, v76
	v_sub_f32_e32 v75, v70, v75
	v_sub_f32_e32 v70, v72, v70
	v_add_f32_e32 v63, v63, v70
	v_sub_f32_e32 v69, v75, v69
	v_add_f32_e32 v63, v69, v63
	v_add_f32_e32 v69, v73, v74
	v_add_f32_e32 v63, v76, v63
	v_sub_f32_e32 v70, v69, v73
	v_mul_f32_e32 v63, v71, v63
	v_sub_f32_e32 v70, v74, v70
	v_add_f32_e32 v63, v70, v63
	v_mul_f32_e32 v73, 0x3f317218, v62
	v_add_f32_e32 v70, v69, v63
	v_fma_f32 v74, v62, s48, -v73
	v_mul_f32_e32 v71, v70, v70
	v_fmac_f32_e32 v74, 0xb102e308, v62
	v_sub_f32_e32 v62, v70, v69
	v_fmamk_f32 v72, v71, 0x3e9b6dac, v171
	v_sub_f32_e32 v62, v63, v62
	v_add_f32_e32 v63, v73, v74
	v_fmaak_f32 v72, v71, v72, 0x3f2aaada
	v_sub_f32_e32 v69, v63, v73
	v_ldexp_f32 v73, v70, 1
	v_mul_f32_e32 v70, v70, v71
	v_mul_f32_e32 v70, v70, v72
	v_add_f32_e32 v71, v73, v70
	v_sub_f32_e32 v72, v71, v73
	v_ldexp_f32 v62, v62, 1
	v_sub_f32_e32 v70, v70, v72
	v_add_f32_e32 v62, v62, v70
	v_add_f32_e32 v70, v71, v62
	v_sub_f32_e32 v71, v70, v71
	v_sub_f32_e32 v62, v62, v71
	v_add_f32_e32 v71, v63, v70
	v_sub_f32_e32 v72, v71, v63
	v_sub_f32_e32 v73, v71, v72
	v_sub_f32_e32 v69, v74, v69
	v_sub_f32_e32 v63, v63, v73
	v_sub_f32_e32 v70, v70, v72
	v_add_f32_e32 v63, v70, v63
	v_add_f32_e32 v70, v69, v62
	v_sub_f32_e32 v72, v70, v69
	v_sub_f32_e32 v73, v70, v72
	v_sub_f32_e32 v69, v69, v73
	v_sub_f32_e32 v62, v62, v72
	v_add_f32_e32 v63, v70, v63
	v_add_f32_e32 v62, v62, v69
	v_add_f32_e32 v69, v71, v63
	v_sub_f32_e32 v70, v69, v71
	v_sub_f32_e32 v63, v63, v70
	v_add_f32_e32 v62, v62, v63
	v_add_f32_e32 v62, v69, v62
	v_cndmask_b32_e32 v62, v178, v62, vcc
	v_cmp_ngt_f32_e32 vcc, -1.0, v68
	s_nop 1
	v_cndmask_b32_e32 v62, v179, v62, vcc
	v_cmp_neq_f32_e32 vcc, -1.0, v68
	s_nop 1
	v_cndmask_b32_e32 v62, v180, v62, vcc
	v_cmp_lt_f32_e64 vcc, |v68|, s50
	s_nop 1
	v_cndmask_b32_e32 v62, v62, v68, vcc
	v_sub_f32_e32 v62, v65, v62
	global_store_dword v[60:61], v62, off offset:-32
	global_load_dword v63, v160, s[60:61] offset:4
	s_waitcnt vmcnt(0)
; template <bool SWAP> DI void inproj_tile(const Params& p, int layer, int tm, int tn, bf16_t* smem) {
;     ...
;         } else {
; #pragma unroll
;           for (int r = 0; r < 4; ++r) { const int h = (quad - 2) * 4 + r; const float xx = acc[i][1][r] * rs + p.b_forget[layer * 8 + h]; lf[h] = fminf(xx, 0.f) - log1pf(__expf(-fabsf(xx))); }
;         }
	v_fmac_f32_e32 v63, v57, v64
	v_min_f32_e32 v62, 0, v63
	v_mul_f32_e64 v63, |v63|, s46
	v_exp_f32_e32 v63, v63
	s_nop 0
	v_add_f32_e32 v65, 1.0, v63
	v_add_f32_e32 v68, -1.0, v65
	v_sub_f32_e32 v69, v68, v65
	v_add_f32_e32 v69, 1.0, v69
	v_sub_f32_e32 v68, v63, v68
	v_add_f32_e32 v70, v68, v69
	v_frexp_mant_f32_e32 v68, v65
	v_cmp_gt_f32_e32 vcc, s47, v68
	v_cvt_f64_f32_e32 v[68:69], v65
	v_frexp_exp_i32_f64_e32 v68, v[68:69]
	v_subbrev_co_u32_e32 v68, vcc, 0, v68, vcc
	v_sub_u32_e32 v69, 0, v68
	v_ldexp_f32 v65, v65, v69
	v_ldexp_f32 v69, v70, v69
	v_add_f32_e32 v70, -1.0, v65
	v_add_f32_e32 v71, 1.0, v70
	v_sub_f32_e32 v71, v65, v71
	v_add_f32_e32 v71, v69, v71
	v_add_f32_e32 v72, v70, v71
	v_sub_f32_e32 v70, v72, v70
	v_sub_f32_e32 v70, v71, v70
	v_add_f32_e32 v71, 1.0, v65
	v_add_f32_e32 v73, -1.0, v71
	v_sub_f32_e32 v65, v65, v73
	v_add_f32_e32 v65, v69, v65
	v_add_f32_e32 v69, v71, v65
	v_sub_f32_e32 v71, v69, v71
	v_sub_f32_e32 v65, v65, v71
	v_rcp_f32_e32 v71, v69
	v_cvt_f32_i32_e32 v68, v68
	v_cmp_neq_f32_e32 vcc, s49, v63
	v_mul_f32_e32 v73, v72, v71
	v_mul_f32_e32 v74, v69, v73
	v_fma_f32 v75, v73, v69, -v74
	v_fmac_f32_e32 v75, v73, v65
	v_add_f32_e32 v76, v74, v75
	v_sub_f32_e32 v77, v72, v76
	v_sub_f32_e32 v72, v72, v77
	v_sub_f32_e32 v74, v76, v74
	v_sub_f32_e32 v72, v72, v76
	v_add_f32_e32 v70, v70, v72
	v_sub_f32_e32 v72, v74, v75
	v_add_f32_e32 v70, v72, v70
	v_add_f32_e32 v72, v77, v70
	v_mul_f32_e32 v74, v71, v72
	v_mul_f32_e32 v75, v69, v74
	v_fma_f32 v69, v74, v69, -v75
	v_fmac_f32_e32 v69, v74, v65
	v_sub_f32_e32 v65, v77, v72
	v_add_f32_e32 v65, v70, v65
	v_add_f32_e32 v70, v75, v69
	v_sub_f32_e32 v76, v72, v70
	v_sub_f32_e32 v72, v72, v76
	v_sub_f32_e32 v75, v70, v75
	v_sub_f32_e32 v70, v72, v70
	v_add_f32_e32 v65, v65, v70
	v_sub_f32_e32 v69, v75, v69
	v_add_f32_e32 v65, v69, v65
	v_add_f32_e32 v69, v73, v74
	v_add_f32_e32 v65, v76, v65
	v_sub_f32_e32 v70, v69, v73
	v_mul_f32_e32 v65, v71, v65
	v_sub_f32_e32 v70, v74, v70
	v_add_f32_e32 v65, v70, v65
	v_mul_f32_e32 v73, 0x3f317218, v68
	v_add_f32_e32 v70, v69, v65
	v_fma_f32 v74, v68, s48, -v73
	v_mul_f32_e32 v71, v70, v70
	v_fmac_f32_e32 v74, 0xb102e308, v68
	v_sub_f32_e32 v68, v70, v69
	v_fmamk_f32 v72, v71, 0x3e9b6dac, v171
	v_sub_f32_e32 v65, v65, v68
	v_add_f32_e32 v68, v73, v74
	v_fmaak_f32 v72, v71, v72, 0x3f2aaada
	v_sub_f32_e32 v69, v68, v73
	v_ldexp_f32 v73, v70, 1
	v_mul_f32_e32 v70, v70, v71
	v_mul_f32_e32 v70, v70, v72
	v_add_f32_e32 v71, v73, v70
	v_sub_f32_e32 v72, v71, v73
	v_ldexp_f32 v65, v65, 1
	v_sub_f32_e32 v70, v70, v72
	v_add_f32_e32 v65, v65, v70
	v_add_f32_e32 v70, v71, v65
	v_sub_f32_e32 v71, v70, v71
	v_sub_f32_e32 v65, v65, v71
	v_add_f32_e32 v71, v68, v70
	v_sub_f32_e32 v72, v71, v68
	v_sub_f32_e32 v73, v71, v72
	v_sub_f32_e32 v69, v74, v69
	v_sub_f32_e32 v68, v68, v73
	v_sub_f32_e32 v70, v70, v72
	v_add_f32_e32 v68, v70, v68
	v_add_f32_e32 v70, v69, v65
	v_sub_f32_e32 v72, v70, v69
	v_sub_f32_e32 v73, v70, v72
	v_sub_f32_e32 v69, v69, v73
	v_sub_f32_e32 v65, v65, v72
	v_add_f32_e32 v68, v70, v68
	v_add_f32_e32 v65, v65, v69
	v_add_f32_e32 v69, v71, v68
	v_sub_f32_e32 v70, v69, v71
	v_sub_f32_e32 v68, v68, v70
	v_add_f32_e32 v65, v65, v68
	v_add_f32_e32 v65, v69, v65
	v_cndmask_b32_e32 v65, v178, v65, vcc
	v_cmp_ngt_f32_e32 vcc, -1.0, v63
	s_nop 1
	v_cndmask_b32_e32 v65, v179, v65, vcc
	v_cmp_neq_f32_e32 vcc, -1.0, v63
	s_nop 1
	v_cndmask_b32_e32 v65, v180, v65, vcc
	v_cmp_lt_f32_e64 vcc, |v63|, s50
	s_nop 1
	v_cndmask_b32_e32 v63, v65, v63, vcc
	v_sub_f32_e32 v62, v62, v63
	global_store_dword v[60:61], v62, off offset:-28
	global_load_dword v63, v160, s[60:61] offset:8
	s_waitcnt vmcnt(0)
	v_fmac_f32_e32 v63, v58, v64
	v_min_f32_e32 v62, 0, v63
	v_mul_f32_e64 v63, |v63|, s46
	v_exp_f32_e32 v63, v63
	s_nop 0
	v_add_f32_e32 v65, 1.0, v63
	v_add_f32_e32 v68, -1.0, v65
	v_sub_f32_e32 v69, v68, v65
	v_add_f32_e32 v69, 1.0, v69
	v_sub_f32_e32 v68, v63, v68
	v_add_f32_e32 v70, v68, v69
	v_frexp_mant_f32_e32 v68, v65
	v_cmp_gt_f32_e32 vcc, s47, v68
	v_cvt_f64_f32_e32 v[68:69], v65
	v_frexp_exp_i32_f64_e32 v68, v[68:69]
	v_subbrev_co_u32_e32 v68, vcc, 0, v68, vcc
	v_sub_u32_e32 v69, 0, v68
	v_ldexp_f32 v65, v65, v69
	v_ldexp_f32 v69, v70, v69
	v_add_f32_e32 v70, -1.0, v65
	v_add_f32_e32 v71, 1.0, v70
	v_sub_f32_e32 v71, v65, v71
	v_add_f32_e32 v71, v69, v71
	v_add_f32_e32 v72, v70, v71
	v_sub_f32_e32 v70, v72, v70
	v_sub_f32_e32 v70, v71, v70
	v_add_f32_e32 v71, 1.0, v65
	v_add_f32_e32 v73, -1.0, v71
	v_sub_f32_e32 v65, v65, v73
	v_add_f32_e32 v65, v69, v65
	v_add_f32_e32 v69, v71, v65
	v_sub_f32_e32 v71, v69, v71
	v_sub_f32_e32 v65, v65, v71
	v_rcp_f32_e32 v71, v69
	v_cvt_f32_i32_e32 v68, v68
	v_cmp_neq_f32_e32 vcc, s49, v63
	v_mul_f32_e32 v73, v72, v71
	v_mul_f32_e32 v74, v69, v73
	v_fma_f32 v75, v73, v69, -v74
	v_fmac_f32_e32 v75, v73, v65
	v_add_f32_e32 v76, v74, v75
	v_sub_f32_e32 v77, v72, v76
	v_sub_f32_e32 v72, v72, v77
	v_sub_f32_e32 v74, v76, v74
	v_sub_f32_e32 v72, v72, v76
	v_add_f32_e32 v70, v70, v72
	v_sub_f32_e32 v72, v74, v75
	v_add_f32_e32 v70, v72, v70
	v_add_f32_e32 v72, v77, v70
	v_mul_f32_e32 v74, v71, v72
	v_mul_f32_e32 v75, v69, v74
	v_fma_f32 v69, v74, v69, -v75
	v_fmac_f32_e32 v69, v74, v65
	v_sub_f32_e32 v65, v77, v72
	v_add_f32_e32 v65, v70, v65
	v_add_f32_e32 v70, v75, v69
	v_sub_f32_e32 v76, v72, v70
	v_sub_f32_e32 v72, v72, v76
	v_sub_f32_e32 v75, v70, v75
	v_sub_f32_e32 v70, v72, v70
	v_add_f32_e32 v65, v65, v70
	v_sub_f32_e32 v69, v75, v69
; template <bool SWAP> DI void inproj_tile(const Params& p, int layer, int tm, int tn, bf16_t* smem) {
;     ...
;         } else {
; #pragma unroll
;           for (int r = 0; r < 4; ++r) { const int h = (quad - 2) * 4 + r; const float xx = acc[i][1][r] * rs + p.b_forget[layer * 8 + h]; lf[h] = fminf(xx, 0.f) - log1pf(__expf(-fabsf(xx))); }
;         }
	v_add_f32_e32 v65, v69, v65
	v_add_f32_e32 v69, v73, v74
	v_add_f32_e32 v65, v76, v65
	v_sub_f32_e32 v70, v69, v73
	v_mul_f32_e32 v65, v71, v65
	v_sub_f32_e32 v70, v74, v70
	v_add_f32_e32 v65, v70, v65
	v_mul_f32_e32 v73, 0x3f317218, v68
	v_add_f32_e32 v70, v69, v65
	v_fma_f32 v74, v68, s48, -v73
	v_mul_f32_e32 v71, v70, v70
	v_fmac_f32_e32 v74, 0xb102e308, v68
	v_sub_f32_e32 v68, v70, v69
	v_fmamk_f32 v72, v71, 0x3e9b6dac, v171
	v_sub_f32_e32 v65, v65, v68
	v_add_f32_e32 v68, v73, v74
	v_fmaak_f32 v72, v71, v72, 0x3f2aaada
	v_sub_f32_e32 v69, v68, v73
	v_ldexp_f32 v73, v70, 1
	v_mul_f32_e32 v70, v70, v71
	v_mul_f32_e32 v70, v70, v72
	v_add_f32_e32 v71, v73, v70
	v_sub_f32_e32 v72, v71, v73
	v_ldexp_f32 v65, v65, 1
	v_sub_f32_e32 v70, v70, v72
	v_add_f32_e32 v65, v65, v70
	v_add_f32_e32 v70, v71, v65
	v_sub_f32_e32 v71, v70, v71
	v_sub_f32_e32 v65, v65, v71
	v_add_f32_e32 v71, v68, v70
	v_sub_f32_e32 v72, v71, v68
	v_sub_f32_e32 v73, v71, v72
	v_sub_f32_e32 v69, v74, v69
	v_sub_f32_e32 v68, v68, v73
	v_sub_f32_e32 v70, v70, v72
	v_add_f32_e32 v68, v70, v68
	v_add_f32_e32 v70, v69, v65
	v_sub_f32_e32 v72, v70, v69
	v_sub_f32_e32 v73, v70, v72
	v_sub_f32_e32 v69, v69, v73
	v_sub_f32_e32 v65, v65, v72
	v_add_f32_e32 v68, v70, v68
	v_add_f32_e32 v65, v65, v69
	v_add_f32_e32 v69, v71, v68
	v_sub_f32_e32 v70, v69, v71
	v_sub_f32_e32 v68, v68, v70
	v_add_f32_e32 v65, v65, v68
	v_add_f32_e32 v65, v69, v65
	v_cndmask_b32_e32 v65, v178, v65, vcc
	v_cmp_ngt_f32_e32 vcc, -1.0, v63
	s_nop 1
	v_cndmask_b32_e32 v65, v179, v65, vcc
	v_cmp_neq_f32_e32 vcc, -1.0, v63
	s_nop 1
	v_cndmask_b32_e32 v65, v180, v65, vcc
	v_cmp_lt_f32_e64 vcc, |v63|, s50
	s_nop 1
	v_cndmask_b32_e32 v63, v65, v63, vcc
	v_sub_f32_e32 v62, v62, v63
	global_store_dword v[60:61], v62, off offset:-24
	global_load_dword v63, v160, s[60:61] offset:12
	s_waitcnt vmcnt(0)
	v_fmac_f32_e32 v63, v59, v64
	v_min_f32_e32 v62, 0, v63
	v_mul_f32_e64 v63, |v63|, s46
	v_exp_f32_e32 v63, v63
	s_nop 0
	v_add_f32_e32 v65, 1.0, v63
	v_add_f32_e32 v68, -1.0, v65
	v_sub_f32_e32 v69, v68, v65
	v_add_f32_e32 v69, 1.0, v69
	v_sub_f32_e32 v68, v63, v68
	v_add_f32_e32 v70, v68, v69
	v_frexp_mant_f32_e32 v68, v65
	v_cmp_gt_f32_e32 vcc, s47, v68
	v_cvt_f64_f32_e32 v[68:69], v65
	v_frexp_exp_i32_f64_e32 v68, v[68:69]
	v_subbrev_co_u32_e32 v68, vcc, 0, v68, vcc
	v_sub_u32_e32 v69, 0, v68
	v_ldexp_f32 v65, v65, v69
	v_ldexp_f32 v69, v70, v69
	v_add_f32_e32 v70, -1.0, v65
	v_add_f32_e32 v71, 1.0, v70
	v_sub_f32_e32 v71, v65, v71
	v_add_f32_e32 v71, v69, v71
	v_add_f32_e32 v72, v70, v71
	v_sub_f32_e32 v70, v72, v70
	v_sub_f32_e32 v70, v71, v70
	v_add_f32_e32 v71, 1.0, v65
	v_add_f32_e32 v73, -1.0, v71
	v_sub_f32_e32 v65, v65, v73
	v_add_f32_e32 v65, v69, v65
	v_add_f32_e32 v69, v71, v65
	v_sub_f32_e32 v71, v69, v71
	v_sub_f32_e32 v65, v65, v71
	v_rcp_f32_e32 v71, v69
	v_cvt_f32_i32_e32 v68, v68
	v_cmp_neq_f32_e32 vcc, s49, v63
	v_mul_f32_e32 v73, v72, v71
	v_mul_f32_e32 v74, v69, v73
	v_fma_f32 v75, v73, v69, -v74
	v_fmac_f32_e32 v75, v73, v65
	v_add_f32_e32 v76, v74, v75
	v_sub_f32_e32 v77, v72, v76
	v_sub_f32_e32 v72, v72, v77
	v_sub_f32_e32 v74, v76, v74
	v_sub_f32_e32 v72, v72, v76
	v_add_f32_e32 v70, v70, v72
	v_sub_f32_e32 v72, v74, v75
	v_add_f32_e32 v70, v72, v70
	v_add_f32_e32 v72, v77, v70
	v_mul_f32_e32 v74, v71, v72
	v_mul_f32_e32 v75, v69, v74
	v_fma_f32 v69, v74, v69, -v75
	v_fmac_f32_e32 v69, v74, v65
	v_sub_f32_e32 v65, v77, v72
	v_add_f32_e32 v65, v70, v65
	v_add_f32_e32 v70, v75, v69
	v_sub_f32_e32 v76, v72, v70
	v_sub_f32_e32 v72, v72, v76
	v_sub_f32_e32 v75, v70, v75
	v_sub_f32_e32 v70, v72, v70
	v_add_f32_e32 v65, v65, v70
	v_sub_f32_e32 v69, v75, v69
	v_add_f32_e32 v65, v69, v65
	v_add_f32_e32 v69, v73, v74
	v_add_f32_e32 v65, v76, v65
	v_sub_f32_e32 v70, v69, v73
	v_mul_f32_e32 v65, v71, v65
	v_sub_f32_e32 v70, v74, v70
	v_add_f32_e32 v65, v70, v65
	v_mul_f32_e32 v73, 0x3f317218, v68
	v_add_f32_e32 v70, v69, v65
	v_fma_f32 v74, v68, s48, -v73
	v_mul_f32_e32 v71, v70, v70
	v_fmac_f32_e32 v74, 0xb102e308, v68
	v_sub_f32_e32 v68, v70, v69
	v_fmamk_f32 v72, v71, 0x3e9b6dac, v171
	v_sub_f32_e32 v65, v65, v68
	v_add_f32_e32 v68, v73, v74
	v_fmaak_f32 v72, v71, v72, 0x3f2aaada
	v_sub_f32_e32 v69, v68, v73
	v_ldexp_f32 v73, v70, 1
	v_mul_f32_e32 v70, v70, v71
	v_mul_f32_e32 v70, v70, v72
	v_add_f32_e32 v71, v73, v70
	v_sub_f32_e32 v72, v71, v73
	v_ldexp_f32 v65, v65, 1
	v_sub_f32_e32 v70, v70, v72
	v_add_f32_e32 v65, v65, v70
	v_add_f32_e32 v70, v71, v65
	v_sub_f32_e32 v71, v70, v71
	v_sub_f32_e32 v65, v65, v71
	v_add_f32_e32 v71, v68, v70
	v_sub_f32_e32 v72, v71, v68
	v_sub_f32_e32 v73, v71, v72
	v_sub_f32_e32 v69, v74, v69
	v_sub_f32_e32 v68, v68, v73
	v_sub_f32_e32 v70, v70, v72
	v_add_f32_e32 v68, v70, v68
	v_add_f32_e32 v70, v69, v65
	v_sub_f32_e32 v72, v70, v69
	v_sub_f32_e32 v73, v70, v72
	v_sub_f32_e32 v69, v69, v73
	v_sub_f32_e32 v65, v65, v72
	v_add_f32_e32 v68, v70, v68
	v_add_f32_e32 v65, v65, v69
	v_add_f32_e32 v69, v71, v68
	v_sub_f32_e32 v70, v69, v71
	v_sub_f32_e32 v68, v68, v70
	v_add_f32_e32 v65, v65, v68
	v_add_f32_e32 v65, v69, v65
	v_cndmask_b32_e32 v65, v178, v65, vcc
	v_cmp_ngt_f32_e32 vcc, -1.0, v63
	s_nop 1
	v_cndmask_b32_e32 v65, v179, v65, vcc
	v_cmp_neq_f32_e32 vcc, -1.0, v63
	s_nop 1
	v_cndmask_b32_e32 v65, v180, v65, vcc
	v_cmp_lt_f32_e64 vcc, |v63|, s50
	s_nop 1
	v_cndmask_b32_e32 v63, v65, v63, vcc
	v_sub_f32_e32 v62, v62, v63
	global_store_dword v[60:61], v62, off offset:-20

; DI unsigned pk2(float lo, float hi) { f32x2 v = {lo, hi}; return __builtin_bit_cast(unsigned, __builtin_convertvector(v, bfx2)); }
; DI float sigmoidf_(float x) { return 1.f / (1.f + __expf(-x)); }
; template <bool SWAP> DI void inproj_tile(const Params& p, int layer, int tm, int tn, bf16_t* smem) {
;     ...
;       for (int i = 0; i < 8; ++i) {
;         const int t = trow0 + i * 16 + l15; const float rs = rstd_from16(ssq + (size_t)t * 16, 1.f / 1024.f);
;         float* gt = (float*)(p.ws + O_GATES) + (size_t)t * 24; float* lf = (float*)(p.ws + O_LOGF) + (size_t)t * 8;
; #pragma unroll
;         for (int r = 0; r < 4; ++r) gt[quad * 4 + r] = sigmoidf_(acc[i][0][r] * rs);
;         if (quad < 2) {
; #pragma unroll
;           for (int r = 0; r < 4; ++r) gt[16 + quad * 4 + r] = sigmoidf_(acc[i][1][r] * rs);
;         } else {
; #pragma unroll
;           for (int r = 0; r < 4; ++r) { const int h = (quad - 2) * 4 + r; const float xx = acc[i][1][r] * rs + p.b_forget[layer * 8 + h]; lf[h] = fminf(xx, 0.f) - log1pf(__expf(-fabsf(xx))); }
;         }
;         const float* rp = (const float*)(p.ws + O_ROPE16) + (size_t)t * 32 + quad * 8; float o1[4], o2[4];
; #pragma unroll
;         for (int r = 0; r < 4; ++r) { const float cs = rp[2 * r], sn = rp[2 * r + 1], x1 = acc[i][2][r] * rs, x2 = acc[i][3][r] * rs; o1[r] = x1 * cs - x2 * sn; o2[r] = x2 * cs + x1 * sn; }
;         bf16_t* kp = (bf16_t*)(p.ws + O_MLAKPE) + (size_t)t * 32 + quad * 4;
;         *(u32x2*)kp = (u32x2){pk2(o1[0], o1[1]), pk2(o1[2], o1[3])}; *(u32x2*)(kp + 16) = (u32x2){pk2(o2[0], o2[1]), pk2(o2[2], o2[3])};
.LBB0_1315:
	s_or_b64 exec, exec, s[2:3]
	s_nop 0
	v_lshl_add_u64 v[56:57], v[66:67], 2, s[10:11]
	v_mov_b32_e32 v105, v161
	v_lshl_add_u64 v[60:61], v[56:57], 0, v[104:105]
	global_load_dwordx4 v[56:59], v[60:61], off offset:16
	s_nop 0
	global_load_dwordx4 v[60:63], v[60:61], off
	v_pk_mul_f32 v[48:49], v[48:49], v[64:65] op_sel_hi:[1,0]
	v_pk_mul_f32 v[52:53], v[52:53], v[64:65] op_sel_hi:[1,0]
	v_pk_mul_f32 v[50:51], v[50:51], v[64:65] op_sel_hi:[1,0]
	v_readlane_b32 s2, v240, 32
	v_readlane_b32 s3, v240, 33
	v_mov_b32_e32 v113, v161
	s_waitcnt vmcnt(0)
	v_mov_b32_e32 v69, v62
	v_mov_b32_e32 v62, v61
	v_mov_b32_e32 v68, v60
	v_pk_mul_f32 v[60:61], v[48:49], v[62:63]
	s_nop 0
	v_pk_fma_f32 v[60:61], v[52:53], v[68:69], v[60:61] neg_lo:[0,0,1] neg_hi:[0,0,1]
	v_pk_mul_f32 v[52:53], v[52:53], v[62:63]
	s_nop 0
	v_pk_fma_f32 v[48:49], v[48:49], v[68:69], v[52:53]
	v_pk_mul_f32 v[52:53], v[54:55], v[64:65] op_sel_hi:[1,0]
	v_mov_b32_e32 v55, v58
	v_mov_b32_e32 v58, v57
	v_mov_b32_e32 v54, v56
	v_pk_mul_f32 v[56:57], v[50:51], v[58:59]
	v_or_b32_e32 v64, 0x50, v128
	v_pk_fma_f32 v[56:57], v[52:53], v[54:55], v[56:57] neg_lo:[0,0,1] neg_hi:[0,0,1]
	v_pk_mul_f32 v[52:53], v[52:53], v[58:59]
	v_cvt_pk_bf16_f32 v48, v48, v49
	v_pk_fma_f32 v[50:51], v[50:51], v[54:55], v[52:53]
	v_lshl_add_u64 v[52:53], v[66:67], 1, s[2:3]
	v_lshl_add_u64 v[52:53], v[52:53], 0, v[112:113]
	v_cvt_pk_bf16_f32 v49, v50, v51
	v_ashrrev_i32_e32 v65, 31, v64
	v_cvt_pk_bf16_f32 v54, v60, v61
	v_cvt_pk_bf16_f32 v55, v56, v57
	global_store_dwordx2 v[52:53], v[48:49], off offset:32
	v_lshlrev_b64 v[48:49], 6, v[64:65]
	global_store_dwordx2 v[52:53], v[54:55], off
	v_lshl_add_u64 v[60:61], s[6:7], 0, v[48:49]
	v_bfe_u32 v244, v60, 6, 8
	v_lshlrev_b32_e32 v244, 3, v244
	v_add_u32_e32 v244, 0x24010, v244
	v_or_b32_e32 v246, 3, v60
	ds_read_b64 v[248:249], v244
	s_waitcnt lgkmcnt(0)
	v_cmp_ne_u32_e64 s[100:101], v248, v246
	s_nop 1
	s_and_saveexec_b64 s[98:99], s[100:101]
	s_cbranch_execz .LrcA1_13
	global_load_dwordx4 v[48:51], v[60:61], off offset:48
	global_load_dwordx4 v[52:55], v[60:61], off offset:32
	global_load_dwordx4 v[56:59], v[60:61], off offset:16
	s_nop 0
	global_load_dwordx4 v[60:63], v[60:61], off
	s_waitcnt vmcnt(2)
	v_add_f32_e32 v52, v52, v53
	v_add_f32_e32 v54, v54, v55
	s_waitcnt vmcnt(0)
	v_mov_b32_e32 v66, v61
	v_mov_b32_e32 v67, v62
	v_mov_b32_e32 v61, v63
	v_mov_b32_e32 v62, v57
	v_mov_b32_e32 v63, v58
	v_mov_b32_e32 v57, v59
	v_pk_add_f32 v[60:61], v[66:67], v[60:61]
	v_pk_add_f32 v[56:57], v[62:63], v[56:57]
	v_pk_add_f32 v[60:61], v[60:61], v[60:61] op_sel:[0,1] op_sel_hi:[1,0]
	v_pk_add_f32 v[56:57], v[56:57], v[56:57] op_sel:[0,1] op_sel_hi:[1,0]
	v_mov_b32_e32 v61, v48
	v_mov_b32_e32 v57, v49
	v_mov_b32_e32 v53, v50
	v_mov_b32_e32 v55, v51
	v_pk_add_f32 v[48:49], v[60:61], v[56:57]
	v_pk_add_f32 v[50:51], v[52:53], v[54:55]
	s_nop 0
	v_pk_add_f32 v[48:49], v[48:49], v[50:51]
	v_add_f32_e32 v48, v48, v49
	v_fmamk_f32 v48, v48, 0x3a800000, v170
	v_cmp_gt_f32_e32 vcc, s43, v48
	v_mul_f32_e32 v49, 0x4b800000, v48
	v_cndmask_b32_e32 v48, v48, v49, vcc
	v_rsq_f32_e32 v48, v48
	v_mul_f32_e32 v49, 0x45800000, v48
	v_cndmask_b32_e32 v48, v48, v49, vcc
	s_nop 0
	v_mov_b32_e32 v247, v48
	ds_write_b64 v244, v[246:247]
.LrcA1_13:
	s_or_b64 exec, exec, s[98:99]
	s_waitcnt vmcnt(0)
	v_cndmask_b32_e64 v48, v249, v48, s[100:101]
	v_readlane_b32 s2, v240, 35
	v_readlane_b32 s3, v240, 36
	v_mov_b64_e32 v[50:51], s[2:3]
	v_mad_i64_i32 v[52:53], s[2:3], v64, s45, v[50:51]
	v_lshlrev_b64 v[50:51], 5, v[64:65]
	v_lshl_add_u64 v[52:53], v[52:53], 0, v[160:161]
	v_mul_f32_e32 v44, v44, v48
	v_mul_f32_e32 v45, v45, v48
	v_mul_f32_e32 v44, 0xbfb8aa3b, v44
	v_mul_f32_e32 v45, 0xbfb8aa3b, v45
	v_exp_f32_e32 v44, v44
	v_exp_f32_e32 v45, v45
	v_mul_f32_e32 v46, v46, v48
	v_mul_f32_e32 v47, v47, v48
	v_mul_f32_e32 v46, 0xbfb8aa3b, v46
	v_pk_add_f32 v[44:45], v[44:45], 1.0 op_sel_hi:[1,0]
	v_mul_f32_e32 v47, 0xbfb8aa3b, v47
	v_div_scale_f32 v49, s[2:3], v45, v45, 1.0
	v_rcp_f32_e32 v54, v49
	v_exp_f32_e32 v46, v46
	v_exp_f32_e32 v47, v47
	v_fma_f32 v55, -v49, v54, 1.0
	v_fmac_f32_e32 v54, v55, v54
	v_div_scale_f32 v55, vcc, 1.0, v45, 1.0
	v_mul_f32_e32 v56, v55, v54
	v_fma_f32 v57, -v49, v56, v55
	v_fmac_f32_e32 v56, v57, v54
	v_fma_f32 v49, -v49, v56, v55
	v_div_fmas_f32 v49, v49, v54, v56
	v_div_fixup_f32 v45, v49, v45, 1.0
	v_div_scale_f32 v49, s[2:3], v44, v44, 1.0
	v_rcp_f32_e32 v54, v49
	v_pk_add_f32 v[46:47], v[46:47], 1.0 op_sel_hi:[1,0]
	v_fma_f32 v55, -v49, v54, 1.0
	v_fmac_f32_e32 v54, v55, v54
	v_div_scale_f32 v55, vcc, 1.0, v44, 1.0
	v_mul_f32_e32 v56, v55, v54
	v_fma_f32 v57, -v49, v56, v55
	v_fmac_f32_e32 v56, v57, v54
	v_fma_f32 v49, -v49, v56, v55
	v_div_fmas_f32 v49, v49, v54, v56
	v_div_fixup_f32 v44, v49, v44, 1.0
	v_div_scale_f32 v49, s[2:3], v47, v47, 1.0
	v_rcp_f32_e32 v54, v49
	s_nop 0
	v_fma_f32 v55, -v49, v54, 1.0
	v_fmac_f32_e32 v54, v55, v54
	v_div_scale_f32 v55, vcc, 1.0, v47, 1.0
	v_mul_f32_e32 v56, v55, v54
	v_fma_f32 v57, -v49, v56, v55
	v_fmac_f32_e32 v56, v57, v54
	v_fma_f32 v49, -v49, v56, v55
	v_div_fmas_f32 v49, v49, v54, v56
	v_div_fixup_f32 v47, v49, v47, 1.0
	v_div_scale_f32 v49, s[2:3], v46, v46, 1.0
	v_rcp_f32_e32 v54, v49
	s_nop 0
	v_fma_f32 v55, -v49, v54, 1.0
	v_fmac_f32_e32 v54, v55, v54
	v_div_scale_f32 v55, vcc, 1.0, v46, 1.0
	v_mul_f32_e32 v56, v55, v54
	v_fma_f32 v57, -v49, v56, v55
	v_fmac_f32_e32 v56, v57, v54
	v_fma_f32 v49, -v49, v56, v55
	v_div_fmas_f32 v49, v49, v54, v56
	v_div_fixup_f32 v46, v49, v46, 1.0
	global_store_dwordx4 v[52:53], v[44:47], off
	s_and_saveexec_b64 s[2:3], s[4:5]
	s_xor_b64 s[2:3], exec, s[2:3]
	s_cbranch_execz .LBB0_1317
; DI float sigmoidf_(float x) { return 1.f / (1.f + __expf(-x)); }
; template <bool SWAP> DI void inproj_tile(const Params& p, int layer, int tm, int tn, bf16_t* smem) {
;     ...
;         if (quad < 2) {
; #pragma unroll
;           for (int r = 0; r < 4; ++r) gt[16 + quad * 4 + r] = sigmoidf_(acc[i][1][r] * rs);
;         } else {
; #pragma unroll
;           for (int r = 0; r < 4; ++r) { const int h = (quad - 2) * 4 + r; const float xx = acc[i][1][r] * rs + p.b_forget[layer * 8 + h]; lf[h] = fminf(xx, 0.f) - log1pf(__expf(-fabsf(xx))); }
;         }
	v_readlane_b32 s52, v241, 8
	v_readlane_b32 s60, v241, 16
	v_readlane_b32 s61, v241, 17
	v_lshl_add_u64 v[44:45], s[8:9], 0, v[50:51]
	v_lshl_add_u64 v[44:45], v[44:45], 0, v[160:161]
	v_readlane_b32 s53, v241, 9
	v_readlane_b32 s54, v241, 10
	v_readlane_b32 s55, v241, 11
	global_load_dword v46, v160, s[60:61]
	v_readlane_b32 s56, v241, 12
	v_readlane_b32 s57, v241, 13
	v_readlane_b32 s58, v241, 14
	v_readlane_b32 s59, v241, 15
	v_readlane_b32 s62, v241, 18
	v_readlane_b32 s63, v241, 19
	v_readlane_b32 s64, v241, 20
	v_readlane_b32 s65, v241, 21
	v_readlane_b32 s66, v241, 22
	v_readlane_b32 s67, v241, 23
	s_waitcnt vmcnt(0)
	v_fmac_f32_e32 v46, v40, v48
	v_min_f32_e32 v49, 0, v46
	v_mul_f32_e64 v46, |v46|, s46
	v_exp_f32_e32 v52, v46
	s_nop 0
	v_add_f32_e32 v53, 1.0, v52
	v_add_f32_e32 v46, -1.0, v53
	v_sub_f32_e32 v47, v46, v53
	v_add_f32_e32 v47, 1.0, v47
	v_sub_f32_e32 v46, v52, v46
	v_add_f32_e32 v54, v46, v47
	v_frexp_mant_f32_e32 v46, v53
	v_cmp_gt_f32_e32 vcc, s47, v46
	v_cvt_f64_f32_e32 v[46:47], v53
	v_frexp_exp_i32_f64_e32 v46, v[46:47]
	v_subbrev_co_u32_e32 v46, vcc, 0, v46, vcc
	v_sub_u32_e32 v47, 0, v46
	v_ldexp_f32 v53, v53, v47
	v_ldexp_f32 v47, v54, v47
	v_add_f32_e32 v54, -1.0, v53
	v_add_f32_e32 v55, 1.0, v54
	v_sub_f32_e32 v55, v53, v55
	v_add_f32_e32 v55, v47, v55
	v_add_f32_e32 v56, v54, v55
	v_sub_f32_e32 v54, v56, v54
	v_sub_f32_e32 v54, v55, v54
	v_add_f32_e32 v55, 1.0, v53
	v_add_f32_e32 v57, -1.0, v55
	v_sub_f32_e32 v53, v53, v57
	v_add_f32_e32 v47, v47, v53
	v_add_f32_e32 v53, v55, v47
	v_sub_f32_e32 v55, v53, v55
	v_sub_f32_e32 v47, v47, v55
	v_rcp_f32_e32 v55, v53
	v_cvt_f32_i32_e32 v46, v46
	v_cmp_neq_f32_e32 vcc, s49, v52
	v_mul_f32_e32 v57, v56, v55
	v_mul_f32_e32 v58, v53, v57
	v_fma_f32 v59, v57, v53, -v58
	v_fmac_f32_e32 v59, v57, v47
	v_add_f32_e32 v60, v58, v59
	v_sub_f32_e32 v61, v56, v60
	v_sub_f32_e32 v56, v56, v61
	v_sub_f32_e32 v58, v60, v58
	v_sub_f32_e32 v56, v56, v60
	v_add_f32_e32 v54, v54, v56
	v_sub_f32_e32 v56, v58, v59
	v_add_f32_e32 v54, v56, v54
	v_add_f32_e32 v56, v61, v54
	v_mul_f32_e32 v58, v55, v56
	v_mul_f32_e32 v59, v53, v58
	v_fma_f32 v53, v58, v53, -v59
	v_fmac_f32_e32 v53, v58, v47
	v_sub_f32_e32 v47, v61, v56
	v_add_f32_e32 v47, v54, v47
	v_add_f32_e32 v54, v59, v53
	v_sub_f32_e32 v60, v56, v54
	v_sub_f32_e32 v56, v56, v60
	v_sub_f32_e32 v59, v54, v59
	v_sub_f32_e32 v54, v56, v54
	v_add_f32_e32 v47, v47, v54
	v_sub_f32_e32 v53, v59, v53
	v_add_f32_e32 v47, v53, v47
	v_add_f32_e32 v53, v57, v58
	v_add_f32_e32 v47, v60, v47
	v_sub_f32_e32 v54, v53, v57
	v_mul_f32_e32 v47, v55, v47
	v_sub_f32_e32 v54, v58, v54
	v_add_f32_e32 v47, v54, v47
	v_mul_f32_e32 v57, 0x3f317218, v46
	v_add_f32_e32 v54, v53, v47
	v_fma_f32 v58, v46, s48, -v57
	v_mul_f32_e32 v55, v54, v54
	v_fmac_f32_e32 v58, 0xb102e308, v46
	v_sub_f32_e32 v46, v54, v53
	v_fmamk_f32 v56, v55, 0x3e9b6dac, v171
	v_sub_f32_e32 v46, v47, v46
	v_add_f32_e32 v47, v57, v58
	v_fmaak_f32 v56, v55, v56, 0x3f2aaada
	v_sub_f32_e32 v53, v47, v57
	v_ldexp_f32 v57, v54, 1
	v_mul_f32_e32 v54, v54, v55
	v_mul_f32_e32 v54, v54, v56
	v_add_f32_e32 v55, v57, v54
	v_sub_f32_e32 v56, v55, v57
	v_ldexp_f32 v46, v46, 1
	v_sub_f32_e32 v54, v54, v56
	v_add_f32_e32 v46, v46, v54
	v_add_f32_e32 v54, v55, v46
	v_sub_f32_e32 v55, v54, v55
	v_sub_f32_e32 v46, v46, v55
	v_add_f32_e32 v55, v47, v54
	v_sub_f32_e32 v56, v55, v47
	v_sub_f32_e32 v57, v55, v56
	v_sub_f32_e32 v53, v58, v53
	v_sub_f32_e32 v47, v47, v57
	v_sub_f32_e32 v54, v54, v56
	v_add_f32_e32 v47, v54, v47
	v_add_f32_e32 v54, v53, v46
	v_sub_f32_e32 v56, v54, v53
	v_sub_f32_e32 v57, v54, v56
	v_sub_f32_e32 v53, v53, v57
	v_sub_f32_e32 v46, v46, v56
	v_add_f32_e32 v47, v54, v47
	v_add_f32_e32 v46, v46, v53
	v_add_f32_e32 v53, v55, v47
	v_sub_f32_e32 v54, v53, v55
	v_sub_f32_e32 v47, v47, v54
	v_add_f32_e32 v46, v46, v47
	v_add_f32_e32 v46, v53, v46
	v_cndmask_b32_e32 v46, v178, v46, vcc
	v_cmp_ngt_f32_e32 vcc, -1.0, v52
	s_nop 1
	v_cndmask_b32_e32 v46, v179, v46, vcc
	v_cmp_neq_f32_e32 vcc, -1.0, v52
	s_nop 1
	v_cndmask_b32_e32 v46, v180, v46, vcc
	v_cmp_lt_f32_e64 vcc, |v52|, s50
	s_nop 1
	v_cndmask_b32_e32 v46, v46, v52, vcc
	v_sub_f32_e32 v46, v49, v46
	global_store_dword v[44:45], v46, off offset:-32
	global_load_dword v47, v160, s[60:61] offset:4
	s_waitcnt vmcnt(0)
; template <bool SWAP> DI void inproj_tile(const Params& p, int layer, int tm, int tn, bf16_t* smem) {
;     ...
;         } else {
; #pragma unroll
;           for (int r = 0; r < 4; ++r) { const int h = (quad - 2) * 4 + r; const float xx = acc[i][1][r] * rs + p.b_forget[layer * 8 + h]; lf[h] = fminf(xx, 0.f) - log1pf(__expf(-fabsf(xx))); }
;         }
	v_fmac_f32_e32 v47, v41, v48
	v_min_f32_e32 v46, 0, v47
	v_mul_f32_e64 v47, |v47|, s46
	v_exp_f32_e32 v47, v47
	s_nop 0
	v_add_f32_e32 v49, 1.0, v47
	v_add_f32_e32 v52, -1.0, v49
	v_sub_f32_e32 v53, v52, v49
	v_add_f32_e32 v53, 1.0, v53
	v_sub_f32_e32 v52, v47, v52
	v_add_f32_e32 v54, v52, v53
	v_frexp_mant_f32_e32 v52, v49
	v_cmp_gt_f32_e32 vcc, s47, v52
	v_cvt_f64_f32_e32 v[52:53], v49
	v_frexp_exp_i32_f64_e32 v52, v[52:53]
	v_subbrev_co_u32_e32 v52, vcc, 0, v52, vcc
	v_sub_u32_e32 v53, 0, v52
	v_ldexp_f32 v49, v49, v53
	v_ldexp_f32 v53, v54, v53
	v_add_f32_e32 v54, -1.0, v49
	v_add_f32_e32 v55, 1.0, v54
	v_sub_f32_e32 v55, v49, v55
	v_add_f32_e32 v55, v53, v55
	v_add_f32_e32 v56, v54, v55
	v_sub_f32_e32 v54, v56, v54
	v_sub_f32_e32 v54, v55, v54
	v_add_f32_e32 v55, 1.0, v49
	v_add_f32_e32 v57, -1.0, v55
	v_sub_f32_e32 v49, v49, v57
	v_add_f32_e32 v49, v53, v49
	v_add_f32_e32 v53, v55, v49
	v_sub_f32_e32 v55, v53, v55
	v_sub_f32_e32 v49, v49, v55
	v_rcp_f32_e32 v55, v53
	v_cvt_f32_i32_e32 v52, v52
	v_cmp_neq_f32_e32 vcc, s49, v47
	v_mul_f32_e32 v57, v56, v55
	v_mul_f32_e32 v58, v53, v57
	v_fma_f32 v59, v57, v53, -v58
	v_fmac_f32_e32 v59, v57, v49
	v_add_f32_e32 v60, v58, v59
	v_sub_f32_e32 v61, v56, v60
	v_sub_f32_e32 v56, v56, v61
	v_sub_f32_e32 v58, v60, v58
	v_sub_f32_e32 v56, v56, v60
	v_add_f32_e32 v54, v54, v56
	v_sub_f32_e32 v56, v58, v59
	v_add_f32_e32 v54, v56, v54
	v_add_f32_e32 v56, v61, v54
	v_mul_f32_e32 v58, v55, v56
	v_mul_f32_e32 v59, v53, v58
	v_fma_f32 v53, v58, v53, -v59
	v_fmac_f32_e32 v53, v58, v49
	v_sub_f32_e32 v49, v61, v56
	v_add_f32_e32 v49, v54, v49
	v_add_f32_e32 v54, v59, v53
	v_sub_f32_e32 v60, v56, v54
	v_sub_f32_e32 v56, v56, v60
	v_sub_f32_e32 v59, v54, v59
	v_sub_f32_e32 v54, v56, v54
	v_add_f32_e32 v49, v49, v54
	v_sub_f32_e32 v53, v59, v53
	v_add_f32_e32 v49, v53, v49
	v_add_f32_e32 v53, v57, v58
	v_add_f32_e32 v49, v60, v49
	v_sub_f32_e32 v54, v53, v57
	v_mul_f32_e32 v49, v55, v49
	v_sub_f32_e32 v54, v58, v54
	v_add_f32_e32 v49, v54, v49
	v_mul_f32_e32 v57, 0x3f317218, v52
	v_add_f32_e32 v54, v53, v49
	v_fma_f32 v58, v52, s48, -v57
	v_mul_f32_e32 v55, v54, v54
	v_fmac_f32_e32 v58, 0xb102e308, v52
	v_sub_f32_e32 v52, v54, v53
	v_fmamk_f32 v56, v55, 0x3e9b6dac, v171
	v_sub_f32_e32 v49, v49, v52
	v_add_f32_e32 v52, v57, v58
	v_fmaak_f32 v56, v55, v56, 0x3f2aaada
	v_sub_f32_e32 v53, v52, v57
	v_ldexp_f32 v57, v54, 1
	v_mul_f32_e32 v54, v54, v55
	v_mul_f32_e32 v54, v54, v56
	v_add_f32_e32 v55, v57, v54
	v_sub_f32_e32 v56, v55, v57
	v_ldexp_f32 v49, v49, 1
	v_sub_f32_e32 v54, v54, v56
	v_add_f32_e32 v49, v49, v54
	v_add_f32_e32 v54, v55, v49
	v_sub_f32_e32 v55, v54, v55
	v_sub_f32_e32 v49, v49, v55
	v_add_f32_e32 v55, v52, v54
	v_sub_f32_e32 v56, v55, v52
	v_sub_f32_e32 v57, v55, v56
	v_sub_f32_e32 v53, v58, v53
	v_sub_f32_e32 v52, v52, v57
	v_sub_f32_e32 v54, v54, v56
	v_add_f32_e32 v52, v54, v52
	v_add_f32_e32 v54, v53, v49
	v_sub_f32_e32 v56, v54, v53
	v_sub_f32_e32 v57, v54, v56
	v_sub_f32_e32 v53, v53, v57
	v_sub_f32_e32 v49, v49, v56
	v_add_f32_e32 v52, v54, v52
	v_add_f32_e32 v49, v49, v53
	v_add_f32_e32 v53, v55, v52
	v_sub_f32_e32 v54, v53, v55
	v_sub_f32_e32 v52, v52, v54
	v_add_f32_e32 v49, v49, v52
	v_add_f32_e32 v49, v53, v49
	v_cndmask_b32_e32 v49, v178, v49, vcc
	v_cmp_ngt_f32_e32 vcc, -1.0, v47
	s_nop 1
	v_cndmask_b32_e32 v49, v179, v49, vcc
	v_cmp_neq_f32_e32 vcc, -1.0, v47
	s_nop 1
	v_cndmask_b32_e32 v49, v180, v49, vcc
	v_cmp_lt_f32_e64 vcc, |v47|, s50
	s_nop 1
	v_cndmask_b32_e32 v47, v49, v47, vcc
	v_sub_f32_e32 v46, v46, v47
	global_store_dword v[44:45], v46, off offset:-28
	global_load_dword v47, v160, s[60:61] offset:8
	s_waitcnt vmcnt(0)
	v_fmac_f32_e32 v47, v42, v48
	v_min_f32_e32 v46, 0, v47
	v_mul_f32_e64 v47, |v47|, s46
	v_exp_f32_e32 v47, v47
	s_nop 0
	v_add_f32_e32 v49, 1.0, v47
	v_add_f32_e32 v52, -1.0, v49
	v_sub_f32_e32 v53, v52, v49
	v_add_f32_e32 v53, 1.0, v53
	v_sub_f32_e32 v52, v47, v52
	v_add_f32_e32 v54, v52, v53
	v_frexp_mant_f32_e32 v52, v49
	v_cmp_gt_f32_e32 vcc, s47, v52
	v_cvt_f64_f32_e32 v[52:53], v49
	v_frexp_exp_i32_f64_e32 v52, v[52:53]
	v_subbrev_co_u32_e32 v52, vcc, 0, v52, vcc
	v_sub_u32_e32 v53, 0, v52
	v_ldexp_f32 v49, v49, v53
	v_ldexp_f32 v53, v54, v53
	v_add_f32_e32 v54, -1.0, v49
	v_add_f32_e32 v55, 1.0, v54
	v_sub_f32_e32 v55, v49, v55
	v_add_f32_e32 v55, v53, v55
	v_add_f32_e32 v56, v54, v55
	v_sub_f32_e32 v54, v56, v54
	v_sub_f32_e32 v54, v55, v54
	v_add_f32_e32 v55, 1.0, v49
	v_add_f32_e32 v57, -1.0, v55
	v_sub_f32_e32 v49, v49, v57
	v_add_f32_e32 v49, v53, v49
	v_add_f32_e32 v53, v55, v49
	v_sub_f32_e32 v55, v53, v55
	v_sub_f32_e32 v49, v49, v55
	v_rcp_f32_e32 v55, v53
	v_cvt_f32_i32_e32 v52, v52
	v_cmp_neq_f32_e32 vcc, s49, v47
	v_mul_f32_e32 v57, v56, v55
	v_mul_f32_e32 v58, v53, v57
	v_fma_f32 v59, v57, v53, -v58
	v_fmac_f32_e32 v59, v57, v49
	v_add_f32_e32 v60, v58, v59
	v_sub_f32_e32 v61, v56, v60
	v_sub_f32_e32 v56, v56, v61
	v_sub_f32_e32 v58, v60, v58
	v_sub_f32_e32 v56, v56, v60
	v_add_f32_e32 v54, v54, v56
	v_sub_f32_e32 v56, v58, v59
	v_add_f32_e32 v54, v56, v54
	v_add_f32_e32 v56, v61, v54
	v_mul_f32_e32 v58, v55, v56
	v_mul_f32_e32 v59, v53, v58
	v_fma_f32 v53, v58, v53, -v59
	v_fmac_f32_e32 v53, v58, v49
	v_sub_f32_e32 v49, v61, v56
	v_add_f32_e32 v49, v54, v49
	v_add_f32_e32 v54, v59, v53
	v_sub_f32_e32 v60, v56, v54
	v_sub_f32_e32 v56, v56, v60
	v_sub_f32_e32 v59, v54, v59
	v_sub_f32_e32 v54, v56, v54
	v_add_f32_e32 v49, v49, v54
	v_sub_f32_e32 v53, v59, v53
; template <bool SWAP> DI void inproj_tile(const Params& p, int layer, int tm, int tn, bf16_t* smem) {
;     ...
;         } else {
; #pragma unroll
;           for (int r = 0; r < 4; ++r) { const int h = (quad - 2) * 4 + r; const float xx = acc[i][1][r] * rs + p.b_forget[layer * 8 + h]; lf[h] = fminf(xx, 0.f) - log1pf(__expf(-fabsf(xx))); }
;         }
	v_add_f32_e32 v49, v53, v49
	v_add_f32_e32 v53, v57, v58
	v_add_f32_e32 v49, v60, v49
	v_sub_f32_e32 v54, v53, v57
	v_mul_f32_e32 v49, v55, v49
	v_sub_f32_e32 v54, v58, v54
	v_add_f32_e32 v49, v54, v49
	v_mul_f32_e32 v57, 0x3f317218, v52
	v_add_f32_e32 v54, v53, v49
	v_fma_f32 v58, v52, s48, -v57
	v_mul_f32_e32 v55, v54, v54
	v_fmac_f32_e32 v58, 0xb102e308, v52
	v_sub_f32_e32 v52, v54, v53
	v_fmamk_f32 v56, v55, 0x3e9b6dac, v171
	v_sub_f32_e32 v49, v49, v52
	v_add_f32_e32 v52, v57, v58
	v_fmaak_f32 v56, v55, v56, 0x3f2aaada
	v_sub_f32_e32 v53, v52, v57
	v_ldexp_f32 v57, v54, 1
	v_mul_f32_e32 v54, v54, v55
	v_mul_f32_e32 v54, v54, v56
	v_add_f32_e32 v55, v57, v54
	v_sub_f32_e32 v56, v55, v57
	v_ldexp_f32 v49, v49, 1
	v_sub_f32_e32 v54, v54, v56
	v_add_f32_e32 v49, v49, v54
	v_add_f32_e32 v54, v55, v49
	v_sub_f32_e32 v55, v54, v55
	v_sub_f32_e32 v49, v49, v55
	v_add_f32_e32 v55, v52, v54
	v_sub_f32_e32 v56, v55, v52
	v_sub_f32_e32 v57, v55, v56
	v_sub_f32_e32 v53, v58, v53
	v_sub_f32_e32 v52, v52, v57
	v_sub_f32_e32 v54, v54, v56
	v_add_f32_e32 v52, v54, v52
	v_add_f32_e32 v54, v53, v49
	v_sub_f32_e32 v56, v54, v53
	v_sub_f32_e32 v57, v54, v56
	v_sub_f32_e32 v53, v53, v57
	v_sub_f32_e32 v49, v49, v56
	v_add_f32_e32 v52, v54, v52
	v_add_f32_e32 v49, v49, v53
	v_add_f32_e32 v53, v55, v52
	v_sub_f32_e32 v54, v53, v55
	v_sub_f32_e32 v52, v52, v54
	v_add_f32_e32 v49, v49, v52
	v_add_f32_e32 v49, v53, v49
	v_cndmask_b32_e32 v49, v178, v49, vcc
	v_cmp_ngt_f32_e32 vcc, -1.0, v47
	s_nop 1
	v_cndmask_b32_e32 v49, v179, v49, vcc
	v_cmp_neq_f32_e32 vcc, -1.0, v47
	s_nop 1
	v_cndmask_b32_e32 v49, v180, v49, vcc
	v_cmp_lt_f32_e64 vcc, |v47|, s50
	s_nop 1
	v_cndmask_b32_e32 v47, v49, v47, vcc
	v_sub_f32_e32 v46, v46, v47
	global_store_dword v[44:45], v46, off offset:-24
	global_load_dword v47, v160, s[60:61] offset:12
	s_waitcnt vmcnt(0)
	v_fmac_f32_e32 v47, v43, v48
	v_min_f32_e32 v46, 0, v47
	v_mul_f32_e64 v47, |v47|, s46
	v_exp_f32_e32 v47, v47
	s_nop 0
	v_add_f32_e32 v49, 1.0, v47
	v_add_f32_e32 v52, -1.0, v49
	v_sub_f32_e32 v53, v52, v49
	v_add_f32_e32 v53, 1.0, v53
	v_sub_f32_e32 v52, v47, v52
	v_add_f32_e32 v54, v52, v53
	v_frexp_mant_f32_e32 v52, v49
	v_cmp_gt_f32_e32 vcc, s47, v52
	v_cvt_f64_f32_e32 v[52:53], v49
	v_frexp_exp_i32_f64_e32 v52, v[52:53]
	v_subbrev_co_u32_e32 v52, vcc, 0, v52, vcc
	v_sub_u32_e32 v53, 0, v52
	v_ldexp_f32 v49, v49, v53
	v_ldexp_f32 v53, v54, v53
	v_add_f32_e32 v54, -1.0, v49
	v_add_f32_e32 v55, 1.0, v54
	v_sub_f32_e32 v55, v49, v55
	v_add_f32_e32 v55, v53, v55
	v_add_f32_e32 v56, v54, v55
	v_sub_f32_e32 v54, v56, v54
	v_sub_f32_e32 v54, v55, v54
	v_add_f32_e32 v55, 1.0, v49
	v_add_f32_e32 v57, -1.0, v55
	v_sub_f32_e32 v49, v49, v57
	v_add_f32_e32 v49, v53, v49
	v_add_f32_e32 v53, v55, v49
	v_sub_f32_e32 v55, v53, v55
	v_sub_f32_e32 v49, v49, v55
	v_rcp_f32_e32 v55, v53
	v_cvt_f32_i32_e32 v52, v52
	v_cmp_neq_f32_e32 vcc, s49, v47
	v_mul_f32_e32 v57, v56, v55
	v_mul_f32_e32 v58, v53, v57
	v_fma_f32 v59, v57, v53, -v58
	v_fmac_f32_e32 v59, v57, v49
	v_add_f32_e32 v60, v58, v59
	v_sub_f32_e32 v61, v56, v60
	v_sub_f32_e32 v56, v56, v61
	v_sub_f32_e32 v58, v60, v58
	v_sub_f32_e32 v56, v56, v60
	v_add_f32_e32 v54, v54, v56
	v_sub_f32_e32 v56, v58, v59
	v_add_f32_e32 v54, v56, v54
	v_add_f32_e32 v56, v61, v54
	v_mul_f32_e32 v58, v55, v56
	v_mul_f32_e32 v59, v53, v58
	v_fma_f32 v53, v58, v53, -v59
	v_fmac_f32_e32 v53, v58, v49
	v_sub_f32_e32 v49, v61, v56
	v_add_f32_e32 v49, v54, v49
	v_add_f32_e32 v54, v59, v53
	v_sub_f32_e32 v60, v56, v54
	v_sub_f32_e32 v56, v56, v60
	v_sub_f32_e32 v59, v54, v59
	v_sub_f32_e32 v54, v56, v54
	v_add_f32_e32 v49, v49, v54
	v_sub_f32_e32 v53, v59, v53
	v_add_f32_e32 v49, v53, v49
	v_add_f32_e32 v53, v57, v58
	v_add_f32_e32 v49, v60, v49
	v_sub_f32_e32 v54, v53, v57
	v_mul_f32_e32 v49, v55, v49
	v_sub_f32_e32 v54, v58, v54
	v_add_f32_e32 v49, v54, v49
	v_mul_f32_e32 v57, 0x3f317218, v52
	v_add_f32_e32 v54, v53, v49
	v_fma_f32 v58, v52, s48, -v57
	v_mul_f32_e32 v55, v54, v54
	v_fmac_f32_e32 v58, 0xb102e308, v52
	v_sub_f32_e32 v52, v54, v53
	v_fmamk_f32 v56, v55, 0x3e9b6dac, v171
	v_sub_f32_e32 v49, v49, v52
	v_add_f32_e32 v52, v57, v58
	v_fmaak_f32 v56, v55, v56, 0x3f2aaada
	v_sub_f32_e32 v53, v52, v57
	v_ldexp_f32 v57, v54, 1
	v_mul_f32_e32 v54, v54, v55
	v_mul_f32_e32 v54, v54, v56
	v_add_f32_e32 v55, v57, v54
	v_sub_f32_e32 v56, v55, v57
	v_ldexp_f32 v49, v49, 1
	v_sub_f32_e32 v54, v54, v56
	v_add_f32_e32 v49, v49, v54
	v_add_f32_e32 v54, v55, v49
	v_sub_f32_e32 v55, v54, v55
	v_sub_f32_e32 v49, v49, v55
	v_add_f32_e32 v55, v52, v54
	v_sub_f32_e32 v56, v55, v52
	v_sub_f32_e32 v57, v55, v56
	v_sub_f32_e32 v53, v58, v53
	v_sub_f32_e32 v52, v52, v57
	v_sub_f32_e32 v54, v54, v56
	v_add_f32_e32 v52, v54, v52
	v_add_f32_e32 v54, v53, v49
	v_sub_f32_e32 v56, v54, v53
	v_sub_f32_e32 v57, v54, v56
	v_sub_f32_e32 v53, v53, v57
	v_sub_f32_e32 v49, v49, v56
	v_add_f32_e32 v52, v54, v52
	v_add_f32_e32 v49, v49, v53
	v_add_f32_e32 v53, v55, v52
	v_sub_f32_e32 v54, v53, v55
	v_sub_f32_e32 v52, v52, v54
	v_add_f32_e32 v49, v49, v52
	v_add_f32_e32 v49, v53, v49
	v_cndmask_b32_e32 v49, v178, v49, vcc
	v_cmp_ngt_f32_e32 vcc, -1.0, v47
	s_nop 1
	v_cndmask_b32_e32 v49, v179, v49, vcc
	v_cmp_neq_f32_e32 vcc, -1.0, v47
	s_nop 1
	v_cndmask_b32_e32 v49, v180, v49, vcc
	v_cmp_lt_f32_e64 vcc, |v47|, s50
	s_nop 1
	v_cndmask_b32_e32 v47, v49, v47, vcc
	v_sub_f32_e32 v46, v46, v47
	global_store_dword v[44:45], v46, off offset:-20

; DI unsigned pk2(float lo, float hi) { f32x2 v = {lo, hi}; return __builtin_bit_cast(unsigned, __builtin_convertvector(v, bfx2)); }
; DI float sigmoidf_(float x) { return 1.f / (1.f + __expf(-x)); }
; template <bool SWAP> DI void inproj_tile(const Params& p, int layer, int tm, int tn, bf16_t* smem) {
;     ...
;       for (int i = 0; i < 8; ++i) {
;         const int t = trow0 + i * 16 + l15; const float rs = rstd_from16(ssq + (size_t)t * 16, 1.f / 1024.f);
;         float* gt = (float*)(p.ws + O_GATES) + (size_t)t * 24; float* lf = (float*)(p.ws + O_LOGF) + (size_t)t * 8;
; #pragma unroll
;         for (int r = 0; r < 4; ++r) gt[quad * 4 + r] = sigmoidf_(acc[i][0][r] * rs);
;         if (quad < 2) {
; #pragma unroll
;           for (int r = 0; r < 4; ++r) gt[16 + quad * 4 + r] = sigmoidf_(acc[i][1][r] * rs);
;         } else {
; #pragma unroll
;           for (int r = 0; r < 4; ++r) { const int h = (quad - 2) * 4 + r; const float xx = acc[i][1][r] * rs + p.b_forget[layer * 8 + h]; lf[h] = fminf(xx, 0.f) - log1pf(__expf(-fabsf(xx))); }
;         }
;         const float* rp = (const float*)(p.ws + O_ROPE16) + (size_t)t * 32 + quad * 8; float o1[4], o2[4];
; #pragma unroll
;         for (int r = 0; r < 4; ++r) { const float cs = rp[2 * r], sn = rp[2 * r + 1], x1 = acc[i][2][r] * rs, x2 = acc[i][3][r] * rs; o1[r] = x1 * cs - x2 * sn; o2[r] = x2 * cs + x1 * sn; }
;         bf16_t* kp = (bf16_t*)(p.ws + O_MLAKPE) + (size_t)t * 32 + quad * 4;
;         *(u32x2*)kp = (u32x2){pk2(o1[0], o1[1]), pk2(o1[2], o1[3])}; *(u32x2*)(kp + 16) = (u32x2){pk2(o2[0], o2[1]), pk2(o2[2], o2[3])};
.LBB0_1319:
	s_or_b64 exec, exec, s[2:3]
	s_nop 0
	v_lshl_add_u64 v[40:41], v[50:51], 2, s[10:11]
	v_mov_b32_e32 v105, v161
	v_lshl_add_u64 v[44:45], v[40:41], 0, v[104:105]
	global_load_dwordx4 v[40:43], v[44:45], off offset:16
	s_nop 0
	global_load_dwordx4 v[44:47], v[44:45], off
	v_pk_mul_f32 v[32:33], v[32:33], v[48:49] op_sel_hi:[1,0]
	v_pk_mul_f32 v[36:37], v[36:37], v[48:49] op_sel_hi:[1,0]
	v_pk_mul_f32 v[34:35], v[34:35], v[48:49] op_sel_hi:[1,0]
	v_readlane_b32 s2, v240, 32
	v_readlane_b32 s3, v240, 33
	v_mov_b32_e32 v113, v161
	s_waitcnt vmcnt(0)
	v_mov_b32_e32 v53, v46
	v_mov_b32_e32 v46, v45
	v_mov_b32_e32 v52, v44
	v_pk_mul_f32 v[44:45], v[32:33], v[46:47]
	s_nop 0
	v_pk_fma_f32 v[44:45], v[36:37], v[52:53], v[44:45] neg_lo:[0,0,1] neg_hi:[0,0,1]
	v_pk_mul_f32 v[36:37], v[36:37], v[46:47]
	s_nop 0
	v_pk_fma_f32 v[32:33], v[32:33], v[52:53], v[36:37]
	v_pk_mul_f32 v[36:37], v[38:39], v[48:49] op_sel_hi:[1,0]
	v_mov_b32_e32 v39, v42
	v_mov_b32_e32 v42, v41
	v_mov_b32_e32 v38, v40
	v_pk_mul_f32 v[40:41], v[34:35], v[42:43]
	v_or_b32_e32 v48, 0x60, v128
	v_pk_fma_f32 v[40:41], v[36:37], v[38:39], v[40:41] neg_lo:[0,0,1] neg_hi:[0,0,1]
	v_pk_mul_f32 v[36:37], v[36:37], v[42:43]
	v_cvt_pk_bf16_f32 v32, v32, v33
	v_pk_fma_f32 v[34:35], v[34:35], v[38:39], v[36:37]
	v_lshl_add_u64 v[36:37], v[50:51], 1, s[2:3]
	v_lshl_add_u64 v[36:37], v[36:37], 0, v[112:113]
	v_cvt_pk_bf16_f32 v33, v34, v35
	v_ashrrev_i32_e32 v49, 31, v48
	v_cvt_pk_bf16_f32 v38, v44, v45
	v_cvt_pk_bf16_f32 v39, v40, v41
	global_store_dwordx2 v[36:37], v[32:33], off offset:32
	v_lshlrev_b64 v[32:33], 6, v[48:49]
	global_store_dwordx2 v[36:37], v[38:39], off
	v_lshl_add_u64 v[44:45], s[6:7], 0, v[32:33]
	v_bfe_u32 v244, v44, 6, 8
	v_lshlrev_b32_e32 v244, 3, v244
	v_add_u32_e32 v244, 0x24010, v244
	v_or_b32_e32 v246, 3, v44
	ds_read_b64 v[248:249], v244
	s_waitcnt lgkmcnt(0)
	v_cmp_ne_u32_e64 s[100:101], v248, v246
	s_nop 1
	s_and_saveexec_b64 s[98:99], s[100:101]
	s_cbranch_execz .LrcA1_14
	global_load_dwordx4 v[32:35], v[44:45], off offset:48
	global_load_dwordx4 v[36:39], v[44:45], off offset:32
	global_load_dwordx4 v[40:43], v[44:45], off offset:16
	s_nop 0
	global_load_dwordx4 v[44:47], v[44:45], off
	s_waitcnt vmcnt(2)
	v_add_f32_e32 v36, v36, v37
	v_add_f32_e32 v38, v38, v39
	s_waitcnt vmcnt(0)
	v_mov_b32_e32 v50, v45
	v_mov_b32_e32 v51, v46
	v_mov_b32_e32 v45, v47
	v_mov_b32_e32 v46, v41
	v_mov_b32_e32 v47, v42
	v_mov_b32_e32 v41, v43
	v_pk_add_f32 v[44:45], v[50:51], v[44:45]
	v_pk_add_f32 v[40:41], v[46:47], v[40:41]
	v_pk_add_f32 v[44:45], v[44:45], v[44:45] op_sel:[0,1] op_sel_hi:[1,0]
	v_pk_add_f32 v[40:41], v[40:41], v[40:41] op_sel:[0,1] op_sel_hi:[1,0]
	v_mov_b32_e32 v45, v32
	v_mov_b32_e32 v41, v33
	v_mov_b32_e32 v37, v34
	v_mov_b32_e32 v39, v35
	v_pk_add_f32 v[32:33], v[44:45], v[40:41]
	v_pk_add_f32 v[34:35], v[36:37], v[38:39]
	s_nop 0
	v_pk_add_f32 v[32:33], v[32:33], v[34:35]
	v_add_f32_e32 v32, v32, v33
	v_fmamk_f32 v32, v32, 0x3a800000, v170
	v_cmp_gt_f32_e32 vcc, s43, v32
	v_mul_f32_e32 v33, 0x4b800000, v32
	v_cndmask_b32_e32 v32, v32, v33, vcc
	v_rsq_f32_e32 v32, v32
	v_mul_f32_e32 v33, 0x45800000, v32
	v_cndmask_b32_e32 v32, v32, v33, vcc
	s_nop 0
	v_mov_b32_e32 v247, v32
	ds_write_b64 v244, v[246:247]
.LrcA1_14:
	s_or_b64 exec, exec, s[98:99]
	s_waitcnt vmcnt(0)
	v_cndmask_b32_e64 v32, v249, v32, s[100:101]
	v_readlane_b32 s2, v240, 35
	v_readlane_b32 s3, v240, 36
	v_mov_b64_e32 v[34:35], s[2:3]
	v_mad_i64_i32 v[36:37], s[2:3], v48, s45, v[34:35]
	v_lshlrev_b64 v[34:35], 5, v[48:49]
	v_lshl_add_u64 v[36:37], v[36:37], 0, v[160:161]
	v_mul_f32_e32 v28, v28, v32
	v_mul_f32_e32 v29, v29, v32
	v_mul_f32_e32 v28, 0xbfb8aa3b, v28
	v_mul_f32_e32 v29, 0xbfb8aa3b, v29
	v_exp_f32_e32 v28, v28
	v_exp_f32_e32 v29, v29
	v_mul_f32_e32 v30, v30, v32
	v_mul_f32_e32 v31, v31, v32
	v_mul_f32_e32 v30, 0xbfb8aa3b, v30
	v_pk_add_f32 v[28:29], v[28:29], 1.0 op_sel_hi:[1,0]
	v_mul_f32_e32 v31, 0xbfb8aa3b, v31
	v_div_scale_f32 v33, s[2:3], v29, v29, 1.0
	v_rcp_f32_e32 v38, v33
	v_exp_f32_e32 v30, v30
	v_exp_f32_e32 v31, v31
	v_fma_f32 v39, -v33, v38, 1.0
	v_fmac_f32_e32 v38, v39, v38
	v_div_scale_f32 v39, vcc, 1.0, v29, 1.0
	v_mul_f32_e32 v40, v39, v38
	v_fma_f32 v41, -v33, v40, v39
	v_fmac_f32_e32 v40, v41, v38
	v_fma_f32 v33, -v33, v40, v39
	v_div_fmas_f32 v33, v33, v38, v40
	v_div_fixup_f32 v29, v33, v29, 1.0
	v_div_scale_f32 v33, s[2:3], v28, v28, 1.0
	v_rcp_f32_e32 v38, v33
	v_pk_add_f32 v[30:31], v[30:31], 1.0 op_sel_hi:[1,0]
	v_fma_f32 v39, -v33, v38, 1.0
	v_fmac_f32_e32 v38, v39, v38
	v_div_scale_f32 v39, vcc, 1.0, v28, 1.0
	v_mul_f32_e32 v40, v39, v38
	v_fma_f32 v41, -v33, v40, v39
	v_fmac_f32_e32 v40, v41, v38
	v_fma_f32 v33, -v33, v40, v39
	v_div_fmas_f32 v33, v33, v38, v40
	v_div_fixup_f32 v28, v33, v28, 1.0
	v_div_scale_f32 v33, s[2:3], v31, v31, 1.0
	v_rcp_f32_e32 v38, v33
	s_nop 0
	v_fma_f32 v39, -v33, v38, 1.0
	v_fmac_f32_e32 v38, v39, v38
	v_div_scale_f32 v39, vcc, 1.0, v31, 1.0
	v_mul_f32_e32 v40, v39, v38
	v_fma_f32 v41, -v33, v40, v39
	v_fmac_f32_e32 v40, v41, v38
	v_fma_f32 v33, -v33, v40, v39
	v_div_fmas_f32 v33, v33, v38, v40
	v_div_fixup_f32 v31, v33, v31, 1.0
	v_div_scale_f32 v33, s[2:3], v30, v30, 1.0
	v_rcp_f32_e32 v38, v33
	s_nop 0
	v_fma_f32 v39, -v33, v38, 1.0
	v_fmac_f32_e32 v38, v39, v38
	v_div_scale_f32 v39, vcc, 1.0, v30, 1.0
	v_mul_f32_e32 v40, v39, v38
	v_fma_f32 v41, -v33, v40, v39
	v_fmac_f32_e32 v40, v41, v38
	v_fma_f32 v33, -v33, v40, v39
	v_div_fmas_f32 v33, v33, v38, v40
	v_div_fixup_f32 v30, v33, v30, 1.0
	global_store_dwordx4 v[36:37], v[28:31], off
	s_and_saveexec_b64 s[2:3], s[4:5]
	s_xor_b64 s[2:3], exec, s[2:3]
	s_cbranch_execz .LBB0_1321
; DI float sigmoidf_(float x) { return 1.f / (1.f + __expf(-x)); }
; template <bool SWAP> DI void inproj_tile(const Params& p, int layer, int tm, int tn, bf16_t* smem) {
;     ...
;         if (quad < 2) {
; #pragma unroll
;           for (int r = 0; r < 4; ++r) gt[16 + quad * 4 + r] = sigmoidf_(acc[i][1][r] * rs);
;         } else {
; #pragma unroll
;           for (int r = 0; r < 4; ++r) { const int h = (quad - 2) * 4 + r; const float xx = acc[i][1][r] * rs + p.b_forget[layer * 8 + h]; lf[h] = fminf(xx, 0.f) - log1pf(__expf(-fabsf(xx))); }
;         }
	v_readlane_b32 s52, v241, 8
	v_readlane_b32 s60, v241, 16
	v_readlane_b32 s61, v241, 17
	v_lshl_add_u64 v[28:29], s[8:9], 0, v[34:35]
	v_lshl_add_u64 v[28:29], v[28:29], 0, v[160:161]
	v_readlane_b32 s53, v241, 9
	v_readlane_b32 s54, v241, 10
	v_readlane_b32 s55, v241, 11
	global_load_dword v30, v160, s[60:61]
	v_readlane_b32 s56, v241, 12
	v_readlane_b32 s57, v241, 13
	v_readlane_b32 s58, v241, 14
	v_readlane_b32 s59, v241, 15
	v_readlane_b32 s62, v241, 18
	v_readlane_b32 s63, v241, 19
	v_readlane_b32 s64, v241, 20
	v_readlane_b32 s65, v241, 21
	v_readlane_b32 s66, v241, 22
	v_readlane_b32 s67, v241, 23
	s_waitcnt vmcnt(0)
	v_fmac_f32_e32 v30, v24, v32
	v_min_f32_e32 v33, 0, v30
	v_mul_f32_e64 v30, |v30|, s46
	v_exp_f32_e32 v36, v30
	s_nop 0
	v_add_f32_e32 v37, 1.0, v36
	v_add_f32_e32 v30, -1.0, v37
	v_sub_f32_e32 v31, v30, v37
	v_add_f32_e32 v31, 1.0, v31
	v_sub_f32_e32 v30, v36, v30
	v_add_f32_e32 v38, v30, v31
	v_frexp_mant_f32_e32 v30, v37
	v_cmp_gt_f32_e32 vcc, s47, v30
	v_cvt_f64_f32_e32 v[30:31], v37
	v_frexp_exp_i32_f64_e32 v30, v[30:31]
	v_subbrev_co_u32_e32 v30, vcc, 0, v30, vcc
	v_sub_u32_e32 v31, 0, v30
	v_ldexp_f32 v37, v37, v31
	v_ldexp_f32 v31, v38, v31
	v_add_f32_e32 v38, -1.0, v37
	v_add_f32_e32 v39, 1.0, v38
	v_sub_f32_e32 v39, v37, v39
	v_add_f32_e32 v39, v31, v39
	v_add_f32_e32 v40, v38, v39
	v_sub_f32_e32 v38, v40, v38
	v_sub_f32_e32 v38, v39, v38
	v_add_f32_e32 v39, 1.0, v37
	v_add_f32_e32 v41, -1.0, v39
	v_sub_f32_e32 v37, v37, v41
	v_add_f32_e32 v31, v31, v37
	v_add_f32_e32 v37, v39, v31
	v_sub_f32_e32 v39, v37, v39
	v_sub_f32_e32 v31, v31, v39
	v_rcp_f32_e32 v39, v37
	v_cvt_f32_i32_e32 v30, v30
	v_cmp_neq_f32_e32 vcc, s49, v36
	v_mul_f32_e32 v41, v40, v39
	v_mul_f32_e32 v42, v37, v41
	v_fma_f32 v43, v41, v37, -v42
	v_fmac_f32_e32 v43, v41, v31
	v_add_f32_e32 v44, v42, v43
	v_sub_f32_e32 v45, v40, v44
	v_sub_f32_e32 v40, v40, v45
	v_sub_f32_e32 v42, v44, v42
	v_sub_f32_e32 v40, v40, v44
	v_add_f32_e32 v38, v38, v40
	v_sub_f32_e32 v40, v42, v43
	v_add_f32_e32 v38, v40, v38
	v_add_f32_e32 v40, v45, v38
	v_mul_f32_e32 v42, v39, v40
	v_mul_f32_e32 v43, v37, v42
	v_fma_f32 v37, v42, v37, -v43
	v_fmac_f32_e32 v37, v42, v31
	v_sub_f32_e32 v31, v45, v40
	v_add_f32_e32 v31, v38, v31
	v_add_f32_e32 v38, v43, v37
	v_sub_f32_e32 v44, v40, v38
	v_sub_f32_e32 v40, v40, v44
	v_sub_f32_e32 v43, v38, v43
	v_sub_f32_e32 v38, v40, v38
	v_add_f32_e32 v31, v31, v38
	v_sub_f32_e32 v37, v43, v37
	v_add_f32_e32 v31, v37, v31
	v_add_f32_e32 v37, v41, v42
	v_add_f32_e32 v31, v44, v31
	v_sub_f32_e32 v38, v37, v41
	v_mul_f32_e32 v31, v39, v31
	v_sub_f32_e32 v38, v42, v38
	v_add_f32_e32 v31, v38, v31
	v_mul_f32_e32 v41, 0x3f317218, v30
	v_add_f32_e32 v38, v37, v31
	v_fma_f32 v42, v30, s48, -v41
	v_mul_f32_e32 v39, v38, v38
	v_fmac_f32_e32 v42, 0xb102e308, v30
	v_sub_f32_e32 v30, v38, v37
	v_fmamk_f32 v40, v39, 0x3e9b6dac, v171
	v_sub_f32_e32 v30, v31, v30
	v_add_f32_e32 v31, v41, v42
	v_fmaak_f32 v40, v39, v40, 0x3f2aaada
	v_sub_f32_e32 v37, v31, v41
	v_ldexp_f32 v41, v38, 1
	v_mul_f32_e32 v38, v38, v39
	v_mul_f32_e32 v38, v38, v40
	v_add_f32_e32 v39, v41, v38
	v_sub_f32_e32 v40, v39, v41
	v_ldexp_f32 v30, v30, 1
	v_sub_f32_e32 v38, v38, v40
	v_add_f32_e32 v30, v30, v38
	v_add_f32_e32 v38, v39, v30
	v_sub_f32_e32 v39, v38, v39
	v_sub_f32_e32 v30, v30, v39
	v_add_f32_e32 v39, v31, v38
	v_sub_f32_e32 v40, v39, v31
	v_sub_f32_e32 v41, v39, v40
	v_sub_f32_e32 v37, v42, v37
	v_sub_f32_e32 v31, v31, v41
	v_sub_f32_e32 v38, v38, v40
	v_add_f32_e32 v31, v38, v31
	v_add_f32_e32 v38, v37, v30
	v_sub_f32_e32 v40, v38, v37
	v_sub_f32_e32 v41, v38, v40
	v_sub_f32_e32 v37, v37, v41
	v_sub_f32_e32 v30, v30, v40
	v_add_f32_e32 v31, v38, v31
	v_add_f32_e32 v30, v30, v37
	v_add_f32_e32 v37, v39, v31
	v_sub_f32_e32 v38, v37, v39
	v_sub_f32_e32 v31, v31, v38
	v_add_f32_e32 v30, v30, v31
	v_add_f32_e32 v30, v37, v30
	v_cndmask_b32_e32 v30, v178, v30, vcc
	v_cmp_ngt_f32_e32 vcc, -1.0, v36
	s_nop 1
	v_cndmask_b32_e32 v30, v179, v30, vcc
	v_cmp_neq_f32_e32 vcc, -1.0, v36
	s_nop 1
	v_cndmask_b32_e32 v30, v180, v30, vcc
	v_cmp_lt_f32_e64 vcc, |v36|, s50
	s_nop 1
	v_cndmask_b32_e32 v30, v30, v36, vcc
	v_sub_f32_e32 v30, v33, v30
	global_store_dword v[28:29], v30, off offset:-32
	global_load_dword v31, v160, s[60:61] offset:4
	s_waitcnt vmcnt(0)
; template <bool SWAP> DI void inproj_tile(const Params& p, int layer, int tm, int tn, bf16_t* smem) {
;     ...
;         } else {
; #pragma unroll
;           for (int r = 0; r < 4; ++r) { const int h = (quad - 2) * 4 + r; const float xx = acc[i][1][r] * rs + p.b_forget[layer * 8 + h]; lf[h] = fminf(xx, 0.f) - log1pf(__expf(-fabsf(xx))); }
;         }
	v_fmac_f32_e32 v31, v25, v32
	v_min_f32_e32 v30, 0, v31
	v_mul_f32_e64 v31, |v31|, s46
	v_exp_f32_e32 v31, v31
	s_nop 0
	v_add_f32_e32 v33, 1.0, v31
	v_add_f32_e32 v36, -1.0, v33
	v_sub_f32_e32 v37, v36, v33
	v_add_f32_e32 v37, 1.0, v37
	v_sub_f32_e32 v36, v31, v36
	v_add_f32_e32 v38, v36, v37
	v_frexp_mant_f32_e32 v36, v33
	v_cmp_gt_f32_e32 vcc, s47, v36
	v_cvt_f64_f32_e32 v[36:37], v33
	v_frexp_exp_i32_f64_e32 v36, v[36:37]
	v_subbrev_co_u32_e32 v36, vcc, 0, v36, vcc
	v_sub_u32_e32 v37, 0, v36
	v_ldexp_f32 v33, v33, v37
	v_ldexp_f32 v37, v38, v37
	v_add_f32_e32 v38, -1.0, v33
	v_add_f32_e32 v39, 1.0, v38
	v_sub_f32_e32 v39, v33, v39
	v_add_f32_e32 v39, v37, v39
	v_add_f32_e32 v40, v38, v39
	v_sub_f32_e32 v38, v40, v38
	v_sub_f32_e32 v38, v39, v38
	v_add_f32_e32 v39, 1.0, v33
	v_add_f32_e32 v41, -1.0, v39
	v_sub_f32_e32 v33, v33, v41
	v_add_f32_e32 v33, v37, v33
	v_add_f32_e32 v37, v39, v33
	v_sub_f32_e32 v39, v37, v39
	v_sub_f32_e32 v33, v33, v39
	v_rcp_f32_e32 v39, v37
	v_cvt_f32_i32_e32 v36, v36
	v_cmp_neq_f32_e32 vcc, s49, v31
	v_mul_f32_e32 v41, v40, v39
	v_mul_f32_e32 v42, v37, v41
	v_fma_f32 v43, v41, v37, -v42
	v_fmac_f32_e32 v43, v41, v33
	v_add_f32_e32 v44, v42, v43
	v_sub_f32_e32 v45, v40, v44
	v_sub_f32_e32 v40, v40, v45
	v_sub_f32_e32 v42, v44, v42
	v_sub_f32_e32 v40, v40, v44
	v_add_f32_e32 v38, v38, v40
	v_sub_f32_e32 v40, v42, v43
	v_add_f32_e32 v38, v40, v38
	v_add_f32_e32 v40, v45, v38
	v_mul_f32_e32 v42, v39, v40
	v_mul_f32_e32 v43, v37, v42
	v_fma_f32 v37, v42, v37, -v43
	v_fmac_f32_e32 v37, v42, v33
	v_sub_f32_e32 v33, v45, v40
	v_add_f32_e32 v33, v38, v33
	v_add_f32_e32 v38, v43, v37
	v_sub_f32_e32 v44, v40, v38
	v_sub_f32_e32 v40, v40, v44
	v_sub_f32_e32 v43, v38, v43
	v_sub_f32_e32 v38, v40, v38
	v_add_f32_e32 v33, v33, v38
	v_sub_f32_e32 v37, v43, v37
	v_add_f32_e32 v33, v37, v33
	v_add_f32_e32 v37, v41, v42
	v_add_f32_e32 v33, v44, v33
	v_sub_f32_e32 v38, v37, v41
	v_mul_f32_e32 v33, v39, v33
	v_sub_f32_e32 v38, v42, v38
	v_add_f32_e32 v33, v38, v33
	v_mul_f32_e32 v41, 0x3f317218, v36
	v_add_f32_e32 v38, v37, v33
	v_fma_f32 v42, v36, s48, -v41
	v_mul_f32_e32 v39, v38, v38
	v_fmac_f32_e32 v42, 0xb102e308, v36
	v_sub_f32_e32 v36, v38, v37
	v_fmamk_f32 v40, v39, 0x3e9b6dac, v171
	v_sub_f32_e32 v33, v33, v36
	v_add_f32_e32 v36, v41, v42
	v_fmaak_f32 v40, v39, v40, 0x3f2aaada
	v_sub_f32_e32 v37, v36, v41
	v_ldexp_f32 v41, v38, 1
	v_mul_f32_e32 v38, v38, v39
	v_mul_f32_e32 v38, v38, v40
	v_add_f32_e32 v39, v41, v38
	v_sub_f32_e32 v40, v39, v41
	v_ldexp_f32 v33, v33, 1
	v_sub_f32_e32 v38, v38, v40
	v_add_f32_e32 v33, v33, v38
	v_add_f32_e32 v38, v39, v33
	v_sub_f32_e32 v39, v38, v39
	v_sub_f32_e32 v33, v33, v39
	v_add_f32_e32 v39, v36, v38
	v_sub_f32_e32 v40, v39, v36
	v_sub_f32_e32 v41, v39, v40
	v_sub_f32_e32 v37, v42, v37
	v_sub_f32_e32 v36, v36, v41
	v_sub_f32_e32 v38, v38, v40
	v_add_f32_e32 v36, v38, v36
	v_add_f32_e32 v38, v37, v33
	v_sub_f32_e32 v40, v38, v37
	v_sub_f32_e32 v41, v38, v40
	v_sub_f32_e32 v37, v37, v41
	v_sub_f32_e32 v33, v33, v40
	v_add_f32_e32 v36, v38, v36
	v_add_f32_e32 v33, v33, v37
	v_add_f32_e32 v37, v39, v36
	v_sub_f32_e32 v38, v37, v39
	v_sub_f32_e32 v36, v36, v38
	v_add_f32_e32 v33, v33, v36
	v_add_f32_e32 v33, v37, v33
	v_cndmask_b32_e32 v33, v178, v33, vcc
	v_cmp_ngt_f32_e32 vcc, -1.0, v31
	s_nop 1
	v_cndmask_b32_e32 v33, v179, v33, vcc
	v_cmp_neq_f32_e32 vcc, -1.0, v31
	s_nop 1
	v_cndmask_b32_e32 v33, v180, v33, vcc
	v_cmp_lt_f32_e64 vcc, |v31|, s50
	s_nop 1
	v_cndmask_b32_e32 v31, v33, v31, vcc
	v_sub_f32_e32 v30, v30, v31
	global_store_dword v[28:29], v30, off offset:-28
	global_load_dword v31, v160, s[60:61] offset:8
	s_waitcnt vmcnt(0)
	v_fmac_f32_e32 v31, v26, v32
	v_min_f32_e32 v30, 0, v31
	v_mul_f32_e64 v31, |v31|, s46
	v_exp_f32_e32 v31, v31
	s_nop 0
	v_add_f32_e32 v33, 1.0, v31
	v_add_f32_e32 v36, -1.0, v33
	v_sub_f32_e32 v37, v36, v33
	v_add_f32_e32 v37, 1.0, v37
	v_sub_f32_e32 v36, v31, v36
	v_add_f32_e32 v38, v36, v37
	v_frexp_mant_f32_e32 v36, v33
	v_cmp_gt_f32_e32 vcc, s47, v36
	v_cvt_f64_f32_e32 v[36:37], v33
	v_frexp_exp_i32_f64_e32 v36, v[36:37]
	v_subbrev_co_u32_e32 v36, vcc, 0, v36, vcc
	v_sub_u32_e32 v37, 0, v36
	v_ldexp_f32 v33, v33, v37
	v_ldexp_f32 v37, v38, v37
	v_add_f32_e32 v38, -1.0, v33
	v_add_f32_e32 v39, 1.0, v38
	v_sub_f32_e32 v39, v33, v39
	v_add_f32_e32 v39, v37, v39
	v_add_f32_e32 v40, v38, v39
	v_sub_f32_e32 v38, v40, v38
	v_sub_f32_e32 v38, v39, v38
	v_add_f32_e32 v39, 1.0, v33
	v_add_f32_e32 v41, -1.0, v39
	v_sub_f32_e32 v33, v33, v41
	v_add_f32_e32 v33, v37, v33
	v_add_f32_e32 v37, v39, v33
	v_sub_f32_e32 v39, v37, v39
	v_sub_f32_e32 v33, v33, v39
	v_rcp_f32_e32 v39, v37
	v_cvt_f32_i32_e32 v36, v36
	v_cmp_neq_f32_e32 vcc, s49, v31
	v_mul_f32_e32 v41, v40, v39
	v_mul_f32_e32 v42, v37, v41
	v_fma_f32 v43, v41, v37, -v42
	v_fmac_f32_e32 v43, v41, v33
	v_add_f32_e32 v44, v42, v43
	v_sub_f32_e32 v45, v40, v44
	v_sub_f32_e32 v40, v40, v45
	v_sub_f32_e32 v42, v44, v42
	v_sub_f32_e32 v40, v40, v44
	v_add_f32_e32 v38, v38, v40
	v_sub_f32_e32 v40, v42, v43
	v_add_f32_e32 v38, v40, v38
	v_add_f32_e32 v40, v45, v38
	v_mul_f32_e32 v42, v39, v40
	v_mul_f32_e32 v43, v37, v42
	v_fma_f32 v37, v42, v37, -v43
	v_fmac_f32_e32 v37, v42, v33
	v_sub_f32_e32 v33, v45, v40
	v_add_f32_e32 v33, v38, v33
	v_add_f32_e32 v38, v43, v37
	v_sub_f32_e32 v44, v40, v38
	v_sub_f32_e32 v40, v40, v44
	v_sub_f32_e32 v43, v38, v43
	v_sub_f32_e32 v38, v40, v38
	v_add_f32_e32 v33, v33, v38
	v_sub_f32_e32 v37, v43, v37
; template <bool SWAP> DI void inproj_tile(const Params& p, int layer, int tm, int tn, bf16_t* smem) {
;     ...
;         } else {
; #pragma unroll
;           for (int r = 0; r < 4; ++r) { const int h = (quad - 2) * 4 + r; const float xx = acc[i][1][r] * rs + p.b_forget[layer * 8 + h]; lf[h] = fminf(xx, 0.f) - log1pf(__expf(-fabsf(xx))); }
;         }
	v_add_f32_e32 v33, v37, v33
	v_add_f32_e32 v37, v41, v42
	v_add_f32_e32 v33, v44, v33
	v_sub_f32_e32 v38, v37, v41
	v_mul_f32_e32 v33, v39, v33
	v_sub_f32_e32 v38, v42, v38
	v_add_f32_e32 v33, v38, v33
	v_mul_f32_e32 v41, 0x3f317218, v36
	v_add_f32_e32 v38, v37, v33
	v_fma_f32 v42, v36, s48, -v41
	v_mul_f32_e32 v39, v38, v38
	v_fmac_f32_e32 v42, 0xb102e308, v36
	v_sub_f32_e32 v36, v38, v37
	v_fmamk_f32 v40, v39, 0x3e9b6dac, v171
	v_sub_f32_e32 v33, v33, v36
	v_add_f32_e32 v36, v41, v42
	v_fmaak_f32 v40, v39, v40, 0x3f2aaada
	v_sub_f32_e32 v37, v36, v41
	v_ldexp_f32 v41, v38, 1
	v_mul_f32_e32 v38, v38, v39
	v_mul_f32_e32 v38, v38, v40
	v_add_f32_e32 v39, v41, v38
	v_sub_f32_e32 v40, v39, v41
	v_ldexp_f32 v33, v33, 1
	v_sub_f32_e32 v38, v38, v40
	v_add_f32_e32 v33, v33, v38
	v_add_f32_e32 v38, v39, v33
	v_sub_f32_e32 v39, v38, v39
	v_sub_f32_e32 v33, v33, v39
	v_add_f32_e32 v39, v36, v38
	v_sub_f32_e32 v40, v39, v36
	v_sub_f32_e32 v41, v39, v40
	v_sub_f32_e32 v37, v42, v37
	v_sub_f32_e32 v36, v36, v41
	v_sub_f32_e32 v38, v38, v40
	v_add_f32_e32 v36, v38, v36
	v_add_f32_e32 v38, v37, v33
	v_sub_f32_e32 v40, v38, v37
	v_sub_f32_e32 v41, v38, v40
	v_sub_f32_e32 v37, v37, v41
	v_sub_f32_e32 v33, v33, v40
	v_add_f32_e32 v36, v38, v36
	v_add_f32_e32 v33, v33, v37
	v_add_f32_e32 v37, v39, v36
	v_sub_f32_e32 v38, v37, v39
	v_sub_f32_e32 v36, v36, v38
	v_add_f32_e32 v33, v33, v36
	v_add_f32_e32 v33, v37, v33
	v_cndmask_b32_e32 v33, v178, v33, vcc
	v_cmp_ngt_f32_e32 vcc, -1.0, v31
	s_nop 1
	v_cndmask_b32_e32 v33, v179, v33, vcc
	v_cmp_neq_f32_e32 vcc, -1.0, v31
	s_nop 1
	v_cndmask_b32_e32 v33, v180, v33, vcc
	v_cmp_lt_f32_e64 vcc, |v31|, s50
	s_nop 1
	v_cndmask_b32_e32 v31, v33, v31, vcc
	v_sub_f32_e32 v30, v30, v31
	global_store_dword v[28:29], v30, off offset:-24
	global_load_dword v31, v160, s[60:61] offset:12
	s_waitcnt vmcnt(0)
	v_fmac_f32_e32 v31, v27, v32
	v_min_f32_e32 v30, 0, v31
	v_mul_f32_e64 v31, |v31|, s46
	v_exp_f32_e32 v31, v31
	s_nop 0
	v_add_f32_e32 v33, 1.0, v31
	v_add_f32_e32 v36, -1.0, v33
	v_sub_f32_e32 v37, v36, v33
	v_add_f32_e32 v37, 1.0, v37
	v_sub_f32_e32 v36, v31, v36
	v_add_f32_e32 v38, v36, v37
	v_frexp_mant_f32_e32 v36, v33
	v_cmp_gt_f32_e32 vcc, s47, v36
	v_cvt_f64_f32_e32 v[36:37], v33
	v_frexp_exp_i32_f64_e32 v36, v[36:37]
	v_subbrev_co_u32_e32 v36, vcc, 0, v36, vcc
	v_sub_u32_e32 v37, 0, v36
	v_ldexp_f32 v33, v33, v37
	v_ldexp_f32 v37, v38, v37
	v_add_f32_e32 v38, -1.0, v33
	v_add_f32_e32 v39, 1.0, v38
	v_sub_f32_e32 v39, v33, v39
	v_add_f32_e32 v39, v37, v39
	v_add_f32_e32 v40, v38, v39
	v_sub_f32_e32 v38, v40, v38
	v_sub_f32_e32 v38, v39, v38
	v_add_f32_e32 v39, 1.0, v33
	v_add_f32_e32 v41, -1.0, v39
	v_sub_f32_e32 v33, v33, v41
	v_add_f32_e32 v33, v37, v33
	v_add_f32_e32 v37, v39, v33
	v_sub_f32_e32 v39, v37, v39
	v_sub_f32_e32 v33, v33, v39
	v_rcp_f32_e32 v39, v37
	v_cvt_f32_i32_e32 v36, v36
	v_cmp_neq_f32_e32 vcc, s49, v31
	v_mul_f32_e32 v41, v40, v39
	v_mul_f32_e32 v42, v37, v41
	v_fma_f32 v43, v41, v37, -v42
	v_fmac_f32_e32 v43, v41, v33
	v_add_f32_e32 v44, v42, v43
	v_sub_f32_e32 v45, v40, v44
	v_sub_f32_e32 v40, v40, v45
	v_sub_f32_e32 v42, v44, v42
	v_sub_f32_e32 v40, v40, v44
	v_add_f32_e32 v38, v38, v40
	v_sub_f32_e32 v40, v42, v43
	v_add_f32_e32 v38, v40, v38
	v_add_f32_e32 v40, v45, v38
	v_mul_f32_e32 v42, v39, v40
	v_mul_f32_e32 v43, v37, v42
	v_fma_f32 v37, v42, v37, -v43
	v_fmac_f32_e32 v37, v42, v33
	v_sub_f32_e32 v33, v45, v40
	v_add_f32_e32 v33, v38, v33
	v_add_f32_e32 v38, v43, v37
	v_sub_f32_e32 v44, v40, v38
	v_sub_f32_e32 v40, v40, v44
	v_sub_f32_e32 v43, v38, v43
	v_sub_f32_e32 v38, v40, v38
	v_add_f32_e32 v33, v33, v38
	v_sub_f32_e32 v37, v43, v37
	v_add_f32_e32 v33, v37, v33
	v_add_f32_e32 v37, v41, v42
	v_add_f32_e32 v33, v44, v33
	v_sub_f32_e32 v38, v37, v41
	v_mul_f32_e32 v33, v39, v33
	v_sub_f32_e32 v38, v42, v38
	v_add_f32_e32 v33, v38, v33
	v_mul_f32_e32 v41, 0x3f317218, v36
	v_add_f32_e32 v38, v37, v33
	v_fma_f32 v42, v36, s48, -v41
	v_mul_f32_e32 v39, v38, v38
	v_fmac_f32_e32 v42, 0xb102e308, v36
	v_sub_f32_e32 v36, v38, v37
	v_fmamk_f32 v40, v39, 0x3e9b6dac, v171
	v_sub_f32_e32 v33, v33, v36
	v_add_f32_e32 v36, v41, v42
	v_fmaak_f32 v40, v39, v40, 0x3f2aaada
	v_sub_f32_e32 v37, v36, v41
	v_ldexp_f32 v41, v38, 1
	v_mul_f32_e32 v38, v38, v39
	v_mul_f32_e32 v38, v38, v40
	v_add_f32_e32 v39, v41, v38
	v_sub_f32_e32 v40, v39, v41
	v_ldexp_f32 v33, v33, 1
	v_sub_f32_e32 v38, v38, v40
	v_add_f32_e32 v33, v33, v38
	v_add_f32_e32 v38, v39, v33
	v_sub_f32_e32 v39, v38, v39
	v_sub_f32_e32 v33, v33, v39
	v_add_f32_e32 v39, v36, v38
	v_sub_f32_e32 v40, v39, v36
	v_sub_f32_e32 v41, v39, v40
	v_sub_f32_e32 v37, v42, v37
	v_sub_f32_e32 v36, v36, v41
	v_sub_f32_e32 v38, v38, v40
	v_add_f32_e32 v36, v38, v36
	v_add_f32_e32 v38, v37, v33
	v_sub_f32_e32 v40, v38, v37
	v_sub_f32_e32 v41, v38, v40
	v_sub_f32_e32 v37, v37, v41
	v_sub_f32_e32 v33, v33, v40
	v_add_f32_e32 v36, v38, v36
	v_add_f32_e32 v33, v33, v37
	v_add_f32_e32 v37, v39, v36
	v_sub_f32_e32 v38, v37, v39
	v_sub_f32_e32 v36, v36, v38
	v_add_f32_e32 v33, v33, v36
	v_add_f32_e32 v33, v37, v33
	v_cndmask_b32_e32 v33, v178, v33, vcc
	v_cmp_ngt_f32_e32 vcc, -1.0, v31
	s_nop 1
	v_cndmask_b32_e32 v33, v179, v33, vcc
	v_cmp_neq_f32_e32 vcc, -1.0, v31
	s_nop 1
	v_cndmask_b32_e32 v33, v180, v33, vcc
	v_cmp_lt_f32_e64 vcc, |v31|, s50
	s_nop 1
	v_cndmask_b32_e32 v31, v33, v31, vcc
	v_sub_f32_e32 v30, v30, v31
	global_store_dword v[28:29], v30, off offset:-20

; DI unsigned pk2(float lo, float hi) { f32x2 v = {lo, hi}; return __builtin_bit_cast(unsigned, __builtin_convertvector(v, bfx2)); }
; DI float sigmoidf_(float x) { return 1.f / (1.f + __expf(-x)); }
; template <bool SWAP> DI void inproj_tile(const Params& p, int layer, int tm, int tn, bf16_t* smem) {
;     ...
;       for (int i = 0; i < 8; ++i) {
;         const int t = trow0 + i * 16 + l15; const float rs = rstd_from16(ssq + (size_t)t * 16, 1.f / 1024.f);
;         float* gt = (float*)(p.ws + O_GATES) + (size_t)t * 24; float* lf = (float*)(p.ws + O_LOGF) + (size_t)t * 8;
; #pragma unroll
;         for (int r = 0; r < 4; ++r) gt[quad * 4 + r] = sigmoidf_(acc[i][0][r] * rs);
;         if (quad < 2) {
; #pragma unroll
;           for (int r = 0; r < 4; ++r) gt[16 + quad * 4 + r] = sigmoidf_(acc[i][1][r] * rs);
;         } else {
; #pragma unroll
;           for (int r = 0; r < 4; ++r) { const int h = (quad - 2) * 4 + r; const float xx = acc[i][1][r] * rs + p.b_forget[layer * 8 + h]; lf[h] = fminf(xx, 0.f) - log1pf(__expf(-fabsf(xx))); }
;         }
;         const float* rp = (const float*)(p.ws + O_ROPE16) + (size_t)t * 32 + quad * 8; float o1[4], o2[4];
; #pragma unroll
;         for (int r = 0; r < 4; ++r) { const float cs = rp[2 * r], sn = rp[2 * r + 1], x1 = acc[i][2][r] * rs, x2 = acc[i][3][r] * rs; o1[r] = x1 * cs - x2 * sn; o2[r] = x2 * cs + x1 * sn; }
;         bf16_t* kp = (bf16_t*)(p.ws + O_MLAKPE) + (size_t)t * 32 + quad * 4;
;         *(u32x2*)kp = (u32x2){pk2(o1[0], o1[1]), pk2(o1[2], o1[3])}; *(u32x2*)(kp + 16) = (u32x2){pk2(o2[0], o2[1]), pk2(o2[2], o2[3])};
.LBB0_1323:
	s_or_b64 exec, exec, s[2:3]
	s_nop 0
	v_lshl_add_u64 v[24:25], v[34:35], 2, s[10:11]
	v_mov_b32_e32 v105, v161
	v_lshl_add_u64 v[28:29], v[24:25], 0, v[104:105]
	global_load_dwordx4 v[24:27], v[28:29], off offset:16
	s_nop 0
	global_load_dwordx4 v[28:31], v[28:29], off
	v_pk_mul_f32 v[16:17], v[16:17], v[32:33] op_sel_hi:[1,0]
	v_pk_mul_f32 v[20:21], v[20:21], v[32:33] op_sel_hi:[1,0]
	v_pk_mul_f32 v[18:19], v[18:19], v[32:33] op_sel_hi:[1,0]
	v_readlane_b32 s2, v240, 32
	v_readlane_b32 s3, v240, 33
	v_mov_b32_e32 v113, v161
	s_waitcnt vmcnt(0)
	v_mov_b32_e32 v37, v30
	v_mov_b32_e32 v30, v29
	v_mov_b32_e32 v36, v28
	v_pk_mul_f32 v[28:29], v[16:17], v[30:31]
	s_nop 0
	v_pk_fma_f32 v[28:29], v[20:21], v[36:37], v[28:29] neg_lo:[0,0,1] neg_hi:[0,0,1]
	v_pk_mul_f32 v[20:21], v[20:21], v[30:31]
	s_nop 0
	v_pk_fma_f32 v[16:17], v[16:17], v[36:37], v[20:21]
	v_pk_mul_f32 v[20:21], v[22:23], v[32:33] op_sel_hi:[1,0]
	v_mov_b32_e32 v23, v26
	v_mov_b32_e32 v26, v25
	v_mov_b32_e32 v22, v24
	v_pk_mul_f32 v[24:25], v[18:19], v[26:27]
	v_or_b32_e32 v32, 0x70, v128
	v_pk_fma_f32 v[24:25], v[20:21], v[22:23], v[24:25] neg_lo:[0,0,1] neg_hi:[0,0,1]
	v_pk_mul_f32 v[20:21], v[20:21], v[26:27]
	v_cvt_pk_bf16_f32 v16, v16, v17
	v_pk_fma_f32 v[18:19], v[18:19], v[22:23], v[20:21]
	v_lshl_add_u64 v[20:21], v[34:35], 1, s[2:3]
	v_lshl_add_u64 v[20:21], v[20:21], 0, v[112:113]
	v_cvt_pk_bf16_f32 v17, v18, v19
	v_ashrrev_i32_e32 v33, 31, v32
	v_cvt_pk_bf16_f32 v22, v28, v29
	v_cvt_pk_bf16_f32 v23, v24, v25
	global_store_dwordx2 v[20:21], v[16:17], off offset:32
	v_lshlrev_b64 v[16:17], 6, v[32:33]
	global_store_dwordx2 v[20:21], v[22:23], off
	v_lshl_add_u64 v[28:29], s[6:7], 0, v[16:17]
	v_bfe_u32 v244, v28, 6, 8
	v_lshlrev_b32_e32 v244, 3, v244
	v_add_u32_e32 v244, 0x24010, v244
	v_or_b32_e32 v246, 3, v28
	ds_read_b64 v[248:249], v244
	s_waitcnt lgkmcnt(0)
	v_cmp_ne_u32_e64 s[100:101], v248, v246
	s_nop 1
	s_and_saveexec_b64 s[98:99], s[100:101]
	s_cbranch_execz .LrcA1_15
	global_load_dwordx4 v[16:19], v[28:29], off offset:48
	global_load_dwordx4 v[20:23], v[28:29], off offset:32
	global_load_dwordx4 v[24:27], v[28:29], off offset:16
	s_nop 0
	global_load_dwordx4 v[28:31], v[28:29], off
	s_waitcnt vmcnt(2)
	v_add_f32_e32 v20, v20, v21
	v_add_f32_e32 v22, v22, v23
	s_waitcnt vmcnt(0)
	v_mov_b32_e32 v34, v29
	v_mov_b32_e32 v35, v30
	v_mov_b32_e32 v29, v31
	v_mov_b32_e32 v30, v25
	v_mov_b32_e32 v31, v26
	v_mov_b32_e32 v25, v27
	v_pk_add_f32 v[28:29], v[34:35], v[28:29]
	v_pk_add_f32 v[24:25], v[30:31], v[24:25]
	v_pk_add_f32 v[28:29], v[28:29], v[28:29] op_sel:[0,1] op_sel_hi:[1,0]
	v_pk_add_f32 v[24:25], v[24:25], v[24:25] op_sel:[0,1] op_sel_hi:[1,0]
	v_mov_b32_e32 v29, v16
	v_mov_b32_e32 v25, v17
	v_mov_b32_e32 v21, v18
	v_mov_b32_e32 v23, v19
	v_pk_add_f32 v[16:17], v[28:29], v[24:25]
	v_pk_add_f32 v[18:19], v[20:21], v[22:23]
	s_nop 0
	v_pk_add_f32 v[16:17], v[16:17], v[18:19]
	v_add_f32_e32 v16, v16, v17
	v_fmamk_f32 v16, v16, 0x3a800000, v170
	v_cmp_gt_f32_e32 vcc, s43, v16
	v_mul_f32_e32 v17, 0x4b800000, v16
	v_cndmask_b32_e32 v16, v16, v17, vcc
	v_rsq_f32_e32 v16, v16
	v_mul_f32_e32 v17, 0x45800000, v16
	v_cndmask_b32_e32 v16, v16, v17, vcc
	s_nop 0
	v_mov_b32_e32 v247, v16
	ds_write_b64 v244, v[246:247]
.LrcA1_15:
	s_or_b64 exec, exec, s[98:99]
	s_waitcnt vmcnt(0)
	v_cndmask_b32_e64 v16, v249, v16, s[100:101]
	v_readlane_b32 s2, v240, 35
	v_readlane_b32 s3, v240, 36
	v_mov_b64_e32 v[18:19], s[2:3]
	v_mad_i64_i32 v[20:21], s[2:3], v32, s45, v[18:19]
	v_lshlrev_b64 v[18:19], 5, v[32:33]
	v_lshl_add_u64 v[20:21], v[20:21], 0, v[160:161]
	v_mul_f32_e32 v12, v12, v16
	v_mul_f32_e32 v13, v13, v16
	v_mul_f32_e32 v12, 0xbfb8aa3b, v12
	v_mul_f32_e32 v13, 0xbfb8aa3b, v13
	v_exp_f32_e32 v12, v12
	v_exp_f32_e32 v13, v13
	v_mul_f32_e32 v14, v14, v16
	v_mul_f32_e32 v15, v15, v16
	v_mul_f32_e32 v14, 0xbfb8aa3b, v14
	v_pk_add_f32 v[12:13], v[12:13], 1.0 op_sel_hi:[1,0]
	v_mul_f32_e32 v15, 0xbfb8aa3b, v15
	v_div_scale_f32 v17, s[2:3], v13, v13, 1.0
	v_rcp_f32_e32 v22, v17
	v_exp_f32_e32 v14, v14
	v_exp_f32_e32 v15, v15
	v_fma_f32 v23, -v17, v22, 1.0
	v_fmac_f32_e32 v22, v23, v22
	v_div_scale_f32 v23, vcc, 1.0, v13, 1.0
	v_mul_f32_e32 v24, v23, v22
	v_fma_f32 v25, -v17, v24, v23
	v_fmac_f32_e32 v24, v25, v22
	v_fma_f32 v17, -v17, v24, v23
	v_div_fmas_f32 v17, v17, v22, v24
	v_div_fixup_f32 v13, v17, v13, 1.0
	v_div_scale_f32 v17, s[2:3], v12, v12, 1.0
	v_rcp_f32_e32 v22, v17
	v_pk_add_f32 v[14:15], v[14:15], 1.0 op_sel_hi:[1,0]
	v_fma_f32 v23, -v17, v22, 1.0
	v_fmac_f32_e32 v22, v23, v22
	v_div_scale_f32 v23, vcc, 1.0, v12, 1.0
	v_mul_f32_e32 v24, v23, v22
	v_fma_f32 v25, -v17, v24, v23
	v_fmac_f32_e32 v24, v25, v22
	v_fma_f32 v17, -v17, v24, v23
	v_div_fmas_f32 v17, v17, v22, v24
	v_div_fixup_f32 v12, v17, v12, 1.0
	v_div_scale_f32 v17, s[2:3], v15, v15, 1.0
	v_rcp_f32_e32 v22, v17
	s_nop 0
	v_fma_f32 v23, -v17, v22, 1.0
	v_fmac_f32_e32 v22, v23, v22
	v_div_scale_f32 v23, vcc, 1.0, v15, 1.0
	v_mul_f32_e32 v24, v23, v22
	v_fma_f32 v25, -v17, v24, v23
	v_fmac_f32_e32 v24, v25, v22
	v_fma_f32 v17, -v17, v24, v23
	v_div_fmas_f32 v17, v17, v22, v24
	v_div_fixup_f32 v15, v17, v15, 1.0
	v_div_scale_f32 v17, s[2:3], v14, v14, 1.0
	v_rcp_f32_e32 v22, v17
	s_nop 0
	v_fma_f32 v23, -v17, v22, 1.0
	v_fmac_f32_e32 v22, v23, v22
	v_div_scale_f32 v23, vcc, 1.0, v14, 1.0
	v_mul_f32_e32 v24, v23, v22
	v_fma_f32 v25, -v17, v24, v23
	v_fmac_f32_e32 v24, v25, v22
	v_fma_f32 v17, -v17, v24, v23
	v_div_fmas_f32 v17, v17, v22, v24
	v_div_fixup_f32 v14, v17, v14, 1.0
	global_store_dwordx4 v[20:21], v[12:15], off
	s_and_saveexec_b64 s[2:3], s[4:5]
	s_xor_b64 s[2:3], exec, s[2:3]
	s_cbranch_execz .LBB0_1325
; DI float sigmoidf_(float x) { return 1.f / (1.f + __expf(-x)); }
; template <bool SWAP> DI void inproj_tile(const Params& p, int layer, int tm, int tn, bf16_t* smem) {
;     ...
;         if (quad < 2) {
; #pragma unroll
;           for (int r = 0; r < 4; ++r) gt[16 + quad * 4 + r] = sigmoidf_(acc[i][1][r] * rs);
;         } else {
; #pragma unroll
;           for (int r = 0; r < 4; ++r) { const int h = (quad - 2) * 4 + r; const float xx = acc[i][1][r] * rs + p.b_forget[layer * 8 + h]; lf[h] = fminf(xx, 0.f) - log1pf(__expf(-fabsf(xx))); }
;         }
	v_readlane_b32 s52, v241, 8
	v_readlane_b32 s60, v241, 16
	v_readlane_b32 s61, v241, 17
	v_lshl_add_u64 v[12:13], s[8:9], 0, v[18:19]
	v_lshl_add_u64 v[12:13], v[12:13], 0, v[160:161]
	v_readlane_b32 s53, v241, 9
	v_readlane_b32 s54, v241, 10
	v_readlane_b32 s55, v241, 11
	global_load_dword v14, v160, s[60:61]
	v_readlane_b32 s56, v241, 12
	v_readlane_b32 s57, v241, 13
	v_readlane_b32 s58, v241, 14
	v_readlane_b32 s59, v241, 15
	v_readlane_b32 s62, v241, 18
	v_readlane_b32 s63, v241, 19
	v_readlane_b32 s64, v241, 20
	v_readlane_b32 s65, v241, 21
	v_readlane_b32 s66, v241, 22
	v_readlane_b32 s67, v241, 23
	s_waitcnt vmcnt(0)
	v_fmac_f32_e32 v14, v8, v16
	v_min_f32_e32 v17, 0, v14
	v_mul_f32_e64 v14, |v14|, s46
	v_exp_f32_e32 v20, v14
	s_nop 0
	v_add_f32_e32 v21, 1.0, v20
	v_add_f32_e32 v14, -1.0, v21
	v_sub_f32_e32 v15, v14, v21
	v_add_f32_e32 v15, 1.0, v15
	v_sub_f32_e32 v14, v20, v14
	v_add_f32_e32 v22, v14, v15
	v_frexp_mant_f32_e32 v14, v21
	v_cmp_gt_f32_e32 vcc, s47, v14
	v_cvt_f64_f32_e32 v[14:15], v21
	v_frexp_exp_i32_f64_e32 v14, v[14:15]
	v_subbrev_co_u32_e32 v14, vcc, 0, v14, vcc
	v_sub_u32_e32 v15, 0, v14
	v_ldexp_f32 v21, v21, v15
	v_ldexp_f32 v15, v22, v15
	v_add_f32_e32 v22, -1.0, v21
	v_add_f32_e32 v23, 1.0, v22
	v_sub_f32_e32 v23, v21, v23
	v_add_f32_e32 v23, v15, v23
	v_add_f32_e32 v24, v22, v23
	v_sub_f32_e32 v22, v24, v22
	v_sub_f32_e32 v22, v23, v22
	v_add_f32_e32 v23, 1.0, v21
	v_add_f32_e32 v25, -1.0, v23
	v_sub_f32_e32 v21, v21, v25
	v_add_f32_e32 v15, v15, v21
	v_add_f32_e32 v21, v23, v15
	v_sub_f32_e32 v23, v21, v23
	v_sub_f32_e32 v15, v15, v23
	v_rcp_f32_e32 v23, v21
	v_cvt_f32_i32_e32 v14, v14
	v_cmp_neq_f32_e32 vcc, s49, v20
	v_mul_f32_e32 v25, v24, v23
	v_mul_f32_e32 v26, v21, v25
	v_fma_f32 v27, v25, v21, -v26
	v_fmac_f32_e32 v27, v25, v15
	v_add_f32_e32 v28, v26, v27
	v_sub_f32_e32 v29, v24, v28
	v_sub_f32_e32 v24, v24, v29
	v_sub_f32_e32 v26, v28, v26
	v_sub_f32_e32 v24, v24, v28
	v_add_f32_e32 v22, v22, v24
	v_sub_f32_e32 v24, v26, v27
	v_add_f32_e32 v22, v24, v22
	v_add_f32_e32 v24, v29, v22
	v_mul_f32_e32 v26, v23, v24
	v_mul_f32_e32 v27, v21, v26
	v_fma_f32 v21, v26, v21, -v27
	v_fmac_f32_e32 v21, v26, v15
	v_sub_f32_e32 v15, v29, v24
	v_add_f32_e32 v15, v22, v15
	v_add_f32_e32 v22, v27, v21
	v_sub_f32_e32 v28, v24, v22
	v_sub_f32_e32 v24, v24, v28
	v_sub_f32_e32 v27, v22, v27
	v_sub_f32_e32 v22, v24, v22
	v_add_f32_e32 v15, v15, v22
	v_sub_f32_e32 v21, v27, v21
	v_add_f32_e32 v15, v21, v15
	v_add_f32_e32 v21, v25, v26
	v_add_f32_e32 v15, v28, v15
	v_sub_f32_e32 v22, v21, v25
	v_mul_f32_e32 v15, v23, v15
	v_sub_f32_e32 v22, v26, v22
	v_add_f32_e32 v15, v22, v15
	v_mul_f32_e32 v25, 0x3f317218, v14
	v_add_f32_e32 v22, v21, v15
	v_fma_f32 v26, v14, s48, -v25
	v_mul_f32_e32 v23, v22, v22
	v_fmac_f32_e32 v26, 0xb102e308, v14
	v_sub_f32_e32 v14, v22, v21
	v_fmamk_f32 v24, v23, 0x3e9b6dac, v171
	v_sub_f32_e32 v14, v15, v14
	v_add_f32_e32 v15, v25, v26
	v_fmaak_f32 v24, v23, v24, 0x3f2aaada
	v_sub_f32_e32 v21, v15, v25
	v_ldexp_f32 v25, v22, 1
	v_mul_f32_e32 v22, v22, v23
	v_mul_f32_e32 v22, v22, v24
	v_add_f32_e32 v23, v25, v22
	v_sub_f32_e32 v24, v23, v25
	v_ldexp_f32 v14, v14, 1
	v_sub_f32_e32 v22, v22, v24
	v_add_f32_e32 v14, v14, v22
	v_add_f32_e32 v22, v23, v14
	v_sub_f32_e32 v23, v22, v23
	v_sub_f32_e32 v14, v14, v23
	v_add_f32_e32 v23, v15, v22
	v_sub_f32_e32 v24, v23, v15
	v_sub_f32_e32 v25, v23, v24
	v_sub_f32_e32 v21, v26, v21
	v_sub_f32_e32 v15, v15, v25
	v_sub_f32_e32 v22, v22, v24
	v_add_f32_e32 v15, v22, v15
	v_add_f32_e32 v22, v21, v14
	v_sub_f32_e32 v24, v22, v21
	v_sub_f32_e32 v25, v22, v24
	v_sub_f32_e32 v21, v21, v25
	v_sub_f32_e32 v14, v14, v24
	v_add_f32_e32 v15, v22, v15
	v_add_f32_e32 v14, v14, v21
	v_add_f32_e32 v21, v23, v15
	v_sub_f32_e32 v22, v21, v23
	v_sub_f32_e32 v15, v15, v22
	v_add_f32_e32 v14, v14, v15
	v_add_f32_e32 v14, v21, v14
	v_cndmask_b32_e32 v14, v178, v14, vcc
	v_cmp_ngt_f32_e32 vcc, -1.0, v20
	s_nop 1
	v_cndmask_b32_e32 v14, v179, v14, vcc
	v_cmp_neq_f32_e32 vcc, -1.0, v20
	s_nop 1
	v_cndmask_b32_e32 v14, v180, v14, vcc
	v_cmp_lt_f32_e64 vcc, |v20|, s50
	s_nop 1
	v_cndmask_b32_e32 v14, v14, v20, vcc
	v_sub_f32_e32 v14, v17, v14
	global_store_dword v[12:13], v14, off offset:-32
	global_load_dword v15, v160, s[60:61] offset:4
	s_waitcnt vmcnt(0)
; template <bool SWAP> DI void inproj_tile(const Params& p, int layer, int tm, int tn, bf16_t* smem) {
;     ...
;         } else {
; #pragma unroll
;           for (int r = 0; r < 4; ++r) { const int h = (quad - 2) * 4 + r; const float xx = acc[i][1][r] * rs + p.b_forget[layer * 8 + h]; lf[h] = fminf(xx, 0.f) - log1pf(__expf(-fabsf(xx))); }
;         }
	v_fmac_f32_e32 v15, v9, v16
	v_min_f32_e32 v14, 0, v15
	v_mul_f32_e64 v15, |v15|, s46
	v_exp_f32_e32 v15, v15
	s_nop 0
	v_add_f32_e32 v17, 1.0, v15
	v_add_f32_e32 v20, -1.0, v17
	v_sub_f32_e32 v21, v20, v17
	v_add_f32_e32 v21, 1.0, v21
	v_sub_f32_e32 v20, v15, v20
	v_add_f32_e32 v22, v20, v21
	v_frexp_mant_f32_e32 v20, v17
	v_cmp_gt_f32_e32 vcc, s47, v20
	v_cvt_f64_f32_e32 v[20:21], v17
	v_frexp_exp_i32_f64_e32 v20, v[20:21]
	v_subbrev_co_u32_e32 v20, vcc, 0, v20, vcc
	v_sub_u32_e32 v21, 0, v20
	v_ldexp_f32 v17, v17, v21
	v_ldexp_f32 v21, v22, v21
	v_add_f32_e32 v22, -1.0, v17
	v_add_f32_e32 v23, 1.0, v22
	v_sub_f32_e32 v23, v17, v23
	v_add_f32_e32 v23, v21, v23
	v_add_f32_e32 v24, v22, v23
	v_sub_f32_e32 v22, v24, v22
	v_sub_f32_e32 v22, v23, v22
	v_add_f32_e32 v23, 1.0, v17
	v_add_f32_e32 v25, -1.0, v23
	v_sub_f32_e32 v17, v17, v25
	v_add_f32_e32 v17, v21, v17
	v_add_f32_e32 v21, v23, v17
	v_sub_f32_e32 v23, v21, v23
	v_sub_f32_e32 v17, v17, v23
	v_rcp_f32_e32 v23, v21
	v_cvt_f32_i32_e32 v20, v20
	v_cmp_neq_f32_e32 vcc, s49, v15
	v_mul_f32_e32 v25, v24, v23
	v_mul_f32_e32 v26, v21, v25
	v_fma_f32 v27, v25, v21, -v26
	v_fmac_f32_e32 v27, v25, v17
	v_add_f32_e32 v28, v26, v27
	v_sub_f32_e32 v29, v24, v28
	v_sub_f32_e32 v24, v24, v29
	v_sub_f32_e32 v26, v28, v26
	v_sub_f32_e32 v24, v24, v28
	v_add_f32_e32 v22, v22, v24
	v_sub_f32_e32 v24, v26, v27
	v_add_f32_e32 v22, v24, v22
	v_add_f32_e32 v24, v29, v22
	v_mul_f32_e32 v26, v23, v24
	v_mul_f32_e32 v27, v21, v26
	v_fma_f32 v21, v26, v21, -v27
	v_fmac_f32_e32 v21, v26, v17
	v_sub_f32_e32 v17, v29, v24
	v_add_f32_e32 v17, v22, v17
	v_add_f32_e32 v22, v27, v21
	v_sub_f32_e32 v28, v24, v22
	v_sub_f32_e32 v24, v24, v28
	v_sub_f32_e32 v27, v22, v27
	v_sub_f32_e32 v22, v24, v22
	v_add_f32_e32 v17, v17, v22
	v_sub_f32_e32 v21, v27, v21
	v_add_f32_e32 v17, v21, v17
	v_add_f32_e32 v21, v25, v26
	v_add_f32_e32 v17, v28, v17
	v_sub_f32_e32 v22, v21, v25
	v_mul_f32_e32 v17, v23, v17
	v_sub_f32_e32 v22, v26, v22
	v_add_f32_e32 v17, v22, v17
	v_mul_f32_e32 v25, 0x3f317218, v20
	v_add_f32_e32 v22, v21, v17
	v_fma_f32 v26, v20, s48, -v25
	v_mul_f32_e32 v23, v22, v22
	v_fmac_f32_e32 v26, 0xb102e308, v20
	v_sub_f32_e32 v20, v22, v21
	v_fmamk_f32 v24, v23, 0x3e9b6dac, v171
	v_sub_f32_e32 v17, v17, v20
	v_add_f32_e32 v20, v25, v26
	v_fmaak_f32 v24, v23, v24, 0x3f2aaada
	v_sub_f32_e32 v21, v20, v25
	v_ldexp_f32 v25, v22, 1
	v_mul_f32_e32 v22, v22, v23
	v_mul_f32_e32 v22, v22, v24
	v_add_f32_e32 v23, v25, v22
	v_sub_f32_e32 v24, v23, v25
	v_ldexp_f32 v17, v17, 1
	v_sub_f32_e32 v22, v22, v24
	v_add_f32_e32 v17, v17, v22
	v_add_f32_e32 v22, v23, v17
	v_sub_f32_e32 v23, v22, v23
	v_sub_f32_e32 v17, v17, v23
	v_add_f32_e32 v23, v20, v22
	v_sub_f32_e32 v24, v23, v20
	v_sub_f32_e32 v25, v23, v24
	v_sub_f32_e32 v21, v26, v21
	v_sub_f32_e32 v20, v20, v25
	v_sub_f32_e32 v22, v22, v24
	v_add_f32_e32 v20, v22, v20
	v_add_f32_e32 v22, v21, v17
	v_sub_f32_e32 v24, v22, v21
	v_sub_f32_e32 v25, v22, v24
	v_sub_f32_e32 v21, v21, v25
	v_sub_f32_e32 v17, v17, v24
	v_add_f32_e32 v20, v22, v20
	v_add_f32_e32 v17, v17, v21
	v_add_f32_e32 v21, v23, v20
	v_sub_f32_e32 v22, v21, v23
	v_sub_f32_e32 v20, v20, v22
	v_add_f32_e32 v17, v17, v20
	v_add_f32_e32 v17, v21, v17
	v_cndmask_b32_e32 v17, v178, v17, vcc
	v_cmp_ngt_f32_e32 vcc, -1.0, v15
	s_nop 1
	v_cndmask_b32_e32 v17, v179, v17, vcc
	v_cmp_neq_f32_e32 vcc, -1.0, v15
	s_nop 1
	v_cndmask_b32_e32 v17, v180, v17, vcc
	v_cmp_lt_f32_e64 vcc, |v15|, s50
	s_nop 1
	v_cndmask_b32_e32 v15, v17, v15, vcc
	v_sub_f32_e32 v14, v14, v15
	global_store_dword v[12:13], v14, off offset:-28
	global_load_dword v15, v160, s[60:61] offset:8
	s_waitcnt vmcnt(0)
	v_fmac_f32_e32 v15, v10, v16
	v_min_f32_e32 v14, 0, v15
	v_mul_f32_e64 v15, |v15|, s46
	v_exp_f32_e32 v15, v15
	s_nop 0
	v_add_f32_e32 v17, 1.0, v15
	v_add_f32_e32 v20, -1.0, v17
	v_sub_f32_e32 v21, v20, v17
	v_add_f32_e32 v21, 1.0, v21
	v_sub_f32_e32 v20, v15, v20
	v_add_f32_e32 v22, v20, v21
	v_frexp_mant_f32_e32 v20, v17
	v_cmp_gt_f32_e32 vcc, s47, v20
	v_cvt_f64_f32_e32 v[20:21], v17
	v_frexp_exp_i32_f64_e32 v20, v[20:21]
	v_subbrev_co_u32_e32 v20, vcc, 0, v20, vcc
	v_sub_u32_e32 v21, 0, v20
	v_ldexp_f32 v17, v17, v21
	v_ldexp_f32 v21, v22, v21
	v_add_f32_e32 v22, -1.0, v17
	v_add_f32_e32 v23, 1.0, v22
	v_sub_f32_e32 v23, v17, v23
	v_add_f32_e32 v23, v21, v23
	v_add_f32_e32 v24, v22, v23
	v_sub_f32_e32 v22, v24, v22
	v_sub_f32_e32 v22, v23, v22
	v_add_f32_e32 v23, 1.0, v17
	v_add_f32_e32 v25, -1.0, v23
	v_sub_f32_e32 v17, v17, v25
	v_add_f32_e32 v17, v21, v17
	v_add_f32_e32 v21, v23, v17
	v_sub_f32_e32 v23, v21, v23
	v_sub_f32_e32 v17, v17, v23
	v_rcp_f32_e32 v23, v21
	v_cvt_f32_i32_e32 v20, v20
	v_cmp_neq_f32_e32 vcc, s49, v15
	v_mul_f32_e32 v25, v24, v23
	v_mul_f32_e32 v26, v21, v25
	v_fma_f32 v27, v25, v21, -v26
	v_fmac_f32_e32 v27, v25, v17
	v_add_f32_e32 v28, v26, v27
	v_sub_f32_e32 v29, v24, v28
	v_sub_f32_e32 v24, v24, v29
	v_sub_f32_e32 v26, v28, v26
	v_sub_f32_e32 v24, v24, v28
	v_add_f32_e32 v22, v22, v24
	v_sub_f32_e32 v24, v26, v27
	v_add_f32_e32 v22, v24, v22
	v_add_f32_e32 v24, v29, v22
	v_mul_f32_e32 v26, v23, v24
	v_mul_f32_e32 v27, v21, v26
	v_fma_f32 v21, v26, v21, -v27
	v_fmac_f32_e32 v21, v26, v17
	v_sub_f32_e32 v17, v29, v24
	v_add_f32_e32 v17, v22, v17
	v_add_f32_e32 v22, v27, v21
	v_sub_f32_e32 v28, v24, v22
	v_sub_f32_e32 v24, v24, v28
	v_sub_f32_e32 v27, v22, v27
	v_sub_f32_e32 v22, v24, v22
	v_add_f32_e32 v17, v17, v22
	v_sub_f32_e32 v21, v27, v21
; template <bool SWAP> DI void inproj_tile(const Params& p, int layer, int tm, int tn, bf16_t* smem) {
;     ...
;         } else {
; #pragma unroll
;           for (int r = 0; r < 4; ++r) { const int h = (quad - 2) * 4 + r; const float xx = acc[i][1][r] * rs + p.b_forget[layer * 8 + h]; lf[h] = fminf(xx, 0.f) - log1pf(__expf(-fabsf(xx))); }
;         }
	v_add_f32_e32 v17, v21, v17
	v_add_f32_e32 v21, v25, v26
	v_add_f32_e32 v17, v28, v17
	v_sub_f32_e32 v22, v21, v25
	v_mul_f32_e32 v17, v23, v17
	v_sub_f32_e32 v22, v26, v22
	v_add_f32_e32 v17, v22, v17
	v_mul_f32_e32 v25, 0x3f317218, v20
	v_add_f32_e32 v22, v21, v17
	v_fma_f32 v26, v20, s48, -v25
	v_mul_f32_e32 v23, v22, v22
	v_fmac_f32_e32 v26, 0xb102e308, v20
	v_sub_f32_e32 v20, v22, v21
	v_fmamk_f32 v24, v23, 0x3e9b6dac, v171
	v_sub_f32_e32 v17, v17, v20
	v_add_f32_e32 v20, v25, v26
	v_fmaak_f32 v24, v23, v24, 0x3f2aaada
	v_sub_f32_e32 v21, v20, v25
	v_ldexp_f32 v25, v22, 1
	v_mul_f32_e32 v22, v22, v23
	v_mul_f32_e32 v22, v22, v24
	v_add_f32_e32 v23, v25, v22
	v_sub_f32_e32 v24, v23, v25
	v_ldexp_f32 v17, v17, 1
	v_sub_f32_e32 v22, v22, v24
	v_add_f32_e32 v17, v17, v22
	v_add_f32_e32 v22, v23, v17
	v_sub_f32_e32 v23, v22, v23
	v_sub_f32_e32 v17, v17, v23
	v_add_f32_e32 v23, v20, v22
	v_sub_f32_e32 v24, v23, v20
	v_sub_f32_e32 v25, v23, v24
	v_sub_f32_e32 v21, v26, v21
	v_sub_f32_e32 v20, v20, v25
	v_sub_f32_e32 v22, v22, v24
	v_add_f32_e32 v20, v22, v20
	v_add_f32_e32 v22, v21, v17
	v_sub_f32_e32 v24, v22, v21
	v_sub_f32_e32 v25, v22, v24
	v_sub_f32_e32 v21, v21, v25
	v_sub_f32_e32 v17, v17, v24
	v_add_f32_e32 v20, v22, v20
	v_add_f32_e32 v17, v17, v21
	v_add_f32_e32 v21, v23, v20
	v_sub_f32_e32 v22, v21, v23
	v_sub_f32_e32 v20, v20, v22
	v_add_f32_e32 v17, v17, v20
	v_add_f32_e32 v17, v21, v17
	v_cndmask_b32_e32 v17, v178, v17, vcc
	v_cmp_ngt_f32_e32 vcc, -1.0, v15
	s_nop 1
	v_cndmask_b32_e32 v17, v179, v17, vcc
	v_cmp_neq_f32_e32 vcc, -1.0, v15
	s_nop 1
	v_cndmask_b32_e32 v17, v180, v17, vcc
	v_cmp_lt_f32_e64 vcc, |v15|, s50
	s_nop 1
	v_cndmask_b32_e32 v15, v17, v15, vcc
	v_sub_f32_e32 v14, v14, v15
	global_store_dword v[12:13], v14, off offset:-24
	global_load_dword v15, v160, s[60:61] offset:12
	s_waitcnt vmcnt(0)
	v_fmac_f32_e32 v15, v11, v16
	v_min_f32_e32 v14, 0, v15
	v_mul_f32_e64 v15, |v15|, s46
	v_exp_f32_e32 v15, v15
	s_nop 0
	v_add_f32_e32 v17, 1.0, v15
	v_add_f32_e32 v20, -1.0, v17
	v_sub_f32_e32 v21, v20, v17
	v_add_f32_e32 v21, 1.0, v21
	v_sub_f32_e32 v20, v15, v20
	v_add_f32_e32 v22, v20, v21
	v_frexp_mant_f32_e32 v20, v17
	v_cmp_gt_f32_e32 vcc, s47, v20
	v_cvt_f64_f32_e32 v[20:21], v17
	v_frexp_exp_i32_f64_e32 v20, v[20:21]
	v_subbrev_co_u32_e32 v20, vcc, 0, v20, vcc
	v_sub_u32_e32 v21, 0, v20
	v_ldexp_f32 v17, v17, v21
	v_ldexp_f32 v21, v22, v21
	v_add_f32_e32 v22, -1.0, v17
	v_add_f32_e32 v23, 1.0, v22
	v_sub_f32_e32 v23, v17, v23
	v_add_f32_e32 v23, v21, v23
	v_add_f32_e32 v24, v22, v23
	v_sub_f32_e32 v22, v24, v22
	v_sub_f32_e32 v22, v23, v22
	v_add_f32_e32 v23, 1.0, v17
	v_add_f32_e32 v25, -1.0, v23
	v_sub_f32_e32 v17, v17, v25
	v_add_f32_e32 v17, v21, v17
	v_add_f32_e32 v21, v23, v17
	v_sub_f32_e32 v23, v21, v23
	v_sub_f32_e32 v17, v17, v23
	v_rcp_f32_e32 v23, v21
	v_cvt_f32_i32_e32 v20, v20
	v_cmp_neq_f32_e32 vcc, s49, v15
	v_mul_f32_e32 v25, v24, v23
	v_mul_f32_e32 v26, v21, v25
	v_fma_f32 v27, v25, v21, -v26
	v_fmac_f32_e32 v27, v25, v17
	v_add_f32_e32 v28, v26, v27
	v_sub_f32_e32 v29, v24, v28
	v_sub_f32_e32 v24, v24, v29
	v_sub_f32_e32 v26, v28, v26
	v_sub_f32_e32 v24, v24, v28
	v_add_f32_e32 v22, v22, v24
	v_sub_f32_e32 v24, v26, v27
	v_add_f32_e32 v22, v24, v22
	v_add_f32_e32 v24, v29, v22
	v_mul_f32_e32 v26, v23, v24
	v_mul_f32_e32 v27, v21, v26
	v_fma_f32 v21, v26, v21, -v27
	v_fmac_f32_e32 v21, v26, v17
	v_sub_f32_e32 v17, v29, v24
	v_add_f32_e32 v17, v22, v17
	v_add_f32_e32 v22, v27, v21
	v_sub_f32_e32 v28, v24, v22
	v_sub_f32_e32 v24, v24, v28
	v_sub_f32_e32 v27, v22, v27
	v_sub_f32_e32 v22, v24, v22
	v_add_f32_e32 v17, v17, v22
	v_sub_f32_e32 v21, v27, v21
	v_add_f32_e32 v17, v21, v17
	v_add_f32_e32 v21, v25, v26
	v_add_f32_e32 v17, v28, v17
	v_sub_f32_e32 v22, v21, v25
	v_mul_f32_e32 v17, v23, v17
	v_sub_f32_e32 v22, v26, v22
	v_add_f32_e32 v17, v22, v17
	v_mul_f32_e32 v25, 0x3f317218, v20
	v_add_f32_e32 v22, v21, v17
	v_fma_f32 v26, v20, s48, -v25
	v_mul_f32_e32 v23, v22, v22
	v_fmac_f32_e32 v26, 0xb102e308, v20
	v_sub_f32_e32 v20, v22, v21
	v_fmamk_f32 v24, v23, 0x3e9b6dac, v171
	v_sub_f32_e32 v17, v17, v20
	v_add_f32_e32 v20, v25, v26
	v_fmaak_f32 v24, v23, v24, 0x3f2aaada
	v_sub_f32_e32 v21, v20, v25
	v_ldexp_f32 v25, v22, 1
	v_mul_f32_e32 v22, v22, v23
	v_mul_f32_e32 v22, v22, v24
	v_add_f32_e32 v23, v25, v22
	v_sub_f32_e32 v24, v23, v25
	v_ldexp_f32 v17, v17, 1
	v_sub_f32_e32 v22, v22, v24
	v_add_f32_e32 v17, v17, v22
	v_add_f32_e32 v22, v23, v17
	v_sub_f32_e32 v23, v22, v23
	v_sub_f32_e32 v17, v17, v23
	v_add_f32_e32 v23, v20, v22
	v_sub_f32_e32 v24, v23, v20
	v_sub_f32_e32 v25, v23, v24
	v_sub_f32_e32 v21, v26, v21
	v_sub_f32_e32 v20, v20, v25
	v_sub_f32_e32 v22, v22, v24
	v_add_f32_e32 v20, v22, v20
	v_add_f32_e32 v22, v21, v17
	v_sub_f32_e32 v24, v22, v21
	v_sub_f32_e32 v25, v22, v24
	v_sub_f32_e32 v21, v21, v25
	v_sub_f32_e32 v17, v17, v24
	v_add_f32_e32 v20, v22, v20
	v_add_f32_e32 v17, v17, v21
	v_add_f32_e32 v21, v23, v20
	v_sub_f32_e32 v22, v21, v23
	v_sub_f32_e32 v20, v20, v22
	v_add_f32_e32 v17, v17, v20
	v_add_f32_e32 v17, v21, v17
	v_cndmask_b32_e32 v17, v178, v17, vcc
	v_cmp_ngt_f32_e32 vcc, -1.0, v15
	s_nop 1
	v_cndmask_b32_e32 v17, v179, v17, vcc
	v_cmp_neq_f32_e32 vcc, -1.0, v15
	s_nop 1
	v_cndmask_b32_e32 v17, v180, v17, vcc
	v_cmp_lt_f32_e64 vcc, |v15|, s50
	s_nop 1
	v_cndmask_b32_e32 v15, v17, v15, vcc
	v_sub_f32_e32 v14, v14, v15
	global_store_dword v[12:13], v14, off offset:-20

; DI int TIDX() { int t = (int)threadIdx.x; asm volatile("" : "+v"(t)); return t; }
; DI float sigmoidf_(float x) { return 1.f / (1.f + __expf(-x)); }
; DI float rstd_from16(const float* p, float inv_n) {
;   const f32x4 a = *(const f32x4*)p, b = *(const f32x4*)(p + 4), c = *(const f32x4*)(p + 8), d = *(const f32x4*)(p + 12);
;   const float s = ((a[0] + a[1]) + (a[2] + a[3])) + ((b[0] + b[1]) + (b[2] + b[3])) + ((c[0] + c[1]) + (c[2] + c[3])) + ((d[0] + d[1]) + (d[2] + d[3]));
;   return rsqrtf(s * inv_n + EPS_);
; }
; DI void merge_tile(const Params& p, int layer, int tm, int tn, bf16_t* smem) {
;     ...
;     if ((sg & 1) == 0) {
;       const int t2 = TIDX(), row0 = tm * 256 + ((t2 >> 8) & 1) * 128 + (t2 & 15);
; #pragma unroll
;       for (int i = 0; i < 8; ++i) {
;         asm volatile("" ::: "memory");
;         const float rs = rstd_from16((const float*)(p.ws + O_SSQ) + (size_t)(row0 + i * 16) * 16, 1.f / 1024.f);
; #pragma unroll
;         for (int j = 0; j < 2; ++j) {
;           unsigned w = 0;
; #pragma unroll
;           for (int r = 0; r < 4; ++r) w |= (unsigned)__float2int_rn(sigmoidf_(acc[i][j][r] * rs) * 255.f) << (8 * r);
;           gsp[(i * 2 + j) * NTHR] = w;
.LBB0_1885:
	v_mov_b32_e32 v152, v220
	v_mov_b64_e32 v[214:215], v[26:27]
	v_lshrrev_b32_e32 v153, 1, v152
	v_and_b32_e32 v153, 0x80, v153
	v_and_b32_e32 v152, 15, v152
	v_or3_b32 v152, v152, v153, s48
	v_ashrrev_i32_e32 v153, 31, v152
	v_lshlrev_b64 v[154:155], 6, v[152:153]
	v_lshl_add_u64 v[166:167], s[6:7], 0, v[154:155]
	v_mov_b64_e32 v[210:211], v[30:31]
	v_mov_b64_e32 v[206:207], v[34:35]
	v_mov_b64_e32 v[202:203], v[38:39]
	v_mov_b64_e32 v[198:199], v[42:43]
	v_mov_b64_e32 v[194:195], v[46:47]
	v_mov_b64_e32 v[190:191], v[50:51]
	v_mov_b64_e32 v[186:187], v[54:55]
	v_mov_b64_e32 v[182:183], v[58:59]
	v_mov_b64_e32 v[178:179], v[62:63]
	v_mov_b64_e32 v[212:213], v[24:25]
	v_mov_b64_e32 v[208:209], v[28:29]
	v_mov_b64_e32 v[204:205], v[32:33]
	v_mov_b64_e32 v[200:201], v[36:37]
	v_mov_b64_e32 v[196:197], v[40:41]
	v_mov_b64_e32 v[192:193], v[44:45]
	v_mov_b64_e32 v[188:189], v[48:49]
	v_mov_b64_e32 v[184:185], v[52:53]
	v_mov_b64_e32 v[180:181], v[56:57]
	v_mov_b64_e32 v[176:177], v[60:61]
	v_bfe_u32 v244, v166, 6, 8
	v_lshlrev_b32_e32 v244, 3, v244
	v_add_u32_e32 v244, 0x24010, v244
	v_or_b32_e32 v246, 3, v166
	ds_read_b64 v[248:249], v244
	s_waitcnt lgkmcnt(0)
	v_cmp_ne_u32_e64 s[100:101], v248, v246
	s_nop 1
	s_and_saveexec_b64 s[98:99], s[100:101]
	s_cbranch_execz .LrcE1_0
	global_load_dwordx4 v[154:157], v[166:167], off
	global_load_dwordx4 v[158:161], v[166:167], off offset:16
	global_load_dwordx4 v[162:165], v[166:167], off offset:32
	s_nop 0
	global_load_dwordx4 v[166:169], v[166:167], off offset:48
	s_waitcnt vmcnt(3)
	v_mov_b32_e32 v170, v155
	v_mov_b32_e32 v171, v156
	v_mov_b32_e32 v155, v157
	s_waitcnt vmcnt(2)
	v_mov_b32_e32 v156, v159
	v_mov_b32_e32 v157, v160
	v_mov_b32_e32 v159, v161
	v_pk_add_f32 v[154:155], v[170:171], v[154:155]
	v_pk_add_f32 v[156:157], v[156:157], v[158:159]
	v_pk_add_f32 v[154:155], v[154:155], v[154:155] op_sel:[0,1] op_sel_hi:[1,0]
	v_pk_add_f32 v[156:157], v[156:157], v[156:157] op_sel:[0,1] op_sel_hi:[1,0]
	s_waitcnt vmcnt(1)
	v_add_f32_e32 v160, v162, v163
	v_add_f32_e32 v162, v164, v165
	s_waitcnt vmcnt(0)
	v_mov_b32_e32 v161, v168
	v_mov_b32_e32 v163, v169
	v_mov_b32_e32 v155, v166
	v_mov_b32_e32 v157, v167
	v_pk_add_f32 v[158:159], v[160:161], v[162:163]
	v_pk_add_f32 v[154:155], v[154:155], v[156:157]
	s_nop 0
	v_pk_add_f32 v[154:155], v[154:155], v[158:159]
	s_nop 0
	v_add_f32_e32 v153, v154, v155
	v_fmamk_f32 v153, v153, 0x3a800000, v225
	v_mul_f32_e32 v154, 0x4b800000, v153
	v_cmp_gt_f32_e32 vcc, s45, v153
	s_nop 1
	v_cndmask_b32_e32 v153, v153, v154, vcc
	v_rsq_f32_e32 v153, v153
	s_nop 0
	v_mul_f32_e32 v154, 0x45800000, v153
	v_cndmask_b32_e32 v153, v153, v154, vcc
	s_nop 0
	v_mov_b32_e32 v247, v153
	ds_write_b64 v244, v[246:247]
.LrcE1_0:
	s_or_b64 exec, exec, s[98:99]
	s_waitcnt vmcnt(0)
	v_cndmask_b32_e64 v153, v249, v153, s[100:101]
	v_mul_f32_e32 v148, v148, v153
	v_mul_f32_e32 v149, v149, v153
	v_mul_f32_e32 v148, 0xbfb8aa3b, v148
	v_mul_f32_e32 v150, v150, v153
	v_mul_f32_e32 v149, 0xbfb8aa3b, v149
	v_exp_f32_e32 v148, v148
	v_mul_f32_e32 v151, v151, v153
	v_mul_f32_e32 v150, 0xbfb8aa3b, v150
	v_exp_f32_e32 v149, v149
	v_mul_f32_e32 v151, 0xbfb8aa3b, v151
	v_exp_f32_e32 v150, v150
	v_exp_f32_e32 v151, v151
	v_add_f32_e32 v148, 1.0, v148
	v_add_f32_e32 v149, 1.0, v149
	v_div_scale_f32 v154, s[0:1], v148, v148, 1.0
	v_add_f32_e32 v150, 1.0, v150
	v_div_scale_f32 v156, s[0:1], v149, v149, 1.0
	v_rcp_f32_e32 v163, v154
	v_add_f32_e32 v151, 1.0, v151
	v_div_scale_f32 v158, s[2:3], v150, v150, 1.0
	v_rcp_f32_e32 v164, v156
	v_mul_f32_e32 v144, v144, v153
	v_div_scale_f32 v160, s[4:5], v151, v151, 1.0
	v_rcp_f32_e32 v165, v158
	v_mul_f32_e32 v144, 0xbfb8aa3b, v144
	v_rcp_f32_e32 v166, v160
	v_exp_f32_e32 v144, v144
	v_fma_f32 v168, -v154, v163, 1.0
	v_div_scale_f32 v155, vcc, 1.0, v148, 1.0
	v_fma_f32 v169, -v156, v164, 1.0
	v_fmac_f32_e32 v163, v168, v163
	v_div_scale_f32 v157, s[0:1], 1.0, v149, 1.0
	v_fma_f32 v170, -v158, v165, 1.0
	v_fmac_f32_e32 v164, v169, v164
	v_mul_f32_e32 v168, v155, v163
	v_div_scale_f32 v159, s[2:3], 1.0, v150, 1.0
	v_fma_f32 v171, -v160, v166, 1.0
	v_fmac_f32_e32 v165, v170, v165
	v_mul_f32_e32 v169, v157, v164
	v_fma_f32 v172, -v154, v168, v155
	v_add_f32_e32 v144, 1.0, v144
	v_div_scale_f32 v161, s[4:5], 1.0, v151, 1.0
	v_fmac_f32_e32 v166, v171, v166
	v_mul_f32_e32 v170, v159, v165
	v_fma_f32 v173, -v156, v169, v157
	v_fmac_f32_e32 v168, v172, v163
	v_div_scale_f32 v162, s[56:57], v144, v144, 1.0
	v_mul_f32_e32 v171, v161, v166
	v_fma_f32 v174, -v158, v170, v159
	v_fmac_f32_e32 v169, v173, v164
	v_fma_f32 v154, -v154, v168, v155
	v_rcp_f32_e32 v167, v162
	v_fma_f32 v175, -v160, v171, v161
	v_fmac_f32_e32 v170, v174, v165
	v_fma_f32 v155, -v156, v169, v157
	v_div_fmas_f32 v154, v154, v163, v168
	s_mov_b64 vcc, s[0:1]
	v_fmac_f32_e32 v171, v175, v166
	v_fma_f32 v156, -v158, v170, v159
	v_div_fixup_f32 v148, v154, v148, 1.0
	v_div_fmas_f32 v154, v155, v164, v169
	s_mov_b64 vcc, s[2:3]
	v_fma_f32 v157, -v160, v171, v161
	v_div_fixup_f32 v149, v154, v149, 1.0
	v_div_fmas_f32 v154, v156, v165, v170
	s_mov_b64 vcc, s[4:5]
	v_div_fixup_f32 v150, v154, v150, 1.0
	v_div_fmas_f32 v154, v157, v166, v171
	v_div_fixup_f32 v151, v154, v151, 1.0
	v_fma_f32 v154, -v162, v167, 1.0
	v_mul_f32_e32 v145, v145, v153
	v_fmac_f32_e32 v167, v154, v167
	v_div_scale_f32 v154, vcc, 1.0, v144, 1.0
	v_mul_f32_e32 v145, 0xbfb8aa3b, v145
	v_mul_f32_e32 v155, v154, v167
	v_exp_f32_e32 v145, v145
	v_fma_f32 v156, -v162, v155, v154
	v_fmac_f32_e32 v155, v156, v167
	v_fma_f32 v154, -v162, v155, v154
	v_div_fmas_f32 v154, v154, v167, v155
	v_add_f32_e32 v145, 1.0, v145
; DI float sigmoidf_(float x) { return 1.f / (1.f + __expf(-x)); }
; DI float rstd_from16(const float* p, float inv_n) {
;   const f32x4 a = *(const f32x4*)p, b = *(const f32x4*)(p + 4), c = *(const f32x4*)(p + 8), d = *(const f32x4*)(p + 12);
;   const float s = ((a[0] + a[1]) + (a[2] + a[3])) + ((b[0] + b[1]) + (b[2] + b[3])) + ((c[0] + c[1]) + (c[2] + c[3])) + ((d[0] + d[1]) + (d[2] + d[3]));
;   return rsqrtf(s * inv_n + EPS_);
; }
; DI void merge_tile(const Params& p, int layer, int tm, int tn, bf16_t* smem) {
;     ...
;       for (int i = 0; i < 8; ++i) {
;         asm volatile("" ::: "memory");
;         const float rs = rstd_from16((const float*)(p.ws + O_SSQ) + (size_t)(row0 + i * 16) * 16, 1.f / 1024.f);
; #pragma unroll
;         for (int j = 0; j < 2; ++j) {
;           unsigned w = 0;
; #pragma unroll
;           for (int r = 0; r < 4; ++r) w |= (unsigned)__float2int_rn(sigmoidf_(acc[i][j][r] * rs) * 255.f) << (8 * r);
;           gsp[(i * 2 + j) * NTHR] = w;
	v_div_fixup_f32 v144, v154, v144, 1.0
	v_div_scale_f32 v154, s[0:1], v145, v145, 1.0
	v_rcp_f32_e32 v155, v154
	v_mul_f32_e32 v146, v146, v153
	v_mul_f32_e32 v146, 0xbfb8aa3b, v146
	v_exp_f32_e32 v146, v146
	v_fma_f32 v156, -v154, v155, 1.0
	v_fmac_f32_e32 v155, v156, v155
	v_div_scale_f32 v156, vcc, 1.0, v145, 1.0
	v_mul_f32_e32 v157, v156, v155
	v_fma_f32 v158, -v154, v157, v156
	v_fmac_f32_e32 v157, v158, v155
	v_fma_f32 v154, -v154, v157, v156
	v_div_fmas_f32 v154, v154, v155, v157
	v_add_f32_e32 v146, 1.0, v146
	v_div_fixup_f32 v145, v154, v145, 1.0
	v_div_scale_f32 v154, s[0:1], v146, v146, 1.0
	v_rcp_f32_e32 v155, v154
	v_mul_f32_e32 v147, v147, v153
	v_mul_f32_e32 v147, 0xbfb8aa3b, v147
	v_exp_f32_e32 v147, v147
	v_fma_f32 v156, -v154, v155, 1.0
	v_fmac_f32_e32 v155, v156, v155
	v_div_scale_f32 v156, vcc, 1.0, v146, 1.0
	v_mul_f32_e32 v157, v156, v155
	v_fma_f32 v158, -v154, v157, v156
	v_fmac_f32_e32 v157, v158, v155
	v_fma_f32 v154, -v154, v157, v156
	v_div_fmas_f32 v153, v154, v155, v157
	v_add_f32_e32 v147, 1.0, v147
	v_div_fixup_f32 v146, v153, v146, 1.0
	v_div_scale_f32 v153, s[0:1], v147, v147, 1.0
	v_rcp_f32_e32 v154, v153
	v_mul_f32_e32 v148, 0x437f0000, v148
	v_mul_f32_e32 v149, 0x437f0000, v149
	v_mul_f32_e32 v144, 0x437f0000, v144
	v_fma_f32 v155, -v153, v154, 1.0
	v_fmac_f32_e32 v154, v155, v154
	v_div_scale_f32 v155, vcc, 1.0, v147, 1.0
	v_mul_f32_e32 v156, v155, v154
	v_fma_f32 v157, -v153, v156, v155
	v_fmac_f32_e32 v156, v157, v154
	v_fma_f32 v153, -v153, v156, v155
	v_div_fmas_f32 v153, v153, v154, v156
	v_mul_f32_e32 v145, 0x437f0000, v145
	v_div_fixup_f32 v147, v153, v147, 1.0
	v_rndne_f32_e32 v148, v148
	v_rndne_f32_e32 v149, v149
	v_mul_f32_e32 v150, 0x437f0000, v150
	v_mul_f32_e32 v151, 0x437f0000, v151
	v_rndne_f32_e32 v144, v144
	v_rndne_f32_e32 v145, v145
	v_mul_f32_e32 v146, 0x437f0000, v146
	v_mul_f32_e32 v147, 0x437f0000, v147
	v_cvt_i32_f32_e32 v148, v148
	v_cvt_i32_f32_e32 v149, v149
	v_rndne_f32_e32 v150, v150
	v_rndne_f32_e32 v151, v151
	v_cvt_i32_f32_e32 v144, v144
	v_cvt_i32_f32_e32 v145, v145
	v_rndne_f32_e32 v146, v146
	v_rndne_f32_e32 v147, v147
	v_cvt_i32_f32_sdwa v150, v150 dst_sel:WORD_1 dst_unused:UNUSED_PAD src0_sel:DWORD
	v_cvt_i32_f32_sdwa v151, v151 dst_sel:BYTE_3 dst_unused:UNUSED_PAD src0_sel:DWORD
	v_cvt_i32_f32_sdwa v146, v146 dst_sel:WORD_1 dst_unused:UNUSED_PAD src0_sel:DWORD
	v_cvt_i32_f32_sdwa v147, v147 dst_sel:BYTE_3 dst_unused:UNUSED_PAD src0_sel:DWORD
	v_lshl_or_b32 v148, v149, 8, v148
	v_lshl_or_b32 v144, v145, 8, v144
	v_or3_b32 v148, v148, v150, v151
	v_or3_b32 v144, v144, v146, v147
	ds_write2st64_b32 v228, v148, v144 offset1:8
	v_or_b32_e32 v144, 16, v152
	v_ashrrev_i32_e32 v145, 31, v144
	v_lshlrev_b64 v[144:145], 6, v[144:145]
	v_lshl_add_u64 v[158:159], s[6:7], 0, v[144:145]
	v_bfe_u32 v244, v158, 6, 8
	v_lshlrev_b32_e32 v244, 3, v244
	v_add_u32_e32 v244, 0x24010, v244
	v_or_b32_e32 v246, 3, v158
	ds_read_b64 v[248:249], v244
	s_waitcnt lgkmcnt(0)
	v_cmp_ne_u32_e64 s[100:101], v248, v246
	s_nop 1
	s_and_saveexec_b64 s[98:99], s[100:101]
	s_cbranch_execz .LrcE1_1
	global_load_dwordx4 v[144:147], v[158:159], off
	global_load_dwordx4 v[148:151], v[158:159], off offset:16
	global_load_dwordx4 v[154:157], v[158:159], off offset:32
	s_nop 0
	global_load_dwordx4 v[158:161], v[158:159], off offset:48
	s_waitcnt vmcnt(3)
	v_mov_b32_e32 v162, v145
	v_mov_b32_e32 v163, v146
	v_mov_b32_e32 v145, v147
	s_waitcnt vmcnt(2)
	v_mov_b32_e32 v146, v149
	v_mov_b32_e32 v147, v150
	v_mov_b32_e32 v149, v151
	v_pk_add_f32 v[144:145], v[162:163], v[144:145]
	v_pk_add_f32 v[146:147], v[146:147], v[148:149]
	v_pk_add_f32 v[144:145], v[144:145], v[144:145] op_sel:[0,1] op_sel_hi:[1,0]
	v_pk_add_f32 v[146:147], v[146:147], v[146:147] op_sel:[0,1] op_sel_hi:[1,0]
	s_waitcnt vmcnt(1)
	v_add_f32_e32 v148, v154, v155
	v_add_f32_e32 v150, v156, v157
	s_waitcnt vmcnt(0)
	v_mov_b32_e32 v145, v158
	v_mov_b32_e32 v147, v159
	v_mov_b32_e32 v149, v160
	v_mov_b32_e32 v151, v161
	v_pk_add_f32 v[144:145], v[144:145], v[146:147]
	v_pk_add_f32 v[146:147], v[148:149], v[150:151]
	v_pk_add_f32 v[144:145], v[144:145], v[146:147]
	v_add_f32_e32 v144, v144, v145
	v_fmamk_f32 v144, v144, 0x3a800000, v225
	v_mul_f32_e32 v145, 0x4b800000, v144
	v_cmp_gt_f32_e32 vcc, s45, v144
	v_cndmask_b32_e32 v144, v144, v145, vcc
	v_rsq_f32_e32 v144, v144
	s_nop 0
	v_mul_f32_e32 v145, 0x45800000, v144
	v_cndmask_b32_e32 v144, v144, v145, vcc
	s_nop 0
	v_mov_b32_e32 v247, v144
	ds_write_b64 v244, v[246:247]
; DI float sigmoidf_(float x) { return 1.f / (1.f + __expf(-x)); }
; DI float rstd_from16(const float* p, float inv_n) {
;   const f32x4 a = *(const f32x4*)p, b = *(const f32x4*)(p + 4), c = *(const f32x4*)(p + 8), d = *(const f32x4*)(p + 12);
;   const float s = ((a[0] + a[1]) + (a[2] + a[3])) + ((b[0] + b[1]) + (b[2] + b[3])) + ((c[0] + c[1]) + (c[2] + c[3])) + ((d[0] + d[1]) + (d[2] + d[3]));
;   return rsqrtf(s * inv_n + EPS_);
; DI void merge_tile(const Params& p, int layer, int tm, int tn, bf16_t* smem) {
;     ...
;       for (int i = 0; i < 8; ++i) {
;         asm volatile("" ::: "memory");
;         const float rs = rstd_from16((const float*)(p.ws + O_SSQ) + (size_t)(row0 + i * 16) * 16, 1.f / 1024.f);
; #pragma unroll
;         for (int j = 0; j < 2; ++j) {
;           unsigned w = 0;
; #pragma unroll
;           for (int r = 0; r < 4; ++r) w |= (unsigned)__float2int_rn(sigmoidf_(acc[i][j][r] * rs) * 255.f) << (8 * r);
;           gsp[(i * 2 + j) * NTHR] = w;
;         }
.LrcE1_1:
	s_or_b64 exec, exec, s[98:99]
	s_waitcnt vmcnt(0)
	v_cndmask_b32_e64 v144, v249, v144, s[100:101]
	v_mov_b64_e32 v[174:175], v[66:67]
	v_mov_b64_e32 v[170:171], v[70:71]
	v_mov_b64_e32 v[166:167], v[74:75]
	v_mov_b64_e32 v[172:173], v[64:65]
	v_mov_b64_e32 v[168:169], v[68:69]
	v_mov_b64_e32 v[164:165], v[72:73]
	v_mov_b64_e32 v[162:163], v[78:79]
	v_mov_b64_e32 v[158:159], v[82:83]
	v_mov_b64_e32 v[160:161], v[76:77]
	v_mov_b64_e32 v[156:157], v[80:81]
	v_mul_f32_e32 v140, v140, v144
	v_mul_f32_e32 v140, 0xbfb8aa3b, v140
	v_exp_f32_e32 v140, v140
	v_mul_f32_e32 v141, v141, v144
	v_mul_f32_e32 v141, 0xbfb8aa3b, v141
	v_exp_f32_e32 v141, v141
	v_add_f32_e32 v140, 1.0, v140
	v_div_scale_f32 v145, s[0:1], v140, v140, 1.0
	v_rcp_f32_e32 v146, v145
	v_add_f32_e32 v141, 1.0, v141
	v_mul_f32_e32 v142, v142, v144
	v_mul_f32_e32 v142, 0xbfb8aa3b, v142
	v_fma_f32 v147, -v145, v146, 1.0
	v_fmac_f32_e32 v146, v147, v146
	v_div_scale_f32 v147, vcc, 1.0, v140, 1.0
	v_mul_f32_e32 v148, v147, v146
	v_fma_f32 v149, -v145, v148, v147
	v_fmac_f32_e32 v148, v149, v146
	v_fma_f32 v145, -v145, v148, v147
	v_div_fmas_f32 v145, v145, v146, v148
	v_div_fixup_f32 v140, v145, v140, 1.0
	v_div_scale_f32 v145, s[0:1], v141, v141, 1.0
	v_rcp_f32_e32 v146, v145
	v_exp_f32_e32 v142, v142
	v_mul_f32_e32 v143, v143, v144
	v_mul_f32_e32 v143, 0xbfb8aa3b, v143
	v_fma_f32 v147, -v145, v146, 1.0
	v_fmac_f32_e32 v146, v147, v146
	v_div_scale_f32 v147, vcc, 1.0, v141, 1.0
	v_mul_f32_e32 v148, v147, v146
	v_fma_f32 v149, -v145, v148, v147
	v_fmac_f32_e32 v148, v149, v146
	v_fma_f32 v145, -v145, v148, v147
	v_div_fmas_f32 v145, v145, v146, v148
	v_add_f32_e32 v142, 1.0, v142
	v_div_fixup_f32 v141, v145, v141, 1.0
	v_div_scale_f32 v145, s[0:1], v142, v142, 1.0
	v_rcp_f32_e32 v146, v145
	v_exp_f32_e32 v143, v143
	v_mul_f32_e32 v136, v136, v144
	v_mul_f32_e32 v136, 0xbfb8aa3b, v136
	v_fma_f32 v147, -v145, v146, 1.0
	v_fmac_f32_e32 v146, v147, v146
	v_div_scale_f32 v147, vcc, 1.0, v142, 1.0
	v_mul_f32_e32 v148, v147, v146
	v_fma_f32 v149, -v145, v148, v147
	v_fmac_f32_e32 v148, v149, v146
	v_fma_f32 v145, -v145, v148, v147
	v_div_fmas_f32 v145, v145, v146, v148
	v_add_f32_e32 v143, 1.0, v143
	v_div_fixup_f32 v142, v145, v142, 1.0
	v_div_scale_f32 v145, s[0:1], v143, v143, 1.0
	v_rcp_f32_e32 v146, v145
	v_exp_f32_e32 v136, v136
	v_mul_f32_e32 v137, v137, v144
	v_mul_f32_e32 v137, 0xbfb8aa3b, v137
	v_fma_f32 v147, -v145, v146, 1.0
	v_fmac_f32_e32 v146, v147, v146
	v_div_scale_f32 v147, vcc, 1.0, v143, 1.0
	v_mul_f32_e32 v148, v147, v146
	v_fma_f32 v149, -v145, v148, v147
	v_fmac_f32_e32 v148, v149, v146
	v_fma_f32 v145, -v145, v148, v147
	v_div_fmas_f32 v145, v145, v146, v148
	v_add_f32_e32 v136, 1.0, v136
	v_div_fixup_f32 v143, v145, v143, 1.0
	v_div_scale_f32 v145, s[0:1], v136, v136, 1.0
	v_rcp_f32_e32 v146, v145
	v_exp_f32_e32 v137, v137
	v_mul_f32_e32 v138, v138, v144
	v_mul_f32_e32 v138, 0xbfb8aa3b, v138
	v_fma_f32 v147, -v145, v146, 1.0
	v_fmac_f32_e32 v146, v147, v146
	v_div_scale_f32 v147, vcc, 1.0, v136, 1.0
	v_mul_f32_e32 v148, v147, v146
	v_fma_f32 v149, -v145, v148, v147
	v_fmac_f32_e32 v148, v149, v146
	v_fma_f32 v145, -v145, v148, v147
	v_div_fmas_f32 v145, v145, v146, v148
	v_add_f32_e32 v137, 1.0, v137
	v_div_fixup_f32 v136, v145, v136, 1.0
	v_div_scale_f32 v145, s[0:1], v137, v137, 1.0
	v_rcp_f32_e32 v146, v145
	v_exp_f32_e32 v138, v138
	v_mul_f32_e32 v139, v139, v144
	v_mul_f32_e32 v139, 0xbfb8aa3b, v139
	v_fma_f32 v147, -v145, v146, 1.0
	v_fmac_f32_e32 v146, v147, v146
	v_div_scale_f32 v147, vcc, 1.0, v137, 1.0
	v_mul_f32_e32 v148, v147, v146
	v_fma_f32 v149, -v145, v148, v147
	v_fmac_f32_e32 v148, v149, v146
	v_fma_f32 v145, -v145, v148, v147
	v_div_fmas_f32 v145, v145, v146, v148
	v_add_f32_e32 v138, 1.0, v138
	v_div_fixup_f32 v137, v145, v137, 1.0
	v_div_scale_f32 v145, s[0:1], v138, v138, 1.0
	v_rcp_f32_e32 v146, v145
	v_exp_f32_e32 v139, v139
	v_mul_f32_e32 v140, 0x437f0000, v140
	v_mul_f32_e32 v141, 0x437f0000, v141
	v_fma_f32 v147, -v145, v146, 1.0
	v_fmac_f32_e32 v146, v147, v146
	v_div_scale_f32 v147, vcc, 1.0, v138, 1.0
	v_mul_f32_e32 v148, v147, v146
	v_fma_f32 v149, -v145, v148, v147
	v_fmac_f32_e32 v148, v149, v146
	v_fma_f32 v145, -v145, v148, v147
	v_div_fmas_f32 v144, v145, v146, v148
	v_add_f32_e32 v139, 1.0, v139
	v_div_fixup_f32 v138, v144, v138, 1.0
	v_div_scale_f32 v144, s[0:1], v139, v139, 1.0
	v_rcp_f32_e32 v145, v144
	v_mul_f32_e32 v136, 0x437f0000, v136
	v_mul_f32_e32 v137, 0x437f0000, v137
	v_rndne_f32_e32 v140, v140
	v_fma_f32 v146, -v144, v145, 1.0
	v_fmac_f32_e32 v145, v146, v145
	v_div_scale_f32 v146, vcc, 1.0, v139, 1.0
	v_mul_f32_e32 v147, v146, v145
	v_fma_f32 v148, -v144, v147, v146
	v_fmac_f32_e32 v147, v148, v145
	v_fma_f32 v144, -v144, v147, v146
	v_div_fmas_f32 v144, v144, v145, v147
	v_div_fixup_f32 v139, v144, v139, 1.0
	v_rndne_f32_e32 v141, v141
	v_mul_f32_e32 v142, 0x437f0000, v142
	v_mul_f32_e32 v143, 0x437f0000, v143
	v_rndne_f32_e32 v136, v136
	v_rndne_f32_e32 v137, v137
	v_mul_f32_e32 v138, 0x437f0000, v138
	v_mul_f32_e32 v139, 0x437f0000, v139
	v_cvt_i32_f32_e32 v140, v140
	v_cvt_i32_f32_e32 v141, v141
	v_rndne_f32_e32 v142, v142
	v_rndne_f32_e32 v143, v143
	v_cvt_i32_f32_e32 v136, v136
	v_cvt_i32_f32_e32 v137, v137
	v_rndne_f32_e32 v138, v138
	v_rndne_f32_e32 v139, v139
	v_cvt_i32_f32_sdwa v142, v142 dst_sel:WORD_1 dst_unused:UNUSED_PAD src0_sel:DWORD
	v_cvt_i32_f32_sdwa v143, v143 dst_sel:BYTE_3 dst_unused:UNUSED_PAD src0_sel:DWORD
	v_cvt_i32_f32_sdwa v138, v138 dst_sel:WORD_1 dst_unused:UNUSED_PAD src0_sel:DWORD
	v_cvt_i32_f32_sdwa v139, v139 dst_sel:BYTE_3 dst_unused:UNUSED_PAD src0_sel:DWORD
	v_lshl_or_b32 v140, v141, 8, v140
	v_lshl_or_b32 v136, v137, 8, v136
	v_or3_b32 v140, v140, v142, v143
	v_or3_b32 v136, v136, v138, v139
	ds_write2st64_b32 v228, v140, v136 offset0:16 offset1:24
	v_or_b32_e32 v136, 32, v152
	v_ashrrev_i32_e32 v137, 31, v136
	v_lshlrev_b64 v[136:137], 6, v[136:137]
	v_lshl_add_u64 v[148:149], s[6:7], 0, v[136:137]
	v_bfe_u32 v244, v148, 6, 8
	v_lshlrev_b32_e32 v244, 3, v244
	v_add_u32_e32 v244, 0x24010, v244
	v_or_b32_e32 v246, 3, v148
	ds_read_b64 v[248:249], v244
	s_waitcnt lgkmcnt(0)
	v_cmp_ne_u32_e64 s[100:101], v248, v246
	s_nop 1
	s_and_saveexec_b64 s[98:99], s[100:101]
	s_cbranch_execz .LrcE1_2
; DI float sigmoidf_(float x) { return 1.f / (1.f + __expf(-x)); }
; DI float rstd_from16(const float* p, float inv_n) {
;   const f32x4 a = *(const f32x4*)p, b = *(const f32x4*)(p + 4), c = *(const f32x4*)(p + 8), d = *(const f32x4*)(p + 12);
;   const float s = ((a[0] + a[1]) + (a[2] + a[3])) + ((b[0] + b[1]) + (b[2] + b[3])) + ((c[0] + c[1]) + (c[2] + c[3])) + ((d[0] + d[1]) + (d[2] + d[3]));
;   return rsqrtf(s * inv_n + EPS_);
; DI void merge_tile(const Params& p, int layer, int tm, int tn, bf16_t* smem) {
;     ...
;         const float rs = rstd_from16((const float*)(p.ws + O_SSQ) + (size_t)(row0 + i * 16) * 16, 1.f / 1024.f);
; #pragma unroll
;         for (int j = 0; j < 2; ++j) {
;           unsigned w = 0;
; #pragma unroll
;           for (int r = 0; r < 4; ++r) w |= (unsigned)__float2int_rn(sigmoidf_(acc[i][j][r] * rs) * 255.f) << (8 * r);
;           gsp[(i * 2 + j) * NTHR] = w;
	global_load_dwordx4 v[136:139], v[148:149], off
	global_load_dwordx4 v[140:143], v[148:149], off offset:16
	global_load_dwordx4 v[144:147], v[148:149], off offset:32
	s_nop 0
	global_load_dwordx4 v[148:151], v[148:149], off offset:48
	s_waitcnt vmcnt(3)
	v_mov_b32_e32 v154, v137
	v_mov_b32_e32 v155, v138
	v_mov_b32_e32 v137, v139
	s_waitcnt vmcnt(2)
	v_mov_b32_e32 v138, v141
	v_mov_b32_e32 v139, v142
	v_mov_b32_e32 v141, v143
	v_pk_add_f32 v[136:137], v[154:155], v[136:137]
	v_pk_add_f32 v[138:139], v[138:139], v[140:141]
	v_pk_add_f32 v[136:137], v[136:137], v[136:137] op_sel:[0,1] op_sel_hi:[1,0]
	v_pk_add_f32 v[138:139], v[138:139], v[138:139] op_sel:[0,1] op_sel_hi:[1,0]
	s_waitcnt vmcnt(1)
	v_add_f32_e32 v140, v144, v145
	v_add_f32_e32 v142, v146, v147
	s_waitcnt vmcnt(0)
	v_mov_b32_e32 v137, v148
	v_mov_b32_e32 v139, v149
	v_mov_b32_e32 v141, v150
	v_mov_b32_e32 v143, v151
	v_pk_add_f32 v[136:137], v[136:137], v[138:139]
	v_pk_add_f32 v[138:139], v[140:141], v[142:143]
	s_nop 0
	v_pk_add_f32 v[136:137], v[136:137], v[138:139]
	s_nop 0
	v_add_f32_e32 v136, v136, v137
	v_fmamk_f32 v136, v136, 0x3a800000, v225
	v_mul_f32_e32 v137, 0x4b800000, v136
	v_cmp_gt_f32_e32 vcc, s45, v136
	s_nop 1
	v_cndmask_b32_e32 v136, v136, v137, vcc
	v_rsq_f32_e32 v136, v136
	s_nop 0
	v_mul_f32_e32 v137, 0x45800000, v136
	v_cndmask_b32_e32 v136, v136, v137, vcc
	s_nop 0
	v_mov_b32_e32 v247, v136
	ds_write_b64 v244, v[246:247]
.LrcE1_2:
	s_or_b64 exec, exec, s[98:99]
	s_waitcnt vmcnt(0)
	v_cndmask_b32_e64 v136, v249, v136, s[100:101]
	v_mul_f32_e32 v132, v132, v136
	v_mul_f32_e32 v132, 0xbfb8aa3b, v132
	v_exp_f32_e32 v132, v132
	v_mul_f32_e32 v133, v133, v136
	v_mul_f32_e32 v133, 0xbfb8aa3b, v133
	v_exp_f32_e32 v133, v133
	v_add_f32_e32 v132, 1.0, v132
	v_div_scale_f32 v137, s[0:1], v132, v132, 1.0
	v_rcp_f32_e32 v138, v137
	v_add_f32_e32 v133, 1.0, v133
	v_mul_f32_e32 v134, v134, v136
	v_mul_f32_e32 v134, 0xbfb8aa3b, v134
	v_fma_f32 v139, -v137, v138, 1.0
	v_fmac_f32_e32 v138, v139, v138
	v_div_scale_f32 v139, vcc, 1.0, v132, 1.0
	v_mul_f32_e32 v140, v139, v138
	v_fma_f32 v141, -v137, v140, v139
	v_fmac_f32_e32 v140, v141, v138
	v_fma_f32 v137, -v137, v140, v139
	v_div_fmas_f32 v137, v137, v138, v140
	v_div_fixup_f32 v132, v137, v132, 1.0
	v_div_scale_f32 v137, s[0:1], v133, v133, 1.0
	v_rcp_f32_e32 v138, v137
	v_exp_f32_e32 v134, v134
	v_mul_f32_e32 v135, v135, v136
	v_mul_f32_e32 v135, 0xbfb8aa3b, v135
	v_fma_f32 v139, -v137, v138, 1.0
	v_fmac_f32_e32 v138, v139, v138
	v_div_scale_f32 v139, vcc, 1.0, v133, 1.0
	v_mul_f32_e32 v140, v139, v138
	v_fma_f32 v141, -v137, v140, v139
	v_fmac_f32_e32 v140, v141, v138
	v_fma_f32 v137, -v137, v140, v139
	v_div_fmas_f32 v137, v137, v138, v140
	v_add_f32_e32 v134, 1.0, v134
	v_div_fixup_f32 v133, v137, v133, 1.0
	v_div_scale_f32 v137, s[0:1], v134, v134, 1.0
	v_rcp_f32_e32 v138, v137
	v_exp_f32_e32 v135, v135
	v_mul_f32_e32 v128, v128, v136
	v_mul_f32_e32 v128, 0xbfb8aa3b, v128
	v_fma_f32 v139, -v137, v138, 1.0
	v_fmac_f32_e32 v138, v139, v138
	v_div_scale_f32 v139, vcc, 1.0, v134, 1.0
	v_mul_f32_e32 v140, v139, v138
	v_fma_f32 v141, -v137, v140, v139
	v_fmac_f32_e32 v140, v141, v138
	v_fma_f32 v137, -v137, v140, v139
	v_div_fmas_f32 v137, v137, v138, v140
	v_add_f32_e32 v135, 1.0, v135
	v_div_fixup_f32 v134, v137, v134, 1.0
	v_div_scale_f32 v137, s[0:1], v135, v135, 1.0
	v_rcp_f32_e32 v138, v137
	v_exp_f32_e32 v128, v128
	v_mul_f32_e32 v129, v129, v136
	v_mul_f32_e32 v129, 0xbfb8aa3b, v129
	v_fma_f32 v139, -v137, v138, 1.0
	v_fmac_f32_e32 v138, v139, v138
	v_div_scale_f32 v139, vcc, 1.0, v135, 1.0
	v_mul_f32_e32 v140, v139, v138
	v_fma_f32 v141, -v137, v140, v139
	v_fmac_f32_e32 v140, v141, v138
	v_fma_f32 v137, -v137, v140, v139
	v_div_fmas_f32 v137, v137, v138, v140
	v_add_f32_e32 v128, 1.0, v128
	v_div_fixup_f32 v135, v137, v135, 1.0
	v_div_scale_f32 v137, s[0:1], v128, v128, 1.0
	v_rcp_f32_e32 v138, v137
	v_exp_f32_e32 v129, v129
	v_mul_f32_e32 v130, v130, v136
	v_mul_f32_e32 v130, 0xbfb8aa3b, v130
	v_fma_f32 v139, -v137, v138, 1.0
	v_fmac_f32_e32 v138, v139, v138
	v_div_scale_f32 v139, vcc, 1.0, v128, 1.0
	v_mul_f32_e32 v140, v139, v138
	v_fma_f32 v141, -v137, v140, v139
	v_fmac_f32_e32 v140, v141, v138
	v_fma_f32 v137, -v137, v140, v139
	v_div_fmas_f32 v137, v137, v138, v140
	v_add_f32_e32 v129, 1.0, v129
	v_div_fixup_f32 v128, v137, v128, 1.0
	v_div_scale_f32 v137, s[0:1], v129, v129, 1.0
	v_rcp_f32_e32 v138, v137
	v_exp_f32_e32 v130, v130
	v_mul_f32_e32 v131, v131, v136
	v_mul_f32_e32 v131, 0xbfb8aa3b, v131
	v_fma_f32 v139, -v137, v138, 1.0
	v_fmac_f32_e32 v138, v139, v138
	v_div_scale_f32 v139, vcc, 1.0, v129, 1.0
	v_mul_f32_e32 v140, v139, v138
	v_fma_f32 v141, -v137, v140, v139
	v_fmac_f32_e32 v140, v141, v138
	v_fma_f32 v137, -v137, v140, v139
	v_div_fmas_f32 v137, v137, v138, v140
	v_add_f32_e32 v130, 1.0, v130
	v_div_fixup_f32 v129, v137, v129, 1.0
	v_div_scale_f32 v137, s[0:1], v130, v130, 1.0
	v_rcp_f32_e32 v138, v137
	v_exp_f32_e32 v131, v131
	v_mul_f32_e32 v132, 0x437f0000, v132
	v_mul_f32_e32 v133, 0x437f0000, v133
	v_fma_f32 v139, -v137, v138, 1.0
	v_fmac_f32_e32 v138, v139, v138
	v_div_scale_f32 v139, vcc, 1.0, v130, 1.0
	v_mul_f32_e32 v140, v139, v138
	v_fma_f32 v141, -v137, v140, v139
	v_fmac_f32_e32 v140, v141, v138
	v_fma_f32 v137, -v137, v140, v139
	v_div_fmas_f32 v136, v137, v138, v140
	v_add_f32_e32 v131, 1.0, v131
	v_div_fixup_f32 v130, v136, v130, 1.0
	v_div_scale_f32 v136, s[0:1], v131, v131, 1.0
	v_rcp_f32_e32 v137, v136
	v_mul_f32_e32 v128, 0x437f0000, v128
	v_mul_f32_e32 v129, 0x437f0000, v129
	v_rndne_f32_e32 v132, v132
	v_fma_f32 v138, -v136, v137, 1.0
	v_fmac_f32_e32 v137, v138, v137
; DI float sigmoidf_(float x) { return 1.f / (1.f + __expf(-x)); }
; DI float rstd_from16(const float* p, float inv_n) {
;   const f32x4 a = *(const f32x4*)p, b = *(const f32x4*)(p + 4), c = *(const f32x4*)(p + 8), d = *(const f32x4*)(p + 12);
;   const float s = ((a[0] + a[1]) + (a[2] + a[3])) + ((b[0] + b[1]) + (b[2] + b[3])) + ((c[0] + c[1]) + (c[2] + c[3])) + ((d[0] + d[1]) + (d[2] + d[3]));
;   return rsqrtf(s * inv_n + EPS_);
; DI void merge_tile(const Params& p, int layer, int tm, int tn, bf16_t* smem) {
;     ...
;         const float rs = rstd_from16((const float*)(p.ws + O_SSQ) + (size_t)(row0 + i * 16) * 16, 1.f / 1024.f);
; #pragma unroll
;         for (int j = 0; j < 2; ++j) {
;           unsigned w = 0;
; #pragma unroll
;           for (int r = 0; r < 4; ++r) w |= (unsigned)__float2int_rn(sigmoidf_(acc[i][j][r] * rs) * 255.f) << (8 * r);
;           gsp[(i * 2 + j) * NTHR] = w;
	v_div_scale_f32 v138, vcc, 1.0, v131, 1.0
	v_mul_f32_e32 v139, v138, v137
	v_fma_f32 v140, -v136, v139, v138
	v_fmac_f32_e32 v139, v140, v137
	v_fma_f32 v136, -v136, v139, v138
	v_div_fmas_f32 v136, v136, v137, v139
	v_div_fixup_f32 v131, v136, v131, 1.0
	v_rndne_f32_e32 v133, v133
	v_mul_f32_e32 v134, 0x437f0000, v134
	v_mul_f32_e32 v135, 0x437f0000, v135
	v_rndne_f32_e32 v128, v128
	v_rndne_f32_e32 v129, v129
	v_mul_f32_e32 v130, 0x437f0000, v130
	v_mul_f32_e32 v131, 0x437f0000, v131
	v_cvt_i32_f32_e32 v132, v132
	v_cvt_i32_f32_e32 v133, v133
	v_rndne_f32_e32 v134, v134
	v_rndne_f32_e32 v135, v135
	v_cvt_i32_f32_e32 v128, v128
	v_cvt_i32_f32_e32 v129, v129
	v_rndne_f32_e32 v130, v130
	v_rndne_f32_e32 v131, v131
	v_cvt_i32_f32_sdwa v134, v134 dst_sel:WORD_1 dst_unused:UNUSED_PAD src0_sel:DWORD
	v_cvt_i32_f32_sdwa v135, v135 dst_sel:BYTE_3 dst_unused:UNUSED_PAD src0_sel:DWORD
	v_cvt_i32_f32_sdwa v130, v130 dst_sel:WORD_1 dst_unused:UNUSED_PAD src0_sel:DWORD
	v_cvt_i32_f32_sdwa v131, v131 dst_sel:BYTE_3 dst_unused:UNUSED_PAD src0_sel:DWORD
	v_lshl_or_b32 v132, v133, 8, v132
	v_lshl_or_b32 v128, v129, 8, v128
	v_or3_b32 v132, v132, v134, v135
	v_or3_b32 v128, v128, v130, v131
	ds_write2st64_b32 v228, v132, v128 offset0:32 offset1:40
	v_or_b32_e32 v128, 48, v152
	v_ashrrev_i32_e32 v129, 31, v128
	v_lshlrev_b64 v[128:129], 6, v[128:129]
	v_lshl_add_u64 v[140:141], s[6:7], 0, v[128:129]
	v_bfe_u32 v244, v140, 6, 8
	v_lshlrev_b32_e32 v244, 3, v244
	v_add_u32_e32 v244, 0x24010, v244
	v_or_b32_e32 v246, 3, v140
	ds_read_b64 v[248:249], v244
	s_waitcnt lgkmcnt(0)
	v_cmp_ne_u32_e64 s[100:101], v248, v246
	s_nop 1
	s_and_saveexec_b64 s[98:99], s[100:101]
	s_cbranch_execz .LrcE1_3
	global_load_dwordx4 v[128:131], v[140:141], off
	global_load_dwordx4 v[132:135], v[140:141], off offset:16
	global_load_dwordx4 v[136:139], v[140:141], off offset:32
	s_nop 0
	global_load_dwordx4 v[140:143], v[140:141], off offset:48
	s_waitcnt vmcnt(3)
	v_mov_b32_e32 v144, v129
	v_mov_b32_e32 v145, v130
	v_mov_b32_e32 v129, v131
	s_waitcnt vmcnt(2)
	v_mov_b32_e32 v130, v133
	v_mov_b32_e32 v131, v134
	v_mov_b32_e32 v133, v135
	v_pk_add_f32 v[128:129], v[144:145], v[128:129]
	v_pk_add_f32 v[130:131], v[130:131], v[132:133]
	v_pk_add_f32 v[128:129], v[128:129], v[128:129] op_sel:[0,1] op_sel_hi:[1,0]
	v_pk_add_f32 v[130:131], v[130:131], v[130:131] op_sel:[0,1] op_sel_hi:[1,0]
	s_waitcnt vmcnt(1)
	v_add_f32_e32 v132, v136, v137
	v_add_f32_e32 v134, v138, v139
	s_waitcnt vmcnt(0)
	v_mov_b32_e32 v129, v140
	v_mov_b32_e32 v131, v141
	v_mov_b32_e32 v133, v142
	v_mov_b32_e32 v135, v143
	v_pk_add_f32 v[128:129], v[128:129], v[130:131]
	v_pk_add_f32 v[130:131], v[132:133], v[134:135]
	s_nop 0
	v_pk_add_f32 v[128:129], v[128:129], v[130:131]
	s_nop 0
	v_add_f32_e32 v128, v128, v129
	v_fmamk_f32 v128, v128, 0x3a800000, v225
	v_mul_f32_e32 v129, 0x4b800000, v128
	v_cmp_gt_f32_e32 vcc, s45, v128
	s_nop 1
	v_cndmask_b32_e32 v128, v128, v129, vcc
	v_rsq_f32_e32 v128, v128
	s_nop 0
	v_mul_f32_e32 v129, 0x45800000, v128
	v_cndmask_b32_e32 v128, v128, v129, vcc
	s_nop 0
	v_mov_b32_e32 v247, v128
	ds_write_b64 v244, v[246:247]
.LrcE1_3:
	s_or_b64 exec, exec, s[98:99]
	s_waitcnt vmcnt(0)
	v_cndmask_b32_e64 v128, v249, v128, s[100:101]
	v_mul_f32_e32 v124, v124, v128
	v_mul_f32_e32 v124, 0xbfb8aa3b, v124
	v_exp_f32_e32 v124, v124
	v_mul_f32_e32 v125, v125, v128
	v_mul_f32_e32 v125, 0xbfb8aa3b, v125
	v_exp_f32_e32 v125, v125
	v_add_f32_e32 v124, 1.0, v124
	v_div_scale_f32 v129, s[0:1], v124, v124, 1.0
	v_rcp_f32_e32 v130, v129
	v_add_f32_e32 v125, 1.0, v125
	v_mul_f32_e32 v126, v126, v128
	v_mul_f32_e32 v126, 0xbfb8aa3b, v126
	v_fma_f32 v131, -v129, v130, 1.0
	v_fmac_f32_e32 v130, v131, v130
	v_div_scale_f32 v131, vcc, 1.0, v124, 1.0
	v_mul_f32_e32 v132, v131, v130
	v_fma_f32 v133, -v129, v132, v131
	v_fmac_f32_e32 v132, v133, v130
	v_fma_f32 v129, -v129, v132, v131
	v_div_fmas_f32 v129, v129, v130, v132
	v_div_fixup_f32 v124, v129, v124, 1.0
	v_div_scale_f32 v129, s[0:1], v125, v125, 1.0
	v_rcp_f32_e32 v130, v129
	v_exp_f32_e32 v126, v126
	v_mul_f32_e32 v127, v127, v128
	v_mul_f32_e32 v127, 0xbfb8aa3b, v127
	v_fma_f32 v131, -v129, v130, 1.0
	v_fmac_f32_e32 v130, v131, v130
	v_div_scale_f32 v131, vcc, 1.0, v125, 1.0
	v_mul_f32_e32 v132, v131, v130
	v_fma_f32 v133, -v129, v132, v131
	v_fmac_f32_e32 v132, v133, v130
	v_fma_f32 v129, -v129, v132, v131
	v_div_fmas_f32 v129, v129, v130, v132
	v_add_f32_e32 v126, 1.0, v126
	v_div_fixup_f32 v125, v129, v125, 1.0
	v_div_scale_f32 v129, s[0:1], v126, v126, 1.0
	v_rcp_f32_e32 v130, v129
	v_exp_f32_e32 v127, v127
	v_mul_f32_e32 v120, v120, v128
	v_mul_f32_e32 v120, 0xbfb8aa3b, v120
	v_fma_f32 v131, -v129, v130, 1.0
	v_fmac_f32_e32 v130, v131, v130
	v_div_scale_f32 v131, vcc, 1.0, v126, 1.0
	v_mul_f32_e32 v132, v131, v130
	v_fma_f32 v133, -v129, v132, v131
	v_fmac_f32_e32 v132, v133, v130
	v_fma_f32 v129, -v129, v132, v131
	v_div_fmas_f32 v129, v129, v130, v132
	v_add_f32_e32 v127, 1.0, v127
	v_div_fixup_f32 v126, v129, v126, 1.0
	v_div_scale_f32 v129, s[0:1], v127, v127, 1.0
	v_rcp_f32_e32 v130, v129
	v_exp_f32_e32 v120, v120
	v_mul_f32_e32 v121, v121, v128
	v_mul_f32_e32 v121, 0xbfb8aa3b, v121
	v_fma_f32 v131, -v129, v130, 1.0
	v_fmac_f32_e32 v130, v131, v130
	v_div_scale_f32 v131, vcc, 1.0, v127, 1.0
	v_mul_f32_e32 v132, v131, v130
	v_fma_f32 v133, -v129, v132, v131
	v_fmac_f32_e32 v132, v133, v130
	v_fma_f32 v129, -v129, v132, v131
	v_div_fmas_f32 v129, v129, v130, v132
	v_add_f32_e32 v120, 1.0, v120
	v_div_fixup_f32 v127, v129, v127, 1.0
	v_div_scale_f32 v129, s[0:1], v120, v120, 1.0
	v_rcp_f32_e32 v130, v129
	v_exp_f32_e32 v121, v121
; DI float sigmoidf_(float x) { return 1.f / (1.f + __expf(-x)); }
; DI float rstd_from16(const float* p, float inv_n) {
;   const f32x4 a = *(const f32x4*)p, b = *(const f32x4*)(p + 4), c = *(const f32x4*)(p + 8), d = *(const f32x4*)(p + 12);
;   const float s = ((a[0] + a[1]) + (a[2] + a[3])) + ((b[0] + b[1]) + (b[2] + b[3])) + ((c[0] + c[1]) + (c[2] + c[3])) + ((d[0] + d[1]) + (d[2] + d[3]));
;   return rsqrtf(s * inv_n + EPS_);
; DI void merge_tile(const Params& p, int layer, int tm, int tn, bf16_t* smem) {
;     ...
;         const float rs = rstd_from16((const float*)(p.ws + O_SSQ) + (size_t)(row0 + i * 16) * 16, 1.f / 1024.f);
; #pragma unroll
;         for (int j = 0; j < 2; ++j) {
;           unsigned w = 0;
; #pragma unroll
;           for (int r = 0; r < 4; ++r) w |= (unsigned)__float2int_rn(sigmoidf_(acc[i][j][r] * rs) * 255.f) << (8 * r);
;           gsp[(i * 2 + j) * NTHR] = w;
	v_mul_f32_e32 v122, v122, v128
	v_mul_f32_e32 v122, 0xbfb8aa3b, v122
	v_fma_f32 v131, -v129, v130, 1.0
	v_fmac_f32_e32 v130, v131, v130
	v_div_scale_f32 v131, vcc, 1.0, v120, 1.0
	v_mul_f32_e32 v132, v131, v130
	v_fma_f32 v133, -v129, v132, v131
	v_fmac_f32_e32 v132, v133, v130
	v_fma_f32 v129, -v129, v132, v131
	v_div_fmas_f32 v129, v129, v130, v132
	v_add_f32_e32 v121, 1.0, v121
	v_div_fixup_f32 v120, v129, v120, 1.0
	v_div_scale_f32 v129, s[0:1], v121, v121, 1.0
	v_rcp_f32_e32 v130, v129
	v_exp_f32_e32 v122, v122
	v_mul_f32_e32 v123, v123, v128
	v_mul_f32_e32 v123, 0xbfb8aa3b, v123
	v_fma_f32 v131, -v129, v130, 1.0
	v_fmac_f32_e32 v130, v131, v130
	v_div_scale_f32 v131, vcc, 1.0, v121, 1.0
	v_mul_f32_e32 v132, v131, v130
	v_fma_f32 v133, -v129, v132, v131
	v_fmac_f32_e32 v132, v133, v130
	v_fma_f32 v129, -v129, v132, v131
	v_div_fmas_f32 v129, v129, v130, v132
	v_add_f32_e32 v122, 1.0, v122
	v_div_fixup_f32 v121, v129, v121, 1.0
	v_div_scale_f32 v129, s[0:1], v122, v122, 1.0
	v_rcp_f32_e32 v130, v129
	v_exp_f32_e32 v123, v123
	v_mul_f32_e32 v124, 0x437f0000, v124
	v_mul_f32_e32 v125, 0x437f0000, v125
	v_fma_f32 v131, -v129, v130, 1.0
	v_fmac_f32_e32 v130, v131, v130
	v_div_scale_f32 v131, vcc, 1.0, v122, 1.0
	v_mul_f32_e32 v132, v131, v130
	v_fma_f32 v133, -v129, v132, v131
	v_fmac_f32_e32 v132, v133, v130
	v_fma_f32 v129, -v129, v132, v131
	v_div_fmas_f32 v128, v129, v130, v132
	v_add_f32_e32 v123, 1.0, v123
	v_div_fixup_f32 v122, v128, v122, 1.0
	v_div_scale_f32 v128, s[0:1], v123, v123, 1.0
	v_rcp_f32_e32 v129, v128
	v_mul_f32_e32 v120, 0x437f0000, v120
	v_mul_f32_e32 v121, 0x437f0000, v121
	v_rndne_f32_e32 v124, v124
	v_fma_f32 v130, -v128, v129, 1.0
	v_fmac_f32_e32 v129, v130, v129
	v_div_scale_f32 v130, vcc, 1.0, v123, 1.0
	v_mul_f32_e32 v131, v130, v129
	v_fma_f32 v132, -v128, v131, v130
	v_fmac_f32_e32 v131, v132, v129
	v_fma_f32 v128, -v128, v131, v130
	v_div_fmas_f32 v128, v128, v129, v131
	v_div_fixup_f32 v123, v128, v123, 1.0
	v_rndne_f32_e32 v125, v125
	v_mul_f32_e32 v126, 0x437f0000, v126
	v_mul_f32_e32 v127, 0x437f0000, v127
	v_rndne_f32_e32 v120, v120
	v_rndne_f32_e32 v121, v121
	v_mul_f32_e32 v122, 0x437f0000, v122
	v_mul_f32_e32 v123, 0x437f0000, v123
	v_cvt_i32_f32_e32 v124, v124
	v_cvt_i32_f32_e32 v125, v125
	v_rndne_f32_e32 v126, v126
	v_rndne_f32_e32 v127, v127
	v_cvt_i32_f32_e32 v120, v120
	v_cvt_i32_f32_e32 v121, v121
	v_rndne_f32_e32 v122, v122
	v_rndne_f32_e32 v123, v123
	v_cvt_i32_f32_sdwa v126, v126 dst_sel:WORD_1 dst_unused:UNUSED_PAD src0_sel:DWORD
	v_cvt_i32_f32_sdwa v127, v127 dst_sel:BYTE_3 dst_unused:UNUSED_PAD src0_sel:DWORD
	v_cvt_i32_f32_sdwa v122, v122 dst_sel:WORD_1 dst_unused:UNUSED_PAD src0_sel:DWORD
	v_cvt_i32_f32_sdwa v123, v123 dst_sel:BYTE_3 dst_unused:UNUSED_PAD src0_sel:DWORD
	v_lshl_or_b32 v124, v125, 8, v124
	v_lshl_or_b32 v120, v121, 8, v120
	v_or3_b32 v124, v124, v126, v127
	v_or3_b32 v120, v120, v122, v123
	ds_write2st64_b32 v228, v124, v120 offset0:48 offset1:56
	v_or_b32_e32 v120, 64, v152
	v_ashrrev_i32_e32 v121, 31, v120
	v_lshlrev_b64 v[120:121], 6, v[120:121]
	v_lshl_add_u64 v[132:133], s[6:7], 0, v[120:121]
	v_bfe_u32 v244, v132, 6, 8
	v_lshlrev_b32_e32 v244, 3, v244
	v_add_u32_e32 v244, 0x24010, v244
	v_or_b32_e32 v246, 3, v132
	ds_read_b64 v[248:249], v244
	s_waitcnt lgkmcnt(0)
	v_cmp_ne_u32_e64 s[100:101], v248, v246
	s_nop 1
	s_and_saveexec_b64 s[98:99], s[100:101]
	s_cbranch_execz .LrcE1_4
	global_load_dwordx4 v[120:123], v[132:133], off
	global_load_dwordx4 v[124:127], v[132:133], off offset:16
	global_load_dwordx4 v[128:131], v[132:133], off offset:32
	s_nop 0
	global_load_dwordx4 v[132:135], v[132:133], off offset:48
	s_waitcnt vmcnt(3)
	v_mov_b32_e32 v136, v121
	v_mov_b32_e32 v137, v122
	v_mov_b32_e32 v121, v123
	s_waitcnt vmcnt(2)
	v_mov_b32_e32 v122, v125
	v_mov_b32_e32 v123, v126
	v_mov_b32_e32 v125, v127
	v_pk_add_f32 v[120:121], v[136:137], v[120:121]
	v_pk_add_f32 v[122:123], v[122:123], v[124:125]
	v_pk_add_f32 v[120:121], v[120:121], v[120:121] op_sel:[0,1] op_sel_hi:[1,0]
	v_pk_add_f32 v[122:123], v[122:123], v[122:123] op_sel:[0,1] op_sel_hi:[1,0]
	s_waitcnt vmcnt(1)
	v_add_f32_e32 v124, v128, v129
	v_add_f32_e32 v126, v130, v131
	s_waitcnt vmcnt(0)
	v_mov_b32_e32 v121, v132
	v_mov_b32_e32 v123, v133
	v_mov_b32_e32 v125, v134
	v_mov_b32_e32 v127, v135
	v_pk_add_f32 v[120:121], v[120:121], v[122:123]
	v_pk_add_f32 v[122:123], v[124:125], v[126:127]
	s_nop 0
	v_pk_add_f32 v[120:121], v[120:121], v[122:123]
	s_nop 0
	v_add_f32_e32 v120, v120, v121
	v_fmamk_f32 v120, v120, 0x3a800000, v225
	v_mul_f32_e32 v121, 0x4b800000, v120
	v_cmp_gt_f32_e32 vcc, s45, v120
	s_nop 1
	v_cndmask_b32_e32 v120, v120, v121, vcc
	v_rsq_f32_e32 v120, v120
	s_nop 0
	v_mul_f32_e32 v121, 0x45800000, v120
	v_cndmask_b32_e32 v120, v120, v121, vcc
	s_nop 0
	v_mov_b32_e32 v247, v120
	ds_write_b64 v244, v[246:247]
; DI float sigmoidf_(float x) { return 1.f / (1.f + __expf(-x)); }
; DI float rstd_from16(const float* p, float inv_n) {
;   const f32x4 a = *(const f32x4*)p, b = *(const f32x4*)(p + 4), c = *(const f32x4*)(p + 8), d = *(const f32x4*)(p + 12);
;   const float s = ((a[0] + a[1]) + (a[2] + a[3])) + ((b[0] + b[1]) + (b[2] + b[3])) + ((c[0] + c[1]) + (c[2] + c[3])) + ((d[0] + d[1]) + (d[2] + d[3]));
;   return rsqrtf(s * inv_n + EPS_);
; DI void merge_tile(const Params& p, int layer, int tm, int tn, bf16_t* smem) {
;     ...
;         const float rs = rstd_from16((const float*)(p.ws + O_SSQ) + (size_t)(row0 + i * 16) * 16, 1.f / 1024.f);
; #pragma unroll
;         for (int j = 0; j < 2; ++j) {
;           unsigned w = 0;
; #pragma unroll
;           for (int r = 0; r < 4; ++r) w |= (unsigned)__float2int_rn(sigmoidf_(acc[i][j][r] * rs) * 255.f) << (8 * r);
;           gsp[(i * 2 + j) * NTHR] = w;
.LrcE1_4:
	s_or_b64 exec, exec, s[98:99]
	s_waitcnt vmcnt(0)
	v_cndmask_b32_e64 v120, v249, v120, s[100:101]
	v_mul_f32_e32 v116, v116, v120
	v_mul_f32_e32 v116, 0xbfb8aa3b, v116
	v_exp_f32_e32 v116, v116
	v_mul_f32_e32 v117, v117, v120
	v_mul_f32_e32 v117, 0xbfb8aa3b, v117
	v_exp_f32_e32 v117, v117
	v_add_f32_e32 v116, 1.0, v116
	v_div_scale_f32 v121, s[0:1], v116, v116, 1.0
	v_rcp_f32_e32 v122, v121
	v_add_f32_e32 v117, 1.0, v117
	v_mul_f32_e32 v118, v118, v120
	v_mul_f32_e32 v118, 0xbfb8aa3b, v118
	v_fma_f32 v123, -v121, v122, 1.0
	v_fmac_f32_e32 v122, v123, v122
	v_div_scale_f32 v123, vcc, 1.0, v116, 1.0
	v_mul_f32_e32 v124, v123, v122
	v_fma_f32 v125, -v121, v124, v123
	v_fmac_f32_e32 v124, v125, v122
	v_fma_f32 v121, -v121, v124, v123
	v_div_fmas_f32 v121, v121, v122, v124
	v_div_fixup_f32 v116, v121, v116, 1.0
	v_div_scale_f32 v121, s[0:1], v117, v117, 1.0
	v_rcp_f32_e32 v122, v121
	v_exp_f32_e32 v118, v118
	v_mul_f32_e32 v119, v119, v120
	v_mul_f32_e32 v119, 0xbfb8aa3b, v119
	v_fma_f32 v123, -v121, v122, 1.0
	v_fmac_f32_e32 v122, v123, v122
	v_div_scale_f32 v123, vcc, 1.0, v117, 1.0
	v_mul_f32_e32 v124, v123, v122
	v_fma_f32 v125, -v121, v124, v123
	v_fmac_f32_e32 v124, v125, v122
	v_fma_f32 v121, -v121, v124, v123
	v_div_fmas_f32 v121, v121, v122, v124
	v_add_f32_e32 v118, 1.0, v118
	v_div_fixup_f32 v117, v121, v117, 1.0
	v_div_scale_f32 v121, s[0:1], v118, v118, 1.0
	v_rcp_f32_e32 v122, v121
	v_exp_f32_e32 v119, v119
	v_mul_f32_e32 v112, v112, v120
	v_mul_f32_e32 v112, 0xbfb8aa3b, v112
	v_fma_f32 v123, -v121, v122, 1.0
	v_fmac_f32_e32 v122, v123, v122
	v_div_scale_f32 v123, vcc, 1.0, v118, 1.0
	v_mul_f32_e32 v124, v123, v122
	v_fma_f32 v125, -v121, v124, v123
	v_fmac_f32_e32 v124, v125, v122
	v_fma_f32 v121, -v121, v124, v123
	v_div_fmas_f32 v121, v121, v122, v124
	v_add_f32_e32 v119, 1.0, v119
	v_div_fixup_f32 v118, v121, v118, 1.0
	v_div_scale_f32 v121, s[0:1], v119, v119, 1.0
	v_rcp_f32_e32 v122, v121
	v_exp_f32_e32 v112, v112
	v_mul_f32_e32 v113, v113, v120
	v_mul_f32_e32 v113, 0xbfb8aa3b, v113
	v_fma_f32 v123, -v121, v122, 1.0
	v_fmac_f32_e32 v122, v123, v122
	v_div_scale_f32 v123, vcc, 1.0, v119, 1.0
	v_mul_f32_e32 v124, v123, v122
	v_fma_f32 v125, -v121, v124, v123
	v_fmac_f32_e32 v124, v125, v122
	v_fma_f32 v121, -v121, v124, v123
	v_div_fmas_f32 v121, v121, v122, v124
	v_add_f32_e32 v112, 1.0, v112
	v_div_fixup_f32 v119, v121, v119, 1.0
	v_div_scale_f32 v121, s[0:1], v112, v112, 1.0
	v_rcp_f32_e32 v122, v121
	v_exp_f32_e32 v113, v113
	v_mul_f32_e32 v114, v114, v120
	v_mul_f32_e32 v114, 0xbfb8aa3b, v114
	v_fma_f32 v123, -v121, v122, 1.0
	v_fmac_f32_e32 v122, v123, v122
	v_div_scale_f32 v123, vcc, 1.0, v112, 1.0
	v_mul_f32_e32 v124, v123, v122
	v_fma_f32 v125, -v121, v124, v123
	v_fmac_f32_e32 v124, v125, v122
	v_fma_f32 v121, -v121, v124, v123
	v_div_fmas_f32 v121, v121, v122, v124
	v_add_f32_e32 v113, 1.0, v113
	v_div_fixup_f32 v112, v121, v112, 1.0
	v_div_scale_f32 v121, s[0:1], v113, v113, 1.0
	v_rcp_f32_e32 v122, v121
	v_exp_f32_e32 v114, v114
	v_mul_f32_e32 v115, v115, v120
	v_mul_f32_e32 v115, 0xbfb8aa3b, v115
	v_fma_f32 v123, -v121, v122, 1.0
	v_fmac_f32_e32 v122, v123, v122
	v_div_scale_f32 v123, vcc, 1.0, v113, 1.0
	v_mul_f32_e32 v124, v123, v122
	v_fma_f32 v125, -v121, v124, v123
	v_fmac_f32_e32 v124, v125, v122
	v_fma_f32 v121, -v121, v124, v123
	v_div_fmas_f32 v121, v121, v122, v124
	v_add_f32_e32 v114, 1.0, v114
	v_div_fixup_f32 v113, v121, v113, 1.0
	v_div_scale_f32 v121, s[0:1], v114, v114, 1.0
	v_rcp_f32_e32 v122, v121
	v_exp_f32_e32 v115, v115
	v_mul_f32_e32 v116, 0x437f0000, v116
	v_mul_f32_e32 v117, 0x437f0000, v117
	v_fma_f32 v123, -v121, v122, 1.0
	v_fmac_f32_e32 v122, v123, v122
	v_div_scale_f32 v123, vcc, 1.0, v114, 1.0
	v_mul_f32_e32 v124, v123, v122
	v_fma_f32 v125, -v121, v124, v123
	v_fmac_f32_e32 v124, v125, v122
	v_fma_f32 v121, -v121, v124, v123
	v_div_fmas_f32 v120, v121, v122, v124
	v_add_f32_e32 v115, 1.0, v115
	v_div_fixup_f32 v114, v120, v114, 1.0
	v_div_scale_f32 v120, s[0:1], v115, v115, 1.0
	v_rcp_f32_e32 v121, v120
	v_mul_f32_e32 v112, 0x437f0000, v112
	v_mul_f32_e32 v113, 0x437f0000, v113
	v_rndne_f32_e32 v116, v116
	v_fma_f32 v122, -v120, v121, 1.0
	v_fmac_f32_e32 v121, v122, v121
	v_div_scale_f32 v122, vcc, 1.0, v115, 1.0
	v_mul_f32_e32 v123, v122, v121
	v_fma_f32 v124, -v120, v123, v122
	v_fmac_f32_e32 v123, v124, v121
	v_fma_f32 v120, -v120, v123, v122
	v_div_fmas_f32 v120, v120, v121, v123
	v_div_fixup_f32 v115, v120, v115, 1.0
	v_rndne_f32_e32 v117, v117
	v_mul_f32_e32 v118, 0x437f0000, v118
	v_mul_f32_e32 v119, 0x437f0000, v119
	v_rndne_f32_e32 v112, v112
	v_rndne_f32_e32 v113, v113
	v_mul_f32_e32 v114, 0x437f0000, v114
	v_mul_f32_e32 v115, 0x437f0000, v115
	v_cvt_i32_f32_e32 v116, v116
	v_cvt_i32_f32_e32 v117, v117
	v_rndne_f32_e32 v118, v118
	v_rndne_f32_e32 v119, v119
	v_cvt_i32_f32_e32 v112, v112
	v_cvt_i32_f32_e32 v113, v113
	v_rndne_f32_e32 v114, v114
	v_rndne_f32_e32 v115, v115
	v_cvt_i32_f32_sdwa v118, v118 dst_sel:WORD_1 dst_unused:UNUSED_PAD src0_sel:DWORD
	v_cvt_i32_f32_sdwa v119, v119 dst_sel:BYTE_3 dst_unused:UNUSED_PAD src0_sel:DWORD
	v_cvt_i32_f32_sdwa v114, v114 dst_sel:WORD_1 dst_unused:UNUSED_PAD src0_sel:DWORD
	v_cvt_i32_f32_sdwa v115, v115 dst_sel:BYTE_3 dst_unused:UNUSED_PAD src0_sel:DWORD
	v_lshl_or_b32 v116, v117, 8, v116
	v_lshl_or_b32 v112, v113, 8, v112
	v_or3_b32 v116, v116, v118, v119
	v_or3_b32 v112, v112, v114, v115
	ds_write2st64_b32 v228, v116, v112 offset0:64 offset1:72
	v_or_b32_e32 v112, 0x50, v152
	v_ashrrev_i32_e32 v113, 31, v112
	v_lshlrev_b64 v[112:113], 6, v[112:113]
	v_lshl_add_u64 v[124:125], s[6:7], 0, v[112:113]
	v_bfe_u32 v244, v124, 6, 8
	v_lshlrev_b32_e32 v244, 3, v244
	v_add_u32_e32 v244, 0x24010, v244
	v_or_b32_e32 v246, 3, v124
	ds_read_b64 v[248:249], v244
	s_waitcnt lgkmcnt(0)
	v_cmp_ne_u32_e64 s[100:101], v248, v246
	s_nop 1
	s_and_saveexec_b64 s[98:99], s[100:101]
	s_cbranch_execz .LrcE1_5
; DI float sigmoidf_(float x) { return 1.f / (1.f + __expf(-x)); }
; DI float rstd_from16(const float* p, float inv_n) {
;   const f32x4 a = *(const f32x4*)p, b = *(const f32x4*)(p + 4), c = *(const f32x4*)(p + 8), d = *(const f32x4*)(p + 12);
;   const float s = ((a[0] + a[1]) + (a[2] + a[3])) + ((b[0] + b[1]) + (b[2] + b[3])) + ((c[0] + c[1]) + (c[2] + c[3])) + ((d[0] + d[1]) + (d[2] + d[3]));
;   return rsqrtf(s * inv_n + EPS_);
; DI void merge_tile(const Params& p, int layer, int tm, int tn, bf16_t* smem) {
;     ...
;         const float rs = rstd_from16((const float*)(p.ws + O_SSQ) + (size_t)(row0 + i * 16) * 16, 1.f / 1024.f);
; #pragma unroll
;         for (int j = 0; j < 2; ++j) {
;           unsigned w = 0;
; #pragma unroll
;           for (int r = 0; r < 4; ++r) w |= (unsigned)__float2int_rn(sigmoidf_(acc[i][j][r] * rs) * 255.f) << (8 * r);
;           gsp[(i * 2 + j) * NTHR] = w;
	global_load_dwordx4 v[112:115], v[124:125], off
	global_load_dwordx4 v[116:119], v[124:125], off offset:16
	global_load_dwordx4 v[120:123], v[124:125], off offset:32
	s_nop 0
	global_load_dwordx4 v[124:127], v[124:125], off offset:48
	s_waitcnt vmcnt(3)
	v_mov_b32_e32 v128, v113
	v_mov_b32_e32 v129, v114
	v_mov_b32_e32 v113, v115
	s_waitcnt vmcnt(2)
	v_mov_b32_e32 v114, v117
	v_mov_b32_e32 v115, v118
	v_mov_b32_e32 v117, v119
	v_pk_add_f32 v[112:113], v[128:129], v[112:113]
	v_pk_add_f32 v[114:115], v[114:115], v[116:117]
	v_pk_add_f32 v[112:113], v[112:113], v[112:113] op_sel:[0,1] op_sel_hi:[1,0]
	v_pk_add_f32 v[114:115], v[114:115], v[114:115] op_sel:[0,1] op_sel_hi:[1,0]
	s_waitcnt vmcnt(1)
	v_add_f32_e32 v116, v120, v121
	v_add_f32_e32 v118, v122, v123
	s_waitcnt vmcnt(0)
	v_mov_b32_e32 v113, v124
	v_mov_b32_e32 v115, v125
	v_mov_b32_e32 v117, v126
	v_mov_b32_e32 v119, v127
	v_pk_add_f32 v[112:113], v[112:113], v[114:115]
	v_pk_add_f32 v[114:115], v[116:117], v[118:119]
	s_nop 0
	v_pk_add_f32 v[112:113], v[112:113], v[114:115]
	s_nop 0
	v_add_f32_e32 v112, v112, v113
	v_fmamk_f32 v112, v112, 0x3a800000, v225
	v_mul_f32_e32 v113, 0x4b800000, v112
	v_cmp_gt_f32_e32 vcc, s45, v112
	s_nop 1
	v_cndmask_b32_e32 v112, v112, v113, vcc
	v_rsq_f32_e32 v112, v112
	s_nop 0
	v_mul_f32_e32 v113, 0x45800000, v112
	v_cndmask_b32_e32 v112, v112, v113, vcc
	s_nop 0
	v_mov_b32_e32 v247, v112
	ds_write_b64 v244, v[246:247]
.LrcE1_5:
	s_or_b64 exec, exec, s[98:99]
	s_waitcnt vmcnt(0)
	v_cndmask_b32_e64 v112, v249, v112, s[100:101]
	v_mul_f32_e32 v108, v108, v112
	v_mul_f32_e32 v108, 0xbfb8aa3b, v108
	v_exp_f32_e32 v108, v108
	v_mul_f32_e32 v109, v109, v112
	v_mul_f32_e32 v109, 0xbfb8aa3b, v109
	v_exp_f32_e32 v109, v109
	v_add_f32_e32 v108, 1.0, v108
	v_div_scale_f32 v113, s[0:1], v108, v108, 1.0
	v_rcp_f32_e32 v114, v113
	v_add_f32_e32 v109, 1.0, v109
	v_mul_f32_e32 v110, v110, v112
	v_mul_f32_e32 v110, 0xbfb8aa3b, v110
	v_fma_f32 v115, -v113, v114, 1.0
	v_fmac_f32_e32 v114, v115, v114
	v_div_scale_f32 v115, vcc, 1.0, v108, 1.0
	v_mul_f32_e32 v116, v115, v114
	v_fma_f32 v117, -v113, v116, v115
	v_fmac_f32_e32 v116, v117, v114
	v_fma_f32 v113, -v113, v116, v115
	v_div_fmas_f32 v113, v113, v114, v116
	v_div_fixup_f32 v108, v113, v108, 1.0
	v_div_scale_f32 v113, s[0:1], v109, v109, 1.0
	v_rcp_f32_e32 v114, v113
	v_exp_f32_e32 v110, v110
	v_mul_f32_e32 v111, v111, v112
	v_mul_f32_e32 v111, 0xbfb8aa3b, v111
	v_fma_f32 v115, -v113, v114, 1.0
	v_fmac_f32_e32 v114, v115, v114
	v_div_scale_f32 v115, vcc, 1.0, v109, 1.0
	v_mul_f32_e32 v116, v115, v114
	v_fma_f32 v117, -v113, v116, v115
	v_fmac_f32_e32 v116, v117, v114
	v_fma_f32 v113, -v113, v116, v115
	v_div_fmas_f32 v113, v113, v114, v116
	v_add_f32_e32 v110, 1.0, v110
	v_div_fixup_f32 v109, v113, v109, 1.0
	v_div_scale_f32 v113, s[0:1], v110, v110, 1.0
	v_rcp_f32_e32 v114, v113
	v_exp_f32_e32 v111, v111
	v_mul_f32_e32 v104, v104, v112
	v_mul_f32_e32 v104, 0xbfb8aa3b, v104
	v_fma_f32 v115, -v113, v114, 1.0
	v_fmac_f32_e32 v114, v115, v114
	v_div_scale_f32 v115, vcc, 1.0, v110, 1.0
	v_mul_f32_e32 v116, v115, v114
	v_fma_f32 v117, -v113, v116, v115
	v_fmac_f32_e32 v116, v117, v114
	v_fma_f32 v113, -v113, v116, v115
	v_div_fmas_f32 v113, v113, v114, v116
	v_add_f32_e32 v111, 1.0, v111
	v_div_fixup_f32 v110, v113, v110, 1.0
	v_div_scale_f32 v113, s[0:1], v111, v111, 1.0
	v_rcp_f32_e32 v114, v113
	v_exp_f32_e32 v104, v104
	v_mul_f32_e32 v105, v105, v112
	v_mul_f32_e32 v105, 0xbfb8aa3b, v105
	v_fma_f32 v115, -v113, v114, 1.0
	v_fmac_f32_e32 v114, v115, v114
	v_div_scale_f32 v115, vcc, 1.0, v111, 1.0
	v_mul_f32_e32 v116, v115, v114
	v_fma_f32 v117, -v113, v116, v115
	v_fmac_f32_e32 v116, v117, v114
	v_fma_f32 v113, -v113, v116, v115
	v_div_fmas_f32 v113, v113, v114, v116
	v_add_f32_e32 v104, 1.0, v104
	v_div_fixup_f32 v111, v113, v111, 1.0
	v_div_scale_f32 v113, s[0:1], v104, v104, 1.0
	v_rcp_f32_e32 v114, v113
	v_exp_f32_e32 v105, v105
	v_mul_f32_e32 v106, v106, v112
	v_mul_f32_e32 v106, 0xbfb8aa3b, v106
	v_fma_f32 v115, -v113, v114, 1.0
	v_fmac_f32_e32 v114, v115, v114
	v_div_scale_f32 v115, vcc, 1.0, v104, 1.0
	v_mul_f32_e32 v116, v115, v114
	v_fma_f32 v117, -v113, v116, v115
	v_fmac_f32_e32 v116, v117, v114
	v_fma_f32 v113, -v113, v116, v115
	v_div_fmas_f32 v113, v113, v114, v116
	v_add_f32_e32 v105, 1.0, v105
	v_div_fixup_f32 v104, v113, v104, 1.0
	v_div_scale_f32 v113, s[0:1], v105, v105, 1.0
	v_rcp_f32_e32 v114, v113
	v_exp_f32_e32 v106, v106
	v_mul_f32_e32 v107, v107, v112
	v_mul_f32_e32 v107, 0xbfb8aa3b, v107
	v_fma_f32 v115, -v113, v114, 1.0
	v_fmac_f32_e32 v114, v115, v114
	v_div_scale_f32 v115, vcc, 1.0, v105, 1.0
	v_mul_f32_e32 v116, v115, v114
	v_fma_f32 v117, -v113, v116, v115
	v_fmac_f32_e32 v116, v117, v114
	v_fma_f32 v113, -v113, v116, v115
	v_div_fmas_f32 v113, v113, v114, v116
	v_add_f32_e32 v106, 1.0, v106
	v_div_fixup_f32 v105, v113, v105, 1.0
	v_div_scale_f32 v113, s[0:1], v106, v106, 1.0
	v_rcp_f32_e32 v114, v113
	v_exp_f32_e32 v107, v107
	v_mul_f32_e32 v108, 0x437f0000, v108
	v_mul_f32_e32 v109, 0x437f0000, v109
	v_fma_f32 v115, -v113, v114, 1.0
	v_fmac_f32_e32 v114, v115, v114
	v_div_scale_f32 v115, vcc, 1.0, v106, 1.0
	v_mul_f32_e32 v116, v115, v114
	v_fma_f32 v117, -v113, v116, v115
	v_fmac_f32_e32 v116, v117, v114
	v_fma_f32 v113, -v113, v116, v115
	v_div_fmas_f32 v112, v113, v114, v116
	v_add_f32_e32 v107, 1.0, v107
	v_div_fixup_f32 v106, v112, v106, 1.0
	v_div_scale_f32 v112, s[0:1], v107, v107, 1.0
	v_rcp_f32_e32 v113, v112
	v_mul_f32_e32 v104, 0x437f0000, v104
	v_mul_f32_e32 v105, 0x437f0000, v105
	v_rndne_f32_e32 v108, v108
	v_fma_f32 v114, -v112, v113, 1.0
	v_fmac_f32_e32 v113, v114, v113
; DI float sigmoidf_(float x) { return 1.f / (1.f + __expf(-x)); }
; DI float rstd_from16(const float* p, float inv_n) {
;   const f32x4 a = *(const f32x4*)p, b = *(const f32x4*)(p + 4), c = *(const f32x4*)(p + 8), d = *(const f32x4*)(p + 12);
;   const float s = ((a[0] + a[1]) + (a[2] + a[3])) + ((b[0] + b[1]) + (b[2] + b[3])) + ((c[0] + c[1]) + (c[2] + c[3])) + ((d[0] + d[1]) + (d[2] + d[3]));
;   return rsqrtf(s * inv_n + EPS_);
; DI void merge_tile(const Params& p, int layer, int tm, int tn, bf16_t* smem) {
;     ...
;         const float rs = rstd_from16((const float*)(p.ws + O_SSQ) + (size_t)(row0 + i * 16) * 16, 1.f / 1024.f);
; #pragma unroll
;         for (int j = 0; j < 2; ++j) {
;           unsigned w = 0;
; #pragma unroll
;           for (int r = 0; r < 4; ++r) w |= (unsigned)__float2int_rn(sigmoidf_(acc[i][j][r] * rs) * 255.f) << (8 * r);
;           gsp[(i * 2 + j) * NTHR] = w;
	v_div_scale_f32 v114, vcc, 1.0, v107, 1.0
	v_mul_f32_e32 v115, v114, v113
	v_fma_f32 v116, -v112, v115, v114
	v_fmac_f32_e32 v115, v116, v113
	v_fma_f32 v112, -v112, v115, v114
	v_div_fmas_f32 v112, v112, v113, v115
	v_div_fixup_f32 v107, v112, v107, 1.0
	v_rndne_f32_e32 v109, v109
	v_mul_f32_e32 v110, 0x437f0000, v110
	v_mul_f32_e32 v111, 0x437f0000, v111
	v_rndne_f32_e32 v104, v104
	v_rndne_f32_e32 v105, v105
	v_mul_f32_e32 v106, 0x437f0000, v106
	v_mul_f32_e32 v107, 0x437f0000, v107
	v_cvt_i32_f32_e32 v108, v108
	v_cvt_i32_f32_e32 v109, v109
	v_rndne_f32_e32 v110, v110
	v_rndne_f32_e32 v111, v111
	v_cvt_i32_f32_e32 v104, v104
	v_cvt_i32_f32_e32 v105, v105
	v_rndne_f32_e32 v106, v106
	v_rndne_f32_e32 v107, v107
	v_cvt_i32_f32_sdwa v110, v110 dst_sel:WORD_1 dst_unused:UNUSED_PAD src0_sel:DWORD
	v_cvt_i32_f32_sdwa v111, v111 dst_sel:BYTE_3 dst_unused:UNUSED_PAD src0_sel:DWORD
	v_cvt_i32_f32_sdwa v106, v106 dst_sel:WORD_1 dst_unused:UNUSED_PAD src0_sel:DWORD
	v_cvt_i32_f32_sdwa v107, v107 dst_sel:BYTE_3 dst_unused:UNUSED_PAD src0_sel:DWORD
	v_lshl_or_b32 v108, v109, 8, v108
	v_lshl_or_b32 v104, v105, 8, v104
	v_or3_b32 v108, v108, v110, v111
	v_or3_b32 v104, v104, v106, v107
	ds_write2st64_b32 v228, v108, v104 offset0:80 offset1:88
	v_or_b32_e32 v104, 0x60, v152
	v_ashrrev_i32_e32 v105, 31, v104
	v_lshlrev_b64 v[104:105], 6, v[104:105]
	v_lshl_add_u64 v[116:117], s[6:7], 0, v[104:105]
	v_bfe_u32 v244, v116, 6, 8
	v_lshlrev_b32_e32 v244, 3, v244
	v_add_u32_e32 v244, 0x24010, v244
	v_or_b32_e32 v246, 3, v116
	ds_read_b64 v[248:249], v244
	s_waitcnt lgkmcnt(0)
	v_cmp_ne_u32_e64 s[100:101], v248, v246
	s_nop 1
	s_and_saveexec_b64 s[98:99], s[100:101]
	s_cbranch_execz .LrcE1_6
	global_load_dwordx4 v[104:107], v[116:117], off
	global_load_dwordx4 v[108:111], v[116:117], off offset:16
	global_load_dwordx4 v[112:115], v[116:117], off offset:32
	s_nop 0
	global_load_dwordx4 v[116:119], v[116:117], off offset:48
	s_waitcnt vmcnt(3)
	v_mov_b32_e32 v120, v105
	v_mov_b32_e32 v121, v106
	v_mov_b32_e32 v105, v107
	s_waitcnt vmcnt(2)
	v_mov_b32_e32 v106, v109
	v_mov_b32_e32 v107, v110
	v_mov_b32_e32 v109, v111
	v_pk_add_f32 v[104:105], v[120:121], v[104:105]
	v_pk_add_f32 v[106:107], v[106:107], v[108:109]
	v_pk_add_f32 v[104:105], v[104:105], v[104:105] op_sel:[0,1] op_sel_hi:[1,0]
	v_pk_add_f32 v[106:107], v[106:107], v[106:107] op_sel:[0,1] op_sel_hi:[1,0]
	s_waitcnt vmcnt(1)
	v_add_f32_e32 v108, v112, v113
	v_add_f32_e32 v110, v114, v115
	s_waitcnt vmcnt(0)
	v_mov_b32_e32 v105, v116
	v_mov_b32_e32 v107, v117
	v_mov_b32_e32 v109, v118
	v_mov_b32_e32 v111, v119
	v_pk_add_f32 v[104:105], v[104:105], v[106:107]
	v_pk_add_f32 v[106:107], v[108:109], v[110:111]
	s_nop 0
	v_pk_add_f32 v[104:105], v[104:105], v[106:107]
	s_nop 0
	v_add_f32_e32 v104, v104, v105
	v_fmamk_f32 v104, v104, 0x3a800000, v225
	v_mul_f32_e32 v105, 0x4b800000, v104
	v_cmp_gt_f32_e32 vcc, s45, v104
	s_nop 1
	v_cndmask_b32_e32 v104, v104, v105, vcc
	v_rsq_f32_e32 v104, v104
	s_nop 0
	v_mul_f32_e32 v105, 0x45800000, v104
	v_cndmask_b32_e32 v104, v104, v105, vcc
	s_nop 0
	v_mov_b32_e32 v247, v104
	ds_write_b64 v244, v[246:247]
.LrcE1_6:
	s_or_b64 exec, exec, s[98:99]
	s_waitcnt vmcnt(0)
	v_cndmask_b32_e64 v104, v249, v104, s[100:101]
	v_mul_f32_e32 v100, v100, v104
	v_mul_f32_e32 v100, 0xbfb8aa3b, v100
	v_exp_f32_e32 v100, v100
	v_mul_f32_e32 v101, v101, v104
	v_mul_f32_e32 v101, 0xbfb8aa3b, v101
	v_exp_f32_e32 v101, v101
	v_add_f32_e32 v100, 1.0, v100
	v_div_scale_f32 v105, s[0:1], v100, v100, 1.0
	v_rcp_f32_e32 v106, v105
	v_add_f32_e32 v101, 1.0, v101
	v_mul_f32_e32 v102, v102, v104
	v_mul_f32_e32 v102, 0xbfb8aa3b, v102
	v_fma_f32 v107, -v105, v106, 1.0
	v_fmac_f32_e32 v106, v107, v106
	v_div_scale_f32 v107, vcc, 1.0, v100, 1.0
	v_mul_f32_e32 v108, v107, v106
	v_fma_f32 v109, -v105, v108, v107
	v_fmac_f32_e32 v108, v109, v106
	v_fma_f32 v105, -v105, v108, v107
	v_div_fmas_f32 v105, v105, v106, v108
	v_div_fixup_f32 v100, v105, v100, 1.0
	v_div_scale_f32 v105, s[0:1], v101, v101, 1.0
	v_rcp_f32_e32 v106, v105
	v_exp_f32_e32 v102, v102
	v_mul_f32_e32 v103, v103, v104
	v_mul_f32_e32 v103, 0xbfb8aa3b, v103
	v_fma_f32 v107, -v105, v106, 1.0
	v_fmac_f32_e32 v106, v107, v106
	v_div_scale_f32 v107, vcc, 1.0, v101, 1.0
	v_mul_f32_e32 v108, v107, v106
	v_fma_f32 v109, -v105, v108, v107
	v_fmac_f32_e32 v108, v109, v106
	v_fma_f32 v105, -v105, v108, v107
	v_div_fmas_f32 v105, v105, v106, v108
	v_add_f32_e32 v102, 1.0, v102
	v_div_fixup_f32 v101, v105, v101, 1.0
	v_div_scale_f32 v105, s[0:1], v102, v102, 1.0
	v_rcp_f32_e32 v106, v105
	v_exp_f32_e32 v103, v103
	v_mul_f32_e32 v96, v96, v104
	v_mul_f32_e32 v96, 0xbfb8aa3b, v96
	v_fma_f32 v107, -v105, v106, 1.0
	v_fmac_f32_e32 v106, v107, v106
	v_div_scale_f32 v107, vcc, 1.0, v102, 1.0
	v_mul_f32_e32 v108, v107, v106
	v_fma_f32 v109, -v105, v108, v107
	v_fmac_f32_e32 v108, v109, v106
	v_fma_f32 v105, -v105, v108, v107
	v_div_fmas_f32 v105, v105, v106, v108
	v_add_f32_e32 v103, 1.0, v103
	v_div_fixup_f32 v102, v105, v102, 1.0
	v_div_scale_f32 v105, s[0:1], v103, v103, 1.0
	v_rcp_f32_e32 v106, v105
	v_exp_f32_e32 v96, v96
	v_mul_f32_e32 v97, v97, v104
	v_mul_f32_e32 v97, 0xbfb8aa3b, v97
	v_fma_f32 v107, -v105, v106, 1.0
	v_fmac_f32_e32 v106, v107, v106
	v_div_scale_f32 v107, vcc, 1.0, v103, 1.0
	v_mul_f32_e32 v108, v107, v106
	v_fma_f32 v109, -v105, v108, v107
	v_fmac_f32_e32 v108, v109, v106
	v_fma_f32 v105, -v105, v108, v107
	v_div_fmas_f32 v105, v105, v106, v108
	v_add_f32_e32 v96, 1.0, v96
	v_div_fixup_f32 v103, v105, v103, 1.0
	v_div_scale_f32 v105, s[0:1], v96, v96, 1.0
	v_rcp_f32_e32 v106, v105
	v_exp_f32_e32 v97, v97
	v_mul_f32_e32 v98, v98, v104
; DI float sigmoidf_(float x) { return 1.f / (1.f + __expf(-x)); }
; DI float rstd_from16(const float* p, float inv_n) {
;   const f32x4 a = *(const f32x4*)p, b = *(const f32x4*)(p + 4), c = *(const f32x4*)(p + 8), d = *(const f32x4*)(p + 12);
;   const float s = ((a[0] + a[1]) + (a[2] + a[3])) + ((b[0] + b[1]) + (b[2] + b[3])) + ((c[0] + c[1]) + (c[2] + c[3])) + ((d[0] + d[1]) + (d[2] + d[3]));
;   return rsqrtf(s * inv_n + EPS_);
; DI void merge_tile(const Params& p, int layer, int tm, int tn, bf16_t* smem) {
;     ...
;         const float rs = rstd_from16((const float*)(p.ws + O_SSQ) + (size_t)(row0 + i * 16) * 16, 1.f / 1024.f);
; #pragma unroll
;         for (int j = 0; j < 2; ++j) {
;           unsigned w = 0;
; #pragma unroll
;           for (int r = 0; r < 4; ++r) w |= (unsigned)__float2int_rn(sigmoidf_(acc[i][j][r] * rs) * 255.f) << (8 * r);
;           gsp[(i * 2 + j) * NTHR] = w;
	v_mul_f32_e32 v98, 0xbfb8aa3b, v98
	v_fma_f32 v107, -v105, v106, 1.0
	v_fmac_f32_e32 v106, v107, v106
	v_div_scale_f32 v107, vcc, 1.0, v96, 1.0
	v_mul_f32_e32 v108, v107, v106
	v_fma_f32 v109, -v105, v108, v107
	v_fmac_f32_e32 v108, v109, v106
	v_fma_f32 v105, -v105, v108, v107
	v_div_fmas_f32 v105, v105, v106, v108
	v_add_f32_e32 v97, 1.0, v97
	v_div_fixup_f32 v96, v105, v96, 1.0
	v_div_scale_f32 v105, s[0:1], v97, v97, 1.0
	v_rcp_f32_e32 v106, v105
	v_exp_f32_e32 v98, v98
	v_mul_f32_e32 v99, v99, v104
	v_mul_f32_e32 v99, 0xbfb8aa3b, v99
	v_fma_f32 v107, -v105, v106, 1.0
	v_fmac_f32_e32 v106, v107, v106
	v_div_scale_f32 v107, vcc, 1.0, v97, 1.0
	v_mul_f32_e32 v108, v107, v106
	v_fma_f32 v109, -v105, v108, v107
	v_fmac_f32_e32 v108, v109, v106
	v_fma_f32 v105, -v105, v108, v107
	v_div_fmas_f32 v105, v105, v106, v108
	v_add_f32_e32 v98, 1.0, v98
	v_div_fixup_f32 v97, v105, v97, 1.0
	v_div_scale_f32 v105, s[0:1], v98, v98, 1.0
	v_rcp_f32_e32 v106, v105
	v_exp_f32_e32 v99, v99
	v_mul_f32_e32 v100, 0x437f0000, v100
	v_mul_f32_e32 v101, 0x437f0000, v101
	v_fma_f32 v107, -v105, v106, 1.0
	v_fmac_f32_e32 v106, v107, v106
	v_div_scale_f32 v107, vcc, 1.0, v98, 1.0
	v_mul_f32_e32 v108, v107, v106
	v_fma_f32 v109, -v105, v108, v107
	v_fmac_f32_e32 v108, v109, v106
	v_fma_f32 v105, -v105, v108, v107
	v_div_fmas_f32 v104, v105, v106, v108
	v_add_f32_e32 v99, 1.0, v99
	v_div_fixup_f32 v98, v104, v98, 1.0
	v_div_scale_f32 v104, s[0:1], v99, v99, 1.0
	v_rcp_f32_e32 v105, v104
	v_mul_f32_e32 v96, 0x437f0000, v96
	v_mul_f32_e32 v97, 0x437f0000, v97
	v_rndne_f32_e32 v100, v100
	v_fma_f32 v106, -v104, v105, 1.0
	v_fmac_f32_e32 v105, v106, v105
	v_div_scale_f32 v106, vcc, 1.0, v99, 1.0
	v_mul_f32_e32 v107, v106, v105
	v_fma_f32 v108, -v104, v107, v106
	v_fmac_f32_e32 v107, v108, v105
	v_fma_f32 v104, -v104, v107, v106
	v_div_fmas_f32 v104, v104, v105, v107
	v_div_fixup_f32 v99, v104, v99, 1.0
	v_rndne_f32_e32 v101, v101
	v_mul_f32_e32 v102, 0x437f0000, v102
	v_mul_f32_e32 v103, 0x437f0000, v103
	v_rndne_f32_e32 v96, v96
	v_rndne_f32_e32 v97, v97
	v_mul_f32_e32 v98, 0x437f0000, v98
	v_mul_f32_e32 v99, 0x437f0000, v99
	v_cvt_i32_f32_e32 v100, v100
	v_cvt_i32_f32_e32 v101, v101
	v_rndne_f32_e32 v102, v102
	v_rndne_f32_e32 v103, v103
	v_cvt_i32_f32_e32 v96, v96
	v_cvt_i32_f32_e32 v97, v97
	v_rndne_f32_e32 v98, v98
	v_rndne_f32_e32 v99, v99
	v_cvt_i32_f32_sdwa v102, v102 dst_sel:WORD_1 dst_unused:UNUSED_PAD src0_sel:DWORD
	v_cvt_i32_f32_sdwa v103, v103 dst_sel:BYTE_3 dst_unused:UNUSED_PAD src0_sel:DWORD
	v_cvt_i32_f32_sdwa v98, v98 dst_sel:WORD_1 dst_unused:UNUSED_PAD src0_sel:DWORD
	v_cvt_i32_f32_sdwa v99, v99 dst_sel:BYTE_3 dst_unused:UNUSED_PAD src0_sel:DWORD
	v_lshl_or_b32 v100, v101, 8, v100
	v_lshl_or_b32 v96, v97, 8, v96
	v_or3_b32 v100, v100, v102, v103
	v_or3_b32 v96, v96, v98, v99
	ds_write2st64_b32 v228, v100, v96 offset0:96 offset1:104
	v_or_b32_e32 v96, 0x70, v152
	v_ashrrev_i32_e32 v97, 31, v96
	v_lshlrev_b64 v[96:97], 6, v[96:97]
	v_lshl_add_u64 v[108:109], s[6:7], 0, v[96:97]
	v_mov_b64_e32 v[154:155], v[86:87]
	v_mov_b64_e32 v[152:153], v[84:85]
	v_bfe_u32 v244, v108, 6, 8
	v_lshlrev_b32_e32 v244, 3, v244
	v_add_u32_e32 v244, 0x24010, v244
	v_or_b32_e32 v246, 3, v108
	ds_read_b64 v[248:249], v244
	s_waitcnt lgkmcnt(0)
	v_cmp_ne_u32_e64 s[100:101], v248, v246
	s_nop 1
	s_and_saveexec_b64 s[98:99], s[100:101]
	s_cbranch_execz .LrcE1_7
	global_load_dwordx4 v[96:99], v[108:109], off
	global_load_dwordx4 v[100:103], v[108:109], off offset:16
	global_load_dwordx4 v[104:107], v[108:109], off offset:32
	s_nop 0
	global_load_dwordx4 v[108:111], v[108:109], off offset:48
	s_waitcnt vmcnt(3)
	v_mov_b32_e32 v112, v97
	v_mov_b32_e32 v113, v98
	v_mov_b32_e32 v97, v99
	s_waitcnt vmcnt(2)
	v_mov_b32_e32 v98, v101
	v_mov_b32_e32 v99, v102
	v_mov_b32_e32 v101, v103
	v_pk_add_f32 v[96:97], v[112:113], v[96:97]
	v_pk_add_f32 v[98:99], v[98:99], v[100:101]
	v_pk_add_f32 v[96:97], v[96:97], v[96:97] op_sel:[0,1] op_sel_hi:[1,0]
	v_pk_add_f32 v[98:99], v[98:99], v[98:99] op_sel:[0,1] op_sel_hi:[1,0]
	s_waitcnt vmcnt(1)
	v_add_f32_e32 v100, v104, v105
	v_add_f32_e32 v102, v106, v107
	s_waitcnt vmcnt(0)
	v_mov_b32_e32 v97, v108
	v_mov_b32_e32 v99, v109
	v_mov_b32_e32 v101, v110
	v_mov_b32_e32 v103, v111
	v_pk_add_f32 v[96:97], v[96:97], v[98:99]
	v_pk_add_f32 v[98:99], v[100:101], v[102:103]
	s_nop 0
	v_pk_add_f32 v[96:97], v[96:97], v[98:99]
	s_nop 0
	v_add_f32_e32 v96, v96, v97
	v_fmamk_f32 v96, v96, 0x3a800000, v225
	v_mul_f32_e32 v97, 0x4b800000, v96
	v_cmp_gt_f32_e32 vcc, s45, v96
	s_nop 1
	v_cndmask_b32_e32 v96, v96, v97, vcc
	v_rsq_f32_e32 v96, v96
	s_nop 0
	v_mul_f32_e32 v97, 0x45800000, v96
	v_cndmask_b32_e32 v96, v96, v97, vcc
	s_nop 0
	v_mov_b32_e32 v247, v96
	ds_write_b64 v244, v[246:247]
; DI int TIDX() { int t = (int)threadIdx.x; asm volatile("" : "+v"(t)); return t; }
; DI float sigmoidf_(float x) { return 1.f / (1.f + __expf(-x)); }
; DI f32x4 mfma16(bf16x8 a, bf16x8 b, f32x4 c) { return __builtin_amdgcn_mfma_f32_16x16x32_bf16(a, b, c, 0, 0, 0); }
; DI void merge_tile(const Params& p, int layer, int tm, int tn, bf16_t* smem) {
;     ...
;   for (int sg = 0; sg < 6; ++sg) {
;     const int nk = (sg & 1) ? 8 : 16;
; #pragma unroll 1
;     for (int kt = 0; kt < nk; ++kt) {
;       sstore(buf ^ 1);
;       gload_next();
;       __builtin_amdgcn_sched_barrier(0);
;       const bf16_t* As = smem + buf * L::STAGE + (wm * 128 + l15) * LDT + quad * 8;
;       const bf16_t* Bs = smem + buf * L::STAGE + L::A_ELEMS + (wn * 32 + l15) * LDT + quad * 8;
; #pragma unroll
;       for (int ks = 0; ks < 2; ++ks) {
;         if (ks == 1) asm volatile("" ::: "memory");
;         bf16x8 b[2];
; #pragma unroll
;         for (int j = 0; j < 2; ++j) b[j] = *(const bf16x8*)(Bs + j * 16 * LDT + ks * 32);
; #pragma unroll
;         for (int i = 0; i < 8; ++i) {
;           const bf16x8 a = *(const bf16x8*)(As + i * 16 * LDT + ks * 32);
; #pragma unroll
;           for (int j = 0; j < 2; ++j) acc[i][j] = mfma16(b[j], a, acc[i][j]);
;         }
;       }
;       __syncthreads();
;       buf ^= 1;
;     }
;     if ((sg & 1) == 0) {
;       const int t2 = TIDX(), row0 = tm * 256 + ((t2 >> 8) & 1) * 128 + (t2 & 15);
; #pragma unroll
;       for (int i = 0; i < 8; ++i) {
;         asm volatile("" ::: "memory");
;         const float rs = rstd_from16((const float*)(p.ws + O_SSQ) + (size_t)(row0 + i * 16) * 16, 1.f / 1024.f);
; #pragma unroll
;         for (int j = 0; j < 2; ++j) {
;           unsigned w = 0;
; #pragma unroll
;           for (int r = 0; r < 4; ++r) w |= (unsigned)__float2int_rn(sigmoidf_(acc[i][j][r] * rs) * 255.f) << (8 * r);
;           gsp[(i * 2 + j) * NTHR] = w;
;         }
;       }
;     } else {
; #pragma unroll
;       for (int i = 0; i < 8; ++i)
; #pragma unroll
;         for (int j = 0; j < 2; ++j) {
;           asm volatile("" ::: "memory");
;           const unsigned w = gsp[(i * 2 + j) * NTHR];
; #pragma unroll
;           for (int r = 0; r < 4; ++r) mg[i][j][r] += (float)((w >> (8 * r)) & 0xffu) * (1.f / 255.f) * acc[i][j][r];
;         }
;     }
;     zero_acc<8, 2>(acc);
;   }
.LrcE1_7:
	s_or_b64 exec, exec, s[98:99]
	s_waitcnt vmcnt(0)
	v_cndmask_b32_e64 v96, v249, v96, s[100:101]
	v_mul_f32_e32 v92, v92, v96
	v_mul_f32_e32 v92, 0xbfb8aa3b, v92
	v_exp_f32_e32 v92, v92
	v_mul_f32_e32 v93, v93, v96
	v_mul_f32_e32 v93, 0xbfb8aa3b, v93
	v_exp_f32_e32 v93, v93
	v_add_f32_e32 v92, 1.0, v92
	v_div_scale_f32 v97, s[0:1], v92, v92, 1.0
	v_rcp_f32_e32 v98, v97
	v_add_f32_e32 v93, 1.0, v93
	v_mul_f32_e32 v94, v94, v96
	v_mul_f32_e32 v94, 0xbfb8aa3b, v94
	v_fma_f32 v99, -v97, v98, 1.0
	v_fmac_f32_e32 v98, v99, v98
	v_div_scale_f32 v99, vcc, 1.0, v92, 1.0
	v_mul_f32_e32 v100, v99, v98
	v_fma_f32 v101, -v97, v100, v99
	v_fmac_f32_e32 v100, v101, v98
	v_fma_f32 v97, -v97, v100, v99
	v_div_fmas_f32 v97, v97, v98, v100
	v_div_fixup_f32 v92, v97, v92, 1.0
	v_div_scale_f32 v97, s[0:1], v93, v93, 1.0
	v_rcp_f32_e32 v98, v97
	v_exp_f32_e32 v94, v94
	v_mul_f32_e32 v95, v95, v96
	v_mul_f32_e32 v95, 0xbfb8aa3b, v95
	v_fma_f32 v99, -v97, v98, 1.0
	v_fmac_f32_e32 v98, v99, v98
	v_div_scale_f32 v99, vcc, 1.0, v93, 1.0
	v_mul_f32_e32 v100, v99, v98
	v_fma_f32 v101, -v97, v100, v99
	v_fmac_f32_e32 v100, v101, v98
	v_fma_f32 v97, -v97, v100, v99
	v_div_fmas_f32 v97, v97, v98, v100
	v_add_f32_e32 v94, 1.0, v94
	v_div_fixup_f32 v93, v97, v93, 1.0
	v_div_scale_f32 v97, s[0:1], v94, v94, 1.0
	v_rcp_f32_e32 v98, v97
	v_exp_f32_e32 v95, v95
	v_mul_f32_e32 v88, v88, v96
	v_mul_f32_e32 v88, 0xbfb8aa3b, v88
	v_fma_f32 v99, -v97, v98, 1.0
	v_fmac_f32_e32 v98, v99, v98
	v_div_scale_f32 v99, vcc, 1.0, v94, 1.0
	v_mul_f32_e32 v100, v99, v98
	v_fma_f32 v101, -v97, v100, v99
	v_fmac_f32_e32 v100, v101, v98
	v_fma_f32 v97, -v97, v100, v99
	v_div_fmas_f32 v97, v97, v98, v100
	v_add_f32_e32 v95, 1.0, v95
	v_div_fixup_f32 v94, v97, v94, 1.0
	v_div_scale_f32 v97, s[0:1], v95, v95, 1.0
	v_rcp_f32_e32 v98, v97
	v_exp_f32_e32 v88, v88
	v_mul_f32_e32 v89, v89, v96
	v_mul_f32_e32 v89, 0xbfb8aa3b, v89
	v_fma_f32 v99, -v97, v98, 1.0
	v_fmac_f32_e32 v98, v99, v98
	v_div_scale_f32 v99, vcc, 1.0, v95, 1.0
	v_mul_f32_e32 v100, v99, v98
	v_fma_f32 v101, -v97, v100, v99
	v_fmac_f32_e32 v100, v101, v98
	v_fma_f32 v97, -v97, v100, v99
	v_div_fmas_f32 v97, v97, v98, v100
	v_add_f32_e32 v88, 1.0, v88
	v_div_fixup_f32 v95, v97, v95, 1.0
	v_div_scale_f32 v97, s[0:1], v88, v88, 1.0
	v_rcp_f32_e32 v98, v97
	v_exp_f32_e32 v89, v89
	v_mul_f32_e32 v90, v90, v96
	v_mul_f32_e32 v90, 0xbfb8aa3b, v90
	v_fma_f32 v99, -v97, v98, 1.0
	v_fmac_f32_e32 v98, v99, v98
	v_div_scale_f32 v99, vcc, 1.0, v88, 1.0
	v_mul_f32_e32 v100, v99, v98
	v_fma_f32 v101, -v97, v100, v99
	v_fmac_f32_e32 v100, v101, v98
	v_fma_f32 v97, -v97, v100, v99
	v_div_fmas_f32 v97, v97, v98, v100
	v_add_f32_e32 v89, 1.0, v89
	v_div_fixup_f32 v88, v97, v88, 1.0
	v_div_scale_f32 v97, s[0:1], v89, v89, 1.0
	v_rcp_f32_e32 v98, v97
	v_exp_f32_e32 v90, v90
	v_mul_f32_e32 v91, v91, v96
	v_mul_f32_e32 v91, 0xbfb8aa3b, v91
	v_fma_f32 v99, -v97, v98, 1.0
	v_fmac_f32_e32 v98, v99, v98
	v_div_scale_f32 v99, vcc, 1.0, v89, 1.0
	v_mul_f32_e32 v100, v99, v98
	v_fma_f32 v101, -v97, v100, v99
	v_fmac_f32_e32 v100, v101, v98
	v_fma_f32 v97, -v97, v100, v99
	v_div_fmas_f32 v97, v97, v98, v100
	v_add_f32_e32 v90, 1.0, v90
	v_div_fixup_f32 v89, v97, v89, 1.0
	v_div_scale_f32 v97, s[0:1], v90, v90, 1.0
	v_rcp_f32_e32 v98, v97
	v_exp_f32_e32 v91, v91
	v_mul_f32_e32 v92, 0x437f0000, v92
	v_mul_f32_e32 v93, 0x437f0000, v93
	v_fma_f32 v99, -v97, v98, 1.0
	v_fmac_f32_e32 v98, v99, v98
	v_div_scale_f32 v99, vcc, 1.0, v90, 1.0
	v_mul_f32_e32 v100, v99, v98
	v_fma_f32 v101, -v97, v100, v99
	v_fmac_f32_e32 v100, v101, v98
	v_fma_f32 v97, -v97, v100, v99
	v_div_fmas_f32 v96, v97, v98, v100
	v_add_f32_e32 v91, 1.0, v91
	v_div_fixup_f32 v90, v96, v90, 1.0
	v_div_scale_f32 v96, s[0:1], v91, v91, 1.0
	v_rcp_f32_e32 v97, v96
	v_mul_f32_e32 v88, 0x437f0000, v88
	v_mul_f32_e32 v89, 0x437f0000, v89
	v_rndne_f32_e32 v92, v92
	v_fma_f32 v98, -v96, v97, 1.0
	v_fmac_f32_e32 v97, v98, v97
	v_div_scale_f32 v98, vcc, 1.0, v91, 1.0
	v_mul_f32_e32 v99, v98, v97
	v_fma_f32 v100, -v96, v99, v98
	v_fmac_f32_e32 v99, v100, v97
	v_fma_f32 v96, -v96, v99, v98
	v_div_fmas_f32 v96, v96, v97, v99
	v_div_fixup_f32 v91, v96, v91, 1.0
	v_rndne_f32_e32 v93, v93
	v_mul_f32_e32 v94, 0x437f0000, v94
	v_mul_f32_e32 v95, 0x437f0000, v95
	v_rndne_f32_e32 v88, v88
	v_rndne_f32_e32 v89, v89
	v_mul_f32_e32 v90, 0x437f0000, v90
	v_mul_f32_e32 v91, 0x437f0000, v91
	v_cvt_i32_f32_e32 v92, v92
	v_cvt_i32_f32_e32 v93, v93
	v_rndne_f32_e32 v94, v94
	v_rndne_f32_e32 v95, v95
	v_cvt_i32_f32_e32 v88, v88
	v_cvt_i32_f32_e32 v89, v89
	v_rndne_f32_e32 v90, v90
	v_rndne_f32_e32 v91, v91
	v_cvt_i32_f32_sdwa v94, v94 dst_sel:WORD_1 dst_unused:UNUSED_PAD src0_sel:DWORD
	v_cvt_i32_f32_sdwa v95, v95 dst_sel:BYTE_3 dst_unused:UNUSED_PAD src0_sel:DWORD
	v_cvt_i32_f32_sdwa v90, v90 dst_sel:WORD_1 dst_unused:UNUSED_PAD src0_sel:DWORD
	v_cvt_i32_f32_sdwa v91, v91 dst_sel:BYTE_3 dst_unused:UNUSED_PAD src0_sel:DWORD
	v_lshl_or_b32 v92, v93, 8, v92
	v_lshl_or_b32 v88, v89, 8, v88
	v_or3_b32 v92, v92, v94, v95
	v_or3_b32 v88, v88, v90, v91
	ds_write2st64_b32 v228, v92, v88 offset0:112 offset1:120
	s_add_i32 s51, s51, 1
	s_cmp_lg_u32 s51, 6
	s_cbranch_scc0 .LBB0_1867

; DI void store4(bf16_t* dst, const f32x4& v, float s) { *(u32x2*)dst = (u32x2){pk2(v[0] * s, v[1] * s), pk2(v[2] * s, v[3] * s)}; }
; DI float rstd_from16(const float* p, float inv_n) {
;   const f32x4 a = *(const f32x4*)p, b = *(const f32x4*)(p + 4), c = *(const f32x4*)(p + 8), d = *(const f32x4*)(p + 12);
;   const float s = ((a[0] + a[1]) + (a[2] + a[3])) + ((b[0] + b[1]) + (b[2] + b[3])) + ((c[0] + c[1]) + (c[2] + c[3])) + ((d[0] + d[1]) + (d[2] + d[3]));
;   return rsqrtf(s * inv_n + EPS_);
; DI void ffnup_tile(const Params& p, int layer, int b, int mt, int tn, bf16_t* smem) {
;     ...
;     for (int i = 0; i < 8; ++i) {
;       const int row = wm * 128 + i * 16 + l15, s = s0 + row;
;       const float rs = (s >= 0 && s < S_) ? rstd_from16((const float*)(p.ws + O_SSQ) + ((size_t)b * S_ + s) * 16, 1.f / 1024.f) : 0.f;
; #pragma unroll
;       for (int j = 0; j < 4; ++j) store4(dstb + row * LDU + j * 16, acc[i][j], rs);
.Lgm14_exit:
	v_mfma_f32_16x16x32_bf16 v[28:31], v[182:185], v[242:245], v[28:31]
	v_mfma_f32_16x16x32_bf16 v[8:11], v[182:185], v[246:249], v[8:11]
	v_mfma_f32_16x16x32_bf16 v[24:27], v[186:189], v[242:245], v[24:27]
	v_mfma_f32_16x16x32_bf16 v[4:7], v[186:189], v[246:249], v[4:7]
	v_mfma_f32_16x16x32_bf16 v[20:23], v[190:193], v[242:245], v[20:23]
	v_mfma_f32_16x16x32_bf16 v[0:3], v[190:193], v[246:249], v[0:3]
	v_mfma_f32_16x16x32_bf16 v[12:15], v[194:197], v[242:245], v[12:15]
	v_mfma_f32_16x16x32_bf16 v[16:19], v[194:197], v[246:249], v[16:19]
	s_nop 7
	s_waitcnt vmcnt(5)
	v_mov_b32_e32 v115, v220
	s_lshl_b64 s[2:3], s[16:17], 12
	v_and_b32_e32 v113, 15, v115
	v_ashrrev_i32_e32 v112, 1, v115
	s_waitcnt vmcnt(3)
	v_and_or_b32 v118, v112, s33, v113
	v_add_u32_e32 v117, s42, v118
	v_cmp_gt_u32_e32 vcc, s28, v117
	v_mov_b32_e32 v112, 0
	v_mov_b32_e32 v114, 0
	s_and_saveexec_b64 s[0:1], vcc
	s_cbranch_execz .LBB0_2086
	s_waitcnt vmcnt(2)
	v_or_b32_e32 v120, s2, v117
	v_mov_b32_e32 v121, s3
	v_lshlrev_b64 v[120:121], 6, v[120:121]
	v_lshl_add_u64 v[132:133], s[6:7], 0, v[120:121]
	v_bfe_u32 v244, v132, 6, 8
	v_lshlrev_b32_e32 v244, 3, v244
	v_add_u32_e32 v244, 0x24010, v244
	v_or_b32_e32 v246, 4, v132
	ds_read_b64 v[248:249], v244
	s_waitcnt lgkmcnt(0)
	v_cmp_ne_u32_e64 s[100:101], v248, v246
	s_nop 1
	s_and_saveexec_b64 s[98:99], s[100:101]
	s_cbranch_execz .LrcG1_0
	global_load_dwordx4 v[120:123], v[132:133], off
	global_load_dwordx4 v[124:127], v[132:133], off offset:16
	global_load_dwordx4 v[128:131], v[132:133], off offset:32
	s_nop 0
	global_load_dwordx4 v[132:135], v[132:133], off offset:48
	s_waitcnt vmcnt(3)
	v_mov_b32_e32 v136, v121
	v_mov_b32_e32 v137, v122
	v_mov_b32_e32 v121, v123
	s_waitcnt vmcnt(2)
	v_mov_b32_e32 v122, v125
	v_mov_b32_e32 v123, v126
	v_mov_b32_e32 v125, v127
	v_pk_add_f32 v[120:121], v[136:137], v[120:121]
	v_pk_add_f32 v[122:123], v[122:123], v[124:125]
	v_pk_add_f32 v[120:121], v[120:121], v[120:121] op_sel:[0,1] op_sel_hi:[1,0]
	v_pk_add_f32 v[122:123], v[122:123], v[122:123] op_sel:[0,1] op_sel_hi:[1,0]
	s_waitcnt vmcnt(1)
	v_add_f32_e32 v126, v128, v129
	v_add_f32_e32 v128, v130, v131
	s_waitcnt vmcnt(0)
	v_mov_b32_e32 v127, v134
	v_mov_b32_e32 v129, v135
	v_mov_b32_e32 v121, v132
	v_mov_b32_e32 v123, v133
	v_pk_add_f32 v[124:125], v[126:127], v[128:129]
	v_pk_add_f32 v[120:121], v[120:121], v[122:123]
	s_nop 0
	v_pk_add_f32 v[120:121], v[120:121], v[124:125]
	s_nop 0
	v_add_f32_e32 v114, v120, v121
	v_fmamk_f32 v114, v114, 0x3a800000, v168
	v_mul_f32_e32 v116, 0x4b800000, v114
	v_cmp_gt_f32_e32 vcc, s34, v114
	s_nop 1
	v_cndmask_b32_e32 v114, v114, v116, vcc
	v_rsq_f32_e32 v114, v114
	s_nop 0
	v_mul_f32_e32 v116, 0x45800000, v114
	v_cndmask_b32_e32 v114, v114, v116, vcc
	s_nop 0
	v_mov_b32_e32 v247, v114
	ds_write_b64 v244, v[246:247]

; DI void store4(bf16_t* dst, const f32x4& v, float s) { *(u32x2*)dst = (u32x2){pk2(v[0] * s, v[1] * s), pk2(v[2] * s, v[3] * s)}; }
; DI float rstd_from16(const float* p, float inv_n) {
;   const f32x4 a = *(const f32x4*)p, b = *(const f32x4*)(p + 4), c = *(const f32x4*)(p + 8), d = *(const f32x4*)(p + 12);
;   const float s = ((a[0] + a[1]) + (a[2] + a[3])) + ((b[0] + b[1]) + (b[2] + b[3])) + ((c[0] + c[1]) + (c[2] + c[3])) + ((d[0] + d[1]) + (d[2] + d[3]));
;   return rsqrtf(s * inv_n + EPS_);
; DI void ffnup_tile(const Params& p, int layer, int b, int mt, int tn, bf16_t* smem) {
;     ...
;     for (int i = 0; i < 8; ++i) {
;       const int row = wm * 128 + i * 16 + l15, s = s0 + row;
;       const float rs = (s >= 0 && s < S_) ? rstd_from16((const float*)(p.ws + O_SSQ) + ((size_t)b * S_ + s) * 16, 1.f / 1024.f) : 0.f;
; #pragma unroll
;       for (int j = 0; j < 4; ++j) store4(dstb + row * LDU + j * 16, acc[i][j], rs);
.LBB0_2086:
	s_or_b64 exec, exec, s[0:1]
	v_bfe_i32 v116, v115, 7, 1
	v_and_b32_e32 v119, 64, v115
	s_waitcnt vmcnt(2)
	v_lshrrev_b32_e32 v120, 1, v115
	v_and_b32_e32 v116, 0x11000, v116
	v_lshlrev_b32_e32 v119, 1, v119
	v_and_b32_e32 v120, 24, v120
	v_or3_b32 v116, v116, v119, v120
	v_pk_mul_f32 v[120:121], v[156:157], v[114:115] op_sel_hi:[1,0]
	v_pk_mul_f32 v[122:123], v[158:159], v[114:115] op_sel_hi:[1,0]
	v_mul_lo_u32 v119, v118, s35
	v_cvt_pk_bf16_f32 v120, v120, v121
	v_cvt_pk_bf16_f32 v121, v122, v123
	v_pk_mul_f32 v[122:123], v[152:153], v[114:115] op_sel_hi:[1,0]
	s_waitcnt vmcnt(1)
	v_pk_mul_f32 v[124:125], v[154:155], v[114:115] op_sel_hi:[1,0]
	v_add_u32_e32 v116, v116, v119
	v_cvt_pk_bf16_f32 v122, v122, v123
	v_cvt_pk_bf16_f32 v123, v124, v125
	ds_write2_b64 v116, v[120:121], v[122:123] offset1:4
	v_pk_mul_f32 v[120:121], v[148:149], v[114:115] op_sel_hi:[1,0]
	v_pk_mul_f32 v[122:123], v[150:151], v[114:115] op_sel_hi:[1,0]
	v_cvt_pk_bf16_f32 v120, v120, v121
	v_cvt_pk_bf16_f32 v121, v122, v123
	v_pk_mul_f32 v[122:123], v[144:145], v[114:115] op_sel_hi:[1,0]
	v_pk_mul_f32 v[124:125], v[146:147], v[114:115] op_sel_hi:[1,0]
	v_add3_u32 v114, s42, v118, 16
	v_cvt_pk_bf16_f32 v122, v122, v123
	v_cvt_pk_bf16_f32 v123, v124, v125
	v_cmp_gt_u32_e32 vcc, s28, v114
	ds_write2_b64 v116, v[120:121], v[122:123] offset0:8 offset1:12
	s_and_saveexec_b64 s[0:1], vcc
	s_cbranch_execz .LBB0_2088
	v_or_b32_e32 v120, s2, v114
	v_mov_b32_e32 v121, s3
	v_lshlrev_b64 v[120:121], 6, v[120:121]
	v_lshl_add_u64 v[132:133], s[6:7], 0, v[120:121]
	v_bfe_u32 v244, v132, 6, 8
	v_lshlrev_b32_e32 v244, 3, v244
	v_add_u32_e32 v244, 0x24010, v244
	v_or_b32_e32 v246, 4, v132
	ds_read_b64 v[248:249], v244
	s_waitcnt lgkmcnt(0)
	v_cmp_ne_u32_e64 s[100:101], v248, v246
	s_nop 1
	s_and_saveexec_b64 s[98:99], s[100:101]
	s_cbranch_execz .LrcG1_1
	global_load_dwordx4 v[120:123], v[132:133], off
	global_load_dwordx4 v[124:127], v[132:133], off offset:16
	global_load_dwordx4 v[128:131], v[132:133], off offset:32
	s_nop 0
	global_load_dwordx4 v[132:135], v[132:133], off offset:48
	s_waitcnt vmcnt(3)
	v_mov_b32_e32 v136, v121
	v_mov_b32_e32 v137, v122
	v_mov_b32_e32 v121, v123
	s_waitcnt vmcnt(2)
	v_mov_b32_e32 v122, v125
	v_mov_b32_e32 v123, v126
	v_mov_b32_e32 v125, v127
	v_pk_add_f32 v[120:121], v[136:137], v[120:121]
	v_pk_add_f32 v[122:123], v[122:123], v[124:125]
	v_pk_add_f32 v[120:121], v[120:121], v[120:121] op_sel:[0,1] op_sel_hi:[1,0]
	v_pk_add_f32 v[122:123], v[122:123], v[122:123] op_sel:[0,1] op_sel_hi:[1,0]
	s_waitcnt vmcnt(1)
	v_add_f32_e32 v126, v128, v129
	v_add_f32_e32 v128, v130, v131
	s_waitcnt vmcnt(0)
	v_mov_b32_e32 v127, v134
	v_mov_b32_e32 v129, v135
	v_mov_b32_e32 v121, v132
	v_mov_b32_e32 v123, v133
	v_pk_add_f32 v[124:125], v[126:127], v[128:129]
	v_pk_add_f32 v[120:121], v[120:121], v[122:123]
	s_nop 0
	v_pk_add_f32 v[120:121], v[120:121], v[124:125]
	s_nop 0
	v_add_f32_e32 v112, v120, v121
	v_fmamk_f32 v112, v112, 0x3a800000, v168
	v_mul_f32_e32 v114, 0x4b800000, v112
	v_cmp_gt_f32_e32 vcc, s34, v112
	s_nop 1
	v_cndmask_b32_e32 v112, v112, v114, vcc
	v_rsq_f32_e32 v112, v112
	s_nop 0
	v_mul_f32_e32 v114, 0x45800000, v112
	v_cndmask_b32_e32 v112, v112, v114, vcc
	s_nop 0
	v_mov_b32_e32 v247, v112
	ds_write_b64 v244, v[246:247]

; DI void store4(bf16_t* dst, const f32x4& v, float s) { *(u32x2*)dst = (u32x2){pk2(v[0] * s, v[1] * s), pk2(v[2] * s, v[3] * s)}; }
; DI float rstd_from16(const float* p, float inv_n) {
;   const f32x4 a = *(const f32x4*)p, b = *(const f32x4*)(p + 4), c = *(const f32x4*)(p + 8), d = *(const f32x4*)(p + 12);
;   const float s = ((a[0] + a[1]) + (a[2] + a[3])) + ((b[0] + b[1]) + (b[2] + b[3])) + ((c[0] + c[1]) + (c[2] + c[3])) + ((d[0] + d[1]) + (d[2] + d[3]));
;   return rsqrtf(s * inv_n + EPS_);
; DI void ffnup_tile(const Params& p, int layer, int b, int mt, int tn, bf16_t* smem) {
;     ...
;     for (int i = 0; i < 8; ++i) {
;       const int row = wm * 128 + i * 16 + l15, s = s0 + row;
;       const float rs = (s >= 0 && s < S_) ? rstd_from16((const float*)(p.ws + O_SSQ) + ((size_t)b * S_ + s) * 16, 1.f / 1024.f) : 0.f;
; #pragma unroll
;       for (int j = 0; j < 4; ++j) store4(dstb + row * LDU + j * 16, acc[i][j], rs);
.LBB0_2088:
	s_or_b64 exec, exec, s[0:1]
	v_pk_mul_f32 v[104:105], v[104:105], v[112:113] op_sel_hi:[1,0]
	v_pk_mul_f32 v[106:107], v[106:107], v[112:113] op_sel_hi:[1,0]
	v_pk_mul_f32 v[100:101], v[100:101], v[112:113] op_sel_hi:[1,0]
	v_pk_mul_f32 v[102:103], v[102:103], v[112:113] op_sel_hi:[1,0]
	v_pk_mul_f32 v[96:97], v[96:97], v[112:113] op_sel_hi:[1,0]
	v_pk_mul_f32 v[98:99], v[98:99], v[112:113] op_sel_hi:[1,0]
	v_cvt_pk_bf16_f32 v104, v104, v105
	v_cvt_pk_bf16_f32 v105, v106, v107
	v_add_u32_e32 v106, 0x1000, v116
	v_cvt_pk_bf16_f32 v100, v100, v101
	v_cvt_pk_bf16_f32 v101, v102, v103
	v_cvt_pk_bf16_f32 v96, v96, v97
	v_cvt_pk_bf16_f32 v97, v98, v99
	v_pk_mul_f32 v[108:109], v[108:109], v[112:113] op_sel_hi:[1,0]
	v_pk_mul_f32 v[110:111], v[110:111], v[112:113] op_sel_hi:[1,0]
	ds_write2_b64 v106, v[100:101], v[96:97] offset0:40 offset1:44
	v_add3_u32 v97, s42, v118, 32
	v_cvt_pk_bf16_f32 v108, v108, v109
	v_cvt_pk_bf16_f32 v109, v110, v111
	v_cmp_gt_u32_e32 vcc, s28, v97
	v_mov_b32_e32 v96, 0
	v_mov_b32_e32 v98, 0
	ds_write2_b64 v106, v[108:109], v[104:105] offset0:32 offset1:36
	s_and_saveexec_b64 s[0:1], vcc
	s_cbranch_execz .LBB0_2090
	v_or_b32_e32 v98, s2, v97
	v_mov_b32_e32 v99, s3
	v_lshlrev_b64 v[98:99], 6, v[98:99]
	v_lshl_add_u64 v[110:111], s[6:7], 0, v[98:99]
	v_bfe_u32 v244, v110, 6, 8
	v_lshlrev_b32_e32 v244, 3, v244
	v_add_u32_e32 v244, 0x24010, v244
	v_or_b32_e32 v246, 4, v110
	ds_read_b64 v[248:249], v244
	s_waitcnt lgkmcnt(0)
	v_cmp_ne_u32_e64 s[100:101], v248, v246
	s_nop 1
	s_and_saveexec_b64 s[98:99], s[100:101]
	s_cbranch_execz .LrcG1_2
	global_load_dwordx4 v[98:101], v[110:111], off
	global_load_dwordx4 v[102:105], v[110:111], off offset:16
	global_load_dwordx4 v[106:109], v[110:111], off offset:32
	global_load_dwordx4 v[120:123], v[110:111], off offset:48
	s_waitcnt vmcnt(3)
	v_mov_b32_e32 v110, v99
	v_mov_b32_e32 v111, v100
	v_mov_b32_e32 v99, v101
	s_waitcnt vmcnt(2)
	v_mov_b32_e32 v100, v103
	v_mov_b32_e32 v101, v104
	v_mov_b32_e32 v103, v105
	v_pk_add_f32 v[98:99], v[110:111], v[98:99]
	v_pk_add_f32 v[100:101], v[100:101], v[102:103]
	v_pk_add_f32 v[98:99], v[98:99], v[98:99] op_sel:[0,1] op_sel_hi:[1,0]
	v_pk_add_f32 v[100:101], v[100:101], v[100:101] op_sel:[0,1] op_sel_hi:[1,0]
	s_waitcnt vmcnt(1)
	v_add_f32_e32 v104, v106, v107
	v_add_f32_e32 v106, v108, v109
	s_waitcnt vmcnt(0)
	v_mov_b32_e32 v105, v122
	v_mov_b32_e32 v107, v123
	v_mov_b32_e32 v99, v120
	v_mov_b32_e32 v101, v121
	v_pk_add_f32 v[102:103], v[104:105], v[106:107]
	v_pk_add_f32 v[98:99], v[98:99], v[100:101]
	s_nop 0
	v_pk_add_f32 v[98:99], v[98:99], v[102:103]
	s_nop 0
	v_add_f32_e32 v97, v98, v99
	v_fmamk_f32 v97, v97, 0x3a800000, v168
	v_mul_f32_e32 v98, 0x4b800000, v97
	v_cmp_gt_f32_e32 vcc, s34, v97
	s_nop 1
	v_cndmask_b32_e32 v97, v97, v98, vcc
	v_rsq_f32_e32 v97, v97
	s_nop 0
	v_mul_f32_e32 v98, 0x45800000, v97
	v_cndmask_b32_e32 v98, v97, v98, vcc
	s_nop 0
	v_mov_b32_e32 v247, v98
	ds_write_b64 v244, v[246:247]

; DI void store4(bf16_t* dst, const f32x4& v, float s) { *(u32x2*)dst = (u32x2){pk2(v[0] * s, v[1] * s), pk2(v[2] * s, v[3] * s)}; }
; DI float rstd_from16(const float* p, float inv_n) {
;   const f32x4 a = *(const f32x4*)p, b = *(const f32x4*)(p + 4), c = *(const f32x4*)(p + 8), d = *(const f32x4*)(p + 12);
;   const float s = ((a[0] + a[1]) + (a[2] + a[3])) + ((b[0] + b[1]) + (b[2] + b[3])) + ((c[0] + c[1]) + (c[2] + c[3])) + ((d[0] + d[1]) + (d[2] + d[3]));
;   return rsqrtf(s * inv_n + EPS_);
; DI void ffnup_tile(const Params& p, int layer, int b, int mt, int tn, bf16_t* smem) {
;     ...
;     for (int i = 0; i < 8; ++i) {
;       const int row = wm * 128 + i * 16 + l15, s = s0 + row;
;       const float rs = (s >= 0 && s < S_) ? rstd_from16((const float*)(p.ws + O_SSQ) + ((size_t)b * S_ + s) * 16, 1.f / 1024.f) : 0.f;
; #pragma unroll
;       for (int j = 0; j < 4; ++j) store4(dstb + row * LDU + j * 16, acc[i][j], rs);
.LBB0_2090:
	s_or_b64 exec, exec, s[0:1]
	v_pk_mul_f32 v[88:89], v[88:89], v[98:99] op_sel_hi:[1,0]
	v_pk_mul_f32 v[90:91], v[90:91], v[98:99] op_sel_hi:[1,0]
	v_pk_mul_f32 v[84:85], v[84:85], v[98:99] op_sel_hi:[1,0]
	v_pk_mul_f32 v[86:87], v[86:87], v[98:99] op_sel_hi:[1,0]
	v_pk_mul_f32 v[80:81], v[80:81], v[98:99] op_sel_hi:[1,0]
	v_pk_mul_f32 v[82:83], v[82:83], v[98:99] op_sel_hi:[1,0]
	v_cvt_pk_bf16_f32 v88, v88, v89
	v_cvt_pk_bf16_f32 v89, v90, v91
	v_add_u32_e32 v90, 0x2000, v116
	v_cvt_pk_bf16_f32 v84, v84, v85
	v_cvt_pk_bf16_f32 v85, v86, v87
	v_cvt_pk_bf16_f32 v80, v80, v81
	v_cvt_pk_bf16_f32 v81, v82, v83
	v_pk_mul_f32 v[92:93], v[92:93], v[98:99] op_sel_hi:[1,0]
	v_pk_mul_f32 v[94:95], v[94:95], v[98:99] op_sel_hi:[1,0]
	ds_write2_b64 v90, v[84:85], v[80:81] offset0:72 offset1:76
	v_add3_u32 v80, s42, v118, 48
	v_cvt_pk_bf16_f32 v92, v92, v93
	v_cvt_pk_bf16_f32 v93, v94, v95
	v_cmp_gt_u32_e32 vcc, s28, v80
	ds_write2_b64 v90, v[92:93], v[88:89] offset0:64 offset1:68
	s_and_saveexec_b64 s[0:1], vcc
	s_cbranch_execz .LBB0_2092
	v_or_b32_e32 v80, s2, v80
	v_mov_b32_e32 v81, s3
	v_lshlrev_b64 v[80:81], 6, v[80:81]
	v_lshl_add_u64 v[92:93], s[6:7], 0, v[80:81]
	v_bfe_u32 v244, v92, 6, 8
	v_lshlrev_b32_e32 v244, 3, v244
	v_add_u32_e32 v244, 0x24010, v244
	v_or_b32_e32 v246, 4, v92
	ds_read_b64 v[248:249], v244
	s_waitcnt lgkmcnt(0)
	v_cmp_ne_u32_e64 s[100:101], v248, v246
	s_nop 1
	s_and_saveexec_b64 s[98:99], s[100:101]
	s_cbranch_execz .LrcG1_3
	global_load_dwordx4 v[80:83], v[92:93], off
	global_load_dwordx4 v[84:87], v[92:93], off offset:16
	global_load_dwordx4 v[88:91], v[92:93], off offset:32
	s_nop 0
	global_load_dwordx4 v[92:95], v[92:93], off offset:48
	s_waitcnt vmcnt(3)
	v_mov_b32_e32 v96, v81
	v_mov_b32_e32 v97, v82
	v_mov_b32_e32 v81, v83
	s_waitcnt vmcnt(2)
	v_mov_b32_e32 v82, v85
	v_mov_b32_e32 v83, v86
	v_mov_b32_e32 v85, v87
	v_pk_add_f32 v[80:81], v[96:97], v[80:81]
	v_pk_add_f32 v[82:83], v[82:83], v[84:85]
	v_pk_add_f32 v[80:81], v[80:81], v[80:81] op_sel:[0,1] op_sel_hi:[1,0]
	v_pk_add_f32 v[82:83], v[82:83], v[82:83] op_sel:[0,1] op_sel_hi:[1,0]
	s_waitcnt vmcnt(1)
	v_add_f32_e32 v86, v88, v89
	v_add_f32_e32 v88, v90, v91
	s_waitcnt vmcnt(0)
	v_mov_b32_e32 v87, v94
	v_mov_b32_e32 v89, v95
	v_mov_b32_e32 v81, v92
	v_mov_b32_e32 v83, v93
	v_pk_add_f32 v[84:85], v[86:87], v[88:89]
	v_pk_add_f32 v[80:81], v[80:81], v[82:83]
	s_nop 0
	v_pk_add_f32 v[80:81], v[80:81], v[84:85]
	s_nop 0
	v_add_f32_e32 v80, v80, v81
	v_fmamk_f32 v80, v80, 0x3a800000, v168
	v_mul_f32_e32 v81, 0x4b800000, v80
	v_cmp_gt_f32_e32 vcc, s34, v80
	s_nop 1
	v_cndmask_b32_e32 v80, v80, v81, vcc
	v_rsq_f32_e32 v80, v80
	s_nop 0
	v_mul_f32_e32 v81, 0x45800000, v80
	v_cndmask_b32_e32 v96, v80, v81, vcc
	s_nop 0
	v_mov_b32_e32 v247, v96
	ds_write_b64 v244, v[246:247]

; DI void store4(bf16_t* dst, const f32x4& v, float s) { *(u32x2*)dst = (u32x2){pk2(v[0] * s, v[1] * s), pk2(v[2] * s, v[3] * s)}; }
; DI float rstd_from16(const float* p, float inv_n) {
;   const f32x4 a = *(const f32x4*)p, b = *(const f32x4*)(p + 4), c = *(const f32x4*)(p + 8), d = *(const f32x4*)(p + 12);
;   const float s = ((a[0] + a[1]) + (a[2] + a[3])) + ((b[0] + b[1]) + (b[2] + b[3])) + ((c[0] + c[1]) + (c[2] + c[3])) + ((d[0] + d[1]) + (d[2] + d[3]));
;   return rsqrtf(s * inv_n + EPS_);
; DI void ffnup_tile(const Params& p, int layer, int b, int mt, int tn, bf16_t* smem) {
;     ...
;     for (int i = 0; i < 8; ++i) {
;       const int row = wm * 128 + i * 16 + l15, s = s0 + row;
;       const float rs = (s >= 0 && s < S_) ? rstd_from16((const float*)(p.ws + O_SSQ) + ((size_t)b * S_ + s) * 16, 1.f / 1024.f) : 0.f;
; #pragma unroll
;       for (int j = 0; j < 4; ++j) store4(dstb + row * LDU + j * 16, acc[i][j], rs);
.LBB0_2092:
	s_or_b64 exec, exec, s[0:1]
	v_pk_mul_f32 v[72:73], v[72:73], v[96:97] op_sel_hi:[1,0]
	v_pk_mul_f32 v[74:75], v[74:75], v[96:97] op_sel_hi:[1,0]
	v_pk_mul_f32 v[68:69], v[68:69], v[96:97] op_sel_hi:[1,0]
	v_pk_mul_f32 v[70:71], v[70:71], v[96:97] op_sel_hi:[1,0]
	v_pk_mul_f32 v[64:65], v[64:65], v[96:97] op_sel_hi:[1,0]
	v_pk_mul_f32 v[66:67], v[66:67], v[96:97] op_sel_hi:[1,0]
	v_cvt_pk_bf16_f32 v72, v72, v73
	v_cvt_pk_bf16_f32 v73, v74, v75
	v_add_u32_e32 v74, 0x3000, v116
	v_cvt_pk_bf16_f32 v68, v68, v69
	v_cvt_pk_bf16_f32 v69, v70, v71
	v_cvt_pk_bf16_f32 v64, v64, v65
	v_cvt_pk_bf16_f32 v65, v66, v67
	v_pk_mul_f32 v[76:77], v[76:77], v[96:97] op_sel_hi:[1,0]
	v_pk_mul_f32 v[78:79], v[78:79], v[96:97] op_sel_hi:[1,0]
	ds_write2_b64 v74, v[68:69], v[64:65] offset0:104 offset1:108
	v_add3_u32 v65, s42, v118, 64
	v_cvt_pk_bf16_f32 v76, v76, v77
	v_cvt_pk_bf16_f32 v77, v78, v79
	v_cmp_gt_u32_e32 vcc, s28, v65
	v_mov_b32_e32 v64, 0
	v_mov_b32_e32 v66, 0
	ds_write2_b64 v74, v[76:77], v[72:73] offset0:96 offset1:100
	s_and_saveexec_b64 s[0:1], vcc
	s_cbranch_execz .LBB0_2094
	v_or_b32_e32 v66, s2, v65
	v_mov_b32_e32 v67, s3
	v_lshlrev_b64 v[66:67], 6, v[66:67]
	v_lshl_add_u64 v[78:79], s[6:7], 0, v[66:67]
	v_bfe_u32 v244, v78, 6, 8
	v_lshlrev_b32_e32 v244, 3, v244
	v_add_u32_e32 v244, 0x24010, v244
	v_or_b32_e32 v246, 4, v78
	ds_read_b64 v[248:249], v244
	s_waitcnt lgkmcnt(0)
	v_cmp_ne_u32_e64 s[100:101], v248, v246
	s_nop 1
	s_and_saveexec_b64 s[98:99], s[100:101]
	s_cbranch_execz .LrcG1_4
	global_load_dwordx4 v[66:69], v[78:79], off
	global_load_dwordx4 v[70:73], v[78:79], off offset:16
	global_load_dwordx4 v[74:77], v[78:79], off offset:32
	s_nop 0
	global_load_dwordx4 v[78:81], v[78:79], off offset:48
	s_waitcnt vmcnt(3)
	v_mov_b32_e32 v82, v67
	v_mov_b32_e32 v83, v68
	v_mov_b32_e32 v67, v69
	s_waitcnt vmcnt(2)
	v_mov_b32_e32 v68, v71
	v_mov_b32_e32 v69, v72
	v_mov_b32_e32 v71, v73
	v_pk_add_f32 v[66:67], v[82:83], v[66:67]
	v_pk_add_f32 v[68:69], v[68:69], v[70:71]
	v_pk_add_f32 v[66:67], v[66:67], v[66:67] op_sel:[0,1] op_sel_hi:[1,0]
	v_pk_add_f32 v[68:69], v[68:69], v[68:69] op_sel:[0,1] op_sel_hi:[1,0]
	s_waitcnt vmcnt(1)
	v_add_f32_e32 v72, v74, v75
	v_add_f32_e32 v74, v76, v77
	s_waitcnt vmcnt(0)
	v_mov_b32_e32 v73, v80
	v_mov_b32_e32 v75, v81
	v_mov_b32_e32 v67, v78
	v_mov_b32_e32 v69, v79
	v_pk_add_f32 v[70:71], v[72:73], v[74:75]
	v_pk_add_f32 v[66:67], v[66:67], v[68:69]
	s_nop 0
	v_pk_add_f32 v[66:67], v[66:67], v[70:71]
	s_nop 0
	v_add_f32_e32 v65, v66, v67
	v_fmamk_f32 v65, v65, 0x3a800000, v168
	v_mul_f32_e32 v66, 0x4b800000, v65
	v_cmp_gt_f32_e32 vcc, s34, v65
	s_nop 1
	v_cndmask_b32_e32 v65, v65, v66, vcc
	v_rsq_f32_e32 v65, v65
	s_nop 0
	v_mul_f32_e32 v66, 0x45800000, v65
	v_cndmask_b32_e32 v66, v65, v66, vcc
	s_nop 0
	v_mov_b32_e32 v247, v66
	ds_write_b64 v244, v[246:247]

; DI void store4(bf16_t* dst, const f32x4& v, float s) { *(u32x2*)dst = (u32x2){pk2(v[0] * s, v[1] * s), pk2(v[2] * s, v[3] * s)}; }
; DI float rstd_from16(const float* p, float inv_n) {
;   const f32x4 a = *(const f32x4*)p, b = *(const f32x4*)(p + 4), c = *(const f32x4*)(p + 8), d = *(const f32x4*)(p + 12);
;   const float s = ((a[0] + a[1]) + (a[2] + a[3])) + ((b[0] + b[1]) + (b[2] + b[3])) + ((c[0] + c[1]) + (c[2] + c[3])) + ((d[0] + d[1]) + (d[2] + d[3]));
;   return rsqrtf(s * inv_n + EPS_);
; DI void ffnup_tile(const Params& p, int layer, int b, int mt, int tn, bf16_t* smem) {
;     ...
;     for (int i = 0; i < 8; ++i) {
;       const int row = wm * 128 + i * 16 + l15, s = s0 + row;
;       const float rs = (s >= 0 && s < S_) ? rstd_from16((const float*)(p.ws + O_SSQ) + ((size_t)b * S_ + s) * 16, 1.f / 1024.f) : 0.f;
; #pragma unroll
;       for (int j = 0; j < 4; ++j) store4(dstb + row * LDU + j * 16, acc[i][j], rs);
.LBB0_2094:
	s_or_b64 exec, exec, s[0:1]
	v_pk_mul_f32 v[56:57], v[56:57], v[66:67] op_sel_hi:[1,0]
	v_pk_mul_f32 v[58:59], v[58:59], v[66:67] op_sel_hi:[1,0]
	v_pk_mul_f32 v[52:53], v[52:53], v[66:67] op_sel_hi:[1,0]
	v_pk_mul_f32 v[54:55], v[54:55], v[66:67] op_sel_hi:[1,0]
	v_pk_mul_f32 v[48:49], v[48:49], v[66:67] op_sel_hi:[1,0]
	v_pk_mul_f32 v[50:51], v[50:51], v[66:67] op_sel_hi:[1,0]
	v_cvt_pk_bf16_f32 v56, v56, v57
	v_cvt_pk_bf16_f32 v57, v58, v59
	v_add_u32_e32 v58, 0x4000, v116
	v_cvt_pk_bf16_f32 v52, v52, v53
	v_cvt_pk_bf16_f32 v53, v54, v55
	v_cvt_pk_bf16_f32 v48, v48, v49
	v_cvt_pk_bf16_f32 v49, v50, v51
	v_pk_mul_f32 v[60:61], v[60:61], v[66:67] op_sel_hi:[1,0]
	v_pk_mul_f32 v[62:63], v[62:63], v[66:67] op_sel_hi:[1,0]
	ds_write2_b64 v58, v[52:53], v[48:49] offset0:136 offset1:140
	v_add_u32_e32 v48, 0x50, v117
	v_cvt_pk_bf16_f32 v60, v60, v61
	v_cvt_pk_bf16_f32 v61, v62, v63
	v_cmp_gt_u32_e32 vcc, s28, v48
	ds_write2_b64 v58, v[60:61], v[56:57] offset0:128 offset1:132
	s_and_saveexec_b64 s[0:1], vcc
	s_cbranch_execz .LBB0_2096
	v_or_b32_e32 v48, s2, v48
	v_mov_b32_e32 v49, s3
	v_lshlrev_b64 v[48:49], 6, v[48:49]
	v_lshl_add_u64 v[60:61], s[6:7], 0, v[48:49]
	v_bfe_u32 v244, v60, 6, 8
	v_lshlrev_b32_e32 v244, 3, v244
	v_add_u32_e32 v244, 0x24010, v244
	v_or_b32_e32 v246, 4, v60
	ds_read_b64 v[248:249], v244
	s_waitcnt lgkmcnt(0)
	v_cmp_ne_u32_e64 s[100:101], v248, v246
	s_nop 1
	s_and_saveexec_b64 s[98:99], s[100:101]
	s_cbranch_execz .LrcG1_5
	global_load_dwordx4 v[48:51], v[60:61], off
	global_load_dwordx4 v[52:55], v[60:61], off offset:16
	global_load_dwordx4 v[56:59], v[60:61], off offset:32
	s_nop 0
	global_load_dwordx4 v[60:63], v[60:61], off offset:48
	s_waitcnt vmcnt(3)
	v_mov_b32_e32 v64, v49
	v_mov_b32_e32 v65, v50
	v_mov_b32_e32 v49, v51
	s_waitcnt vmcnt(2)
	v_mov_b32_e32 v50, v53
	v_mov_b32_e32 v51, v54
	v_mov_b32_e32 v53, v55
	v_pk_add_f32 v[48:49], v[64:65], v[48:49]
	v_pk_add_f32 v[50:51], v[50:51], v[52:53]
	v_pk_add_f32 v[48:49], v[48:49], v[48:49] op_sel:[0,1] op_sel_hi:[1,0]
	v_pk_add_f32 v[50:51], v[50:51], v[50:51] op_sel:[0,1] op_sel_hi:[1,0]
	s_waitcnt vmcnt(1)
	v_add_f32_e32 v54, v56, v57
	v_add_f32_e32 v56, v58, v59
	s_waitcnt vmcnt(0)
	v_mov_b32_e32 v55, v62
	v_mov_b32_e32 v57, v63
	v_mov_b32_e32 v49, v60
	v_mov_b32_e32 v51, v61
	v_pk_add_f32 v[52:53], v[54:55], v[56:57]
	v_pk_add_f32 v[48:49], v[48:49], v[50:51]
	s_nop 0
	v_pk_add_f32 v[48:49], v[48:49], v[52:53]
	s_nop 0
	v_add_f32_e32 v48, v48, v49
	v_fmamk_f32 v48, v48, 0x3a800000, v168
	v_mul_f32_e32 v49, 0x4b800000, v48
	v_cmp_gt_f32_e32 vcc, s34, v48
	s_nop 1
	v_cndmask_b32_e32 v48, v48, v49, vcc
	v_rsq_f32_e32 v48, v48
	s_nop 0
	v_mul_f32_e32 v49, 0x45800000, v48
	v_cndmask_b32_e32 v64, v48, v49, vcc
	s_nop 0
	v_mov_b32_e32 v247, v64
	ds_write_b64 v244, v[246:247]

; DI void store4(bf16_t* dst, const f32x4& v, float s) { *(u32x2*)dst = (u32x2){pk2(v[0] * s, v[1] * s), pk2(v[2] * s, v[3] * s)}; }
; DI float rstd_from16(const float* p, float inv_n) {
;   const f32x4 a = *(const f32x4*)p, b = *(const f32x4*)(p + 4), c = *(const f32x4*)(p + 8), d = *(const f32x4*)(p + 12);
;   const float s = ((a[0] + a[1]) + (a[2] + a[3])) + ((b[0] + b[1]) + (b[2] + b[3])) + ((c[0] + c[1]) + (c[2] + c[3])) + ((d[0] + d[1]) + (d[2] + d[3]));
;   return rsqrtf(s * inv_n + EPS_);
; DI void ffnup_tile(const Params& p, int layer, int b, int mt, int tn, bf16_t* smem) {
;     ...
;     for (int i = 0; i < 8; ++i) {
;       const int row = wm * 128 + i * 16 + l15, s = s0 + row;
;       const float rs = (s >= 0 && s < S_) ? rstd_from16((const float*)(p.ws + O_SSQ) + ((size_t)b * S_ + s) * 16, 1.f / 1024.f) : 0.f;
; #pragma unroll
;       for (int j = 0; j < 4; ++j) store4(dstb + row * LDU + j * 16, acc[i][j], rs);
.LBB0_2096:
	s_or_b64 exec, exec, s[0:1]
	v_pk_mul_f32 v[40:41], v[40:41], v[64:65] op_sel_hi:[1,0]
	v_pk_mul_f32 v[42:43], v[42:43], v[64:65] op_sel_hi:[1,0]
	v_pk_mul_f32 v[36:37], v[36:37], v[64:65] op_sel_hi:[1,0]
	v_pk_mul_f32 v[38:39], v[38:39], v[64:65] op_sel_hi:[1,0]
	v_pk_mul_f32 v[32:33], v[32:33], v[64:65] op_sel_hi:[1,0]
	v_pk_mul_f32 v[34:35], v[34:35], v[64:65] op_sel_hi:[1,0]
	v_cvt_pk_bf16_f32 v40, v40, v41
	v_cvt_pk_bf16_f32 v41, v42, v43
	v_add_u32_e32 v42, 0x5000, v116
	v_cvt_pk_bf16_f32 v36, v36, v37
	v_cvt_pk_bf16_f32 v37, v38, v39
	v_cvt_pk_bf16_f32 v32, v32, v33
	v_cvt_pk_bf16_f32 v33, v34, v35
	v_pk_mul_f32 v[44:45], v[44:45], v[64:65] op_sel_hi:[1,0]
	v_pk_mul_f32 v[46:47], v[46:47], v[64:65] op_sel_hi:[1,0]
	ds_write2_b64 v42, v[36:37], v[32:33] offset0:168 offset1:172
	v_add_u32_e32 v33, 0x60, v117
	v_cvt_pk_bf16_f32 v44, v44, v45
	v_cvt_pk_bf16_f32 v45, v46, v47
	v_cmp_gt_u32_e32 vcc, s28, v33
	v_mov_b32_e32 v32, 0
	v_mov_b32_e32 v34, 0
	ds_write2_b64 v42, v[44:45], v[40:41] offset0:160 offset1:164
	s_and_saveexec_b64 s[0:1], vcc
	s_cbranch_execz .LBB0_2098
	v_or_b32_e32 v34, s2, v33
	v_mov_b32_e32 v35, s3
	v_lshlrev_b64 v[34:35], 6, v[34:35]
	v_lshl_add_u64 v[46:47], s[6:7], 0, v[34:35]
	v_bfe_u32 v244, v46, 6, 8
	v_lshlrev_b32_e32 v244, 3, v244
	v_add_u32_e32 v244, 0x24010, v244
	v_or_b32_e32 v246, 4, v46
	ds_read_b64 v[248:249], v244
	s_waitcnt lgkmcnt(0)
	v_cmp_ne_u32_e64 s[100:101], v248, v246
	s_nop 1
	s_and_saveexec_b64 s[98:99], s[100:101]
	s_cbranch_execz .LrcG1_6
	global_load_dwordx4 v[34:37], v[46:47], off
	global_load_dwordx4 v[38:41], v[46:47], off offset:16
	global_load_dwordx4 v[42:45], v[46:47], off offset:32
	s_nop 0
	global_load_dwordx4 v[46:49], v[46:47], off offset:48
	s_waitcnt vmcnt(3)
	v_mov_b32_e32 v50, v35
	v_mov_b32_e32 v51, v36
	v_mov_b32_e32 v35, v37
	s_waitcnt vmcnt(2)
	v_mov_b32_e32 v36, v39
	v_mov_b32_e32 v37, v40
	v_mov_b32_e32 v39, v41
	v_pk_add_f32 v[34:35], v[50:51], v[34:35]
	v_pk_add_f32 v[36:37], v[36:37], v[38:39]
	v_pk_add_f32 v[34:35], v[34:35], v[34:35] op_sel:[0,1] op_sel_hi:[1,0]
	v_pk_add_f32 v[36:37], v[36:37], v[36:37] op_sel:[0,1] op_sel_hi:[1,0]
	s_waitcnt vmcnt(1)
	v_add_f32_e32 v40, v42, v43
	v_add_f32_e32 v42, v44, v45
	s_waitcnt vmcnt(0)
	v_mov_b32_e32 v41, v48
	v_mov_b32_e32 v43, v49
	v_mov_b32_e32 v35, v46
	v_mov_b32_e32 v37, v47
	v_pk_add_f32 v[38:39], v[40:41], v[42:43]
	v_pk_add_f32 v[34:35], v[34:35], v[36:37]
	s_nop 0
	v_pk_add_f32 v[34:35], v[34:35], v[38:39]
	s_nop 0
	v_add_f32_e32 v33, v34, v35
	v_fmamk_f32 v33, v33, 0x3a800000, v168
	v_mul_f32_e32 v34, 0x4b800000, v33
	v_cmp_gt_f32_e32 vcc, s34, v33
	s_nop 1
	v_cndmask_b32_e32 v33, v33, v34, vcc
	v_rsq_f32_e32 v33, v33
	s_nop 0
	v_mul_f32_e32 v34, 0x45800000, v33
	v_cndmask_b32_e32 v34, v33, v34, vcc
	s_nop 0
	v_mov_b32_e32 v247, v34
	ds_write_b64 v244, v[246:247]

; DI void store4(bf16_t* dst, const f32x4& v, float s) { *(u32x2*)dst = (u32x2){pk2(v[0] * s, v[1] * s), pk2(v[2] * s, v[3] * s)}; }
; DI float rstd_from16(const float* p, float inv_n) {
;   const f32x4 a = *(const f32x4*)p, b = *(const f32x4*)(p + 4), c = *(const f32x4*)(p + 8), d = *(const f32x4*)(p + 12);
;   const float s = ((a[0] + a[1]) + (a[2] + a[3])) + ((b[0] + b[1]) + (b[2] + b[3])) + ((c[0] + c[1]) + (c[2] + c[3])) + ((d[0] + d[1]) + (d[2] + d[3]));
;   return rsqrtf(s * inv_n + EPS_);
; DI void ffnup_tile(const Params& p, int layer, int b, int mt, int tn, bf16_t* smem) {
;     ...
;     for (int i = 0; i < 8; ++i) {
;       const int row = wm * 128 + i * 16 + l15, s = s0 + row;
;       const float rs = (s >= 0 && s < S_) ? rstd_from16((const float*)(p.ws + O_SSQ) + ((size_t)b * S_ + s) * 16, 1.f / 1024.f) : 0.f;
; #pragma unroll
;       for (int j = 0; j < 4; ++j) store4(dstb + row * LDU + j * 16, acc[i][j], rs);
.LBB0_2098:
	s_or_b64 exec, exec, s[0:1]
	v_pk_mul_f32 v[24:25], v[24:25], v[34:35] op_sel_hi:[1,0]
	v_pk_mul_f32 v[26:27], v[26:27], v[34:35] op_sel_hi:[1,0]
	v_pk_mul_f32 v[20:21], v[20:21], v[34:35] op_sel_hi:[1,0]
	v_pk_mul_f32 v[22:23], v[22:23], v[34:35] op_sel_hi:[1,0]
	v_pk_mul_f32 v[12:13], v[12:13], v[34:35] op_sel_hi:[1,0]
	v_pk_mul_f32 v[14:15], v[14:15], v[34:35] op_sel_hi:[1,0]
	v_cvt_pk_bf16_f32 v24, v24, v25
	v_cvt_pk_bf16_f32 v25, v26, v27
	v_add_u32_e32 v26, 0x6000, v116
	v_cvt_pk_bf16_f32 v20, v20, v21
	v_cvt_pk_bf16_f32 v21, v22, v23
	v_cvt_pk_bf16_f32 v12, v12, v13
	v_cvt_pk_bf16_f32 v13, v14, v15
	v_pk_mul_f32 v[28:29], v[28:29], v[34:35] op_sel_hi:[1,0]
	v_pk_mul_f32 v[30:31], v[30:31], v[34:35] op_sel_hi:[1,0]
	ds_write2_b64 v26, v[20:21], v[12:13] offset0:200 offset1:204
	v_add_u32_e32 v12, 0x70, v117
	v_cvt_pk_bf16_f32 v28, v28, v29
	v_cvt_pk_bf16_f32 v29, v30, v31
	v_cmp_gt_u32_e32 vcc, s28, v12
	ds_write2_b64 v26, v[28:29], v[24:25] offset0:192 offset1:196
	s_and_saveexec_b64 s[0:1], vcc
	s_cbranch_execz .LBB0_2100
	v_or_b32_e32 v12, s2, v12
	v_mov_b32_e32 v13, s3
	v_lshlrev_b64 v[12:13], 6, v[12:13]
	v_lshl_add_u64 v[28:29], s[6:7], 0, v[12:13]
	v_bfe_u32 v244, v28, 6, 8
	v_lshlrev_b32_e32 v244, 3, v244
	v_add_u32_e32 v244, 0x24010, v244
	v_or_b32_e32 v246, 4, v28
	ds_read_b64 v[248:249], v244
	s_waitcnt lgkmcnt(0)
	v_cmp_ne_u32_e64 s[100:101], v248, v246
	s_nop 1
	s_and_saveexec_b64 s[98:99], s[100:101]
	s_cbranch_execz .LrcG1_7
	global_load_dwordx4 v[12:15], v[28:29], off
	global_load_dwordx4 v[20:23], v[28:29], off offset:16
	global_load_dwordx4 v[24:27], v[28:29], off offset:32
	s_nop 0
	global_load_dwordx4 v[28:31], v[28:29], off offset:48
	s_waitcnt vmcnt(3)
	v_mov_b32_e32 v32, v13
	v_mov_b32_e32 v33, v14
	v_mov_b32_e32 v13, v15
	s_waitcnt vmcnt(2)
	v_mov_b32_e32 v14, v21
	v_mov_b32_e32 v15, v22
	v_mov_b32_e32 v21, v23
	v_pk_add_f32 v[12:13], v[32:33], v[12:13]
	v_pk_add_f32 v[14:15], v[14:15], v[20:21]
	v_pk_add_f32 v[12:13], v[12:13], v[12:13] op_sel:[0,1] op_sel_hi:[1,0]
	v_pk_add_f32 v[14:15], v[14:15], v[14:15] op_sel:[0,1] op_sel_hi:[1,0]
	s_waitcnt vmcnt(1)
	v_add_f32_e32 v22, v24, v25
	v_add_f32_e32 v24, v26, v27
	s_waitcnt vmcnt(0)
	v_mov_b32_e32 v23, v30
	v_mov_b32_e32 v25, v31
	v_mov_b32_e32 v13, v28
	v_mov_b32_e32 v15, v29
	v_pk_add_f32 v[20:21], v[22:23], v[24:25]
	v_pk_add_f32 v[12:13], v[12:13], v[14:15]
	s_nop 0
	v_pk_add_f32 v[12:13], v[12:13], v[20:21]
	s_nop 0
	v_add_f32_e32 v12, v12, v13
	v_fmamk_f32 v12, v12, 0x3a800000, v168
	v_mul_f32_e32 v13, 0x4b800000, v12
	v_cmp_gt_f32_e32 vcc, s34, v12
	s_nop 1
	v_cndmask_b32_e32 v12, v12, v13, vcc
	v_rsq_f32_e32 v12, v12
	s_nop 0
	v_mul_f32_e32 v13, 0x45800000, v12
	v_cndmask_b32_e32 v32, v12, v13, vcc
	s_nop 0
	v_mov_b32_e32 v247, v32
	ds_write_b64 v244, v[246:247]

; __global__ void __launch_bounds__(NTHR, 2) mega_kernel(Params p) {
;   __shared__ __attribute__((aligned(16))) unsigned char smem[SMEM_BYTES];
;   __shared__ uint4 xb_words;
;   if (threadIdx.x == 0) xb_words = make_uint4(0u, 0u, 0u, 0u);
	.amdhsa_kernel _Z11mega_kernel6Params
		.amdhsa_group_segment_fixed_size 151568
		.amdhsa_private_segment_fixed_size 0
		.amdhsa_kernarg_size 472
		.amdhsa_user_sgpr_count 2
		.amdhsa_user_sgpr_dispatch_ptr 0
		.amdhsa_user_sgpr_queue_ptr 0
		.amdhsa_user_sgpr_kernarg_segment_ptr 1
		.amdhsa_user_sgpr_dispatch_id 0
		.amdhsa_user_sgpr_kernarg_preload_length 0
		.amdhsa_user_sgpr_kernarg_preload_offset 0
		.amdhsa_user_sgpr_private_segment_size 0
		.amdhsa_uses_dynamic_stack 0
		.amdhsa_enable_private_segment 0
		.amdhsa_system_sgpr_workgroup_id_x 1
		.amdhsa_system_sgpr_workgroup_id_y 0
		.amdhsa_system_sgpr_workgroup_id_z 0
		.amdhsa_system_sgpr_workgroup_info 0
		.amdhsa_system_vgpr_workitem_id 2
		.amdhsa_next_free_vgpr 256
		.amdhsa_next_free_sgpr 102
		.amdhsa_accum_offset 256
		.amdhsa_reserve_vcc 1
		.amdhsa_float_round_mode_32 0
		.amdhsa_float_round_mode_16_64 0
		.amdhsa_float_denorm_mode_32 3
		.amdhsa_float_denorm_mode_16_64 3
		.amdhsa_dx10_clamp 1
		.amdhsa_ieee_mode 1
		.amdhsa_fp16_overflow 0
		.amdhsa_tg_split 0
		.amdhsa_exception_fp_ieee_invalid_op 0
		.amdhsa_exception_fp_denorm_src 0
		.amdhsa_exception_fp_ieee_div_zero 0
		.amdhsa_exception_fp_ieee_overflow 0
		.amdhsa_exception_fp_ieee_underflow 0
		.amdhsa_exception_fp_ieee_inexact 0
		.amdhsa_exception_int_div_zero 0
	.end_amdhsa_kernel

; __global__ void __launch_bounds__(NTHR, 2) mega_kernel(Params p) {
;   __shared__ __attribute__((aligned(16))) unsigned char smem[SMEM_BYTES];
;   __shared__ uint4 xb_words;
;   if (threadIdx.x == 0) xb_words = make_uint4(0u, 0u, 0u, 0u);
amdhsa.kernels:
  - .agpr_count:     0
    .args:
      - .offset:         0
        .size:           216
        .value_kind:     by_value
      - .offset:         216
        .size:           4
        .value_kind:     hidden_block_count_x
      - .offset:         220
        .size:           4
        .value_kind:     hidden_block_count_y
      - .offset:         224
        .size:           4
        .value_kind:     hidden_block_count_z
      - .offset:         228
        .size:           2
        .value_kind:     hidden_group_size_x
      - .offset:         230
        .size:           2
        .value_kind:     hidden_group_size_y
      - .offset:         232
        .size:           2
        .value_kind:     hidden_group_size_z
      - .offset:         234
        .size:           2
        .value_kind:     hidden_remainder_x
      - .offset:         236
        .size:           2
        .value_kind:     hidden_remainder_y
      - .offset:         238
        .size:           2
        .value_kind:     hidden_remainder_z
      - .offset:         256
        .size:           8
        .value_kind:     hidden_global_offset_x
      - .offset:         264
        .size:           8
        .value_kind:     hidden_global_offset_y
      - .offset:         272
        .size:           8
        .value_kind:     hidden_global_offset_z
      - .offset:         280
        .size:           2
        .value_kind:     hidden_grid_dims
      - .offset:         304
        .size:           8
        .value_kind:     hidden_multigrid_sync_arg
    .group_segment_fixed_size: 151568
    .kernarg_segment_align: 8
    .kernarg_segment_size: 472
    .language:       OpenCL C
    .language_version:
      - 2
      - 0
    .max_flat_workgroup_size: 512
    .name:           _Z11mega_kernel6Params
    .private_segment_fixed_size: 0
    .sgpr_count:     108
    .sgpr_spill_count: 353
    .symbol:         _Z11mega_kernel6Params.kd
    .uniform_work_group_size: 1
    .uses_dynamic_stack: false
    .vgpr_count:     256
    .vgpr_spill_count: 0
    .wavefront_size: 64
